# k12: k11 + pass C gate loads prefetched through a 32/64-deep register window (serialized load-wait-store chain removed)
# speedup vs baseline: 1.0264x; 1.0139x over previous
; template <bool GLA>
; __device__ __forceinline__ void chunk_tile(const ChunkRaw& raw, const bf16x8 (&wfr)[2], const f32x4 (&bfr)[2], int h, int it, int row, int kq, float lg, float (&carry)[8], float (&bq)[8], float (&qv)[8], float (&kv)[8]) {
;     ...
;     if (GLA) {
;         const u32x4 gsel = (kq == 0) ? raw.g0 : (kq == 1) ? raw.g1 : (u32x4){0u, 0u, 0u, 0u};
;         const bf16x8 gfr = __builtin_bit_cast(bf16x8, gsel);
;         const f32x4 z0 = __builtin_amdgcn_mfma_f32_16x16x32_bf16(wfr[0], gfr, bfr[0], 0, 0, 0), z1 = __builtin_amdgcn_mfma_f32_16x16x32_bf16(wfr[1], gfr, bfr[1], 0, 0, 0);
;         const float z[8] = {z0[0], z0[1], z0[2], z0[3], z1[0], z1[1], z1[2], z1[3]};
; #pragma unroll
;         for (int j = 0; j < 8; ++j) {
;             float la = (fminf(z[j], 0.f) - __logf(1.0f + __expf(-fabsf(z[j])))) * (1.0f / 16.0f);
;             la += __int_as_float(__builtin_amdgcn_update_dpp(0, __float_as_int(la), 0x111, 0xf, 0xf, false));
;             la += __int_as_float(__builtin_amdgcn_update_dpp(0, __float_as_int(la), 0x112, 0xf, 0xf, false));
;             la += __int_as_float(__builtin_amdgcn_update_dpp(0, __float_as_int(la), 0x114, 0xf, 0xf, false));
;             la += __int_as_float(__builtin_amdgcn_update_dpp(0, __float_as_int(la), 0x118, 0xf, 0xf, false));
;             bq[j] = la + carry[j];
;             carry[j] += __int_as_float(__builtin_amdgcn_ds_bpermute((16 * kq + 15) * 4, __float_as_int(la)));
;             qv[j] = q[j] * qs; kv[j] = k[j];
;         }
; template <bool GLA>
; __device__ __forceinline__ void chunk_pass_c(const ChunkIn& ci, const float* wgl, int unit, unsigned char* wl, int lane, const float* Sb, const float* ng, bf16_t* omix) {
;     ...
;     for (int it = 0; it < 4; ++it) {
;         float bq[8], qv[8], kv[8];
;         chunk_tile<GLA>(raw[it], wfr, bfr, h, it, row, kq, lg, carry, bq, qv, kv);
;         float a[8], bneg[8], cpos[8], dneg[8];
; #pragma unroll
;         for (int j = 0; j < 8; ++j) { const float eb = __expf(bq[j]), enb = __expf(-bq[j]); a[j] = qv[j] * eb; bneg[j] = kv[j] * enb; cpos[j] = qv[j] * enb; dneg[j] = kv[j] * eb; }
;         qf[it] = __builtin_bit_cast(bf16x8, (u32x4){cvtpk(a[0], a[1]), cvtpk(a[2], a[3]), cvtpk(a[4], a[5]), cvtpk(a[6], a[7])});
;         kf[it] = __builtin_bit_cast(bf16x8, (u32x4){cvtpk(bneg[0], bneg[1]), cvtpk(bneg[2], bneg[3]), cvtpk(bneg[4], bneg[5]), cvtpk(bneg[6], bneg[7])});
.LBB0_213:
	s_andn2_saveexec_b64 s[6:7], s[6:7]
	s_or_b64 exec, exec, s[6:7]
	s_waitcnt vmcnt(1)
	v_mfma_f32_16x16x32_bf16 v[16:19], v[16:19], v[4:7], v[8:11]
	s_waitcnt vmcnt(0)
	v_lshlrev_b32_e32 v0, 16, v82
	v_and_b32_e32 v1, 0xffff0000, v82
	s_mov_b32 s8, 0x3e3504f3
	v_pk_mul_f32 v[138:139], v[0:1], s[8:9] op_sel_hi:[1,0]
	v_lshlrev_b32_e32 v0, 16, v83
	v_and_b32_e32 v1, 0xffff0000, v83
	s_mov_b32 s7, 0xbfb8aa3b
	v_pk_mul_f32 v[82:83], v[0:1], s[8:9] op_sel_hi:[1,0]
	v_lshlrev_b32_e32 v0, 16, v78
	v_and_b32_e32 v1, 0xffff0000, v78
	v_mfma_f32_16x16x32_bf16 v[10:13], v[20:23], v[4:7], v[12:15]
	v_mul_f32_e64 v5, |v16|, s7
	v_pk_mul_f32 v[126:127], v[0:1], s[8:9] op_sel_hi:[1,0]
	v_lshlrev_b32_e32 v0, 16, v79
	v_and_b32_e32 v1, 0xffff0000, v79
	v_exp_f32_e32 v5, v5
	v_pk_mul_f32 v[118:119], v[0:1], s[8:9] op_sel_hi:[1,0]
	v_lshlrev_b32_e32 v0, 16, v70
	v_and_b32_e32 v1, 0xffff0000, v70
	v_pk_mul_f32 v[140:141], v[0:1], s[8:9] op_sel_hi:[1,0]
	v_lshlrev_b32_e32 v0, 16, v71
	v_and_b32_e32 v1, 0xffff0000, v71
	v_lshlrev_b32_e32 v124, 16, v72
	v_and_b32_e32 v125, 0xffff0000, v72
	v_lshlrev_b32_e32 v26, 16, v73
	v_and_b32_e32 v27, 0xffff0000, v73
	v_pk_mul_f32 v[72:73], v[0:1], s[8:9] op_sel_hi:[1,0]
	v_lshlrev_b32_e32 v0, 16, v68
	v_and_b32_e32 v1, 0xffff0000, v68
	v_pk_mul_f32 v[70:71], v[0:1], s[8:9] op_sel_hi:[1,0]
	v_lshlrev_b32_e32 v0, 16, v69
	v_and_b32_e32 v1, 0xffff0000, v69
	v_add_f32_e32 v5, 1.0, v5
	v_pk_mul_f32 v[30:31], v[0:1], s[8:9] op_sel_hi:[1,0]
	v_add_f32_e32 v0, 0, v53
	v_cmp_gt_f32_e32 vcc, s96, v5
	v_mul_f32_e32 v1, 0x3fb8aa3b, v0
	v_exp_f32_e32 v68, v1
	v_cndmask_b32_e64 v6, 0, 32, vcc
	v_add_f32_e32 v1, 0, v55
	v_ldexp_f32 v5, v5, v6
	v_mul_f32_e32 v2, 0x3fb8aa3b, v1
	v_log_f32_e32 v5, v5
	v_exp_f32_e32 v69, v2
	v_add_f32_e32 v2, 0, v63
	v_mul_f32_e32 v3, 0x3fb8aa3b, v2
	v_lshlrev_b32_e32 v136, 16, v76
	v_and_b32_e32 v137, 0xffff0000, v76
	v_exp_f32_e32 v76, v3
	v_add_f32_e32 v3, 0, v75
	v_mul_f32_e32 v53, 0x3fb8aa3b, v3
	v_mul_f32_e32 v6, 0x3f317217, v5
	v_lshlrev_b32_e32 v78, 16, v77
	v_and_b32_e32 v79, 0xffff0000, v77
	v_exp_f32_e32 v77, v53
	v_add_f32_e32 v53, 0, v81
	v_fma_f32 v6, v5, s3, -v6
	v_mul_f32_e32 v55, 0x3fb8aa3b, v53
	v_fmac_f32_e32 v6, 0x3377d1cf, v5
	s_mov_b32 s6, 0x7f800000
	v_lshlrev_b32_e32 v122, 16, v84
	v_and_b32_e32 v123, 0xffff0000, v84
	v_exp_f32_e32 v84, v55
	v_add_f32_e32 v55, 0, v91
	v_fmac_f32_e32 v6, 0x3f317217, v5
	v_cmp_lt_f32_e64 s[42:43], |v5|, s6
	v_mul_f32_e32 v63, 0x3fb8aa3b, v55
	v_max_f32_e32 v4, v16, v16
	v_cndmask_b32_e64 v5, v5, v6, s[42:43]
	v_cndmask_b32_e32 v6, 0, v237, vcc
	v_lshlrev_b32_e32 v116, 16, v85
	v_and_b32_e32 v117, 0xffff0000, v85
	v_exp_f32_e32 v85, v63
	v_add_f32_e32 v63, 0, v93
	v_min_f32_e32 v4, 0, v4
	v_sub_f32_e32 v5, v5, v6
	v_mul_f32_e32 v75, 0x3fb8aa3b, v63
	v_sub_f32_e32 v4, v4, v5
	v_exp_f32_e32 v144, v75
	v_add_f32_e32 v75, 0, v99
	v_mul_f32_e32 v6, 0x3d800000, v4
	v_mov_b32_e32 v5, v211
	v_mul_f32_e32 v81, 0x3fb8aa3b, v75
	v_exp_f32_e32 v145, v81
	v_mov_b32_dpp v5, v6 row_shr:1 row_mask:0xf bank_mask:0xf
	v_fmac_f32_e32 v5, 0x3d800000, v4
	v_mov_b32_e32 v81, v211
	v_mov_b32_e32 v4, v211
	v_mov_b32_e32 v93, v211
	v_mov_b32_dpp v81, v5 row_shr:2 row_mask:0xf bank_mask:0xf
	s_waitcnt lgkmcnt(14)
	v_pk_add_f32 v[4:5], v[4:5], v[80:81]
	v_mov_b32_e32 v99, v211
	v_mul_f32_e32 v0, 0xbfb8aa3b, v0
	v_mov_b32_dpp v93, v5 row_shr:4 row_mask:0xf bank_mask:0xf
	v_pk_add_f32 v[6:7], v[4:5], v[92:93]
	v_add_f32_e32 v4, v4, v89
	v_add_f32_e32 v5, v6, v133
	v_mul_f32_e32 v8, 0x3fb8aa3b, v5
	v_mul_f32_e32 v5, 0xbfb8aa3b, v5
	v_exp_f32_e32 v16, v5
	v_mul_f32_e32 v5, 0x3fb8aa3b, v4
	v_mul_f32_e32 v4, 0xbfb8aa3b, v4
	v_mov_b32_dpp v99, v7 row_shr:8 row_mask:0xf bank_mask:0xf
	v_exp_f32_e32 v20, v5
	v_exp_f32_e32 v22, v4
	s_waitcnt lgkmcnt(7)
	v_pk_add_f32 v[4:5], v[6:7], v[98:99]
	v_exp_f32_e32 v102, v0
	v_add_f32_e32 v14, v4, v5
	v_mul_f32_e64 v5, |v17|, s7
	v_exp_f32_e32 v5, v5
	v_mul_f32_e32 v0, 0xbfb8aa3b, v1
	v_exp_f32_e32 v103, v0
	v_mul_f32_e32 v0, 0xbfb8aa3b, v2
	v_add_f32_e32 v5, 1.0, v5
	v_exp_f32_e32 v104, v0
	v_mul_f32_e32 v0, 0xbfb8aa3b, v3
	v_cmp_gt_f32_e32 vcc, s96, v5
	v_exp_f32_e32 v105, v0
	v_mul_f32_e32 v0, 0xbfb8aa3b, v53
	v_cndmask_b32_e64 v6, 0, 32, vcc
	v_exp_f32_e32 v112, v0
	v_mul_f32_e32 v0, 0xbfb8aa3b, v55
	v_ldexp_f32 v5, v5, v6
	v_exp_f32_e32 v113, v0
	v_mul_f32_e32 v0, 0xbfb8aa3b, v63
	v_log_f32_e32 v5, v5
	v_exp_f32_e32 v148, v0
	v_mul_f32_e32 v0, 0xbfb8aa3b, v75
	v_exp_f32_e32 v149, v0
	v_lshlrev_b32_e32 v0, 16, v66
	v_and_b32_e32 v1, 0xffff0000, v66
	v_pk_mul_f32 v[2:3], v[68:69], v[0:1]
	v_mul_f32_e32 v6, 0x3f317217, v5
	v_cvt_pk_bf16_f32 v106, v2, v3
	v_lshlrev_b32_e32 v2, 16, v67
	v_and_b32_e32 v3, 0xffff0000, v67
	v_pk_mul_f32 v[0:1], v[102:103], v[0:1]
	v_pk_mul_f32 v[66:67], v[76:77], v[2:3]
	v_pk_mul_f32 v[2:3], v[104:105], v[2:3]
	v_fma_f32 v6, v5, s3, -v6
	v_cvt_pk_bf16_f32 v0, v0, v1
	v_cvt_pk_bf16_f32 v1, v2, v3
	v_lshlrev_b32_e32 v2, 16, v64
	v_and_b32_e32 v3, 0xffff0000, v64
	v_fmac_f32_e32 v6, 0x3377d1cf, v5
	v_cvt_pk_bf16_f32 v107, v66, v67
	v_pk_mul_f32 v[66:67], v[84:85], v[2:3]
	v_lshlrev_b32_e32 v64, 16, v65
	v_and_b32_e32 v65, 0xffff0000, v65
	v_fmac_f32_e32 v6, 0x3f317217, v5
	v_cmp_lt_f32_e64 s[42:43], |v5|, s6
	v_cvt_pk_bf16_f32 v108, v66, v67
	v_pk_mul_f32 v[2:3], v[112:113], v[2:3]
	v_pk_mul_f32 v[66:67], v[144:145], v[64:65]
	v_pk_mul_f32 v[64:65], v[148:149], v[64:65]
	v_max_f32_e32 v4, v17, v17
	v_cndmask_b32_e64 v5, v5, v6, s[42:43]
	v_cndmask_b32_e32 v6, 0, v237, vcc
	v_cvt_pk_bf16_f32 v2, v2, v3
	v_cvt_pk_bf16_f32 v3, v64, v65
	v_lshlrev_b32_e32 v64, 16, v60
	v_and_b32_e32 v65, 0xffff0000, v60
; template <bool GLA>
; __device__ __forceinline__ void chunk_tile(const ChunkRaw& raw, const bf16x8 (&wfr)[2], const f32x4 (&bfr)[2], int h, int it, int row, int kq, float lg, float (&carry)[8], float (&bq)[8], float (&qv)[8], float (&kv)[8]) {
;     ...
;     if (GLA) {
;         const u32x4 gsel = (kq == 0) ? raw.g0 : (kq == 1) ? raw.g1 : (u32x4){0u, 0u, 0u, 0u};
;         const bf16x8 gfr = __builtin_bit_cast(bf16x8, gsel);
;         const f32x4 z0 = __builtin_amdgcn_mfma_f32_16x16x32_bf16(wfr[0], gfr, bfr[0], 0, 0, 0), z1 = __builtin_amdgcn_mfma_f32_16x16x32_bf16(wfr[1], gfr, bfr[1], 0, 0, 0);
;         const float z[8] = {z0[0], z0[1], z0[2], z0[3], z1[0], z1[1], z1[2], z1[3]};
; #pragma unroll
;         for (int j = 0; j < 8; ++j) {
;             float la = (fminf(z[j], 0.f) - __logf(1.0f + __expf(-fabsf(z[j])))) * (1.0f / 16.0f);
;             la += __int_as_float(__builtin_amdgcn_update_dpp(0, __float_as_int(la), 0x111, 0xf, 0xf, false));
;             la += __int_as_float(__builtin_amdgcn_update_dpp(0, __float_as_int(la), 0x112, 0xf, 0xf, false));
;             la += __int_as_float(__builtin_amdgcn_update_dpp(0, __float_as_int(la), 0x114, 0xf, 0xf, false));
;             la += __int_as_float(__builtin_amdgcn_update_dpp(0, __float_as_int(la), 0x118, 0xf, 0xf, false));
;             bq[j] = la + carry[j];
;             carry[j] += __int_as_float(__builtin_amdgcn_ds_bpermute((16 * kq + 15) * 4, __float_as_int(la)));
;             qv[j] = q[j] * qs; kv[j] = k[j];
;         }
; template <bool GLA>
; __device__ __forceinline__ void chunk_pass_c(const ChunkIn& ci, const float* wgl, int unit, unsigned char* wl, int lane, const float* Sb, const float* ng, bf16_t* omix) {
;     ...
;     for (int it = 0; it < 4; ++it) {
;         float bq[8], qv[8], kv[8];
;         chunk_tile<GLA>(raw[it], wfr, bfr, h, it, row, kq, lg, carry, bq, qv, kv);
;         float a[8], bneg[8], cpos[8], dneg[8];
; #pragma unroll
;         for (int j = 0; j < 8; ++j) { const float eb = __expf(bq[j]), enb = __expf(-bq[j]); a[j] = qv[j] * eb; bneg[j] = kv[j] * enb; cpos[j] = qv[j] * enb; dneg[j] = kv[j] * eb; }
;         qf[it] = __builtin_bit_cast(bf16x8, (u32x4){cvtpk(a[0], a[1]), cvtpk(a[2], a[3]), cvtpk(a[4], a[5]), cvtpk(a[6], a[7])});
;         kf[it] = __builtin_bit_cast(bf16x8, (u32x4){cvtpk(bneg[0], bneg[1]), cvtpk(bneg[2], bneg[3]), cvtpk(bneg[4], bneg[5]), cvtpk(bneg[6], bneg[7])});
	v_min_f32_e32 v4, 0, v4
	v_sub_f32_e32 v5, v5, v6
	v_pk_mul_f32 v[64:65], v[64:65], s[8:9] op_sel_hi:[1,0]
	v_lshlrev_b32_e32 v60, 16, v61
	v_and_b32_e32 v61, 0xffff0000, v61
	v_sub_f32_e32 v4, v4, v5
	v_cvt_pk_bf16_f32 v109, v66, v67
	v_pk_mul_f32 v[66:67], v[64:65], v[102:103]
	v_pk_mul_f32 v[64:65], v[64:65], v[68:69]
	v_pk_mul_f32 v[60:61], v[60:61], s[8:9] op_sel_hi:[1,0]
	v_mul_f32_e32 v6, 0x3d800000, v4
	v_mov_b32_e32 v5, v211
	v_cvt_pk_bf16_f32 v102, v64, v65
	v_pk_mul_f32 v[64:65], v[60:61], v[104:105]
	v_pk_mul_f32 v[60:61], v[60:61], v[76:77]
	v_mov_b32_dpp v5, v6 row_shr:1 row_mask:0xf bank_mask:0xf
	v_cvt_pk_bf16_f32 v103, v60, v61
	v_lshlrev_b32_e32 v60, 16, v58
	v_and_b32_e32 v61, 0xffff0000, v58
	v_fmac_f32_e32 v5, 0x3d800000, v4
	v_mov_b32_e32 v75, v211
	v_pk_mul_f32 v[60:61], v[60:61], s[8:9] op_sel_hi:[1,0]
	v_lshlrev_b32_e32 v58, 16, v59
	v_and_b32_e32 v59, 0xffff0000, v59
	v_mov_b32_dpp v75, v5 row_shr:2 row_mask:0xf bank_mask:0xf
	v_mov_b32_e32 v4, v211
	v_cvt_pk_bf16_f32 v111, v64, v65
	v_pk_mul_f32 v[64:65], v[60:61], v[112:113]
	v_pk_mul_f32 v[60:61], v[60:61], v[84:85]
	v_pk_mul_f32 v[58:59], v[58:59], s[8:9] op_sel_hi:[1,0]
	v_pk_add_f32 v[6:7], v[4:5], v[74:75]
	v_mov_b32_e32 v89, v211
	v_cvt_pk_bf16_f32 v104, v60, v61
	v_pk_mul_f32 v[60:61], v[58:59], v[148:149]
	v_pk_mul_f32 v[58:59], v[58:59], v[144:145]
	v_mov_b32_dpp v89, v7 row_shr:4 row_mask:0xf bank_mask:0xf
	v_cvt_pk_bf16_f32 v105, v58, v59
	v_pk_add_f32 v[58:59], v[6:7], v[88:89]
	v_exp_f32_e32 v8, v8
	v_add_f32_e32 v4, v58, v131
	v_mul_f32_e32 v5, 0x3fb8aa3b, v4
	v_exp_f32_e32 v9, v5
	v_mul_f32_e32 v4, 0xbfb8aa3b, v4
	v_exp_f32_e32 v17, v4
	v_lshlrev_b32_e32 v134, 16, v86
	v_and_b32_e32 v135, 0xffff0000, v86
	v_pk_mul_f32 v[4:5], v[8:9], v[134:135]
	v_pk_mul_f32 v[8:9], v[138:139], v[8:9]
	v_cvt_pk_bf16_f32 v84, v4, v5
	v_pk_mul_f32 v[4:5], v[16:17], v[134:135]
	v_cvt_pk_bf16_f32 v76, v8, v9
	v_cvt_pk_bf16_f32 v4, v4, v5
	v_add_f32_e32 v5, v6, v57
	v_mul_f32_e32 v6, 0x3fb8aa3b, v5
	v_exp_f32_e32 v21, v6
	v_mul_f32_e32 v5, 0xbfb8aa3b, v5
	v_exp_f32_e32 v23, v5
	v_mov_b32_e32 v133, v211
	v_pk_mul_f32 v[6:7], v[20:21], v[136:137]
	v_max_f32_e32 v5, v18, v18
	v_cvt_pk_bf16_f32 v98, v6, v7
	v_pk_mul_f32 v[6:7], v[22:23], v[136:137]
	v_mov_b32_dpp v133, v59 row_shr:8 row_mask:0xf bank_mask:0xf
	v_cvt_pk_bf16_f32 v8, v6, v7
	v_pk_mul_f32 v[6:7], v[140:141], v[22:23]
	v_min_f32_e32 v5, 0, v5
	v_cvt_pk_bf16_f32 v92, v6, v7
	v_pk_mul_f32 v[6:7], v[140:141], v[20:21]
	v_mov_b32_e32 v63, v211
	v_cvt_pk_bf16_f32 v88, v6, v7
	s_waitcnt lgkmcnt(6)
	v_pk_add_f32 v[6:7], v[58:59], v[132:133]
	v_mov_b32_e32 v95, v211
	v_add_f32_e32 v15, v6, v7
	v_mul_f32_e64 v6, |v18|, s7
	v_exp_f32_e32 v6, v6
	v_pk_mul_f32 v[16:17], v[138:139], v[16:17]
	v_mov_b32_e32 v131, v211
	v_cvt_pk_bf16_f32 v80, v16, v17
	v_add_f32_e32 v6, 1.0, v6
	v_cmp_gt_f32_e32 vcc, s96, v6
	v_mov_b32_e32 v57, v211
	v_mov_b32_e32 v91, v211
	v_cndmask_b32_e64 v7, 0, 32, vcc
	v_ldexp_f32 v6, v6, v7
	v_log_f32_e32 v6, v6
	v_mov_b32_e32 v55, v211
	v_lshlrev_b32_e32 v86, 16, v87
	v_and_b32_e32 v87, 0xffff0000, v87
	v_mul_f32_e32 v7, 0x3f317217, v6
	v_fma_f32 v7, v6, s3, -v7
	v_fmac_f32_e32 v7, 0x3377d1cf, v6
	v_fmac_f32_e32 v7, 0x3f317217, v6
	v_cmp_lt_f32_e64 s[42:43], |v6|, s6
	v_cvt_pk_bf16_f32 v113, v60, v61
	v_mov_b32_e32 v53, v211
	v_cndmask_b32_e64 v6, v6, v7, s[42:43]
	v_cndmask_b32_e32 v7, 0, v237, vcc
	v_sub_f32_e32 v6, v6, v7
	v_sub_f32_e32 v5, v5, v6
	v_mul_f32_e32 v6, 0x3d800000, v5
	v_mov_b32_e32 v7, v211
	s_waitcnt vmcnt(0) expcnt(0) lgkmcnt(0)
	v_lshlrev_b32_e32 v224, 1, v156
	v_mov_b32_e32 v225, v211
	v_or_b32_e32 v226, s5, v97
	v_ashrrev_i32_e32 v227, 31, v226
	v_lshlrev_b64 v[228:229], 12, v[226:227]
	v_lshl_add_u64 v[230:231], s[58:59], 0, v[228:229]
	v_lshl_add_u64 v[232:233], v[230:231], 0, v[224:225]
	global_load_ushort v157, v[232:233], off offset:1888
	v_lshlrev_b32_e32 v224, 1, v156
	v_mov_b32_e32 v225, v211
	v_or_b32_e32 v226, s5, v97
	v_ashrrev_i32_e32 v227, 31, v226
	v_lshlrev_b64 v[228:229], 12, v[226:227]
	v_lshl_add_u64 v[230:231], s[58:59], 0, v[228:229]
	v_lshl_add_u64 v[232:233], v[230:231], 0, v[224:225]
	global_load_ushort v158, v[232:233], off offset:1920
	v_lshlrev_b32_e32 v224, 1, v156
	v_mov_b32_e32 v225, v211
	v_or_b32_e32 v226, s5, v97
	v_ashrrev_i32_e32 v227, 31, v226
	v_lshlrev_b64 v[228:229], 12, v[226:227]
	v_lshl_add_u64 v[230:231], s[58:59], 0, v[228:229]
	v_lshl_add_u64 v[232:233], v[230:231], 0, v[224:225]
	global_load_ushort v159, v[232:233], off offset:1952
	v_or_b32_e32 v224, 48, v147
	v_or_b32_e32 v226, s5, v97
	v_ashrrev_i32_e32 v227, 31, v226
	v_lshlrev_b64 v[228:229], 12, v[226:227]
	v_lshl_add_u64 v[230:231], s[58:59], 0, v[228:229]
	v_lshlrev_b32_e32 v228, 1, v224
	v_mov_b32_e32 v229, v211
	v_lshl_add_u64 v[224:225], v[230:231], 0, v[228:229]
	global_load_ushort v160, v[224:225], off offset:1888
	v_lshlrev_b32_e32 v224, 1, v156
	v_mov_b32_e32 v225, v211
	v_or_b32_e32 v226, s5, v97
	v_or_b32_e32 v228, 1, v226
	v_ashrrev_i32_e32 v229, 31, v228
	v_lshlrev_b64 v[230:231], 12, v[228:229]
	v_lshl_add_u64 v[230:231], s[58:59], 0, v[230:231]
	v_lshl_add_u64 v[232:233], v[230:231], 0, v[224:225]
	global_load_ushort v161, v[232:233], off offset:1888
	v_lshlrev_b32_e32 v224, 1, v156
	v_mov_b32_e32 v225, v211
	v_or_b32_e32 v226, s5, v97
	v_or_b32_e32 v228, 1, v226
	v_ashrrev_i32_e32 v229, 31, v228
	v_lshlrev_b64 v[230:231], 12, v[228:229]
	v_lshl_add_u64 v[230:231], s[58:59], 0, v[230:231]
	v_lshl_add_u64 v[232:233], v[230:231], 0, v[224:225]
	global_load_ushort v162, v[232:233], off offset:1920
	v_lshlrev_b32_e32 v224, 1, v156
	v_mov_b32_e32 v225, v211
; template <bool GLA>
; __device__ __forceinline__ void chunk_pass_c(const ChunkIn& ci, const float* wgl, int unit, unsigned char* wl, int lane, const float* Sb, const float* ng, bf16_t* omix) {
;     ...
;                 const float gt = __uint_as_float((unsigned)ci.proj[(size_t)t * DINP + gcol + e] << 16);
	v_or_b32_e32 v226, s5, v97
	v_or_b32_e32 v228, 1, v226
	v_ashrrev_i32_e32 v229, 31, v228
	v_lshlrev_b64 v[230:231], 12, v[228:229]
	v_lshl_add_u64 v[230:231], s[58:59], 0, v[230:231]
	v_lshl_add_u64 v[232:233], v[230:231], 0, v[224:225]
	global_load_ushort v163, v[232:233], off offset:1952
	v_or_b32_e32 v224, 48, v147
	v_or_b32_e32 v226, s5, v97
	v_lshlrev_b32_e32 v228, 1, v224
	v_mov_b32_e32 v229, v211
	v_or_b32_e32 v230, 1, v226
	v_ashrrev_i32_e32 v231, 31, v230
	v_lshlrev_b64 v[232:233], 12, v[230:231]
	v_lshl_add_u64 v[232:233], s[58:59], 0, v[232:233]
	v_lshl_add_u64 v[242:243], v[232:233], 0, v[228:229]
	global_load_ushort v164, v[242:243], off offset:1888
	v_lshlrev_b32_e32 v224, 1, v156
	v_mov_b32_e32 v225, v211
	v_or_b32_e32 v226, s5, v97
	v_or_b32_e32 v228, 2, v226
	v_ashrrev_i32_e32 v229, 31, v228
	v_lshlrev_b64 v[230:231], 12, v[228:229]
	v_lshl_add_u64 v[230:231], s[58:59], 0, v[230:231]
	v_lshl_add_u64 v[232:233], v[230:231], 0, v[224:225]
	global_load_ushort v165, v[232:233], off offset:1888
	v_lshlrev_b32_e32 v224, 1, v156
	v_mov_b32_e32 v225, v211
	v_or_b32_e32 v226, s5, v97
	v_or_b32_e32 v228, 2, v226
	v_ashrrev_i32_e32 v229, 31, v228
	v_lshlrev_b64 v[230:231], 12, v[228:229]
	v_lshl_add_u64 v[230:231], s[58:59], 0, v[230:231]
	v_lshl_add_u64 v[232:233], v[230:231], 0, v[224:225]
	global_load_ushort v166, v[232:233], off offset:1920
	v_lshlrev_b32_e32 v224, 1, v156
	v_mov_b32_e32 v225, v211
	v_or_b32_e32 v226, s5, v97
	v_or_b32_e32 v228, 2, v226
	v_ashrrev_i32_e32 v229, 31, v228
	v_lshlrev_b64 v[230:231], 12, v[228:229]
	v_lshl_add_u64 v[230:231], s[58:59], 0, v[230:231]
	v_lshl_add_u64 v[232:233], v[230:231], 0, v[224:225]
	global_load_ushort v167, v[232:233], off offset:1952
	v_or_b32_e32 v224, 48, v147
	v_or_b32_e32 v226, s5, v97
	v_lshlrev_b32_e32 v228, 1, v224
	v_mov_b32_e32 v229, v211
	v_or_b32_e32 v230, 2, v226
	v_ashrrev_i32_e32 v231, 31, v230
	v_lshlrev_b64 v[232:233], 12, v[230:231]
	v_lshl_add_u64 v[232:233], s[58:59], 0, v[232:233]
	v_lshl_add_u64 v[232:233], v[232:233], 0, v[228:229]
	global_load_ushort v168, v[232:233], off offset:1888
	v_lshlrev_b32_e32 v224, 1, v156
	v_mov_b32_e32 v225, v211
	v_or_b32_e32 v226, s5, v97
	v_or_b32_e32 v228, 3, v226
	v_ashrrev_i32_e32 v229, 31, v228
	v_lshlrev_b64 v[230:231], 12, v[228:229]
	v_lshl_add_u64 v[230:231], s[58:59], 0, v[230:231]
	v_lshl_add_u64 v[232:233], v[230:231], 0, v[224:225]
	global_load_ushort v169, v[232:233], off offset:1888
	v_lshlrev_b32_e32 v224, 1, v156
	v_mov_b32_e32 v225, v211
	v_or_b32_e32 v226, s5, v97
	v_or_b32_e32 v228, 3, v226
	v_ashrrev_i32_e32 v229, 31, v228
	v_lshlrev_b64 v[230:231], 12, v[228:229]
	v_lshl_add_u64 v[230:231], s[58:59], 0, v[230:231]
	v_lshl_add_u64 v[232:233], v[230:231], 0, v[224:225]
	global_load_ushort v170, v[232:233], off offset:1920
	v_lshlrev_b32_e32 v224, 1, v156
	v_mov_b32_e32 v225, v211
	v_or_b32_e32 v226, s5, v97
	v_or_b32_e32 v228, 3, v226
	v_ashrrev_i32_e32 v229, 31, v228
	v_lshlrev_b64 v[230:231], 12, v[228:229]
	v_lshl_add_u64 v[230:231], s[58:59], 0, v[230:231]
	v_lshl_add_u64 v[232:233], v[230:231], 0, v[224:225]
	global_load_ushort v171, v[232:233], off offset:1952
	v_or_b32_e32 v224, 48, v147
	v_or_b32_e32 v226, s5, v97
	v_lshlrev_b32_e32 v228, 1, v224
	v_mov_b32_e32 v229, v211
	v_or_b32_e32 v230, 3, v226
	v_ashrrev_i32_e32 v231, 31, v230
	v_lshlrev_b64 v[232:233], 12, v[230:231]
	v_lshl_add_u64 v[232:233], s[58:59], 0, v[232:233]
	v_lshl_add_u64 v[232:233], v[232:233], 0, v[228:229]
	global_load_ushort v172, v[232:233], off offset:1888
	v_lshlrev_b32_e32 v224, 1, v156
	v_mov_b32_e32 v225, v211
	v_or_b32_e32 v226, s4, v97
	v_ashrrev_i32_e32 v227, 31, v226
	v_lshlrev_b64 v[228:229], 12, v[226:227]
	v_lshl_add_u64 v[230:231], s[58:59], 0, v[228:229]
	v_lshl_add_u64 v[228:229], v[230:231], 0, v[224:225]
	global_load_ushort v173, v[228:229], off offset:1888
	v_lshlrev_b32_e32 v224, 1, v156
	v_mov_b32_e32 v225, v211
	v_or_b32_e32 v226, s4, v97
	v_ashrrev_i32_e32 v227, 31, v226
	v_lshlrev_b64 v[228:229], 12, v[226:227]
	v_lshl_add_u64 v[230:231], s[58:59], 0, v[228:229]
	v_lshl_add_u64 v[228:229], v[230:231], 0, v[224:225]
	global_load_ushort v174, v[228:229], off offset:1920
	v_lshlrev_b32_e32 v224, 1, v156
	v_mov_b32_e32 v225, v211
	v_or_b32_e32 v226, s4, v97
	v_ashrrev_i32_e32 v227, 31, v226
	v_lshlrev_b64 v[228:229], 12, v[226:227]
	v_lshl_add_u64 v[230:231], s[58:59], 0, v[228:229]
	v_lshl_add_u64 v[228:229], v[230:231], 0, v[224:225]
	global_load_ushort v175, v[228:229], off offset:1952
	v_or_b32_e32 v224, 48, v147
	v_lshlrev_b32_e32 v226, 1, v224
	v_mov_b32_e32 v227, v211
	v_or_b32_e32 v228, s4, v97
	v_ashrrev_i32_e32 v229, 31, v228
	v_lshlrev_b64 v[230:231], 12, v[228:229]
	v_lshl_add_u64 v[232:233], s[58:59], 0, v[230:231]
	v_lshl_add_u64 v[242:243], v[232:233], 0, v[226:227]
	global_load_ushort v176, v[242:243], off offset:1888
	v_lshlrev_b32_e32 v224, 1, v156
	v_mov_b32_e32 v225, v211
	v_or_b32_e32 v226, s4, v97
	v_or_b32_e32 v228, 1, v226
	v_ashrrev_i32_e32 v229, 31, v228
	v_lshlrev_b64 v[230:231], 12, v[228:229]
	v_lshl_add_u64 v[230:231], s[58:59], 0, v[230:231]
	v_lshl_add_u64 v[232:233], v[230:231], 0, v[224:225]
	global_load_ushort v177, v[232:233], off offset:1888
	v_lshlrev_b32_e32 v224, 1, v156
	v_mov_b32_e32 v225, v211
	v_or_b32_e32 v226, s4, v97
	v_or_b32_e32 v228, 1, v226
	v_ashrrev_i32_e32 v229, 31, v228
	v_lshlrev_b64 v[230:231], 12, v[228:229]
	v_lshl_add_u64 v[230:231], s[58:59], 0, v[230:231]
	v_lshl_add_u64 v[232:233], v[230:231], 0, v[224:225]
	global_load_ushort v178, v[232:233], off offset:1920
	v_lshlrev_b32_e32 v224, 1, v156
	v_mov_b32_e32 v225, v211
	v_or_b32_e32 v226, s4, v97
; template <bool GLA>
; __device__ __forceinline__ void chunk_pass_c(const ChunkIn& ci, const float* wgl, int unit, unsigned char* wl, int lane, const float* Sb, const float* ng, bf16_t* omix) {
;     ...
;                 const float gt = __uint_as_float((unsigned)ci.proj[(size_t)t * DINP + gcol + e] << 16);
	v_or_b32_e32 v228, 1, v226
	v_ashrrev_i32_e32 v229, 31, v228
	v_lshlrev_b64 v[230:231], 12, v[228:229]
	v_lshl_add_u64 v[230:231], s[58:59], 0, v[230:231]
	v_lshl_add_u64 v[232:233], v[230:231], 0, v[224:225]
	global_load_ushort v179, v[232:233], off offset:1952
	v_or_b32_e32 v224, 48, v147
	v_lshlrev_b32_e32 v226, 1, v224
	v_mov_b32_e32 v227, v211
	v_or_b32_e32 v228, s4, v97
	v_or_b32_e32 v230, 1, v228
	v_ashrrev_i32_e32 v231, 31, v230
	v_lshlrev_b64 v[232:233], 12, v[230:231]
	v_lshl_add_u64 v[232:233], s[58:59], 0, v[232:233]
	v_lshl_add_u64 v[242:243], v[232:233], 0, v[226:227]
	global_load_ushort v180, v[242:243], off offset:1888
	v_lshlrev_b32_e32 v224, 1, v156
	v_mov_b32_e32 v225, v211
	v_or_b32_e32 v226, s4, v97
	v_or_b32_e32 v228, 2, v226
	v_ashrrev_i32_e32 v229, 31, v228
	v_lshlrev_b64 v[230:231], 12, v[228:229]
	v_lshl_add_u64 v[230:231], s[58:59], 0, v[230:231]
	v_lshl_add_u64 v[232:233], v[230:231], 0, v[224:225]
	global_load_ushort v181, v[232:233], off offset:1888
	v_lshlrev_b32_e32 v224, 1, v156
	v_mov_b32_e32 v225, v211
	v_or_b32_e32 v226, s4, v97
	v_or_b32_e32 v228, 2, v226
	v_ashrrev_i32_e32 v229, 31, v228
	v_lshlrev_b64 v[230:231], 12, v[228:229]
	v_lshl_add_u64 v[230:231], s[58:59], 0, v[230:231]
	v_lshl_add_u64 v[232:233], v[230:231], 0, v[224:225]
	global_load_ushort v182, v[232:233], off offset:1920
	v_lshlrev_b32_e32 v224, 1, v156
	v_mov_b32_e32 v225, v211
	v_or_b32_e32 v226, s4, v97
	v_or_b32_e32 v228, 2, v226
	v_ashrrev_i32_e32 v229, 31, v228
	v_lshlrev_b64 v[230:231], 12, v[228:229]
	v_lshl_add_u64 v[230:231], s[58:59], 0, v[230:231]
	v_lshl_add_u64 v[232:233], v[230:231], 0, v[224:225]
	global_load_ushort v183, v[232:233], off offset:1952
	v_or_b32_e32 v224, 48, v147
	v_lshlrev_b32_e32 v226, 1, v224
	v_mov_b32_e32 v227, v211
	v_or_b32_e32 v228, s4, v97
	v_or_b32_e32 v230, 2, v228
	v_ashrrev_i32_e32 v231, 31, v230
	v_lshlrev_b64 v[232:233], 12, v[230:231]
	v_lshl_add_u64 v[232:233], s[58:59], 0, v[232:233]
	v_lshl_add_u64 v[232:233], v[232:233], 0, v[226:227]
	global_load_ushort v184, v[232:233], off offset:1888
	v_lshlrev_b32_e32 v224, 1, v156
	v_mov_b32_e32 v225, v211
	v_or_b32_e32 v226, s4, v97
	v_or_b32_e32 v228, 3, v226
	v_ashrrev_i32_e32 v229, 31, v228
	v_lshlrev_b64 v[230:231], 12, v[228:229]
	v_lshl_add_u64 v[230:231], s[58:59], 0, v[230:231]
	v_lshl_add_u64 v[232:233], v[230:231], 0, v[224:225]
	global_load_ushort v185, v[232:233], off offset:1888
	v_lshlrev_b32_e32 v224, 1, v156
	v_mov_b32_e32 v225, v211
	v_or_b32_e32 v226, s4, v97
	v_or_b32_e32 v228, 3, v226
	v_ashrrev_i32_e32 v229, 31, v228
	v_lshlrev_b64 v[230:231], 12, v[228:229]
	v_lshl_add_u64 v[230:231], s[58:59], 0, v[230:231]
	v_lshl_add_u64 v[232:233], v[230:231], 0, v[224:225]
	global_load_ushort v186, v[232:233], off offset:1920
	v_lshlrev_b32_e32 v224, 1, v156
	v_mov_b32_e32 v225, v211
	v_or_b32_e32 v226, s4, v97
	v_or_b32_e32 v228, 3, v226
	v_ashrrev_i32_e32 v229, 31, v228
	v_lshlrev_b64 v[230:231], 12, v[228:229]
	v_lshl_add_u64 v[230:231], s[58:59], 0, v[230:231]
	v_lshl_add_u64 v[232:233], v[230:231], 0, v[224:225]
	global_load_ushort v187, v[232:233], off offset:1952
	v_or_b32_e32 v224, 48, v147
	v_lshlrev_b32_e32 v226, 1, v224
	v_mov_b32_e32 v227, v211
	v_or_b32_e32 v228, s4, v97
	v_or_b32_e32 v230, 3, v228
	v_ashrrev_i32_e32 v231, 31, v230
	v_lshlrev_b64 v[232:233], 12, v[230:231]
	v_lshl_add_u64 v[232:233], s[58:59], 0, v[232:233]
	v_lshl_add_u64 v[232:233], v[232:233], 0, v[226:227]
	global_load_ushort v188, v[232:233], off offset:1888
	v_lshlrev_b32_e32 v224, 1, v156
	v_mov_b32_e32 v225, v211
	v_or_b32_e32 v226, s65, v97
	v_ashrrev_i32_e32 v227, 31, v226
	v_lshlrev_b64 v[228:229], 12, v[226:227]
	v_lshl_add_u64 v[230:231], s[58:59], 0, v[228:229]
	v_lshl_add_u64 v[228:229], v[230:231], 0, v[224:225]
	global_load_ushort v189, v[228:229], off offset:1888
	v_lshlrev_b32_e32 v224, 1, v156
	v_mov_b32_e32 v225, v211
	v_or_b32_e32 v226, s65, v97
	v_ashrrev_i32_e32 v227, 31, v226
	v_lshlrev_b64 v[228:229], 12, v[226:227]
	v_lshl_add_u64 v[230:231], s[58:59], 0, v[228:229]
	v_lshl_add_u64 v[228:229], v[230:231], 0, v[224:225]
	global_load_ushort v190, v[228:229], off offset:1920
	v_lshlrev_b32_e32 v224, 1, v156
	v_mov_b32_e32 v225, v211
	v_or_b32_e32 v226, s65, v97
	v_ashrrev_i32_e32 v227, 31, v226
	v_lshlrev_b64 v[228:229], 12, v[226:227]
	v_lshl_add_u64 v[230:231], s[58:59], 0, v[228:229]
	v_lshl_add_u64 v[228:229], v[230:231], 0, v[224:225]
	global_load_ushort v191, v[228:229], off offset:1952
	v_or_b32_e32 v224, 48, v147
	v_lshlrev_b32_e32 v226, 1, v224
	v_mov_b32_e32 v227, v211
	v_or_b32_e32 v228, s65, v97
	v_ashrrev_i32_e32 v229, 31, v228
	v_lshlrev_b64 v[230:231], 12, v[228:229]
	v_lshl_add_u64 v[232:233], s[58:59], 0, v[230:231]
	v_lshl_add_u64 v[242:243], v[232:233], 0, v[226:227]
	global_load_ushort v192, v[242:243], off offset:1888
	v_lshlrev_b32_e32 v224, 1, v156
	v_mov_b32_e32 v225, v211
	v_or_b32_e32 v226, s65, v97
	v_or_b32_e32 v228, 1, v226
	v_ashrrev_i32_e32 v229, 31, v228
	v_lshlrev_b64 v[230:231], 12, v[228:229]
	v_lshl_add_u64 v[230:231], s[58:59], 0, v[230:231]
	v_lshl_add_u64 v[232:233], v[230:231], 0, v[224:225]
	global_load_ushort v193, v[232:233], off offset:1888
	v_lshlrev_b32_e32 v224, 1, v156
	v_mov_b32_e32 v225, v211
	v_or_b32_e32 v226, s65, v97
	v_or_b32_e32 v228, 1, v226
	v_ashrrev_i32_e32 v229, 31, v228
	v_lshlrev_b64 v[230:231], 12, v[228:229]
	v_lshl_add_u64 v[230:231], s[58:59], 0, v[230:231]
	v_lshl_add_u64 v[232:233], v[230:231], 0, v[224:225]
	global_load_ushort v194, v[232:233], off offset:1920
	v_lshlrev_b32_e32 v224, 1, v156
	v_mov_b32_e32 v225, v211
	v_or_b32_e32 v226, s65, v97
; template <bool GLA>
; __device__ __forceinline__ void chunk_pass_c(const ChunkIn& ci, const float* wgl, int unit, unsigned char* wl, int lane, const float* Sb, const float* ng, bf16_t* omix) {
;     ...
;                 const float gt = __uint_as_float((unsigned)ci.proj[(size_t)t * DINP + gcol + e] << 16);
	v_or_b32_e32 v228, 1, v226
	v_ashrrev_i32_e32 v229, 31, v228
	v_lshlrev_b64 v[230:231], 12, v[228:229]
	v_lshl_add_u64 v[230:231], s[58:59], 0, v[230:231]
	v_lshl_add_u64 v[232:233], v[230:231], 0, v[224:225]
	global_load_ushort v195, v[232:233], off offset:1952
	v_or_b32_e32 v224, 48, v147
	v_lshlrev_b32_e32 v226, 1, v224
	v_mov_b32_e32 v227, v211
	v_or_b32_e32 v228, s65, v97
	v_or_b32_e32 v230, 1, v228
	v_ashrrev_i32_e32 v231, 31, v230
	v_lshlrev_b64 v[232:233], 12, v[230:231]
	v_lshl_add_u64 v[232:233], s[58:59], 0, v[232:233]
	v_lshl_add_u64 v[242:243], v[232:233], 0, v[226:227]
	global_load_ushort v196, v[242:243], off offset:1888
	v_lshlrev_b32_e32 v224, 1, v156
	v_mov_b32_e32 v225, v211
	v_or_b32_e32 v226, s65, v97
	v_or_b32_e32 v228, 2, v226
	v_ashrrev_i32_e32 v229, 31, v228
	v_lshlrev_b64 v[230:231], 12, v[228:229]
	v_lshl_add_u64 v[230:231], s[58:59], 0, v[230:231]
	v_lshl_add_u64 v[232:233], v[230:231], 0, v[224:225]
	global_load_ushort v197, v[232:233], off offset:1888
	v_lshlrev_b32_e32 v224, 1, v156
	v_mov_b32_e32 v225, v211
	v_or_b32_e32 v226, s65, v97
	v_or_b32_e32 v228, 2, v226
	v_ashrrev_i32_e32 v229, 31, v228
	v_lshlrev_b64 v[230:231], 12, v[228:229]
	v_lshl_add_u64 v[230:231], s[58:59], 0, v[230:231]
	v_lshl_add_u64 v[232:233], v[230:231], 0, v[224:225]
	global_load_ushort v198, v[232:233], off offset:1920
	v_lshlrev_b32_e32 v224, 1, v156
	v_mov_b32_e32 v225, v211
	v_or_b32_e32 v226, s65, v97
	v_or_b32_e32 v228, 2, v226
	v_ashrrev_i32_e32 v229, 31, v228
	v_lshlrev_b64 v[230:231], 12, v[228:229]
	v_lshl_add_u64 v[230:231], s[58:59], 0, v[230:231]
	v_lshl_add_u64 v[232:233], v[230:231], 0, v[224:225]
	global_load_ushort v199, v[232:233], off offset:1952
	v_or_b32_e32 v224, 48, v147
	v_lshlrev_b32_e32 v226, 1, v224
	v_mov_b32_e32 v227, v211
	v_or_b32_e32 v228, s65, v97
	v_or_b32_e32 v230, 2, v228
	v_ashrrev_i32_e32 v231, 31, v230
	v_lshlrev_b64 v[232:233], 12, v[230:231]
	v_lshl_add_u64 v[232:233], s[58:59], 0, v[232:233]
	v_lshl_add_u64 v[232:233], v[232:233], 0, v[226:227]
	global_load_ushort v200, v[232:233], off offset:1888
	v_lshlrev_b32_e32 v224, 1, v156
	v_mov_b32_e32 v225, v211
	v_or_b32_e32 v226, s65, v97
	v_or_b32_e32 v228, 3, v226
	v_ashrrev_i32_e32 v229, 31, v228
	v_lshlrev_b64 v[230:231], 12, v[228:229]
	v_lshl_add_u64 v[230:231], s[58:59], 0, v[230:231]
	v_lshl_add_u64 v[232:233], v[230:231], 0, v[224:225]
	global_load_ushort v201, v[232:233], off offset:1888
	v_lshlrev_b32_e32 v224, 1, v156
	v_mov_b32_e32 v225, v211
	v_or_b32_e32 v226, s65, v97
	v_or_b32_e32 v228, 3, v226
	v_ashrrev_i32_e32 v229, 31, v228
	v_lshlrev_b64 v[230:231], 12, v[228:229]
	v_lshl_add_u64 v[230:231], s[58:59], 0, v[230:231]
	v_lshl_add_u64 v[232:233], v[230:231], 0, v[224:225]
	global_load_ushort v202, v[232:233], off offset:1920
	v_lshlrev_b32_e32 v224, 1, v156
	v_mov_b32_e32 v225, v211
	v_or_b32_e32 v226, s65, v97
	v_or_b32_e32 v228, 3, v226
	v_ashrrev_i32_e32 v229, 31, v228
	v_lshlrev_b64 v[230:231], 12, v[228:229]
	v_lshl_add_u64 v[230:231], s[58:59], 0, v[230:231]
	v_lshl_add_u64 v[232:233], v[230:231], 0, v[224:225]
	global_load_ushort v203, v[232:233], off offset:1952
	v_or_b32_e32 v224, 48, v147
	v_lshlrev_b32_e32 v226, 1, v224
	v_mov_b32_e32 v227, v211
	v_or_b32_e32 v228, s65, v97
	v_or_b32_e32 v230, 3, v228
	v_ashrrev_i32_e32 v231, 31, v230
	v_lshlrev_b64 v[232:233], 12, v[230:231]
	v_lshl_add_u64 v[232:233], s[58:59], 0, v[232:233]
	v_lshl_add_u64 v[232:233], v[232:233], 0, v[226:227]
	global_load_ushort v204, v[232:233], off offset:1888
	v_lshlrev_b32_e32 v224, 1, v156
	v_mov_b32_e32 v225, v211
	v_or_b32_e32 v226, s27, v97
	v_ashrrev_i32_e32 v227, 31, v226
	v_lshlrev_b64 v[228:229], 12, v[226:227]
	v_lshl_add_u64 v[230:231], s[58:59], 0, v[228:229]
	v_lshl_add_u64 v[228:229], v[230:231], 0, v[224:225]
	global_load_ushort v205, v[228:229], off offset:1888
	v_lshlrev_b32_e32 v224, 1, v156
	v_mov_b32_e32 v225, v211
	v_or_b32_e32 v226, s27, v97
	v_ashrrev_i32_e32 v227, 31, v226
	v_lshlrev_b64 v[228:229], 12, v[226:227]
	v_lshl_add_u64 v[230:231], s[58:59], 0, v[228:229]
	v_lshl_add_u64 v[228:229], v[230:231], 0, v[224:225]
	global_load_ushort v206, v[228:229], off offset:1920
	v_lshlrev_b32_e32 v224, 1, v156
	v_mov_b32_e32 v225, v211
	v_or_b32_e32 v226, s27, v97
	v_ashrrev_i32_e32 v227, 31, v226
	v_lshlrev_b64 v[228:229], 12, v[226:227]
	v_lshl_add_u64 v[230:231], s[58:59], 0, v[228:229]
	v_lshl_add_u64 v[228:229], v[230:231], 0, v[224:225]
	global_load_ushort v207, v[228:229], off offset:1952
	v_or_b32_e32 v224, 48, v147
	v_lshlrev_b32_e32 v226, 1, v224
	v_mov_b32_e32 v227, v211
	v_or_b32_e32 v228, s27, v97
	v_ashrrev_i32_e32 v229, 31, v228
	v_lshlrev_b64 v[230:231], 12, v[228:229]
	v_lshl_add_u64 v[232:233], s[58:59], 0, v[230:231]
	v_lshl_add_u64 v[242:243], v[232:233], 0, v[226:227]
	global_load_ushort v208, v[242:243], off offset:1888
	v_lshlrev_b32_e32 v224, 1, v156
	v_mov_b32_e32 v225, v211
	v_or_b32_e32 v226, s27, v97
	v_or_b32_e32 v228, 1, v226
	v_ashrrev_i32_e32 v229, 31, v228
	v_lshlrev_b64 v[230:231], 12, v[228:229]
	v_lshl_add_u64 v[230:231], s[58:59], 0, v[230:231]
	v_lshl_add_u64 v[232:233], v[230:231], 0, v[224:225]
	global_load_ushort v209, v[232:233], off offset:1888
	v_lshlrev_b32_e32 v224, 1, v156
	v_mov_b32_e32 v225, v211
	v_or_b32_e32 v226, s27, v97
	v_or_b32_e32 v228, 1, v226
	v_ashrrev_i32_e32 v229, 31, v228
	v_lshlrev_b64 v[230:231], 12, v[228:229]
	v_lshl_add_u64 v[230:231], s[58:59], 0, v[230:231]
	v_lshl_add_u64 v[232:233], v[230:231], 0, v[224:225]
	global_load_ushort v212, v[232:233], off offset:1920
	v_lshlrev_b32_e32 v224, 1, v156
	v_mov_b32_e32 v225, v211
	v_or_b32_e32 v226, s27, v97
; template <bool GLA>
; __device__ __forceinline__ void chunk_tile(const ChunkRaw& raw, const bf16x8 (&wfr)[2], const f32x4 (&bfr)[2], int h, int it, int row, int kq, float lg, float (&carry)[8], float (&bq)[8], float (&qv)[8], float (&kv)[8]) {
;     ...
;         for (int j = 0; j < 8; ++j) {
;             float la = (fminf(z[j], 0.f) - __logf(1.0f + __expf(-fabsf(z[j])))) * (1.0f / 16.0f);
;             la += __int_as_float(__builtin_amdgcn_update_dpp(0, __float_as_int(la), 0x111, 0xf, 0xf, false));
;             la += __int_as_float(__builtin_amdgcn_update_dpp(0, __float_as_int(la), 0x112, 0xf, 0xf, false));
;             la += __int_as_float(__builtin_amdgcn_update_dpp(0, __float_as_int(la), 0x114, 0xf, 0xf, false));
;             la += __int_as_float(__builtin_amdgcn_update_dpp(0, __float_as_int(la), 0x118, 0xf, 0xf, false));
;             bq[j] = la + carry[j];
;             carry[j] += __int_as_float(__builtin_amdgcn_ds_bpermute((16 * kq + 15) * 4, __float_as_int(la)));
;             qv[j] = q[j] * qs; kv[j] = k[j];
;         }
; template <bool GLA>
; __device__ __forceinline__ void chunk_pass_c(const ChunkIn& ci, const float* wgl, int unit, unsigned char* wl, int lane, const float* Sb, const float* ng, bf16_t* omix) {
;     ...
;     for (int it = 0; it < 4; ++it) {
;         float bq[8], qv[8], kv[8];
;         chunk_tile<GLA>(raw[it], wfr, bfr, h, it, row, kq, lg, carry, bq, qv, kv);
;         float a[8], bneg[8], cpos[8], dneg[8];
; #pragma unroll
;         for (int j = 0; j < 8; ++j) { const float eb = __expf(bq[j]), enb = __expf(-bq[j]); a[j] = qv[j] * eb; bneg[j] = kv[j] * enb; cpos[j] = qv[j] * enb; dneg[j] = kv[j] * eb; }
;         qf[it] = __builtin_bit_cast(bf16x8, (u32x4){cvtpk(a[0], a[1]), cvtpk(a[2], a[3]), cvtpk(a[4], a[5]), cvtpk(a[6], a[7])});
;         kf[it] = __builtin_bit_cast(bf16x8, (u32x4){cvtpk(bneg[0], bneg[1]), cvtpk(bneg[2], bneg[3]), cvtpk(bneg[4], bneg[5]), cvtpk(bneg[6], bneg[7])});
;         qb[it] = __builtin_bit_cast(bf16x8, (u32x4){cvtpk(cpos[0], cpos[1]), cvtpk(cpos[2], cpos[3]), cvtpk(cpos[4], cpos[5]), cvtpk(cpos[6], cpos[7])});
;         kb[it] = __builtin_bit_cast(bf16x8, (u32x4){cvtpk(dneg[0], dneg[1]), cvtpk(dneg[2], dneg[3]), cvtpk(dneg[4], dneg[5]), cvtpk(dneg[6], dneg[7])});
;     ...
;                 const float gt = __uint_as_float((unsigned)ci.proj[(size_t)t * DINP + gcol + e] << 16);
	v_or_b32_e32 v228, 1, v226
	v_ashrrev_i32_e32 v229, 31, v228
	v_lshlrev_b64 v[230:231], 12, v[228:229]
	v_lshl_add_u64 v[230:231], s[58:59], 0, v[230:231]
	v_lshl_add_u64 v[232:233], v[230:231], 0, v[224:225]
	global_load_ushort v213, v[232:233], off offset:1952
	v_or_b32_e32 v224, 48, v147
	v_lshlrev_b32_e32 v226, 1, v224
	v_mov_b32_e32 v227, v211
	v_or_b32_e32 v228, s27, v97
	v_or_b32_e32 v230, 1, v228
	v_ashrrev_i32_e32 v231, 31, v230
	v_lshlrev_b64 v[232:233], 12, v[230:231]
	v_lshl_add_u64 v[232:233], s[58:59], 0, v[232:233]
	v_lshl_add_u64 v[242:243], v[232:233], 0, v[226:227]
	global_load_ushort v214, v[242:243], off offset:1888
	v_lshlrev_b32_e32 v224, 1, v156
	v_mov_b32_e32 v225, v211
	v_or_b32_e32 v226, s27, v97
	v_or_b32_e32 v228, 2, v226
	v_ashrrev_i32_e32 v229, 31, v228
	v_lshlrev_b64 v[230:231], 12, v[228:229]
	v_lshl_add_u64 v[230:231], s[58:59], 0, v[230:231]
	v_lshl_add_u64 v[232:233], v[230:231], 0, v[224:225]
	global_load_ushort v215, v[232:233], off offset:1888
	v_lshlrev_b32_e32 v224, 1, v156
	v_mov_b32_e32 v225, v211
	v_or_b32_e32 v226, s27, v97
	v_or_b32_e32 v228, 2, v226
	v_ashrrev_i32_e32 v229, 31, v228
	v_lshlrev_b64 v[230:231], 12, v[228:229]
	v_lshl_add_u64 v[230:231], s[58:59], 0, v[230:231]
	v_lshl_add_u64 v[232:233], v[230:231], 0, v[224:225]
	global_load_ushort v216, v[232:233], off offset:1920
	v_lshlrev_b32_e32 v224, 1, v156
	v_mov_b32_e32 v225, v211
	v_or_b32_e32 v226, s27, v97
	v_or_b32_e32 v228, 2, v226
	v_ashrrev_i32_e32 v229, 31, v228
	v_lshlrev_b64 v[230:231], 12, v[228:229]
	v_lshl_add_u64 v[230:231], s[58:59], 0, v[230:231]
	v_lshl_add_u64 v[232:233], v[230:231], 0, v[224:225]
	global_load_ushort v217, v[232:233], off offset:1952
	v_or_b32_e32 v224, 48, v147
	v_lshlrev_b32_e32 v226, 1, v224
	v_mov_b32_e32 v227, v211
	v_or_b32_e32 v228, s27, v97
	v_or_b32_e32 v230, 2, v228
	v_ashrrev_i32_e32 v231, 31, v230
	v_lshlrev_b64 v[232:233], 12, v[230:231]
	v_lshl_add_u64 v[232:233], s[58:59], 0, v[232:233]
	v_lshl_add_u64 v[232:233], v[232:233], 0, v[226:227]
	global_load_ushort v218, v[232:233], off offset:1888
	v_lshlrev_b32_e32 v224, 1, v156
	v_mov_b32_e32 v225, v211
	v_or_b32_e32 v226, s27, v97
	v_or_b32_e32 v228, 3, v226
	v_ashrrev_i32_e32 v229, 31, v228
	v_lshlrev_b64 v[230:231], 12, v[228:229]
	v_lshl_add_u64 v[230:231], s[58:59], 0, v[230:231]
	v_lshl_add_u64 v[232:233], v[230:231], 0, v[224:225]
	global_load_ushort v219, v[232:233], off offset:1888
	v_lshlrev_b32_e32 v224, 1, v156
	v_mov_b32_e32 v225, v211
	v_or_b32_e32 v226, s27, v97
	v_or_b32_e32 v228, 3, v226
	v_ashrrev_i32_e32 v229, 31, v228
	v_lshlrev_b64 v[230:231], 12, v[228:229]
	v_lshl_add_u64 v[230:231], s[58:59], 0, v[230:231]
	v_lshl_add_u64 v[232:233], v[230:231], 0, v[224:225]
	global_load_ushort v220, v[232:233], off offset:1920
	v_lshlrev_b32_e32 v224, 1, v156
	v_mov_b32_e32 v225, v211
	v_or_b32_e32 v226, s27, v97
	v_or_b32_e32 v228, 3, v226
	v_ashrrev_i32_e32 v229, 31, v228
	v_lshlrev_b64 v[230:231], 12, v[228:229]
	v_lshl_add_u64 v[230:231], s[58:59], 0, v[230:231]
	v_lshl_add_u64 v[232:233], v[230:231], 0, v[224:225]
	global_load_ushort v221, v[232:233], off offset:1952
	v_or_b32_e32 v224, 48, v147
	v_lshlrev_b32_e32 v226, 1, v224
	v_mov_b32_e32 v227, v211
	v_or_b32_e32 v228, s27, v97
	v_or_b32_e32 v230, 3, v228
	v_ashrrev_i32_e32 v231, 31, v230
	v_lshlrev_b64 v[232:233], 12, v[230:231]
	v_lshl_add_u64 v[232:233], s[58:59], 0, v[232:233]
	v_lshl_add_u64 v[242:243], v[232:233], 0, v[226:227]
	global_load_ushort v222, v[242:243], off offset:1888
	v_cvt_pk_bf16_f32 v110, v66, v67
	v_mov_b32_dpp v7, v6 row_shr:1 row_mask:0xf bank_mask:0xf
	v_fmac_f32_e32 v7, 0x3d800000, v5
	v_mov_b32_e32 v6, v211
	v_cvt_pk_bf16_f32 v112, v64, v65
	v_mov_b32_dpp v63, v7 row_shr:2 row_mask:0xf bank_mask:0xf
	v_pk_add_f32 v[6:7], v[6:7], v[62:63]
	s_add_u32 s44, s44, s56
	s_addc_u32 s45, s45, s57
	v_mov_b32_dpp v95, v7 row_shr:4 row_mask:0xf bank_mask:0xf
	v_pk_add_f32 v[16:17], v[6:7], v[94:95]
	v_mfma_f32_16x16x32_bf16 v[106:109], v[106:109], v[110:113], 0
	v_add_f32_e32 v5, v16, v129
	v_mul_f32_e32 v7, 0x3fb8aa3b, v5
	v_exp_f32_e32 v18, v7
	v_mul_f32_e64 v7, |v19|, s7
	v_exp_f32_e32 v7, v7
	v_mul_f32_e32 v5, 0xbfb8aa3b, v5
	v_exp_f32_e32 v22, v5
	v_add_f32_e32 v5, v6, v43
	v_add_f32_e32 v7, 1.0, v7
	v_cmp_gt_f32_e32 vcc, s96, v7
	v_mul_f32_e32 v6, 0x3fb8aa3b, v5
	v_mul_f32_e32 v5, 0xbfb8aa3b, v5
	v_cndmask_b32_e64 v9, 0, 32, vcc
	v_ldexp_f32 v7, v7, v9
	v_log_f32_e32 v7, v7
	v_exp_f32_e32 v58, v5
	v_max_f32_e32 v5, v19, v19
	v_mov_b32_dpp v131, v17 row_shr:8 row_mask:0xf bank_mask:0xf
	v_mul_f32_e32 v9, 0x3f317217, v7
	v_fma_f32 v9, v7, s3, -v9
	v_fmac_f32_e32 v9, 0x3377d1cf, v7
	v_fmac_f32_e32 v9, 0x3f317217, v7
	v_cmp_lt_f32_e64 s[42:43], |v7|, s6
	v_min_f32_e32 v5, 0, v5
	v_pk_add_f32 v[16:17], v[16:17], v[130:131]
	v_cndmask_b32_e64 v7, v7, v9, s[42:43]
	v_cndmask_b32_e32 v9, 0, v237, vcc
	v_sub_f32_e32 v7, v7, v9
	v_sub_f32_e32 v5, v5, v7
	v_add_f32_e32 v20, v16, v17
	v_mul_f32_e32 v7, 0x3d800000, v5
	v_mov_b32_e32 v17, v211
	v_mov_b32_e32 v16, v211
	v_exp_f32_e32 v6, v6
	v_mov_b32_dpp v17, v7 row_shr:1 row_mask:0xf bank_mask:0xf
	v_fmac_f32_e32 v17, 0x3d800000, v5
	v_mov_b32_e32 v129, v211
	v_mov_b32_e32 v43, v211
	v_mov_b32_dpp v57, v17 row_shr:2 row_mask:0xf bank_mask:0xf
	v_pk_add_f32 v[16:17], v[16:17], v[56:57]
	v_lshlrev_b32_e32 v210, 1, v156
	v_add_f32_e32 v9, v16, v39
	v_mov_b32_dpp v91, v17 row_shr:4 row_mask:0xf bank_mask:0xf
	v_pk_add_f32 v[56:57], v[16:17], v[90:91]
	v_mov_b32_e32 v39, v211
	v_add_f32_e32 v5, v56, v121
	v_mul_f32_e32 v7, 0x3fb8aa3b, v5
	v_exp_f32_e32 v19, v7
	v_mul_f32_e32 v7, 0x3fb8aa3b, v9
	v_exp_f32_e32 v7, v7
; template <bool GLA>
; __device__ __forceinline__ void chunk_tile(const ChunkRaw& raw, const bf16x8 (&wfr)[2], const f32x4 (&bfr)[2], int h, int it, int row, int kq, float lg, float (&carry)[8], float (&bq)[8], float (&qv)[8], float (&kv)[8]) {
;     ...
;         for (int j = 0; j < 8; ++j) {
;             float la = (fminf(z[j], 0.f) - __logf(1.0f + __expf(-fabsf(z[j])))) * (1.0f / 16.0f);
;             la += __int_as_float(__builtin_amdgcn_update_dpp(0, __float_as_int(la), 0x111, 0xf, 0xf, false));
;             la += __int_as_float(__builtin_amdgcn_update_dpp(0, __float_as_int(la), 0x112, 0xf, 0xf, false));
;             la += __int_as_float(__builtin_amdgcn_update_dpp(0, __float_as_int(la), 0x114, 0xf, 0xf, false));
;             la += __int_as_float(__builtin_amdgcn_update_dpp(0, __float_as_int(la), 0x118, 0xf, 0xf, false));
;             bq[j] = la + carry[j];
;             carry[j] += __int_as_float(__builtin_amdgcn_ds_bpermute((16 * kq + 15) * 4, __float_as_int(la)));
;             qv[j] = q[j] * qs; kv[j] = k[j];
;         }
; template <bool GLA>
; __device__ __forceinline__ void chunk_pass_c(const ChunkIn& ci, const float* wgl, int unit, unsigned char* wl, int lane, const float* Sb, const float* ng, bf16_t* omix) {
;     ...
;     for (int it = 0; it < 4; ++it) {
;         float bq[8], qv[8], kv[8];
;         chunk_tile<GLA>(raw[it], wfr, bfr, h, it, row, kq, lg, carry, bq, qv, kv);
;         float a[8], bneg[8], cpos[8], dneg[8];
; #pragma unroll
;         for (int j = 0; j < 8; ++j) { const float eb = __expf(bq[j]), enb = __expf(-bq[j]); a[j] = qv[j] * eb; bneg[j] = kv[j] * enb; cpos[j] = qv[j] * enb; dneg[j] = kv[j] * eb; }
;         qf[it] = __builtin_bit_cast(bf16x8, (u32x4){cvtpk(a[0], a[1]), cvtpk(a[2], a[3]), cvtpk(a[4], a[5]), cvtpk(a[6], a[7])});
;         kf[it] = __builtin_bit_cast(bf16x8, (u32x4){cvtpk(bneg[0], bneg[1]), cvtpk(bneg[2], bneg[3]), cvtpk(bneg[4], bneg[5]), cvtpk(bneg[6], bneg[7])});
;         qb[it] = __builtin_bit_cast(bf16x8, (u32x4){cvtpk(cpos[0], cpos[1]), cvtpk(cpos[2], cpos[3]), cvtpk(cpos[4], cpos[5]), cvtpk(cpos[6], cpos[7])});
;         kb[it] = __builtin_bit_cast(bf16x8, (u32x4){cvtpk(dneg[0], dneg[1]), cvtpk(dneg[2], dneg[3]), cvtpk(dneg[4], dneg[5]), cvtpk(dneg[6], dneg[7])});
	v_mov_b32_dpp v129, v57 row_shr:8 row_mask:0xf bank_mask:0xf
	v_mul_f32_e32 v9, 0xbfb8aa3b, v9
	v_exp_f32_e32 v59, v9
	v_pk_mul_f32 v[16:17], v[6:7], v[78:79]
	v_pk_mul_f32 v[6:7], v[72:73], v[6:7]
	v_cvt_pk_bf16_f32 v99, v16, v17
	v_cvt_pk_bf16_f32 v89, v6, v7
	v_pk_add_f32 v[6:7], v[56:57], v[128:129]
	v_pk_mul_f32 v[16:17], v[58:59], v[78:79]
	v_add_f32_e32 v21, v6, v7
	v_mul_f32_e64 v7, |v10|, s7
	v_exp_f32_e32 v7, v7
	v_max_f32_e32 v6, v10, v10
	v_min_f32_e32 v6, 0, v6
	v_mul_f32_e32 v5, 0xbfb8aa3b, v5
	v_add_f32_e32 v7, 1.0, v7
	v_cmp_gt_f32_e32 vcc, s96, v7
	v_cvt_pk_bf16_f32 v9, v16, v17
	v_pk_mul_f32 v[16:17], v[72:73], v[58:59]
	v_cndmask_b32_e64 v10, 0, 32, vcc
	v_ldexp_f32 v7, v7, v10
	v_log_f32_e32 v7, v7
	v_exp_f32_e32 v23, v5
	v_cvt_pk_bf16_f32 v93, v16, v17
	v_pk_mul_f32 v[60:61], v[18:19], v[86:87]
	v_mul_f32_e32 v10, 0x3f317217, v7
	v_fma_f32 v10, v7, s3, -v10
	v_fmac_f32_e32 v10, 0x3377d1cf, v7
	v_fmac_f32_e32 v10, 0x3f317217, v7
	v_cmp_lt_f32_e64 s[42:43], |v7|, s6
	v_pk_mul_f32 v[18:19], v[82:83], v[18:19]
	v_cvt_pk_bf16_f32 v85, v60, v61
	v_cndmask_b32_e64 v7, v7, v10, s[42:43]
	v_cndmask_b32_e32 v10, 0, v237, vcc
	v_sub_f32_e32 v7, v7, v10
	v_sub_f32_e32 v6, v6, v7
	v_mul_f32_e32 v10, 0x3d800000, v6
	v_mov_b32_e32 v7, v211
	v_cvt_pk_bf16_f32 v77, v18, v19
	v_pk_mul_f32 v[60:61], v[22:23], v[86:87]
	v_mov_b32_dpp v7, v10 row_shr:1 row_mask:0xf bank_mask:0xf
	v_fmac_f32_e32 v7, 0x3d800000, v6
	v_mov_b32_e32 v6, v211
	v_pk_mul_f32 v[22:23], v[82:83], v[22:23]
	v_mov_b32_dpp v55, v7 row_shr:2 row_mask:0xf bank_mask:0xf
	v_pk_add_f32 v[6:7], v[6:7], v[54:55]
	v_cvt_pk_bf16_f32 v81, v22, v23
	v_mov_b32_e32 v121, v211
	v_mov_b32_dpp v39, v7 row_shr:4 row_mask:0xf bank_mask:0xf
	v_pk_add_f32 v[16:17], v[6:7], v[38:39]
	v_add_f32_e32 v6, v6, v37
	v_add_f32_e32 v7, v16, v101
	v_mul_f32_e32 v10, 0x3fb8aa3b, v7
	v_mul_f32_e32 v7, 0xbfb8aa3b, v7
	v_mov_b32_e32 v101, v211
	v_exp_f32_e32 v18, v7
	v_mul_f32_e32 v7, 0x3fb8aa3b, v6
	v_mul_f32_e32 v6, 0xbfb8aa3b, v6
	v_mov_b32_dpp v101, v17 row_shr:8 row_mask:0xf bank_mask:0xf
	v_exp_f32_e32 v38, v7
	v_exp_f32_e32 v54, v6
	v_pk_add_f32 v[6:7], v[16:17], v[100:101]
	v_mov_b32_e32 v37, v211
	v_add_f32_e32 v22, v6, v7
	v_mul_f32_e64 v7, |v11|, s7
	v_exp_f32_e32 v7, v7
	v_max_f32_e32 v6, v11, v11
	v_min_f32_e32 v6, 0, v6
	v_exp_f32_e32 v10, v10
	v_add_f32_e32 v7, 1.0, v7
	v_cmp_gt_f32_e32 vcc, s96, v7
	v_cvt_pk_bf16_f32 v5, v60, v61
	s_nop 0
	v_cndmask_b32_e64 v11, 0, 32, vcc
	v_ldexp_f32 v7, v7, v11
	v_log_f32_e32 v7, v7
	s_nop 0
	v_mul_f32_e32 v11, 0x3f317217, v7
	v_fma_f32 v11, v7, s3, -v11
	v_fmac_f32_e32 v11, 0x3377d1cf, v7
	v_fmac_f32_e32 v11, 0x3f317217, v7
	v_cmp_lt_f32_e64 s[42:43], |v7|, s6
	s_nop 1
	v_cndmask_b32_e64 v7, v7, v11, s[42:43]
	v_cndmask_b32_e32 v11, 0, v237, vcc
	v_sub_f32_e32 v7, v7, v11
	v_sub_f32_e32 v6, v6, v7
	v_mul_f32_e32 v11, 0x3d800000, v6
	v_mov_b32_e32 v7, v211
	s_nop 1
	v_mov_b32_dpp v7, v11 row_shr:1 row_mask:0xf bank_mask:0xf
	v_fmac_f32_e32 v7, 0x3d800000, v6
	v_mov_b32_e32 v6, v211
	s_nop 0
	v_mov_b32_dpp v53, v7 row_shr:2 row_mask:0xf bank_mask:0xf
	v_pk_add_f32 v[16:17], v[6:7], v[52:53]
	s_nop 1
	v_mov_b32_dpp v37, v17 row_shr:4 row_mask:0xf bank_mask:0xf
	v_pk_add_f32 v[36:37], v[16:17], v[36:37]
	s_nop 0
	v_add_f32_e32 v6, v36, v35
	v_mul_f32_e32 v7, 0x3fb8aa3b, v6
	v_exp_f32_e32 v11, v7
	v_mul_f32_e32 v6, 0xbfb8aa3b, v6
	v_exp_f32_e32 v19, v6
	v_mov_b32_dpp v121, v37 row_shr:8 row_mask:0xf bank_mask:0xf
	v_pk_mul_f32 v[6:7], v[10:11], v[122:123]
	v_pk_mul_f32 v[10:11], v[126:127], v[10:11]
	v_cvt_pk_bf16_f32 v86, v6, v7
	v_pk_mul_f32 v[6:7], v[18:19], v[122:123]
	v_cvt_pk_bf16_f32 v78, v10, v11
	v_cvt_pk_bf16_f32 v6, v6, v7
	v_add_f32_e32 v7, v16, v41
	v_mul_f32_e32 v10, 0x3fb8aa3b, v7
	v_exp_f32_e32 v39, v10
	v_mul_f32_e32 v7, 0xbfb8aa3b, v7
	v_exp_f32_e32 v55, v7
	v_max_f32_e32 v7, v12, v12
	v_pk_mul_f32 v[10:11], v[38:39], v[124:125]
	v_min_f32_e32 v7, 0, v7
	v_cvt_pk_bf16_f32 v100, v10, v11
	v_pk_mul_f32 v[10:11], v[54:55], v[124:125]
	v_pk_mul_f32 v[16:17], v[70:71], v[54:55]
	v_cvt_pk_bf16_f32 v10, v10, v11
	v_mul_f32_e64 v11, |v12|, s7
	v_exp_f32_e32 v11, v11
	v_cvt_pk_bf16_f32 v94, v16, v17
	v_pk_mul_f32 v[16:17], v[70:71], v[38:39]
	v_mov_b32_e32 v35, v211
	v_add_f32_e32 v11, 1.0, v11
	v_cmp_gt_f32_e32 vcc, s96, v11
	v_cvt_pk_bf16_f32 v90, v16, v17
	v_pk_add_f32 v[16:17], v[36:37], v[120:121]
	v_cndmask_b32_e64 v12, 0, 32, vcc
	v_ldexp_f32 v11, v11, v12
	v_log_f32_e32 v11, v11
	v_add_f32_e32 v23, v16, v17
	v_mov_b32_e32 v17, v211
	v_mov_b32_e32 v16, v211
	v_mul_f32_e32 v12, 0x3f317217, v11
	v_fma_f32 v12, v11, s3, -v12
	v_fmac_f32_e32 v12, 0x3377d1cf, v11
	v_fmac_f32_e32 v12, 0x3f317217, v11
	v_cmp_lt_f32_e64 s[42:43], |v11|, s6
	v_pk_mul_f32 v[18:19], v[126:127], v[18:19]
	v_mov_b32_e32 v41, v211
	v_cndmask_b32_e64 v11, v11, v12, s[42:43]
	v_cndmask_b32_e32 v12, 0, v237, vcc
	v_sub_f32_e32 v11, v11, v12
	v_sub_f32_e32 v7, v7, v11
	v_mul_f32_e32 v11, 0x3d800000, v7
	v_cvt_pk_bf16_f32 v82, v18, v19
	s_nop 0
	v_mov_b32_dpp v17, v11 row_shr:1 row_mask:0xf bank_mask:0xf
	v_fmac_f32_e32 v17, 0x3d800000, v7
	s_nop 1
	v_mov_b32_dpp v43, v17 row_shr:2 row_mask:0xf bank_mask:0xf
	v_pk_add_f32 v[16:17], v[16:17], v[42:43]
	s_nop 1
	v_mov_b32_dpp v35, v17 row_shr:4 row_mask:0xf bank_mask:0xf
	v_pk_add_f32 v[18:19], v[16:17], v[34:35]
	s_nop 0
	v_add_f32_e32 v7, v18, v29
	v_mul_f32_e32 v11, 0x3fb8aa3b, v7
	v_mul_f32_e32 v7, 0xbfb8aa3b, v7
	v_exp_f32_e32 v34, v7
	v_add_f32_e32 v7, v16, v33
	v_exp_f32_e32 v12, v11
	v_mul_f32_e32 v11, 0x3fb8aa3b, v7
	v_exp_f32_e32 v16, v11
	v_mul_f32_e64 v11, |v13|, s7
	v_exp_f32_e32 v11, v11
	v_mul_f32_e32 v7, 0xbfb8aa3b, v7
; template <bool GLA>
; __device__ __forceinline__ void chunk_tile(const ChunkRaw& raw, const bf16x8 (&wfr)[2], const f32x4 (&bfr)[2], int h, int it, int row, int kq, float lg, float (&carry)[8], float (&bq)[8], float (&qv)[8], float (&kv)[8]) {
;     ...
;         for (int j = 0; j < 8; ++j) {
;             float la = (fminf(z[j], 0.f) - __logf(1.0f + __expf(-fabsf(z[j])))) * (1.0f / 16.0f);
;             la += __int_as_float(__builtin_amdgcn_update_dpp(0, __float_as_int(la), 0x111, 0xf, 0xf, false));
;             la += __int_as_float(__builtin_amdgcn_update_dpp(0, __float_as_int(la), 0x112, 0xf, 0xf, false));
;             la += __int_as_float(__builtin_amdgcn_update_dpp(0, __float_as_int(la), 0x114, 0xf, 0xf, false));
;             la += __int_as_float(__builtin_amdgcn_update_dpp(0, __float_as_int(la), 0x118, 0xf, 0xf, false));
;             bq[j] = la + carry[j];
;             carry[j] += __int_as_float(__builtin_amdgcn_ds_bpermute((16 * kq + 15) * 4, __float_as_int(la)));
;             qv[j] = q[j] * qs; kv[j] = k[j];
; template <bool GLA>
; __device__ __forceinline__ void chunk_pass_c(const ChunkIn& ci, const float* wgl, int unit, unsigned char* wl, int lane, const float* Sb, const float* ng, bf16_t* omix) {
;     ...
;         float a[8], bneg[8], cpos[8], dneg[8];
; #pragma unroll
;         for (int j = 0; j < 8; ++j) { const float eb = __expf(bq[j]), enb = __expf(-bq[j]); a[j] = qv[j] * eb; bneg[j] = kv[j] * enb; cpos[j] = qv[j] * enb; dneg[j] = kv[j] * eb; }
;         qf[it] = __builtin_bit_cast(bf16x8, (u32x4){cvtpk(a[0], a[1]), cvtpk(a[2], a[3]), cvtpk(a[4], a[5]), cvtpk(a[6], a[7])});
;         kf[it] = __builtin_bit_cast(bf16x8, (u32x4){cvtpk(bneg[0], bneg[1]), cvtpk(bneg[2], bneg[3]), cvtpk(bneg[4], bneg[5]), cvtpk(bneg[6], bneg[7])});
;         qb[it] = __builtin_bit_cast(bf16x8, (u32x4){cvtpk(cpos[0], cpos[1]), cvtpk(cpos[2], cpos[3]), cvtpk(cpos[4], cpos[5]), cvtpk(cpos[6], cpos[7])});
;         kb[it] = __builtin_bit_cast(bf16x8, (u32x4){cvtpk(dneg[0], dneg[1]), cvtpk(dneg[2], dneg[3]), cvtpk(dneg[4], dneg[5]), cvtpk(dneg[6], dneg[7])});
;         asm volatile("" ::: "memory");
;     }
;     __builtin_amdgcn_s_waitcnt(0); asm volatile("" ::: "memory");
;     bf16x8 vfr[4][2], sfr[4];
; #pragma unroll
;     for (int et = 0; et < 4; ++et) {
; #pragma unroll
;         for (int p = 0; p < 2; ++p) {
	v_exp_f32_e32 v36, v7
	v_max_f32_e32 v7, v13, v13
	v_add_f32_e32 v11, 1.0, v11
	v_cmp_gt_f32_e32 vcc, s96, v11
	v_mov_b32_e32 v29, v211
	v_min_f32_e32 v7, 0, v7
	v_cndmask_b32_e64 v13, 0, 32, vcc
	v_ldexp_f32 v11, v11, v13
	v_log_f32_e32 v11, v11
	v_mov_b32_dpp v29, v19 row_shr:8 row_mask:0xf bank_mask:0xf
	v_pk_add_f32 v[18:19], v[18:19], v[28:29]
	v_mov_b32_e32 v33, v211
	v_mul_f32_e32 v13, 0x3f317217, v11
	v_fma_f32 v13, v11, s3, -v13
	v_fmac_f32_e32 v13, 0x3377d1cf, v11
	v_fmac_f32_e32 v13, 0x3f317217, v11
	v_cmp_lt_f32_e64 s[42:43], |v11|, s6
	v_add_f32_e32 v38, v18, v19
	v_mov_b32_e32 v19, v211
	v_cndmask_b32_e64 v11, v11, v13, s[42:43]
	v_cndmask_b32_e32 v13, 0, v237, vcc
	v_sub_f32_e32 v11, v11, v13
	v_sub_f32_e32 v7, v7, v11
	v_mul_f32_e32 v11, 0x3d800000, v7
	v_mov_b32_e32 v18, v211
	v_readlane_b32 s3, v254, 60
	v_mov_b32_dpp v19, v11 row_shr:1 row_mask:0xf bank_mask:0xf
	v_fmac_f32_e32 v19, 0x3d800000, v7
	v_cmp_gt_u32_e32 vcc, v97, v156
	v_cmp_lt_u32_e64 s[42:43], v97, v156
	v_mov_b32_dpp v41, v19 row_shr:2 row_mask:0xf bank_mask:0xf
	v_pk_add_f32 v[18:19], v[18:19], v[40:41]
	v_lshlrev_b32_e32 v40, 16, v47
	v_and_b32_e32 v41, 0xffff0000, v47
	v_mov_b32_dpp v33, v19 row_shr:4 row_mask:0xf bank_mask:0xf
	v_pk_add_f32 v[28:29], v[18:19], v[32:33]
	v_pk_mul_f32 v[40:41], v[40:41], s[8:9] op_sel_hi:[1,0]
	v_add_f32_e32 v7, v28, v25
	v_mul_f32_e32 v11, 0x3fb8aa3b, v7
	v_exp_f32_e32 v13, v11
	v_add_f32_e32 v11, v18, v143
	v_mov_b32_e32 v25, v211
	v_mul_f32_e32 v7, 0xbfb8aa3b, v7
	v_pk_mul_f32 v[32:33], v[12:13], v[116:117]
	v_pk_mul_f32 v[12:13], v[118:119], v[12:13]
	v_mov_b32_dpp v25, v29 row_shr:8 row_mask:0xf bank_mask:0xf
	v_cvt_pk_bf16_f32 v79, v12, v13
	v_mul_f32_e32 v12, 0x3fb8aa3b, v11
	v_exp_f32_e32 v17, v12
	v_mul_f32_e32 v11, 0xbfb8aa3b, v11
	v_exp_f32_e32 v37, v11
	v_exp_f32_e32 v35, v7
	v_pk_mul_f32 v[12:13], v[16:17], v[26:27]
	v_cvt_pk_bf16_f32 v87, v32, v33
	v_cvt_pk_bf16_f32 v101, v12, v13
	v_pk_mul_f32 v[12:13], v[36:37], v[26:27]
	v_pk_mul_f32 v[32:33], v[34:35], v[116:117]
	v_cvt_pk_bf16_f32 v11, v12, v13
	v_pk_mul_f32 v[12:13], v[30:31], v[36:37]
	v_cvt_pk_bf16_f32 v7, v32, v33
	v_cvt_pk_bf16_f32 v95, v12, v13
	v_pk_mul_f32 v[12:13], v[30:31], v[16:17]
	v_lshlrev_b32_e32 v30, 16, v49
	v_cvt_pk_bf16_f32 v91, v12, v13
	v_pk_add_f32 v[12:13], v[28:29], v[24:25]
	v_lshlrev_b32_e32 v24, 16, v48
	v_add_f32_e32 v39, v12, v13
	v_mul_f32_e32 v12, 0x3fb8aa3b, v14
	v_exp_f32_e32 v16, v12
	v_mul_f32_e32 v12, 0xbfb8aa3b, v14
	v_exp_f32_e32 v14, v12
	v_mul_f32_e32 v12, 0x3fb8aa3b, v15
	v_exp_f32_e32 v17, v12
	v_mul_f32_e32 v12, 0xbfb8aa3b, v15
	v_exp_f32_e32 v15, v12
	v_lshlrev_b32_e32 v12, 16, v50
	v_and_b32_e32 v13, 0xffff0000, v50
	v_pk_mul_f32 v[18:19], v[12:13], s[8:9] op_sel_hi:[1,0]
	v_and_b32_e32 v25, 0xffff0000, v48
	v_pk_mul_f32 v[12:13], v[18:19], v[16:17]
	v_pk_mul_f32 v[18:19], v[18:19], v[14:15]
	v_pk_mul_f32 v[26:27], v[14:15], v[24:25]
	v_mul_f32_e32 v15, 0xbfb8aa3b, v20
	v_mul_f32_e32 v14, 0x3fb8aa3b, v20
	v_exp_f32_e32 v20, v15
	v_mul_f32_e32 v15, 0x3fb8aa3b, v21
	v_mul_f32_e32 v21, 0xbfb8aa3b, v21
	v_exp_f32_e32 v14, v14
	v_exp_f32_e32 v15, v15
	v_exp_f32_e32 v21, v21
	v_pk_mul_f32 v[16:17], v[16:17], v[24:25]
	v_lshlrev_b32_e32 v24, 16, v51
	v_and_b32_e32 v25, 0xffff0000, v51
	v_pk_mul_f32 v[24:25], v[24:25], s[8:9] op_sel_hi:[1,0]
	v_and_b32_e32 v31, 0xffff0000, v49
	v_pk_mul_f32 v[28:29], v[24:25], v[14:15]
	v_pk_mul_f32 v[24:25], v[24:25], v[20:21]
	v_pk_mul_f32 v[20:21], v[20:21], v[30:31]
	v_pk_mul_f32 v[30:31], v[14:15], v[30:31]
	v_mul_f32_e32 v15, 0xbfb8aa3b, v22
	v_mul_f32_e32 v14, 0x3fb8aa3b, v22
	v_exp_f32_e32 v22, v15
	v_mul_f32_e32 v15, 0x3fb8aa3b, v23
	v_mul_f32_e32 v23, 0xbfb8aa3b, v23
	v_exp_f32_e32 v14, v14
	v_exp_f32_e32 v15, v15
	v_exp_f32_e32 v23, v23
	v_pk_mul_f32 v[32:33], v[118:119], v[34:35]
	v_lshlrev_b32_e32 v36, 16, v44
	v_cvt_pk_bf16_f32 v83, v32, v33
	v_lshlrev_b32_e32 v32, 16, v46
	v_and_b32_e32 v33, 0xffff0000, v46
	v_pk_mul_f32 v[32:33], v[32:33], s[8:9] op_sel_hi:[1,0]
	v_and_b32_e32 v37, 0xffff0000, v44
	v_pk_mul_f32 v[34:35], v[32:33], v[14:15]
	v_pk_mul_f32 v[32:33], v[32:33], v[22:23]
	v_pk_mul_f32 v[22:23], v[22:23], v[36:37]
	v_pk_mul_f32 v[36:37], v[14:15], v[36:37]
	v_mul_f32_e32 v15, 0xbfb8aa3b, v38
	v_mul_f32_e32 v14, 0x3fb8aa3b, v38
	v_exp_f32_e32 v38, v15
	v_mul_f32_e32 v15, 0x3fb8aa3b, v39
	v_mul_f32_e32 v39, 0xbfb8aa3b, v39
	v_exp_f32_e32 v14, v14
	v_exp_f32_e32 v15, v15
	v_exp_f32_e32 v39, v39
	v_cvt_pk_bf16_f32 v72, v16, v17
	v_mul_u32_u24_e32 v17, 0x90, v156
	v_lshlrev_b32_e32 v44, 16, v45
	v_and_b32_e32 v45, 0xffff0000, v45
	v_lshlrev_b32_e32 v16, 6, v156
	v_add3_u32 v17, s3, v17, v114
	v_pk_mul_f32 v[42:43], v[40:41], v[14:15]
	v_pk_mul_f32 v[40:41], v[40:41], v[38:39]
	v_pk_mul_f32 v[38:39], v[38:39], v[44:45]
	v_pk_mul_f32 v[44:45], v[14:15], v[44:45]
	v_cvt_pk_bf16_f32 v52, v18, v19
	ds_read2_b64 v[64:67], v17 offset1:4
	ds_read2_b64 v[60:63], v17 offset0:8 offset1:12
	v_add3_u32 v16, s3, v142, v16
	v_add_u32_e32 v18, 0x800, v17
	v_add_u32_e32 v17, 0x1000, v17
	v_or_b32_e32 v142, 48, v147
	v_cvt_pk_bf16_f32 v12, v12, v13
	v_cvt_pk_bf16_f32 v13, v28, v29
	v_cvt_pk_bf16_f32 v14, v34, v35
	v_cvt_pk_bf16_f32 v15, v42, v43
	v_cvt_pk_bf16_f32 v59, v38, v39
	v_cvt_pk_bf16_f32 v54, v32, v33
	v_cvt_pk_bf16_f32 v55, v40, v41
	v_cvt_pk_bf16_f32 v73, v30, v31
	v_cvt_pk_bf16_f32 v74, v36, v37
	v_cvt_pk_bf16_f32 v75, v44, v45
	ds_read_b128 v[68:71], v16 offset:9216
	ds_read2_b64 v[48:51], v18 offset0:32 offset1:36
	ds_read2_b64 v[44:47], v18 offset0:40 offset1:44
	ds_read_b128 v[40:43], v16 offset:10240
	ds_read2_b64 v[36:39], v17 offset0:64 offset1:68
; template <bool GLA>
; __device__ __forceinline__ void chunk_pass_c(const ChunkIn& ci, const float* wgl, int unit, unsigned char* wl, int lane, const float* Sb, const float* ng, bf16_t* omix) {
;     ...
;     for (int it = 0; it < 4; ++it) {
;         f32x4 st[4];
; #pragma unroll
;         for (int jt = 0; jt < 4; ++jt) {
;             const f32x4 z = {0.f, 0.f, 0.f, 0.f};
;             if (jt < it) st[jt] = __builtin_amdgcn_mfma_f32_16x16x32_bf16(kf[jt], qf[it], z, 0, 0, 0);
;             else if (jt > it) st[jt] = __builtin_amdgcn_mfma_f32_16x16x32_bf16(kb[jt], qb[it], z, 0, 0, 0);
;             else {
;                 const f32x4 lo = __builtin_amdgcn_mfma_f32_16x16x32_bf16(kf[jt], qf[it], z, 0, 0, 0), up = __builtin_amdgcn_mfma_f32_16x16x32_bf16(kb[jt], qb[it], z, 0, 0, 0);
; #pragma unroll
;                 for (int r = 0; r < 4; ++r) st[jt][r] = (4 * kq + r <= row) ? lo[r] : up[r];
;             }
;         }
;         bf16x8 af[2];
; #pragma unroll
;         for (int p = 0; p < 2; ++p)
;             af[p] = __builtin_bit_cast(bf16x8, (u32x4){cvtpk(st[2 * p][0], st[2 * p][1]), cvtpk(st[2 * p][2], st[2 * p][3]), cvtpk(st[2 * p + 1][0], st[2 * p + 1][1]), cvtpk(st[2 * p + 1][2], st[2 * p + 1][3])});
;         f32x4 o[4]; float ss[4] = {0.f, 0.f, 0.f, 0.f};
; #pragma unroll
;         for (int et = 0; et < 4; ++et) {
;             f32x4 acc = {0.f, 0.f, 0.f, 0.f};
;             acc = __builtin_amdgcn_mfma_f32_16x16x32_bf16(af[0], vfr[et][0], acc, 0, 0, 0);
;             acc = __builtin_amdgcn_mfma_f32_16x16x32_bf16(af[1], vfr[et][1], acc, 0, 0, 0);
;             acc = __builtin_amdgcn_mfma_f32_16x16x32_bf16(qf[it], sfr[et], acc, 0, 0, 0);
;             o[et] = acc;
; #pragma unroll
;             for (int r = 0; r < 4; ++r) ss[r] += acc[r] * acc[r];
;         }
; #pragma unroll
;         for (int r = 0; r < 4; ++r) {
;             ss[r] += swz_xor<1>(ss[r]); ss[r] += swz_xor<2>(ss[r]); ss[r] += swz_xor<4>(ss[r]); ss[r] += swz_xor<8>(ss[r]);
;             const float rs = rsqrtf(ss[r] * (1.0f / 64.0f) + EPS);
;             const int t = t0 + 16 * it + 4 * kq + r;
; #pragma unroll
;             for (int et = 0; et < 4; ++et) {
;                 const int e = 16 * et + row;
;                 const float gt = __uint_as_float((unsigned)ci.proj[(size_t)t * DINP + gcol + e] << 16);
;                 const float val = o[et][r] * rs * gn[et] * pg8::silu_f(gt);
	ds_read2_b64 v[32:35], v17 offset0:72 offset1:76
	ds_read_b128 v[28:31], v16 offset:11264
	v_mul_u32_u24_e32 v17, 0x90, v142
	v_add3_u32 v17, s3, v17, v114
	v_lshlrev_b32_e32 v114, 2, v142
	v_cvt_pk_bf16_f32 v56, v26, v27
	v_cvt_pk_bf16_f32 v57, v20, v21
	v_cvt_pk_bf16_f32 v58, v22, v23
	v_cvt_pk_bf16_f32 v53, v24, v25
	ds_read2_b64 v[24:27], v17 offset1:4
	ds_read2_b64 v[20:23], v17 offset0:8 offset1:12
	ds_read_b128 v[16:19], v16 offset:12288
	global_load_dword v149, v115, s[44:45]
	global_load_dword v148, v115, s[44:45] offset:64
	global_load_dword v147, v115, s[44:45] offset:128
	global_load_dword v146, v114, s[44:45]
	v_mfma_f32_16x16x32_bf16 v[114:117], v[0:3], v[102:105], 0
	s_mov_b32 s6, 0x358637bd
	v_mfma_f32_16x16x32_bf16 v[56:59], v[56:59], v[12:15], 0
	v_mfma_f32_16x16x32_bf16 v[52:55], v[72:75], v[52:55], 0
	s_nop 4
	v_cndmask_b32_e32 v118, v114, v106, vcc
	v_or_b32_e32 v106, 2, v97
	v_cmp_gt_u32_e64 s[44:45], v106, v156
	v_or_b32_e32 v106, 3, v97
	v_cmp_gt_u32_e64 s[46:47], v106, v156
	v_cndmask_b32_e64 v119, v107, v115, s[42:43]
	v_cndmask_b32_e64 v120, v116, v108, s[44:45]
	v_cndmask_b32_e64 v121, v117, v109, s[46:47]
	v_mfma_f32_16x16x32_bf16 v[106:109], v[98:101], v[110:113], 0
	v_cvt_pk_bf16_f32 v122, v118, v119
	v_cvt_pk_bf16_f32 v123, v120, v121
	v_cndmask_b32_e64 v59, v59, v55, s[46:47]
	v_mfma_f32_16x16x32_bf16 v[114:117], v[84:87], v[110:113], 0
	v_cndmask_b32_e32 v56, v56, v52, vcc
	s_nop 2
	v_cvt_pk_bf16_f32 v124, v106, v107
	v_cvt_pk_bf16_f32 v125, v108, v109
	v_mfma_f32_16x16x32_bf16 v[110:113], v[72:75], v[110:113], 0
	v_cndmask_b32_e64 v57, v53, v57, s[42:43]
	v_cvt_pk_bf16_f32 v130, v114, v115
	v_cvt_pk_bf16_f32 v131, v116, v117
	s_waitcnt lgkmcnt(11)
	v_mfma_f32_16x16x32_bf16 v[106:109], v[122:125], v[64:67], 0
	v_cndmask_b32_e64 v58, v58, v54, s[44:45]
	s_nop 1
	v_cvt_pk_bf16_f32 v132, v110, v111
	v_cvt_pk_bf16_f32 v133, v112, v113
	v_mfma_f32_16x16x32_bf16 v[98:101], v[98:101], v[92:95], 0
	s_waitcnt lgkmcnt(10)
	v_mfma_f32_16x16x32_bf16 v[106:109], v[130:133], v[60:63], v[106:109]
	s_waitcnt lgkmcnt(9)
	v_mfma_f32_16x16x32_bf16 v[114:117], v[102:105], v[68:71], v[106:109]
	s_waitcnt lgkmcnt(8)
	v_mfma_f32_16x16x32_bf16 v[106:109], v[122:125], v[48:51], 0
	s_waitcnt lgkmcnt(7)
	v_mfma_f32_16x16x32_bf16 v[106:109], v[130:133], v[44:47], v[106:109]
	s_nop 3
	v_mov_b32_e32 v110, v114
	s_waitcnt lgkmcnt(6)
	v_mfma_f32_16x16x32_bf16 v[106:109], v[102:105], v[40:43], v[106:109]
	s_nop 7
	v_mov_b32_e32 v111, v106
	v_pk_mul_f32 v[120:121], v[110:111], v[110:111]
	v_mov_b32_e32 v110, v115
	v_mov_b32_e32 v111, v107
	v_pk_mul_f32 v[134:135], v[110:111], v[110:111]
	v_mov_b32_e32 v110, v116
	v_mov_b32_e32 v111, v108
	v_pk_mul_f32 v[126:127], v[110:111], v[110:111]
	v_mov_b32_e32 v110, v117
	v_mov_b32_e32 v111, v109
	v_pk_mul_f32 v[128:129], v[110:111], v[110:111]
	s_waitcnt lgkmcnt(5)
	v_mfma_f32_16x16x32_bf16 v[110:113], v[122:125], v[36:39], 0
	s_waitcnt lgkmcnt(2)
	v_mfma_f32_16x16x32_bf16 v[122:125], v[122:125], v[24:27], 0
	v_mfma_f32_16x16x32_bf16 v[110:113], v[130:133], v[32:35], v[110:113]
	s_waitcnt lgkmcnt(1)
	v_mfma_f32_16x16x32_bf16 v[122:125], v[130:133], v[20:23], v[122:125]
	v_mfma_f32_16x16x32_bf16 v[110:113], v[102:105], v[28:31], v[110:113]
	s_waitcnt lgkmcnt(0)
	v_mfma_f32_16x16x32_bf16 v[102:105], v[102:105], v[16:19], v[122:125]
	s_nop 4
	v_or_b32_e32 v122, s5, v97
	v_mov_b32_e32 v118, v110
	s_nop 0
	v_mov_b32_e32 v119, v102
	v_pk_mul_f32 v[136:137], v[118:119], v[118:119]
	v_mov_b32_e32 v118, v111
	v_mov_b32_e32 v119, v103
	v_pk_mul_f32 v[138:139], v[118:119], v[118:119]
	v_mov_b32_e32 v118, v112
	v_mov_b32_e32 v119, v104
	v_pk_mul_f32 v[124:125], v[118:119], v[118:119]
	v_mov_b32_e32 v118, v113
	v_mov_b32_e32 v119, v105
	v_ashrrev_i32_e32 v123, 31, v122
	v_pk_mul_f32 v[130:131], v[118:119], v[118:119]
	v_lshlrev_b64 v[118:119], 12, v[122:123]
	v_lshl_add_u64 v[132:133], s[58:59], 0, v[118:119]
	v_lshlrev_b64 v[118:119], 11, v[122:123]
	v_lshl_add_u64 v[144:145], v[132:133], 0, v[210:211]
	v_lshl_add_u64 v[150:151], s[60:61], 0, v[118:119]
	v_lshl_add_u64 v[140:141], v[150:151], 0, v[210:211]
	s_waitcnt vmcnt(0)
	v_mov_b32_e32 v118, v157
	v_lshlrev_b32_e32 v118, 16, v118
	v_mul_f32_e32 v119, 0xbfb8aa3b, v118
	v_exp_f32_e32 v119, v119
	s_nop 0
	v_add_f32_e32 v119, 1.0, v119
	v_rcp_f32_e32 v119, v119
	s_nop 0
	v_mul_f32_e32 v123, v119, v118
	v_lshlrev_b32_e32 v118, 1, v142
	v_mov_b32_e32 v119, v211
	v_lshl_add_u64 v[142:143], v[132:133], 0, v[118:119]
	v_lshl_add_u64 v[132:133], v[150:151], 0, v[118:119]
	v_mov_b32_e32 v150, v134
	v_mov_b32_e32 v151, v120
	v_mov_b32_e32 v120, v135
	v_pk_add_f32 v[120:121], v[150:151], v[120:121]
	v_mov_b32_e32 v134, v138
	v_mov_b32_e32 v135, v136
	v_pk_add_f32 v[120:121], v[120:121], v[134:135]
	v_mov_b32_e32 v136, v139
	v_pk_add_f32 v[120:121], v[120:121], v[136:137]
	ds_swizzle_b32 v135, v121 offset:swizzle(SWAP,1)
	ds_swizzle_b32 v134, v120 offset:swizzle(SWAP,1)
	s_waitcnt lgkmcnt(0)
	v_pk_add_f32 v[120:121], v[120:121], v[134:135]
	ds_swizzle_b32 v135, v121 offset:swizzle(SWAP,2)
	ds_swizzle_b32 v134, v120 offset:swizzle(SWAP,2)
	s_waitcnt lgkmcnt(0)
	v_pk_add_f32 v[120:121], v[120:121], v[134:135]
	ds_swizzle_b32 v135, v121 offset:swizzle(SWAP,4)
	ds_swizzle_b32 v134, v120 offset:swizzle(SWAP,4)
	s_waitcnt lgkmcnt(0)
	v_pk_add_f32 v[120:121], v[120:121], v[134:135]
	ds_swizzle_b32 v135, v121 offset:swizzle(SWAP,8)
	ds_swizzle_b32 v134, v120 offset:swizzle(SWAP,8)
	s_waitcnt lgkmcnt(0)
; __device__ __forceinline__ unsigned cvtpk(float lo, float hi) { f32x2_t v = {lo, hi}; bf16x2_t b = __builtin_convertvector(v, bf16x2_t); return __builtin_bit_cast(unsigned, b); }
; template <int X> __device__ __forceinline__ float swz_xor(float v) { return __int_as_float(__builtin_amdgcn_ds_swizzle(__float_as_int(v), (X << 10) | 0x1F)); }
; __device__ __forceinline__ float silu_f(float g) { return g * __builtin_amdgcn_rcpf(1.0f + __expf(-g)); }
; template <bool GLA>
; __device__ __forceinline__ void chunk_pass_c(const ChunkIn& ci, const float* wgl, int unit, unsigned char* wl, int lane, const float* Sb, const float* ng, bf16_t* omix) {
;     ...
;         for (int r = 0; r < 4; ++r) {
;             ss[r] += swz_xor<1>(ss[r]); ss[r] += swz_xor<2>(ss[r]); ss[r] += swz_xor<4>(ss[r]); ss[r] += swz_xor<8>(ss[r]);
;             const float rs = rsqrtf(ss[r] * (1.0f / 64.0f) + EPS);
;             const int t = t0 + 16 * it + 4 * kq + r;
; #pragma unroll
;             for (int et = 0; et < 4; ++et) {
;                 const int e = 16 * et + row;
;                 const float gt = __uint_as_float((unsigned)ci.proj[(size_t)t * DINP + gcol + e] << 16);
;                 const float val = o[et][r] * rs * gn[et] * pg8::silu_f(gt);
;                 omix[(size_t)t * 1024 + ocol + e] = (bf16_t)(cvtpk(val, 0.f) & 0xffffu);
;             }
	v_pk_add_f32 v[134:135], v[120:121], v[134:135]
	v_mov_b64_e32 v[120:121], s[6:7]
	s_mov_b32 s6, 0x3c800000
	v_pk_fma_f32 v[134:135], v[134:135], s[6:7], v[120:121] op_sel_hi:[1,0,0]
	s_nop 0
	v_mul_f32_e32 v136, 0x4b800000, v135
	v_cmp_gt_f32_e64 s[50:51], s96, v135
	v_cmp_gt_f32_e64 s[48:49], s96, v134
	s_nop 0
	v_cndmask_b32_e64 v135, v135, v136, s[50:51]
	v_rsq_f32_e32 v135, v135
	s_nop 0
	v_mul_f32_e32 v136, 0x45800000, v135
	v_cndmask_b32_e64 v135, v135, v136, s[50:51]
	v_mul_f32_e32 v114, v114, v135
	v_mul_f32_e32 v114, v149, v114
	v_mul_f32_e32 v114, v123, v114
	v_cvt_pk_bf16_f32 v114, v114, s0
	global_store_short v[140:141], v114, off offset:1024
	v_mul_f32_e32 v106, v106, v135
	v_mul_f32_e32 v106, v148, v106
	v_mul_f32_e32 v110, v110, v135
	v_mul_f32_e32 v110, v147, v110
	v_mul_f32_e32 v102, v102, v135
	v_mul_f32_e32 v102, v146, v102
	s_waitcnt vmcnt(63)
	v_mov_b32_e32 v114, v158
	v_lshlrev_b32_e32 v114, 16, v114
	v_mul_f32_e32 v123, 0xbfb8aa3b, v114
	v_exp_f32_e32 v123, v123
	s_nop 0
	v_add_f32_e32 v123, 1.0, v123
	v_rcp_f32_e32 v123, v123
	s_nop 0
	v_mul_f32_e32 v114, v123, v114
	v_mul_f32_e32 v106, v114, v106
	v_cvt_pk_bf16_f32 v106, v106, s0
	global_store_short v[140:141], v106, off offset:1056
	s_waitcnt vmcnt(63)
	v_mov_b32_e32 v106, v159
	v_lshlrev_b32_e32 v106, 16, v106
	v_mul_f32_e32 v114, 0xbfb8aa3b, v106
	v_exp_f32_e32 v114, v114
	s_nop 0
	v_add_f32_e32 v114, 1.0, v114
	v_rcp_f32_e32 v114, v114
	s_nop 0
	v_mul_f32_e32 v106, v114, v106
	v_mul_f32_e32 v106, v110, v106
	v_cvt_pk_bf16_f32 v106, v106, s0
	global_store_short v[140:141], v106, off offset:1088
	s_waitcnt vmcnt(63)
	v_mov_b32_e32 v106, v160
	v_lshlrev_b32_e32 v106, 16, v106
	v_mul_f32_e32 v110, 0xbfb8aa3b, v106
	v_exp_f32_e32 v110, v110
	s_nop 0
	v_add_f32_e32 v110, 1.0, v110
	v_rcp_f32_e32 v110, v110
	s_nop 0
	v_mul_f32_e32 v106, v110, v106
	v_mul_f32_e32 v102, v102, v106
	v_cvt_pk_bf16_f32 v102, v102, s0
	global_store_short v[132:133], v102, off offset:1024
	v_mul_f32_e32 v102, 0x4b800000, v134
	v_cndmask_b32_e64 v102, v134, v102, s[48:49]
	v_rsq_f32_e32 v102, v102
	v_or_b32_e32 v132, 1, v122
	v_ashrrev_i32_e32 v133, 31, v132
	v_lshlrev_b64 v[134:135], 12, v[132:133]
	v_lshl_add_u64 v[134:135], s[58:59], 0, v[134:135]
	v_mul_f32_e32 v106, 0x45800000, v102
	v_lshl_add_u64 v[136:137], v[134:135], 0, v[210:211]
	v_cndmask_b32_e64 v102, v102, v106, s[48:49]
	v_mul_f32_e32 v110, v115, v102
	v_lshlrev_b64 v[132:133], 11, v[132:133]
	v_mul_f32_e32 v110, v149, v110
	v_lshl_add_u64 v[132:133], s[60:61], 0, v[132:133]
	v_mul_f32_e32 v107, v107, v102
	v_mul_f32_e32 v107, v148, v107
	s_waitcnt vmcnt(63)
	v_mov_b32_e32 v106, v161
	v_lshlrev_b32_e32 v106, 16, v106
	v_mul_f32_e32 v114, 0xbfb8aa3b, v106
	v_exp_f32_e32 v114, v114
	s_nop 0
	v_add_f32_e32 v114, 1.0, v114
	v_rcp_f32_e32 v114, v114
	s_nop 0
	v_mul_f32_e32 v106, v114, v106
	v_mul_f32_e32 v106, v106, v110
	v_cvt_pk_bf16_f32 v106, v106, s0
	v_lshl_add_u64 v[114:115], v[132:133], 0, v[210:211]
	global_store_short v[114:115], v106, off offset:1024
	s_waitcnt vmcnt(63)
	v_mov_b32_e32 v106, v162
	v_lshlrev_b32_e32 v106, 16, v106
	v_mul_f32_e32 v110, 0xbfb8aa3b, v106
	v_exp_f32_e32 v110, v110
	s_nop 0
	v_add_f32_e32 v110, 1.0, v110
	v_rcp_f32_e32 v110, v110
	s_nop 0
	v_mul_f32_e32 v106, v110, v106
	v_mul_f32_e32 v106, v107, v106
	v_cvt_pk_bf16_f32 v106, v106, s0
	global_store_short v[114:115], v106, off offset:1056
	v_mul_f32_e32 v107, v111, v102
	v_mul_f32_e32 v107, v147, v107
	v_mul_f32_e32 v102, v103, v102
	v_mul_f32_e32 v102, v146, v102
	s_waitcnt vmcnt(63)
	v_mov_b32_e32 v106, v163
	v_lshlrev_b32_e32 v106, 16, v106
	v_mul_f32_e32 v110, 0xbfb8aa3b, v106
	v_exp_f32_e32 v110, v110
	s_nop 0
	v_add_f32_e32 v110, 1.0, v110
	v_rcp_f32_e32 v110, v110
	s_nop 0
	v_mul_f32_e32 v106, v110, v106
	v_mul_f32_e32 v106, v107, v106
	v_cvt_pk_bf16_f32 v106, v106, s0
	global_store_short v[114:115], v106, off offset:1088
	v_lshl_add_u64 v[106:107], v[134:135], 0, v[118:119]
	s_waitcnt vmcnt(63)
	v_mov_b32_e32 v106, v164
	v_lshlrev_b32_e32 v106, 16, v106
	v_mul_f32_e32 v103, 0xbfb8aa3b, v106
	v_exp_f32_e32 v103, v103
	s_nop 0
	v_add_f32_e32 v103, 1.0, v103
	v_rcp_f32_e32 v103, v103
	s_nop 0
	v_mul_f32_e32 v103, v103, v106
	v_mul_f32_e32 v102, v102, v103
	v_cvt_pk_bf16_f32 v106, v102, s0
	v_lshl_add_u64 v[102:103], v[132:133], 0, v[118:119]
	global_store_short v[102:103], v106, off offset:1024
	v_or_b32_e32 v102, 2, v122
	v_ashrrev_i32_e32 v103, 31, v102
	v_lshlrev_b64 v[106:107], 12, v[102:103]
	v_lshl_add_u64 v[106:107], s[58:59], 0, v[106:107]
	v_lshl_add_u64 v[110:111], v[106:107], 0, v[210:211]
	v_mov_b32_e32 v132, v128
	v_mov_b32_e32 v133, v126
	v_mov_b32_e32 v126, v129
	v_pk_add_f32 v[126:127], v[132:133], v[126:127]
	v_mov_b32_e32 v128, v130
	v_mov_b32_e32 v129, v124
	v_pk_add_f32 v[126:127], v[126:127], v[128:129]
	v_mov_b32_e32 v124, v131
	v_pk_add_f32 v[124:125], v[126:127], v[124:125]
	ds_swizzle_b32 v127, v125 offset:swizzle(SWAP,1)
	ds_swizzle_b32 v126, v124 offset:swizzle(SWAP,1)
	v_lshlrev_b64 v[102:103], 11, v[102:103]
	v_lshl_add_u64 v[102:103], s[60:61], 0, v[102:103]
	v_lshl_add_u64 v[106:107], v[106:107], 0, v[118:119]
	s_waitcnt lgkmcnt(0)
	v_pk_add_f32 v[124:125], v[124:125], v[126:127]
	ds_swizzle_b32 v127, v125 offset:swizzle(SWAP,2)
	ds_swizzle_b32 v126, v124 offset:swizzle(SWAP,2)
	s_waitcnt lgkmcnt(0)
	v_pk_add_f32 v[124:125], v[124:125], v[126:127]
	ds_swizzle_b32 v127, v125 offset:swizzle(SWAP,4)
	ds_swizzle_b32 v126, v124 offset:swizzle(SWAP,4)
	s_waitcnt lgkmcnt(0)
	v_pk_add_f32 v[124:125], v[124:125], v[126:127]
	ds_swizzle_b32 v127, v125 offset:swizzle(SWAP,8)
	ds_swizzle_b32 v126, v124 offset:swizzle(SWAP,8)
	s_waitcnt lgkmcnt(0)
; __device__ __forceinline__ unsigned cvtpk(float lo, float hi) { f32x2_t v = {lo, hi}; bf16x2_t b = __builtin_convertvector(v, bf16x2_t); return __builtin_bit_cast(unsigned, b); }
; template <int X> __device__ __forceinline__ float swz_xor(float v) { return __int_as_float(__builtin_amdgcn_ds_swizzle(__float_as_int(v), (X << 10) | 0x1F)); }
; __device__ __forceinline__ float silu_f(float g) { return g * __builtin_amdgcn_rcpf(1.0f + __expf(-g)); }
; template <bool GLA>
; __device__ __forceinline__ void chunk_pass_c(const ChunkIn& ci, const float* wgl, int unit, unsigned char* wl, int lane, const float* Sb, const float* ng, bf16_t* omix) {
;     ...
;         for (int r = 0; r < 4; ++r) {
;             ss[r] += swz_xor<1>(ss[r]); ss[r] += swz_xor<2>(ss[r]); ss[r] += swz_xor<4>(ss[r]); ss[r] += swz_xor<8>(ss[r]);
;             const float rs = rsqrtf(ss[r] * (1.0f / 64.0f) + EPS);
;             const int t = t0 + 16 * it + 4 * kq + r;
; #pragma unroll
;             for (int et = 0; et < 4; ++et) {
;                 const int e = 16 * et + row;
;                 const float gt = __uint_as_float((unsigned)ci.proj[(size_t)t * DINP + gcol + e] << 16);
;                 const float val = o[et][r] * rs * gn[et] * pg8::silu_f(gt);
;                 omix[(size_t)t * 1024 + ocol + e] = (bf16_t)(cvtpk(val, 0.f) & 0xffffu);
;             }
	v_pk_add_f32 v[124:125], v[124:125], v[126:127]
	s_nop 0
	v_pk_fma_f32 v[124:125], v[124:125], s[6:7], v[120:121] op_sel_hi:[1,0,0]
	s_waitcnt vmcnt(63)
	v_mov_b32_e32 v114, v165
	v_lshlrev_b32_e32 v114, 16, v114
	v_mul_f32_e32 v115, 0xbfb8aa3b, v114
	v_exp_f32_e32 v115, v115
	v_mul_f32_e32 v126, 0x4b800000, v125
	v_cmp_gt_f32_e64 s[50:51], s96, v125
	v_cmp_gt_f32_e64 s[48:49], s96, v124
	v_add_f32_e32 v115, 1.0, v115
	v_cndmask_b32_e64 v125, v125, v126, s[50:51]
	v_rsq_f32_e32 v125, v125
	v_rcp_f32_e32 v115, v115
	v_mul_f32_e32 v126, 0x45800000, v125
	v_cndmask_b32_e64 v125, v125, v126, s[50:51]
	v_mul_f32_e32 v116, v116, v125
	v_mul_f32_e32 v123, v115, v114
	v_mul_f32_e32 v116, v149, v116
	v_mul_f32_e32 v116, v123, v116
	v_lshl_add_u64 v[114:115], v[102:103], 0, v[210:211]
	v_cvt_pk_bf16_f32 v116, v116, s0
	global_store_short v[114:115], v116, off offset:1024
	v_mul_f32_e32 v108, v108, v125
	v_mul_f32_e32 v108, v148, v108
	v_mul_f32_e32 v104, v104, v125
	v_mul_f32_e32 v104, v146, v104
	v_lshl_add_u64 v[102:103], v[102:103], 0, v[118:119]
	s_waitcnt vmcnt(63)
	v_mov_b32_e32 v116, v166
	v_lshlrev_b32_e32 v116, 16, v116
	v_mul_f32_e32 v123, 0xbfb8aa3b, v116
	v_exp_f32_e32 v123, v123
	s_nop 0
	v_add_f32_e32 v123, 1.0, v123
	v_rcp_f32_e32 v123, v123
	s_nop 0
	v_mul_f32_e32 v116, v123, v116
	v_mul_f32_e32 v108, v108, v116
	v_cvt_pk_bf16_f32 v108, v108, s0
	global_store_short v[114:115], v108, off offset:1056
	v_mul_f32_e32 v110, v112, v125
	v_mul_f32_e32 v110, v147, v110
	s_waitcnt vmcnt(63)
	v_mov_b32_e32 v108, v167
	v_lshlrev_b32_e32 v108, 16, v108
	v_mul_f32_e32 v111, 0xbfb8aa3b, v108
	v_exp_f32_e32 v111, v111
	s_nop 0
	v_add_f32_e32 v111, 1.0, v111
	v_rcp_f32_e32 v111, v111
	s_nop 0
	v_mul_f32_e32 v108, v111, v108
	v_mul_f32_e32 v108, v110, v108
	v_cvt_pk_bf16_f32 v108, v108, s0
	global_store_short v[114:115], v108, off offset:1088
	s_waitcnt vmcnt(63)
	v_mov_b32_e32 v106, v168
	v_lshlrev_b32_e32 v106, 16, v106
	v_mul_f32_e32 v107, 0xbfb8aa3b, v106
	v_exp_f32_e32 v107, v107
	s_nop 0
	v_add_f32_e32 v107, 1.0, v107
	v_rcp_f32_e32 v107, v107
	s_nop 0
	v_mul_f32_e32 v106, v107, v106
	v_mul_f32_e32 v104, v104, v106
	v_cvt_pk_bf16_f32 v104, v104, s0
	global_store_short v[102:103], v104, off offset:1024
	v_mul_f32_e32 v102, 0x4b800000, v124
	v_cndmask_b32_e64 v102, v124, v102, s[48:49]
	v_rsq_f32_e32 v102, v102
	s_nop 0
	v_mul_f32_e32 v103, 0x45800000, v102
	v_cndmask_b32_e64 v104, v102, v103, s[48:49]
	v_or_b32_e32 v102, 3, v122
	v_ashrrev_i32_e32 v103, 31, v102
	v_lshlrev_b64 v[106:107], 12, v[102:103]
	v_lshl_add_u64 v[106:107], s[58:59], 0, v[106:107]
	v_lshl_add_u64 v[110:111], v[106:107], 0, v[210:211]
	v_mul_f32_e32 v112, v117, v104
	v_lshlrev_b64 v[102:103], 11, v[102:103]
	v_mul_f32_e32 v112, v149, v112
	v_lshl_add_u64 v[102:103], s[60:61], 0, v[102:103]
	v_mul_f32_e32 v109, v109, v104
	v_mul_f32_e32 v109, v148, v109
	v_lshl_add_u64 v[106:107], v[106:107], 0, v[118:119]
	s_waitcnt vmcnt(63)
	v_mov_b32_e32 v108, v169
	v_lshlrev_b32_e32 v108, 16, v108
	v_mul_f32_e32 v114, 0xbfb8aa3b, v108
	v_exp_f32_e32 v114, v114
	s_nop 0
	v_add_f32_e32 v114, 1.0, v114
	v_rcp_f32_e32 v114, v114
	s_nop 0
	v_mul_f32_e32 v108, v114, v108
	v_mul_f32_e32 v108, v108, v112
	v_cvt_pk_bf16_f32 v108, v108, s0
	v_lshl_add_u64 v[114:115], v[102:103], 0, v[210:211]
	global_store_short v[114:115], v108, off offset:1024
	v_lshl_add_u64 v[102:103], v[102:103], 0, v[118:119]
	s_waitcnt vmcnt(63)
	v_mov_b32_e32 v108, v170
	v_lshlrev_b32_e32 v108, 16, v108
	v_mul_f32_e32 v112, 0xbfb8aa3b, v108
	v_exp_f32_e32 v112, v112
	s_nop 0
	v_add_f32_e32 v112, 1.0, v112
	v_rcp_f32_e32 v112, v112
	s_nop 0
	v_mul_f32_e32 v108, v112, v108
	v_mul_f32_e32 v108, v109, v108
	v_cvt_pk_bf16_f32 v108, v108, s0
	global_store_short v[114:115], v108, off offset:1056
	v_mul_f32_e32 v109, v113, v104
	v_mul_f32_e32 v109, v147, v109
	v_mul_f32_e32 v104, v105, v104
	v_mul_f32_e32 v104, v146, v104
	s_waitcnt vmcnt(63)
	v_mov_b32_e32 v108, v171
	v_lshlrev_b32_e32 v108, 16, v108
	v_mul_f32_e32 v110, 0xbfb8aa3b, v108
	v_exp_f32_e32 v110, v110
	s_nop 0
	v_add_f32_e32 v110, 1.0, v110
	v_rcp_f32_e32 v110, v110
	s_nop 0
	v_mul_f32_e32 v108, v110, v108
	v_mul_f32_e32 v108, v109, v108
	v_cvt_pk_bf16_f32 v108, v108, s0
	global_store_short v[114:115], v108, off offset:1088
	s_waitcnt vmcnt(63)
; template <bool GLA>
; __device__ __forceinline__ void chunk_pass_c(const ChunkIn& ci, const float* wgl, int unit, unsigned char* wl, int lane, const float* Sb, const float* ng, bf16_t* omix) {
;     ...
;     for (int it = 0; it < 4; ++it) {
;         f32x4 st[4];
; #pragma unroll
;         for (int jt = 0; jt < 4; ++jt) {
;             const f32x4 z = {0.f, 0.f, 0.f, 0.f};
;             if (jt < it) st[jt] = __builtin_amdgcn_mfma_f32_16x16x32_bf16(kf[jt], qf[it], z, 0, 0, 0);
;             else if (jt > it) st[jt] = __builtin_amdgcn_mfma_f32_16x16x32_bf16(kb[jt], qb[it], z, 0, 0, 0);
;             else {
;                 const f32x4 lo = __builtin_amdgcn_mfma_f32_16x16x32_bf16(kf[jt], qf[it], z, 0, 0, 0), up = __builtin_amdgcn_mfma_f32_16x16x32_bf16(kb[jt], qb[it], z, 0, 0, 0);
; #pragma unroll
;                 for (int r = 0; r < 4; ++r) st[jt][r] = (4 * kq + r <= row) ? lo[r] : up[r];
;             }
;         }
;         bf16x8 af[2];
; #pragma unroll
;         for (int p = 0; p < 2; ++p)
;             af[p] = __builtin_bit_cast(bf16x8, (u32x4){cvtpk(st[2 * p][0], st[2 * p][1]), cvtpk(st[2 * p][2], st[2 * p][3]), cvtpk(st[2 * p + 1][0], st[2 * p + 1][1]), cvtpk(st[2 * p + 1][2], st[2 * p + 1][3])});
;         f32x4 o[4]; float ss[4] = {0.f, 0.f, 0.f, 0.f};
; #pragma unroll
;         for (int et = 0; et < 4; ++et) {
;             f32x4 acc = {0.f, 0.f, 0.f, 0.f};
;             acc = __builtin_amdgcn_mfma_f32_16x16x32_bf16(af[0], vfr[et][0], acc, 0, 0, 0);
;             acc = __builtin_amdgcn_mfma_f32_16x16x32_bf16(af[1], vfr[et][1], acc, 0, 0, 0);
;             acc = __builtin_amdgcn_mfma_f32_16x16x32_bf16(qf[it], sfr[et], acc, 0, 0, 0);
;             o[et] = acc;
; #pragma unroll
;             for (int r = 0; r < 4; ++r) ss[r] += acc[r] * acc[r];
;         }
; #pragma unroll
;         for (int r = 0; r < 4; ++r) {
;             ss[r] += swz_xor<1>(ss[r]); ss[r] += swz_xor<2>(ss[r]); ss[r] += swz_xor<4>(ss[r]); ss[r] += swz_xor<8>(ss[r]);
;             const float rs = rsqrtf(ss[r] * (1.0f / 64.0f) + EPS);
;             const int t = t0 + 16 * it + 4 * kq + r;
; #pragma unroll
;             for (int et = 0; et < 4; ++et) {
;                 const int e = 16 * et + row;
;                 const float gt = __uint_as_float((unsigned)ci.proj[(size_t)t * DINP + gcol + e] << 16);
;                 const float val = o[et][r] * rs * gn[et] * pg8::silu_f(gt);
	v_mov_b32_e32 v106, v172
	v_lshlrev_b32_e32 v106, 16, v106
	v_mul_f32_e32 v105, 0xbfb8aa3b, v106
	v_exp_f32_e32 v105, v105
	s_nop 0
	v_add_f32_e32 v105, 1.0, v105
	v_rcp_f32_e32 v105, v105
	s_nop 0
	v_mul_f32_e32 v105, v105, v106
	v_mul_f32_e32 v104, v104, v105
	v_cvt_pk_bf16_f32 v104, v104, s0
	v_mfma_f32_16x16x32_bf16 v[106:109], v[8:11], v[88:91], 0
	global_store_short v[102:103], v104, off offset:1024
	v_mfma_f32_16x16x32_bf16 v[102:105], v[0:3], v[88:91], 0
	s_nop 5
	v_cndmask_b32_e32 v106, v106, v98, vcc
	v_cndmask_b32_e64 v107, v99, v107, s[42:43]
	v_cndmask_b32_e64 v108, v108, v100, s[44:45]
	v_cndmask_b32_e64 v109, v109, v101, s[46:47]
	v_mfma_f32_16x16x32_bf16 v[98:101], v[84:87], v[92:95], 0
	v_cvt_pk_bf16_f32 v110, v102, v103
	v_cvt_pk_bf16_f32 v111, v104, v105
	v_cvt_pk_bf16_f32 v112, v106, v107
	v_mfma_f32_16x16x32_bf16 v[92:95], v[72:75], v[92:95], 0
	v_cvt_pk_bf16_f32 v113, v108, v109
	s_nop 2
	v_cvt_pk_bf16_f32 v124, v98, v99
	v_cvt_pk_bf16_f32 v125, v100, v101
	v_mfma_f32_16x16x32_bf16 v[84:87], v[84:87], v[80:83], 0
	v_mfma_f32_16x16x32_bf16 v[80:83], v[72:75], v[80:83], 0
	v_cvt_pk_bf16_f32 v126, v92, v93
	v_cvt_pk_bf16_f32 v127, v94, v95
	v_mfma_f32_16x16x32_bf16 v[92:95], v[110:113], v[64:67], 0
	s_nop 0
	v_mfma_f32_16x16x32_bf16 v[92:95], v[124:127], v[60:63], v[92:95]
	v_mfma_f32_16x16x32_bf16 v[98:101], v[88:91], v[68:71], v[92:95]
	v_mfma_f32_16x16x32_bf16 v[92:95], v[110:113], v[48:51], 0
	v_mfma_f32_16x16x32_bf16 v[92:95], v[124:127], v[44:47], v[92:95]
	s_nop 5
	v_mov_b32_e32 v102, v98
	v_mfma_f32_16x16x32_bf16 v[92:95], v[88:91], v[40:43], v[92:95]
	s_nop 7
	v_mov_b32_e32 v103, v92
	v_pk_mul_f32 v[116:117], v[102:103], v[102:103]
	v_mov_b32_e32 v102, v99
	v_mov_b32_e32 v103, v93
	v_pk_mul_f32 v[122:123], v[102:103], v[102:103]
	v_mov_b32_e32 v102, v100
	v_mov_b32_e32 v103, v94
	v_pk_mul_f32 v[106:107], v[102:103], v[102:103]
	v_mov_b32_e32 v102, v101
	v_mov_b32_e32 v103, v95
	v_pk_mul_f32 v[108:109], v[102:103], v[102:103]
	v_mfma_f32_16x16x32_bf16 v[102:105], v[110:113], v[36:39], 0
	v_mfma_f32_16x16x32_bf16 v[110:113], v[110:113], v[24:27], 0
	v_mfma_f32_16x16x32_bf16 v[102:105], v[124:127], v[32:35], v[102:105]
	v_mfma_f32_16x16x32_bf16 v[110:113], v[124:127], v[20:23], v[110:113]
	v_mfma_f32_16x16x32_bf16 v[102:105], v[88:91], v[28:31], v[102:105]
	v_mfma_f32_16x16x32_bf16 v[88:91], v[88:91], v[16:19], v[110:113]
	s_nop 6
	v_mov_b32_e32 v110, v102
	v_mov_b32_e32 v111, v88
	v_pk_mul_f32 v[124:125], v[110:111], v[110:111]
	v_mov_b32_e32 v110, v103
	v_mov_b32_e32 v111, v89
	v_pk_mul_f32 v[126:127], v[110:111], v[110:111]
	v_mov_b32_e32 v110, v104
	v_mov_b32_e32 v111, v90
	v_pk_mul_f32 v[112:113], v[110:111], v[110:111]
	v_mov_b32_e32 v110, v105
	v_mov_b32_e32 v111, v91
	v_pk_mul_f32 v[114:115], v[110:111], v[110:111]
	v_or_b32_e32 v110, s4, v97
	v_ashrrev_i32_e32 v111, 31, v110
	v_lshlrev_b64 v[128:129], 12, v[110:111]
	v_lshl_add_u64 v[130:131], s[58:59], 0, v[128:129]
	v_lshlrev_b64 v[128:129], 11, v[110:111]
	v_lshl_add_u64 v[132:133], s[60:61], 0, v[128:129]
	v_lshl_add_u64 v[128:129], v[130:131], 0, v[210:211]
	v_lshl_add_u64 v[136:137], v[130:131], 0, v[118:119]
	v_lshl_add_u64 v[130:131], v[132:133], 0, v[118:119]
	s_waitcnt vmcnt(63)
	v_mov_b32_e32 v111, v173
	v_lshlrev_b32_e32 v111, 16, v111
	v_mul_f32_e32 v134, 0xbfb8aa3b, v111
	v_exp_f32_e32 v134, v134
	s_nop 0
	v_add_f32_e32 v134, 1.0, v134
	v_rcp_f32_e32 v134, v134
	s_nop 0
	v_mul_f32_e32 v111, v134, v111
	v_lshl_add_u64 v[134:135], v[132:133], 0, v[210:211]
	v_mov_b32_e32 v132, v122
	v_mov_b32_e32 v133, v116
	v_mov_b32_e32 v116, v123
	v_pk_add_f32 v[116:117], v[132:133], v[116:117]
	v_mov_b32_e32 v122, v126
	v_mov_b32_e32 v123, v124
	v_pk_add_f32 v[116:117], v[116:117], v[122:123]
	v_mov_b32_e32 v124, v127
	v_pk_add_f32 v[116:117], v[116:117], v[124:125]
	ds_swizzle_b32 v123, v117 offset:swizzle(SWAP,1)
	ds_swizzle_b32 v122, v116 offset:swizzle(SWAP,1)
	s_waitcnt lgkmcnt(0)
	v_pk_add_f32 v[116:117], v[116:117], v[122:123]
	ds_swizzle_b32 v123, v117 offset:swizzle(SWAP,2)
	ds_swizzle_b32 v122, v116 offset:swizzle(SWAP,2)
	s_waitcnt lgkmcnt(0)
	v_pk_add_f32 v[116:117], v[116:117], v[122:123]
	ds_swizzle_b32 v123, v117 offset:swizzle(SWAP,4)
	ds_swizzle_b32 v122, v116 offset:swizzle(SWAP,4)
	s_waitcnt lgkmcnt(0)
	v_pk_add_f32 v[116:117], v[116:117], v[122:123]
	ds_swizzle_b32 v123, v117 offset:swizzle(SWAP,8)
	ds_swizzle_b32 v122, v116 offset:swizzle(SWAP,8)
	s_waitcnt lgkmcnt(0)
	v_pk_add_f32 v[116:117], v[116:117], v[122:123]
	s_nop 0
	v_pk_fma_f32 v[116:117], v[116:117], s[6:7], v[120:121] op_sel_hi:[1,0,0]
	s_nop 0
	v_mul_f32_e32 v122, 0x4b800000, v117
	v_cmp_gt_f32_e64 s[50:51], s96, v117
	v_cmp_gt_f32_e64 s[48:49], s96, v116
	s_nop 0
	v_cndmask_b32_e64 v117, v117, v122, s[50:51]
	v_rsq_f32_e32 v117, v117
	s_nop 0
	v_mul_f32_e32 v122, 0x45800000, v117
	v_cndmask_b32_e64 v117, v117, v122, s[50:51]
	v_mul_f32_e32 v98, v98, v117
	v_mul_f32_e32 v98, v149, v98
	v_mul_f32_e32 v98, v111, v98
	v_cvt_pk_bf16_f32 v98, v98, s0
	global_store_short v[134:135], v98, off offset:1024
	v_mul_f32_e32 v92, v92, v117
	v_mul_f32_e32 v92, v148, v92
	v_mul_f32_e32 v88, v88, v117
	v_mul_f32_e32 v88, v146, v88
	s_waitcnt vmcnt(63)
	v_mov_b32_e32 v98, v174
	v_lshlrev_b32_e32 v98, 16, v98
	v_mul_f32_e32 v111, 0xbfb8aa3b, v98
	v_exp_f32_e32 v111, v111
	s_nop 0
	v_add_f32_e32 v111, 1.0, v111
	v_rcp_f32_e32 v111, v111
	s_nop 0
	v_mul_f32_e32 v98, v111, v98
	v_mul_f32_e32 v92, v98, v92
	v_cvt_pk_bf16_f32 v92, v92, s0
	global_store_short v[134:135], v92, off offset:1056
	v_mul_f32_e32 v98, v102, v117
	v_mul_f32_e32 v98, v147, v98
	s_waitcnt vmcnt(63)
; __device__ __forceinline__ unsigned cvtpk(float lo, float hi) { f32x2_t v = {lo, hi}; bf16x2_t b = __builtin_convertvector(v, bf16x2_t); return __builtin_bit_cast(unsigned, b); }
; template <int X> __device__ __forceinline__ float swz_xor(float v) { return __int_as_float(__builtin_amdgcn_ds_swizzle(__float_as_int(v), (X << 10) | 0x1F)); }
; __device__ __forceinline__ float silu_f(float g) { return g * __builtin_amdgcn_rcpf(1.0f + __expf(-g)); }
; template <bool GLA>
; __device__ __forceinline__ void chunk_pass_c(const ChunkIn& ci, const float* wgl, int unit, unsigned char* wl, int lane, const float* Sb, const float* ng, bf16_t* omix) {
;     ...
;         for (int r = 0; r < 4; ++r) {
;             ss[r] += swz_xor<1>(ss[r]); ss[r] += swz_xor<2>(ss[r]); ss[r] += swz_xor<4>(ss[r]); ss[r] += swz_xor<8>(ss[r]);
;             const float rs = rsqrtf(ss[r] * (1.0f / 64.0f) + EPS);
;             const int t = t0 + 16 * it + 4 * kq + r;
; #pragma unroll
;             for (int et = 0; et < 4; ++et) {
;                 const int e = 16 * et + row;
;                 const float gt = __uint_as_float((unsigned)ci.proj[(size_t)t * DINP + gcol + e] << 16);
;                 const float val = o[et][r] * rs * gn[et] * pg8::silu_f(gt);
;                 omix[(size_t)t * 1024 + ocol + e] = (bf16_t)(cvtpk(val, 0.f) & 0xffffu);
;             }
	v_mov_b32_e32 v92, v175
	v_lshlrev_b32_e32 v92, 16, v92
	v_mul_f32_e32 v102, 0xbfb8aa3b, v92
	v_exp_f32_e32 v102, v102
	s_nop 0
	v_add_f32_e32 v102, 1.0, v102
	v_rcp_f32_e32 v102, v102
	s_nop 0
	v_mul_f32_e32 v92, v102, v92
	v_mul_f32_e32 v92, v98, v92
	v_cvt_pk_bf16_f32 v92, v92, s0
	global_store_short v[134:135], v92, off offset:1088
	s_waitcnt vmcnt(63)
	v_mov_b32_e32 v92, v176
	v_lshlrev_b32_e32 v92, 16, v92
	v_mul_f32_e32 v98, 0xbfb8aa3b, v92
	v_exp_f32_e32 v98, v98
	s_nop 0
	v_add_f32_e32 v98, 1.0, v98
	v_rcp_f32_e32 v98, v98
	s_nop 0
	v_mul_f32_e32 v92, v98, v92
	v_mul_f32_e32 v88, v88, v92
	v_cvt_pk_bf16_f32 v88, v88, s0
	global_store_short v[130:131], v88, off offset:1024
	v_mul_f32_e32 v88, 0x4b800000, v116
	v_cndmask_b32_e64 v88, v116, v88, s[48:49]
	v_rsq_f32_e32 v88, v88
	v_or_b32_e32 v116, 1, v110
	v_ashrrev_i32_e32 v117, 31, v116
	v_lshlrev_b64 v[122:123], 12, v[116:117]
	v_lshl_add_u64 v[122:123], s[58:59], 0, v[122:123]
	v_mul_f32_e32 v92, 0x45800000, v88
	v_lshl_add_u64 v[124:125], v[122:123], 0, v[210:211]
	v_cndmask_b32_e64 v88, v88, v92, s[48:49]
	v_mul_f32_e32 v98, v99, v88
	v_lshlrev_b64 v[116:117], 11, v[116:117]
	v_mul_f32_e32 v98, v149, v98
	v_lshl_add_u64 v[116:117], s[60:61], 0, v[116:117]
	v_mul_f32_e32 v93, v93, v88
	v_mul_f32_e32 v93, v148, v93
	s_waitcnt vmcnt(63)
	v_mov_b32_e32 v92, v177
	v_lshlrev_b32_e32 v92, 16, v92
	v_mul_f32_e32 v99, 0xbfb8aa3b, v92
	v_exp_f32_e32 v99, v99
	s_nop 0
	v_add_f32_e32 v99, 1.0, v99
	v_rcp_f32_e32 v99, v99
	s_nop 0
	v_mul_f32_e32 v92, v99, v92
	v_mul_f32_e32 v92, v92, v98
	v_cvt_pk_bf16_f32 v92, v92, s0
	v_lshl_add_u64 v[98:99], v[116:117], 0, v[210:211]
	global_store_short v[98:99], v92, off offset:1024
	s_waitcnt vmcnt(63)
	v_mov_b32_e32 v92, v178
	v_lshlrev_b32_e32 v92, 16, v92
	v_mul_f32_e32 v102, 0xbfb8aa3b, v92
	v_exp_f32_e32 v102, v102
	s_nop 0
	v_add_f32_e32 v102, 1.0, v102
	v_rcp_f32_e32 v102, v102
	s_nop 0
	v_mul_f32_e32 v92, v102, v92
	v_mul_f32_e32 v92, v93, v92
	v_cvt_pk_bf16_f32 v92, v92, s0
	global_store_short v[98:99], v92, off offset:1056
	v_mul_f32_e32 v93, v103, v88
	v_mul_f32_e32 v93, v147, v93
	v_mul_f32_e32 v88, v89, v88
	v_mul_f32_e32 v88, v146, v88
	s_waitcnt vmcnt(63)
	v_mov_b32_e32 v92, v179
	v_lshlrev_b32_e32 v92, 16, v92
	v_mul_f32_e32 v102, 0xbfb8aa3b, v92
	v_exp_f32_e32 v102, v102
	s_nop 0
	v_add_f32_e32 v102, 1.0, v102
	v_rcp_f32_e32 v102, v102
	s_nop 0
	v_mul_f32_e32 v92, v102, v92
	v_mul_f32_e32 v92, v93, v92
	v_cvt_pk_bf16_f32 v92, v92, s0
	global_store_short v[98:99], v92, off offset:1088
	v_lshl_add_u64 v[92:93], v[122:123], 0, v[118:119]
	s_waitcnt vmcnt(63)
	v_mov_b32_e32 v92, v180
	v_lshlrev_b32_e32 v92, 16, v92
	v_mul_f32_e32 v89, 0xbfb8aa3b, v92
	v_exp_f32_e32 v89, v89
	s_nop 0
	v_add_f32_e32 v89, 1.0, v89
	v_rcp_f32_e32 v89, v89
	s_nop 0
	v_mul_f32_e32 v89, v89, v92
	v_mul_f32_e32 v88, v88, v89
	v_cvt_pk_bf16_f32 v92, v88, s0
	v_lshl_add_u64 v[88:89], v[116:117], 0, v[118:119]
	global_store_short v[88:89], v92, off offset:1024
	v_or_b32_e32 v88, 2, v110
	v_ashrrev_i32_e32 v89, 31, v88
	v_lshlrev_b64 v[92:93], 12, v[88:89]
	v_lshl_add_u64 v[92:93], s[58:59], 0, v[92:93]
	v_lshl_add_u64 v[98:99], v[92:93], 0, v[210:211]
	v_mov_b32_e32 v116, v108
	v_mov_b32_e32 v117, v106
	v_mov_b32_e32 v106, v109
	v_pk_add_f32 v[106:107], v[116:117], v[106:107]
	v_mov_b32_e32 v108, v114
	v_mov_b32_e32 v109, v112
	v_pk_add_f32 v[106:107], v[106:107], v[108:109]
	v_mov_b32_e32 v112, v115
	v_pk_add_f32 v[106:107], v[106:107], v[112:113]
	ds_swizzle_b32 v109, v107 offset:swizzle(SWAP,1)
	ds_swizzle_b32 v108, v106 offset:swizzle(SWAP,1)
	v_lshlrev_b64 v[88:89], 11, v[88:89]
	v_lshl_add_u64 v[88:89], s[60:61], 0, v[88:89]
	v_lshl_add_u64 v[92:93], v[92:93], 0, v[118:119]
	s_waitcnt lgkmcnt(0)
	v_pk_add_f32 v[106:107], v[106:107], v[108:109]
	ds_swizzle_b32 v109, v107 offset:swizzle(SWAP,2)
	ds_swizzle_b32 v108, v106 offset:swizzle(SWAP,2)
	s_waitcnt lgkmcnt(0)
	v_pk_add_f32 v[106:107], v[106:107], v[108:109]
	ds_swizzle_b32 v109, v107 offset:swizzle(SWAP,4)
	ds_swizzle_b32 v108, v106 offset:swizzle(SWAP,4)
	s_waitcnt lgkmcnt(0)
	v_pk_add_f32 v[106:107], v[106:107], v[108:109]
	ds_swizzle_b32 v109, v107 offset:swizzle(SWAP,8)
	ds_swizzle_b32 v108, v106 offset:swizzle(SWAP,8)
	s_waitcnt lgkmcnt(0)
	v_pk_add_f32 v[106:107], v[106:107], v[108:109]
	s_nop 0
	v_pk_fma_f32 v[106:107], v[106:107], s[6:7], v[120:121] op_sel_hi:[1,0,0]
	s_waitcnt vmcnt(63)
	v_mov_b32_e32 v102, v181
	v_lshlrev_b32_e32 v102, 16, v102
	v_mul_f32_e32 v103, 0xbfb8aa3b, v102
	v_exp_f32_e32 v103, v103
	v_mul_f32_e32 v108, 0x4b800000, v107
	v_cmp_gt_f32_e64 s[50:51], s96, v107
	v_cmp_gt_f32_e64 s[48:49], s96, v106
	v_add_f32_e32 v103, 1.0, v103
	v_cndmask_b32_e64 v107, v107, v108, s[50:51]
	v_rsq_f32_e32 v107, v107
	v_rcp_f32_e32 v103, v103
	v_mul_f32_e32 v108, 0x45800000, v107
	v_cndmask_b32_e64 v107, v107, v108, s[50:51]
	v_mul_f32_e32 v100, v100, v107
	v_mul_f32_e32 v111, v103, v102
	v_mul_f32_e32 v100, v149, v100
	v_mul_f32_e32 v100, v111, v100
	v_lshl_add_u64 v[102:103], v[88:89], 0, v[210:211]
	v_cvt_pk_bf16_f32 v100, v100, s0
	global_store_short v[102:103], v100, off offset:1024
	v_mul_f32_e32 v94, v94, v107
	v_mul_f32_e32 v94, v148, v94
	v_mul_f32_e32 v90, v90, v107
	v_mul_f32_e32 v90, v146, v90
	v_lshl_add_u64 v[88:89], v[88:89], 0, v[118:119]
	v_cvt_pk_bf16_f32 v111, v82, v83
	s_waitcnt vmcnt(63)
	v_mov_b32_e32 v100, v182
	v_lshlrev_b32_e32 v100, 16, v100
	v_mul_f32_e32 v108, 0xbfb8aa3b, v100
	v_exp_f32_e32 v108, v108
	s_nop 0
	v_add_f32_e32 v108, 1.0, v108
	v_rcp_f32_e32 v108, v108
	s_nop 0
	v_mul_f32_e32 v100, v108, v100
	v_mul_f32_e32 v94, v94, v100
	v_cvt_pk_bf16_f32 v94, v94, s0
	global_store_short v[102:103], v94, off offset:1056
	v_mul_f32_e32 v98, v104, v107
	v_mul_f32_e32 v98, v147, v98
	s_waitcnt vmcnt(63)
; template <bool GLA>
; __device__ __forceinline__ void chunk_pass_c(const ChunkIn& ci, const float* wgl, int unit, unsigned char* wl, int lane, const float* Sb, const float* ng, bf16_t* omix) {
;     ...
;     for (int it = 0; it < 4; ++it) {
;         f32x4 st[4];
; #pragma unroll
;         for (int jt = 0; jt < 4; ++jt) {
;             const f32x4 z = {0.f, 0.f, 0.f, 0.f};
;             if (jt < it) st[jt] = __builtin_amdgcn_mfma_f32_16x16x32_bf16(kf[jt], qf[it], z, 0, 0, 0);
;             else if (jt > it) st[jt] = __builtin_amdgcn_mfma_f32_16x16x32_bf16(kb[jt], qb[it], z, 0, 0, 0);
;             else {
;                 const f32x4 lo = __builtin_amdgcn_mfma_f32_16x16x32_bf16(kf[jt], qf[it], z, 0, 0, 0), up = __builtin_amdgcn_mfma_f32_16x16x32_bf16(kb[jt], qb[it], z, 0, 0, 0);
; #pragma unroll
;                 for (int r = 0; r < 4; ++r) st[jt][r] = (4 * kq + r <= row) ? lo[r] : up[r];
;             }
;         }
;         bf16x8 af[2];
; #pragma unroll
;         for (int p = 0; p < 2; ++p)
;             af[p] = __builtin_bit_cast(bf16x8, (u32x4){cvtpk(st[2 * p][0], st[2 * p][1]), cvtpk(st[2 * p][2], st[2 * p][3]), cvtpk(st[2 * p + 1][0], st[2 * p + 1][1]), cvtpk(st[2 * p + 1][2], st[2 * p + 1][3])});
;         f32x4 o[4]; float ss[4] = {0.f, 0.f, 0.f, 0.f};
; #pragma unroll
;         for (int et = 0; et < 4; ++et) {
;             f32x4 acc = {0.f, 0.f, 0.f, 0.f};
;             acc = __builtin_amdgcn_mfma_f32_16x16x32_bf16(af[0], vfr[et][0], acc, 0, 0, 0);
;             acc = __builtin_amdgcn_mfma_f32_16x16x32_bf16(af[1], vfr[et][1], acc, 0, 0, 0);
;             acc = __builtin_amdgcn_mfma_f32_16x16x32_bf16(qf[it], sfr[et], acc, 0, 0, 0);
;             o[et] = acc;
; #pragma unroll
;             for (int r = 0; r < 4; ++r) ss[r] += acc[r] * acc[r];
;         }
; #pragma unroll
;         for (int r = 0; r < 4; ++r) {
;             ss[r] += swz_xor<1>(ss[r]); ss[r] += swz_xor<2>(ss[r]); ss[r] += swz_xor<4>(ss[r]); ss[r] += swz_xor<8>(ss[r]);
;             const float rs = rsqrtf(ss[r] * (1.0f / 64.0f) + EPS);
;             const int t = t0 + 16 * it + 4 * kq + r;
; #pragma unroll
;             for (int et = 0; et < 4; ++et) {
;                 const int e = 16 * et + row;
;                 const float gt = __uint_as_float((unsigned)ci.proj[(size_t)t * DINP + gcol + e] << 16);
;                 const float val = o[et][r] * rs * gn[et] * pg8::silu_f(gt);
	v_mov_b32_e32 v94, v183
	v_lshlrev_b32_e32 v94, 16, v94
	v_mul_f32_e32 v99, 0xbfb8aa3b, v94
	v_exp_f32_e32 v99, v99
	s_nop 0
	v_add_f32_e32 v99, 1.0, v99
	v_rcp_f32_e32 v99, v99
	s_nop 0
	v_mul_f32_e32 v94, v99, v94
	v_mul_f32_e32 v94, v98, v94
	v_cvt_pk_bf16_f32 v94, v94, s0
	global_store_short v[102:103], v94, off offset:1088
	s_waitcnt vmcnt(63)
	v_mov_b32_e32 v92, v184
	v_lshlrev_b32_e32 v92, 16, v92
	v_mul_f32_e32 v93, 0xbfb8aa3b, v92
	v_exp_f32_e32 v93, v93
	s_nop 0
	v_add_f32_e32 v93, 1.0, v93
	v_rcp_f32_e32 v93, v93
	s_nop 0
	v_mul_f32_e32 v92, v93, v92
	v_mul_f32_e32 v90, v90, v92
	v_cvt_pk_bf16_f32 v90, v90, s0
	global_store_short v[88:89], v90, off offset:1024
	v_mul_f32_e32 v88, 0x4b800000, v106
	v_cndmask_b32_e64 v88, v106, v88, s[48:49]
	v_rsq_f32_e32 v88, v88
	s_nop 0
	v_mul_f32_e32 v89, 0x45800000, v88
	v_cndmask_b32_e64 v90, v88, v89, s[48:49]
	v_or_b32_e32 v88, 3, v110
	v_ashrrev_i32_e32 v89, 31, v88
	v_lshlrev_b64 v[92:93], 12, v[88:89]
	v_lshl_add_u64 v[92:93], s[58:59], 0, v[92:93]
	v_lshl_add_u64 v[98:99], v[92:93], 0, v[210:211]
	v_mul_f32_e32 v100, v101, v90
	v_lshlrev_b64 v[88:89], 11, v[88:89]
	v_mul_f32_e32 v100, v149, v100
	v_lshl_add_u64 v[88:89], s[60:61], 0, v[88:89]
	v_mul_f32_e32 v95, v95, v90
	v_mul_f32_e32 v95, v148, v95
	v_lshl_add_u64 v[92:93], v[92:93], 0, v[118:119]
	v_cvt_pk_bf16_f32 v110, v80, v81
	s_waitcnt vmcnt(63)
	v_mov_b32_e32 v94, v185
	v_lshlrev_b32_e32 v94, 16, v94
	v_mul_f32_e32 v101, 0xbfb8aa3b, v94
	v_exp_f32_e32 v101, v101
	s_nop 0
	v_add_f32_e32 v101, 1.0, v101
	v_rcp_f32_e32 v101, v101
	s_nop 0
	v_mul_f32_e32 v94, v101, v94
	v_mul_f32_e32 v94, v94, v100
	v_cvt_pk_bf16_f32 v94, v94, s0
	v_lshl_add_u64 v[100:101], v[88:89], 0, v[210:211]
	global_store_short v[100:101], v94, off offset:1024
	v_lshl_add_u64 v[88:89], v[88:89], 0, v[118:119]
	s_waitcnt vmcnt(63)
	v_mov_b32_e32 v94, v186
	v_lshlrev_b32_e32 v94, 16, v94
	v_mul_f32_e32 v102, 0xbfb8aa3b, v94
	v_exp_f32_e32 v102, v102
	s_nop 0
	v_add_f32_e32 v102, 1.0, v102
	v_rcp_f32_e32 v102, v102
	s_nop 0
	v_mul_f32_e32 v94, v102, v94
	v_mul_f32_e32 v94, v95, v94
	v_cvt_pk_bf16_f32 v94, v94, s0
	global_store_short v[100:101], v94, off offset:1056
	v_mul_f32_e32 v95, v105, v90
	v_mul_f32_e32 v95, v147, v95
	v_mul_f32_e32 v90, v91, v90
	v_mul_f32_e32 v90, v146, v90
	s_waitcnt vmcnt(63)
	v_mov_b32_e32 v94, v187
	v_lshlrev_b32_e32 v94, 16, v94
	v_mul_f32_e32 v98, 0xbfb8aa3b, v94
	v_exp_f32_e32 v98, v98
	s_nop 0
	v_add_f32_e32 v98, 1.0, v98
	v_rcp_f32_e32 v98, v98
	s_nop 0
	v_mul_f32_e32 v94, v98, v94
	v_mul_f32_e32 v94, v95, v94
	v_cvt_pk_bf16_f32 v94, v94, s0
	global_store_short v[100:101], v94, off offset:1088
	v_mfma_f32_16x16x32_bf16 v[98:101], v[4:7], v[76:79], 0
	s_waitcnt vmcnt(63)
	v_mov_b32_e32 v92, v188
	v_lshlrev_b32_e32 v92, 16, v92
	v_mul_f32_e32 v91, 0xbfb8aa3b, v92
	v_exp_f32_e32 v91, v91
	s_nop 3
	v_cndmask_b32_e64 v86, v100, v86, s[44:45]
	v_cndmask_b32_e64 v87, v101, v87, s[46:47]
	v_cndmask_b32_e32 v84, v98, v84, vcc
	v_add_f32_e32 v91, 1.0, v91
	v_rcp_f32_e32 v91, v91
	v_cndmask_b32_e64 v85, v85, v99, s[42:43]
	v_cvt_pk_bf16_f32 v108, v84, v85
	v_cvt_pk_bf16_f32 v109, v86, v87
	v_mul_f32_e32 v91, v91, v92
	v_mul_f32_e32 v90, v90, v91
	v_cvt_pk_bf16_f32 v90, v90, s0
	global_store_short v[88:89], v90, off offset:1024
	v_mfma_f32_16x16x32_bf16 v[88:91], v[0:3], v[76:79], 0
	v_mfma_f32_16x16x32_bf16 v[92:95], v[8:11], v[76:79], 0
	v_mfma_f32_16x16x32_bf16 v[0:3], v[0:3], v[12:15], 0
	s_nop 5
	v_cvt_pk_bf16_f32 v100, v88, v89
	v_cvt_pk_bf16_f32 v101, v90, v91
	v_cvt_pk_bf16_f32 v102, v92, v93
	v_cvt_pk_bf16_f32 v103, v94, v95
	v_mfma_f32_16x16x32_bf16 v[8:11], v[8:11], v[12:15], 0
	v_cvt_pk_bf16_f32 v52, v0, v1
	v_cvt_pk_bf16_f32 v53, v2, v3
	v_mfma_f32_16x16x32_bf16 v[80:83], v[100:103], v[64:67], 0
	v_mfma_f32_16x16x32_bf16 v[80:83], v[108:111], v[60:63], v[80:83]
	s_nop 3
	v_cvt_pk_bf16_f32 v54, v8, v9
	v_cvt_pk_bf16_f32 v55, v10, v11
	v_mfma_f32_16x16x32_bf16 v[84:87], v[76:79], v[68:71], v[80:83]
	v_mfma_f32_16x16x32_bf16 v[80:83], v[100:103], v[48:51], 0
	v_mfma_f32_16x16x32_bf16 v[80:83], v[108:111], v[44:47], v[80:83]
	s_nop 5
	v_mov_b32_e32 v88, v84
	v_mfma_f32_16x16x32_bf16 v[80:83], v[76:79], v[40:43], v[80:83]
	v_mfma_f32_16x16x32_bf16 v[4:7], v[4:7], v[12:15], 0
	v_mfma_f32_16x16x32_bf16 v[0:3], v[52:55], v[64:67], 0
	s_nop 5
	v_mov_b32_e32 v89, v80
	v_pk_mul_f32 v[104:105], v[88:89], v[88:89]
	v_mov_b32_e32 v88, v85
	v_mov_b32_e32 v89, v81
	v_pk_mul_f32 v[106:107], v[88:89], v[88:89]
	v_mov_b32_e32 v88, v86
	v_mov_b32_e32 v89, v82
	v_pk_mul_f32 v[92:93], v[88:89], v[88:89]
	v_mov_b32_e32 v88, v87
	v_mov_b32_e32 v89, v83
	v_pk_mul_f32 v[98:99], v[88:89], v[88:89]
	v_mfma_f32_16x16x32_bf16 v[88:91], v[100:103], v[36:39], 0
	v_cvt_pk_bf16_f32 v4, v4, v5
	v_cvt_pk_bf16_f32 v5, v6, v7
	v_cvt_pk_bf16_f32 v6, v56, v57
	v_mfma_f32_16x16x32_bf16 v[100:103], v[100:103], v[24:27], 0
	v_cvt_pk_bf16_f32 v7, v58, v59
	v_mfma_f32_16x16x32_bf16 v[88:91], v[108:111], v[32:35], v[88:91]
	v_mfma_f32_16x16x32_bf16 v[100:103], v[108:111], v[20:23], v[100:103]
	v_mfma_f32_16x16x32_bf16 v[88:91], v[76:79], v[28:31], v[88:91]
	v_mfma_f32_16x16x32_bf16 v[76:79], v[76:79], v[16:19], v[100:103]
	v_mfma_f32_16x16x32_bf16 v[0:3], v[4:7], v[60:63], v[0:3]
	s_nop 5
	v_mov_b32_e32 v94, v88
	v_mov_b32_e32 v95, v76
	v_pk_mul_f32 v[108:109], v[94:95], v[94:95]
	v_mov_b32_e32 v94, v89
	v_mov_b32_e32 v95, v77
	v_pk_mul_f32 v[110:111], v[94:95], v[94:95]
	v_mov_b32_e32 v94, v90
	v_mov_b32_e32 v95, v78
	v_pk_mul_f32 v[100:101], v[94:95], v[94:95]
	v_mov_b32_e32 v94, v91
	v_mov_b32_e32 v95, v79
	v_pk_mul_f32 v[102:103], v[94:95], v[94:95]
	v_or_b32_e32 v94, s65, v97
	v_ashrrev_i32_e32 v95, 31, v94
	v_lshlrev_b64 v[112:113], 12, v[94:95]
	v_lshl_add_u64 v[114:115], s[58:59], 0, v[112:113]
	v_lshlrev_b64 v[112:113], 11, v[94:95]
	v_lshl_add_u64 v[116:117], s[60:61], 0, v[112:113]
	v_lshl_add_u64 v[112:113], v[114:115], 0, v[210:211]
	v_lshl_add_u64 v[124:125], v[114:115], 0, v[118:119]
	v_lshl_add_u64 v[114:115], v[116:117], 0, v[118:119]
	v_mfma_f32_16x16x32_bf16 v[8:11], v[12:15], v[68:71], v[0:3]
	s_waitcnt vmcnt(63)
; template <bool GLA>
; __device__ __forceinline__ void chunk_pass_c(const ChunkIn& ci, const float* wgl, int unit, unsigned char* wl, int lane, const float* Sb, const float* ng, bf16_t* omix) {
;     ...
;     for (int it = 0; it < 4; ++it) {
;         f32x4 st[4];
; #pragma unroll
;         for (int jt = 0; jt < 4; ++jt) {
;             const f32x4 z = {0.f, 0.f, 0.f, 0.f};
;             if (jt < it) st[jt] = __builtin_amdgcn_mfma_f32_16x16x32_bf16(kf[jt], qf[it], z, 0, 0, 0);
;             else if (jt > it) st[jt] = __builtin_amdgcn_mfma_f32_16x16x32_bf16(kb[jt], qb[it], z, 0, 0, 0);
;             else {
;                 const f32x4 lo = __builtin_amdgcn_mfma_f32_16x16x32_bf16(kf[jt], qf[it], z, 0, 0, 0), up = __builtin_amdgcn_mfma_f32_16x16x32_bf16(kb[jt], qb[it], z, 0, 0, 0);
; #pragma unroll
;                 for (int r = 0; r < 4; ++r) st[jt][r] = (4 * kq + r <= row) ? lo[r] : up[r];
;             }
;         }
;         bf16x8 af[2];
; #pragma unroll
;         for (int p = 0; p < 2; ++p)
;             af[p] = __builtin_bit_cast(bf16x8, (u32x4){cvtpk(st[2 * p][0], st[2 * p][1]), cvtpk(st[2 * p][2], st[2 * p][3]), cvtpk(st[2 * p + 1][0], st[2 * p + 1][1]), cvtpk(st[2 * p + 1][2], st[2 * p + 1][3])});
;         f32x4 o[4]; float ss[4] = {0.f, 0.f, 0.f, 0.f};
; #pragma unroll
;         for (int et = 0; et < 4; ++et) {
;             f32x4 acc = {0.f, 0.f, 0.f, 0.f};
;             acc = __builtin_amdgcn_mfma_f32_16x16x32_bf16(af[0], vfr[et][0], acc, 0, 0, 0);
;             acc = __builtin_amdgcn_mfma_f32_16x16x32_bf16(af[1], vfr[et][1], acc, 0, 0, 0);
;             acc = __builtin_amdgcn_mfma_f32_16x16x32_bf16(qf[it], sfr[et], acc, 0, 0, 0);
;             o[et] = acc;
; #pragma unroll
;             for (int r = 0; r < 4; ++r) ss[r] += acc[r] * acc[r];
;         }
; #pragma unroll
;         for (int r = 0; r < 4; ++r) {
;             ss[r] += swz_xor<1>(ss[r]); ss[r] += swz_xor<2>(ss[r]); ss[r] += swz_xor<4>(ss[r]); ss[r] += swz_xor<8>(ss[r]);
;             const float rs = rsqrtf(ss[r] * (1.0f / 64.0f) + EPS);
;             const int t = t0 + 16 * it + 4 * kq + r;
; #pragma unroll
;             for (int et = 0; et < 4; ++et) {
;                 const int e = 16 * et + row;
;                 const float gt = __uint_as_float((unsigned)ci.proj[(size_t)t * DINP + gcol + e] << 16);
;                 const float val = o[et][r] * rs * gn[et] * pg8::silu_f(gt);
	v_mov_b32_e32 v95, v189
	v_lshlrev_b32_e32 v95, 16, v95
	v_mul_f32_e32 v122, 0xbfb8aa3b, v95
	v_exp_f32_e32 v122, v122
	v_mfma_f32_16x16x32_bf16 v[0:3], v[52:55], v[48:51], 0
	v_add_f32_e32 v122, 1.0, v122
	v_rcp_f32_e32 v122, v122
	v_mfma_f32_16x16x32_bf16 v[36:39], v[52:55], v[36:39], 0
	v_mul_f32_e32 v95, v122, v95
	v_lshl_add_u64 v[122:123], v[116:117], 0, v[210:211]
	v_mov_b32_e32 v116, v106
	v_mov_b32_e32 v117, v104
	v_mov_b32_e32 v104, v107
	v_pk_add_f32 v[104:105], v[116:117], v[104:105]
	v_mov_b32_e32 v106, v110
	v_mov_b32_e32 v107, v108
	v_pk_add_f32 v[104:105], v[104:105], v[106:107]
	v_mov_b32_e32 v108, v111
	v_pk_add_f32 v[104:105], v[104:105], v[108:109]
	ds_swizzle_b32 v107, v105 offset:swizzle(SWAP,1)
	ds_swizzle_b32 v106, v104 offset:swizzle(SWAP,1)
	v_mfma_f32_16x16x32_bf16 v[24:27], v[52:55], v[24:27], 0
	s_waitcnt lgkmcnt(0)
	v_pk_add_f32 v[104:105], v[104:105], v[106:107]
	ds_swizzle_b32 v107, v105 offset:swizzle(SWAP,2)
	ds_swizzle_b32 v106, v104 offset:swizzle(SWAP,2)
	v_mfma_f32_16x16x32_bf16 v[0:3], v[4:7], v[44:47], v[0:3]
	s_waitcnt lgkmcnt(0)
	v_pk_add_f32 v[104:105], v[104:105], v[106:107]
	ds_swizzle_b32 v107, v105 offset:swizzle(SWAP,4)
	ds_swizzle_b32 v106, v104 offset:swizzle(SWAP,4)
	v_mfma_f32_16x16x32_bf16 v[32:35], v[4:7], v[32:35], v[36:39]
	s_waitcnt lgkmcnt(0)
	v_pk_add_f32 v[104:105], v[104:105], v[106:107]
	ds_swizzle_b32 v107, v105 offset:swizzle(SWAP,8)
	ds_swizzle_b32 v106, v104 offset:swizzle(SWAP,8)
	v_mfma_f32_16x16x32_bf16 v[4:7], v[4:7], v[20:23], v[24:27]
	s_waitcnt lgkmcnt(0)
	v_pk_add_f32 v[104:105], v[104:105], v[106:107]
	s_nop 0
	v_pk_fma_f32 v[104:105], v[104:105], s[6:7], v[120:121] op_sel_hi:[1,0,0]
	v_mfma_f32_16x16x32_bf16 v[28:31], v[12:15], v[28:31], v[32:35]
	v_mul_f32_e32 v106, 0x4b800000, v105
	v_cmp_gt_f32_e64 s[50:51], s96, v105
	v_cmp_gt_f32_e64 s[48:49], s96, v104
	v_mfma_f32_16x16x32_bf16 v[4:7], v[12:15], v[16:19], v[4:7]
	v_cndmask_b32_e64 v105, v105, v106, s[50:51]
	v_rsq_f32_e32 v105, v105
	v_mfma_f32_16x16x32_bf16 v[0:3], v[12:15], v[40:43], v[0:3]
	s_nop 0
	v_mov_b32_e32 v12, v28
	v_mul_f32_e32 v106, 0x45800000, v105
	v_cndmask_b32_e64 v105, v105, v106, s[50:51]
	v_mul_f32_e32 v84, v84, v105
	v_mul_f32_e32 v84, v149, v84
	v_mul_f32_e32 v84, v95, v84
	v_cvt_pk_bf16_f32 v84, v84, s0
	global_store_short v[122:123], v84, off offset:1024
	v_mul_f32_e32 v80, v80, v105
	v_mul_f32_e32 v80, v148, v80
	v_mul_f32_e32 v76, v76, v105
	v_mul_f32_e32 v76, v146, v76
	v_mov_b32_e32 v13, v4
	v_pk_mul_f32 v[18:19], v[12:13], v[12:13]
	v_mov_b32_e32 v12, v29
	v_mov_b32_e32 v13, v5
	v_pk_mul_f32 v[20:21], v[12:13], v[12:13]
	v_mov_b32_e32 v12, v30
	v_mov_b32_e32 v13, v6
	v_pk_mul_f32 v[14:15], v[12:13], v[12:13]
	v_mov_b32_e32 v12, v31
	v_mov_b32_e32 v13, v7
	v_pk_mul_f32 v[16:17], v[12:13], v[12:13]
	v_or_b32_e32 v12, s27, v97
	v_ashrrev_i32_e32 v13, 31, v12
	v_lshlrev_b64 v[22:23], 12, v[12:13]
	v_lshl_add_u64 v[24:25], s[58:59], 0, v[22:23]
	v_lshlrev_b64 v[22:23], 11, v[12:13]
	v_lshl_add_u64 v[26:27], s[60:61], 0, v[22:23]
	v_lshl_add_u64 v[22:23], v[24:25], 0, v[210:211]
	v_mov_b32_e32 v40, v8
	v_mov_b32_e32 v41, v0
	v_pk_mul_f32 v[44:45], v[40:41], v[40:41]
	v_mov_b32_e32 v40, v9
	v_mov_b32_e32 v41, v1
	v_pk_mul_f32 v[46:47], v[40:41], v[40:41]
	v_lshl_add_u64 v[34:35], v[24:25], 0, v[118:119]
	v_lshl_add_u64 v[24:25], v[26:27], 0, v[118:119]
	v_mov_b32_e32 v36, v20
	v_mov_b32_e32 v37, v18
	v_mov_b32_e32 v18, v21
	v_mov_b32_e32 v40, v10
	v_mov_b32_e32 v41, v2
	v_mov_b32_e32 v42, v11
	v_mov_b32_e32 v43, v3
	v_pk_mul_f32 v[40:41], v[40:41], v[40:41]
	v_pk_mul_f32 v[42:43], v[42:43], v[42:43]
	s_waitcnt vmcnt(63)
	v_mov_b32_e32 v84, v190
	v_lshlrev_b32_e32 v84, 16, v84
	v_mul_f32_e32 v95, 0xbfb8aa3b, v84
	v_exp_f32_e32 v95, v95
	s_nop 0
	v_add_f32_e32 v95, 1.0, v95
	v_rcp_f32_e32 v95, v95
	s_nop 0
	v_mul_f32_e32 v84, v95, v84
	v_mul_f32_e32 v80, v84, v80
	v_cvt_pk_bf16_f32 v80, v80, s0
	global_store_short v[122:123], v80, off offset:1056
	v_mul_f32_e32 v84, v88, v105
	v_mul_f32_e32 v84, v147, v84
	s_waitcnt vmcnt(63)
	v_mov_b32_e32 v80, v191
	v_lshlrev_b32_e32 v80, 16, v80
	v_mul_f32_e32 v88, 0xbfb8aa3b, v80
	v_exp_f32_e32 v88, v88
	s_nop 0
	v_add_f32_e32 v88, 1.0, v88
	v_rcp_f32_e32 v88, v88
	s_nop 0
	v_mul_f32_e32 v80, v88, v80
	v_mul_f32_e32 v80, v84, v80
	v_cvt_pk_bf16_f32 v80, v80, s0
	global_store_short v[122:123], v80, off offset:1088
	s_waitcnt vmcnt(63)
	v_mov_b32_e32 v80, v192
	v_lshlrev_b32_e32 v80, 16, v80
	v_mul_f32_e32 v84, 0xbfb8aa3b, v80
	v_exp_f32_e32 v84, v84
	s_nop 0
	v_add_f32_e32 v84, 1.0, v84
	v_rcp_f32_e32 v84, v84
	s_nop 0
	v_mul_f32_e32 v80, v84, v80
	v_mul_f32_e32 v76, v76, v80
	v_cvt_pk_bf16_f32 v76, v76, s0
	global_store_short v[114:115], v76, off offset:1024
	v_mul_f32_e32 v76, 0x4b800000, v104
	v_cndmask_b32_e64 v76, v104, v76, s[48:49]
	v_rsq_f32_e32 v76, v76
	v_or_b32_e32 v104, 1, v94
	v_ashrrev_i32_e32 v105, 31, v104
	v_lshlrev_b64 v[106:107], 12, v[104:105]
	v_lshl_add_u64 v[106:107], s[58:59], 0, v[106:107]
	v_mul_f32_e32 v80, 0x45800000, v76
	v_lshl_add_u64 v[108:109], v[106:107], 0, v[210:211]
	v_cndmask_b32_e64 v76, v76, v80, s[48:49]
	v_mul_f32_e32 v84, v85, v76
	v_lshlrev_b64 v[104:105], 11, v[104:105]
	v_mul_f32_e32 v84, v149, v84
	v_lshl_add_u64 v[104:105], s[60:61], 0, v[104:105]
	v_mul_f32_e32 v81, v81, v76
	v_mul_f32_e32 v81, v148, v81
	s_waitcnt vmcnt(63)
	v_mov_b32_e32 v80, v193
	v_lshlrev_b32_e32 v80, 16, v80
	v_mul_f32_e32 v85, 0xbfb8aa3b, v80
	v_exp_f32_e32 v85, v85
	s_nop 0
	v_add_f32_e32 v85, 1.0, v85
	v_rcp_f32_e32 v85, v85
	s_nop 0
	v_mul_f32_e32 v80, v85, v80
	v_mul_f32_e32 v80, v80, v84
	v_cvt_pk_bf16_f32 v80, v80, s0
	v_lshl_add_u64 v[84:85], v[104:105], 0, v[210:211]
	global_store_short v[84:85], v80, off offset:1024
	s_waitcnt vmcnt(63)
; __device__ __forceinline__ unsigned cvtpk(float lo, float hi) { f32x2_t v = {lo, hi}; bf16x2_t b = __builtin_convertvector(v, bf16x2_t); return __builtin_bit_cast(unsigned, b); }
; template <int X> __device__ __forceinline__ float swz_xor(float v) { return __int_as_float(__builtin_amdgcn_ds_swizzle(__float_as_int(v), (X << 10) | 0x1F)); }
; __device__ __forceinline__ float silu_f(float g) { return g * __builtin_amdgcn_rcpf(1.0f + __expf(-g)); }
; template <bool GLA>
; __device__ __forceinline__ void chunk_pass_c(const ChunkIn& ci, const float* wgl, int unit, unsigned char* wl, int lane, const float* Sb, const float* ng, bf16_t* omix) {
;     ...
;         for (int r = 0; r < 4; ++r) {
;             ss[r] += swz_xor<1>(ss[r]); ss[r] += swz_xor<2>(ss[r]); ss[r] += swz_xor<4>(ss[r]); ss[r] += swz_xor<8>(ss[r]);
;             const float rs = rsqrtf(ss[r] * (1.0f / 64.0f) + EPS);
;             const int t = t0 + 16 * it + 4 * kq + r;
; #pragma unroll
;             for (int et = 0; et < 4; ++et) {
;                 const int e = 16 * et + row;
;                 const float gt = __uint_as_float((unsigned)ci.proj[(size_t)t * DINP + gcol + e] << 16);
;                 const float val = o[et][r] * rs * gn[et] * pg8::silu_f(gt);
;                 omix[(size_t)t * 1024 + ocol + e] = (bf16_t)(cvtpk(val, 0.f) & 0xffffu);
;             }
	v_mov_b32_e32 v80, v194
	v_lshlrev_b32_e32 v80, 16, v80
	v_mul_f32_e32 v88, 0xbfb8aa3b, v80
	v_exp_f32_e32 v88, v88
	s_nop 0
	v_add_f32_e32 v88, 1.0, v88
	v_rcp_f32_e32 v88, v88
	s_nop 0
	v_mul_f32_e32 v80, v88, v80
	v_mul_f32_e32 v80, v81, v80
	v_cvt_pk_bf16_f32 v80, v80, s0
	global_store_short v[84:85], v80, off offset:1056
	v_mul_f32_e32 v81, v89, v76
	v_mul_f32_e32 v81, v147, v81
	v_mul_f32_e32 v76, v77, v76
	v_mul_f32_e32 v76, v146, v76
	s_waitcnt vmcnt(63)
	v_mov_b32_e32 v80, v195
	v_lshlrev_b32_e32 v80, 16, v80
	v_mul_f32_e32 v88, 0xbfb8aa3b, v80
	v_exp_f32_e32 v88, v88
	s_nop 0
	v_add_f32_e32 v88, 1.0, v88
	v_rcp_f32_e32 v88, v88
	s_nop 0
	v_mul_f32_e32 v80, v88, v80
	v_mul_f32_e32 v80, v81, v80
	v_cvt_pk_bf16_f32 v80, v80, s0
	global_store_short v[84:85], v80, off offset:1088
	v_lshl_add_u64 v[80:81], v[106:107], 0, v[118:119]
	s_waitcnt vmcnt(63)
	v_mov_b32_e32 v80, v196
	v_lshlrev_b32_e32 v80, 16, v80
	v_mul_f32_e32 v77, 0xbfb8aa3b, v80
	v_exp_f32_e32 v77, v77
	s_nop 0
	v_add_f32_e32 v77, 1.0, v77
	v_rcp_f32_e32 v77, v77
	s_nop 0
	v_mul_f32_e32 v77, v77, v80
	v_mul_f32_e32 v76, v76, v77
	v_cvt_pk_bf16_f32 v80, v76, s0
	v_lshl_add_u64 v[76:77], v[104:105], 0, v[118:119]
	global_store_short v[76:77], v80, off offset:1024
	v_or_b32_e32 v76, 2, v94
	v_ashrrev_i32_e32 v77, 31, v76
	v_lshlrev_b64 v[80:81], 12, v[76:77]
	v_lshl_add_u64 v[80:81], s[58:59], 0, v[80:81]
	v_lshl_add_u64 v[84:85], v[80:81], 0, v[210:211]
	v_mov_b32_e32 v104, v98
	v_mov_b32_e32 v105, v92
	v_mov_b32_e32 v92, v99
	v_pk_add_f32 v[92:93], v[104:105], v[92:93]
	v_mov_b32_e32 v98, v102
	v_mov_b32_e32 v99, v100
	v_pk_add_f32 v[92:93], v[92:93], v[98:99]
	v_mov_b32_e32 v100, v103
	v_pk_add_f32 v[92:93], v[92:93], v[100:101]
	ds_swizzle_b32 v99, v93 offset:swizzle(SWAP,1)
	ds_swizzle_b32 v98, v92 offset:swizzle(SWAP,1)
	v_lshlrev_b64 v[76:77], 11, v[76:77]
	v_lshl_add_u64 v[76:77], s[60:61], 0, v[76:77]
	v_lshl_add_u64 v[80:81], v[80:81], 0, v[118:119]
	s_waitcnt lgkmcnt(0)
	v_pk_add_f32 v[92:93], v[92:93], v[98:99]
	ds_swizzle_b32 v99, v93 offset:swizzle(SWAP,2)
	ds_swizzle_b32 v98, v92 offset:swizzle(SWAP,2)
	s_waitcnt lgkmcnt(0)
	v_pk_add_f32 v[92:93], v[92:93], v[98:99]
	ds_swizzle_b32 v99, v93 offset:swizzle(SWAP,4)
	ds_swizzle_b32 v98, v92 offset:swizzle(SWAP,4)
	s_waitcnt lgkmcnt(0)
	v_pk_add_f32 v[92:93], v[92:93], v[98:99]
	ds_swizzle_b32 v99, v93 offset:swizzle(SWAP,8)
	ds_swizzle_b32 v98, v92 offset:swizzle(SWAP,8)
	s_waitcnt lgkmcnt(0)
	v_pk_add_f32 v[92:93], v[92:93], v[98:99]
	s_nop 0
	v_pk_fma_f32 v[92:93], v[92:93], s[6:7], v[120:121] op_sel_hi:[1,0,0]
	s_waitcnt vmcnt(63)
	v_mov_b32_e32 v88, v197
	v_lshlrev_b32_e32 v88, 16, v88
	v_mul_f32_e32 v89, 0xbfb8aa3b, v88
	v_exp_f32_e32 v89, v89
	v_mul_f32_e32 v98, 0x4b800000, v93
	v_cmp_gt_f32_e64 s[50:51], s96, v93
	v_cmp_gt_f32_e64 s[48:49], s96, v92
	v_add_f32_e32 v89, 1.0, v89
	v_cndmask_b32_e64 v93, v93, v98, s[50:51]
	v_rsq_f32_e32 v93, v93
	v_rcp_f32_e32 v89, v89
	v_mul_f32_e32 v98, 0x45800000, v93
	v_cndmask_b32_e64 v93, v93, v98, s[50:51]
	v_mul_f32_e32 v86, v86, v93
	v_mul_f32_e32 v95, v89, v88
	v_mul_f32_e32 v86, v149, v86
	v_mul_f32_e32 v86, v95, v86
	v_lshl_add_u64 v[88:89], v[76:77], 0, v[210:211]
	v_cvt_pk_bf16_f32 v86, v86, s0
	global_store_short v[88:89], v86, off offset:1024
	v_mul_f32_e32 v82, v82, v93
	v_mul_f32_e32 v82, v148, v82
	v_mul_f32_e32 v78, v78, v93
	v_mul_f32_e32 v78, v146, v78
	v_lshl_add_u64 v[76:77], v[76:77], 0, v[118:119]
	s_waitcnt vmcnt(63)
	v_mov_b32_e32 v86, v198
	v_lshlrev_b32_e32 v86, 16, v86
	v_mul_f32_e32 v95, 0xbfb8aa3b, v86
	v_exp_f32_e32 v95, v95
	s_nop 0
	v_add_f32_e32 v95, 1.0, v95
	v_rcp_f32_e32 v95, v95
	s_nop 0
	v_mul_f32_e32 v86, v95, v86
	v_mul_f32_e32 v82, v82, v86
	v_cvt_pk_bf16_f32 v82, v82, s0
	global_store_short v[88:89], v82, off offset:1056
	v_mul_f32_e32 v84, v90, v93
	v_mul_f32_e32 v84, v147, v84
	s_waitcnt vmcnt(63)
	v_mov_b32_e32 v82, v199
	v_lshlrev_b32_e32 v82, 16, v82
	v_mul_f32_e32 v85, 0xbfb8aa3b, v82
	v_exp_f32_e32 v85, v85
	s_nop 0
	v_add_f32_e32 v85, 1.0, v85
	v_rcp_f32_e32 v85, v85
	s_nop 0
	v_mul_f32_e32 v82, v85, v82
	v_mul_f32_e32 v82, v84, v82
	v_cvt_pk_bf16_f32 v82, v82, s0
	global_store_short v[88:89], v82, off offset:1088
	s_waitcnt vmcnt(63)
	v_mov_b32_e32 v80, v200
	v_lshlrev_b32_e32 v80, 16, v80
	v_mul_f32_e32 v81, 0xbfb8aa3b, v80
	v_exp_f32_e32 v81, v81
	s_nop 0
	v_add_f32_e32 v81, 1.0, v81
	v_rcp_f32_e32 v81, v81
	s_nop 0
	v_mul_f32_e32 v80, v81, v80
	v_mul_f32_e32 v78, v78, v80
	v_cvt_pk_bf16_f32 v78, v78, s0
	global_store_short v[76:77], v78, off offset:1024
	v_mul_f32_e32 v76, 0x4b800000, v92
	v_cndmask_b32_e64 v76, v92, v76, s[48:49]
	v_rsq_f32_e32 v76, v76
	s_nop 0
	v_mul_f32_e32 v77, 0x45800000, v76
	v_cndmask_b32_e64 v78, v76, v77, s[48:49]
	v_or_b32_e32 v76, 3, v94
	v_ashrrev_i32_e32 v77, 31, v76
	v_lshlrev_b64 v[80:81], 12, v[76:77]
	v_lshl_add_u64 v[80:81], s[58:59], 0, v[80:81]
	v_lshl_add_u64 v[84:85], v[80:81], 0, v[210:211]
	v_mul_f32_e32 v86, v87, v78
	v_lshlrev_b64 v[76:77], 11, v[76:77]
	v_mul_f32_e32 v86, v149, v86
	v_lshl_add_u64 v[76:77], s[60:61], 0, v[76:77]
	v_mul_f32_e32 v83, v83, v78
	v_mul_f32_e32 v83, v148, v83
	v_lshl_add_u64 v[80:81], v[80:81], 0, v[118:119]
	s_waitcnt vmcnt(63)
	v_mov_b32_e32 v82, v201
	v_lshlrev_b32_e32 v82, 16, v82
	v_mul_f32_e32 v87, 0xbfb8aa3b, v82
	v_exp_f32_e32 v87, v87
	s_nop 0
	v_add_f32_e32 v87, 1.0, v87
	v_rcp_f32_e32 v87, v87
	s_nop 0
	v_mul_f32_e32 v82, v87, v82
	v_mul_f32_e32 v82, v82, v86
	v_cvt_pk_bf16_f32 v82, v82, s0
	v_lshl_add_u64 v[86:87], v[76:77], 0, v[210:211]
	global_store_short v[86:87], v82, off offset:1024
	v_lshl_add_u64 v[76:77], v[76:77], 0, v[118:119]
	s_waitcnt vmcnt(63)
; __device__ __forceinline__ unsigned cvtpk(float lo, float hi) { f32x2_t v = {lo, hi}; bf16x2_t b = __builtin_convertvector(v, bf16x2_t); return __builtin_bit_cast(unsigned, b); }
; template <int X> __device__ __forceinline__ float swz_xor(float v) { return __int_as_float(__builtin_amdgcn_ds_swizzle(__float_as_int(v), (X << 10) | 0x1F)); }
; __device__ __forceinline__ float silu_f(float g) { return g * __builtin_amdgcn_rcpf(1.0f + __expf(-g)); }
; template <bool GLA>
; __device__ __forceinline__ void chunk_pass_c(const ChunkIn& ci, const float* wgl, int unit, unsigned char* wl, int lane, const float* Sb, const float* ng, bf16_t* omix) {
;     ...
;         for (int r = 0; r < 4; ++r) {
;             ss[r] += swz_xor<1>(ss[r]); ss[r] += swz_xor<2>(ss[r]); ss[r] += swz_xor<4>(ss[r]); ss[r] += swz_xor<8>(ss[r]);
;             const float rs = rsqrtf(ss[r] * (1.0f / 64.0f) + EPS);
;             const int t = t0 + 16 * it + 4 * kq + r;
; #pragma unroll
;             for (int et = 0; et < 4; ++et) {
;                 const int e = 16 * et + row;
;                 const float gt = __uint_as_float((unsigned)ci.proj[(size_t)t * DINP + gcol + e] << 16);
;                 const float val = o[et][r] * rs * gn[et] * pg8::silu_f(gt);
;                 omix[(size_t)t * 1024 + ocol + e] = (bf16_t)(cvtpk(val, 0.f) & 0xffffu);
;             }
	v_mov_b32_e32 v82, v202
	v_lshlrev_b32_e32 v82, 16, v82
	v_mul_f32_e32 v88, 0xbfb8aa3b, v82
	v_exp_f32_e32 v88, v88
	s_nop 0
	v_add_f32_e32 v88, 1.0, v88
	v_rcp_f32_e32 v88, v88
	s_nop 0
	v_mul_f32_e32 v82, v88, v82
	v_mul_f32_e32 v82, v83, v82
	v_cvt_pk_bf16_f32 v82, v82, s0
	global_store_short v[86:87], v82, off offset:1056
	v_mul_f32_e32 v83, v91, v78
	v_mul_f32_e32 v83, v147, v83
	v_mul_f32_e32 v78, v79, v78
	v_mul_f32_e32 v78, v146, v78
	s_waitcnt vmcnt(63)
	v_mov_b32_e32 v82, v203
	v_lshlrev_b32_e32 v82, 16, v82
	v_mul_f32_e32 v84, 0xbfb8aa3b, v82
	v_exp_f32_e32 v84, v84
	s_nop 0
	v_add_f32_e32 v84, 1.0, v84
	v_rcp_f32_e32 v84, v84
	s_nop 0
	v_mul_f32_e32 v82, v84, v82
	v_mul_f32_e32 v82, v83, v82
	v_cvt_pk_bf16_f32 v82, v82, s0
	global_store_short v[86:87], v82, off offset:1088
	s_waitcnt vmcnt(63)
	v_mov_b32_e32 v80, v204
	v_lshlrev_b32_e32 v80, 16, v80
	v_mul_f32_e32 v79, 0xbfb8aa3b, v80
	v_exp_f32_e32 v79, v79
	s_nop 0
	v_add_f32_e32 v79, 1.0, v79
	v_rcp_f32_e32 v79, v79
	s_nop 0
	v_mul_f32_e32 v79, v79, v80
	v_mul_f32_e32 v78, v78, v79
	v_cvt_pk_bf16_f32 v78, v78, s0
	global_store_short v[76:77], v78, off offset:1024
	s_waitcnt vmcnt(63)
	v_mov_b32_e32 v13, v205
	v_lshlrev_b32_e32 v13, 16, v13
	v_mul_f32_e32 v32, 0xbfb8aa3b, v13
	v_exp_f32_e32 v32, v32
	s_nop 0
	v_add_f32_e32 v32, 1.0, v32
	v_rcp_f32_e32 v32, v32
	s_nop 0
	v_mul_f32_e32 v13, v32, v13
	v_lshl_add_u64 v[32:33], v[26:27], 0, v[210:211]
	v_mov_b32_e32 v26, v46
	v_mov_b32_e32 v27, v44
	v_mov_b32_e32 v44, v47
	v_pk_add_f32 v[26:27], v[26:27], v[44:45]
	s_nop 0
	v_pk_add_f32 v[26:27], v[26:27], v[36:37]
	s_nop 0
	v_pk_add_f32 v[18:19], v[26:27], v[18:19]
	ds_swizzle_b32 v21, v19 offset:swizzle(SWAP,1)
	ds_swizzle_b32 v20, v18 offset:swizzle(SWAP,1)
	s_waitcnt lgkmcnt(0)
	v_pk_add_f32 v[18:19], v[18:19], v[20:21]
	ds_swizzle_b32 v21, v19 offset:swizzle(SWAP,2)
	ds_swizzle_b32 v20, v18 offset:swizzle(SWAP,2)
	s_waitcnt lgkmcnt(0)
	v_pk_add_f32 v[18:19], v[18:19], v[20:21]
	ds_swizzle_b32 v21, v19 offset:swizzle(SWAP,4)
	ds_swizzle_b32 v20, v18 offset:swizzle(SWAP,4)
	s_waitcnt lgkmcnt(0)
	v_pk_add_f32 v[18:19], v[18:19], v[20:21]
	ds_swizzle_b32 v21, v19 offset:swizzle(SWAP,8)
	ds_swizzle_b32 v20, v18 offset:swizzle(SWAP,8)
	s_waitcnt lgkmcnt(0)
	v_pk_add_f32 v[18:19], v[18:19], v[20:21]
	s_nop 0
	v_pk_fma_f32 v[18:19], v[18:19], s[6:7], v[120:121] op_sel_hi:[1,0,0]
	s_nop 0
	v_mul_f32_e32 v20, 0x4b800000, v19
	v_cmp_gt_f32_e64 s[42:43], s96, v19
	v_cmp_gt_f32_e32 vcc, s96, v18
	s_nop 0
	v_cndmask_b32_e64 v19, v19, v20, s[42:43]
	v_rsq_f32_e32 v19, v19
	s_nop 0
	v_mul_f32_e32 v20, 0x45800000, v19
	v_cndmask_b32_e64 v19, v19, v20, s[42:43]
	v_mul_f32_e32 v8, v8, v19
	v_mul_f32_e32 v8, v149, v8
	v_mul_f32_e32 v8, v13, v8
	v_cvt_pk_bf16_f32 v8, v8, s0
	global_store_short v[32:33], v8, off offset:1024
	v_mul_f32_e32 v0, v0, v19
	v_mul_f32_e32 v0, v148, v0
	v_mul_f32_e32 v4, v4, v19
	v_mul_f32_e32 v4, v146, v4
	s_waitcnt vmcnt(63)
	v_mov_b32_e32 v8, v206
	v_lshlrev_b32_e32 v8, 16, v8
	v_mul_f32_e32 v13, 0xbfb8aa3b, v8
	v_exp_f32_e32 v13, v13
	s_nop 0
	v_add_f32_e32 v13, 1.0, v13
	v_rcp_f32_e32 v13, v13
	s_nop 0
	v_mul_f32_e32 v8, v13, v8
	v_mul_f32_e32 v0, v8, v0
	v_cvt_pk_bf16_f32 v0, v0, s0
	global_store_short v[32:33], v0, off offset:1056
	v_mul_f32_e32 v8, v28, v19
	v_mul_f32_e32 v8, v147, v8
	s_waitcnt vmcnt(63)
	v_mov_b32_e32 v0, v207
	v_lshlrev_b32_e32 v0, 16, v0
	v_mul_f32_e32 v13, 0xbfb8aa3b, v0
	v_exp_f32_e32 v13, v13
	s_nop 0
	v_add_f32_e32 v13, 1.0, v13
	v_rcp_f32_e32 v13, v13
	s_nop 0
	v_mul_f32_e32 v0, v13, v0
	v_mul_f32_e32 v0, v8, v0
	v_cvt_pk_bf16_f32 v0, v0, s0
	global_store_short v[32:33], v0, off offset:1088
	s_waitcnt vmcnt(63)
	v_mov_b32_e32 v0, v208
	v_lshlrev_b32_e32 v0, 16, v0
	v_mul_f32_e32 v8, 0xbfb8aa3b, v0
	v_exp_f32_e32 v8, v8
	s_nop 0
	v_add_f32_e32 v8, 1.0, v8
	v_rcp_f32_e32 v8, v8
	s_nop 0
	v_mul_f32_e32 v0, v8, v0
	v_mul_f32_e32 v0, v4, v0
	v_cvt_pk_bf16_f32 v0, v0, s0
	global_store_short v[24:25], v0, off offset:1024
	v_mul_f32_e32 v0, 0x4b800000, v18
	v_cndmask_b32_e32 v0, v18, v0, vcc
	v_rsq_f32_e32 v0, v0
	v_or_b32_e32 v18, 1, v12
	v_ashrrev_i32_e32 v19, 31, v18
	v_lshlrev_b64 v[20:21], 12, v[18:19]
	v_lshl_add_u64 v[20:21], s[58:59], 0, v[20:21]
	v_mul_f32_e32 v4, 0x45800000, v0
	v_lshl_add_u64 v[22:23], v[20:21], 0, v[210:211]
	v_cndmask_b32_e32 v4, v0, v4, vcc
	v_mul_f32_e32 v8, v9, v4
	v_lshlrev_b64 v[18:19], 11, v[18:19]
	v_mul_f32_e32 v8, v149, v8
	v_lshl_add_u64 v[18:19], s[60:61], 0, v[18:19]
	v_mul_f32_e32 v1, v1, v4
	v_mul_f32_e32 v1, v148, v1
	s_waitcnt vmcnt(63)
	v_mov_b32_e32 v0, v209
	v_lshlrev_b32_e32 v0, 16, v0
	v_mul_f32_e32 v9, 0xbfb8aa3b, v0
	v_exp_f32_e32 v9, v9
	s_nop 0
	v_add_f32_e32 v9, 1.0, v9
	v_rcp_f32_e32 v9, v9
	s_nop 0
	v_mul_f32_e32 v0, v9, v0
	v_mul_f32_e32 v0, v0, v8
	v_cvt_pk_bf16_f32 v0, v0, s0
	v_lshl_add_u64 v[8:9], v[18:19], 0, v[210:211]
	global_store_short v[8:9], v0, off offset:1024
	s_waitcnt vmcnt(63)
	v_mov_b32_e32 v0, v212
	v_lshlrev_b32_e32 v0, 16, v0
	v_mul_f32_e32 v13, 0xbfb8aa3b, v0
	v_exp_f32_e32 v13, v13
	s_nop 0
	v_add_f32_e32 v13, 1.0, v13
	v_rcp_f32_e32 v13, v13
	s_nop 0
	v_mul_f32_e32 v0, v13, v0
	v_mul_f32_e32 v0, v1, v0
	v_cvt_pk_bf16_f32 v0, v0, s0
	global_store_short v[8:9], v0, off offset:1056
	v_mul_f32_e32 v1, v29, v4
	v_mul_f32_e32 v1, v147, v1
	v_mov_b32_e32 v22, v16
	v_mov_b32_e32 v23, v14
	v_mov_b32_e32 v14, v17
	s_waitcnt vmcnt(63)
; __device__ __forceinline__ unsigned cvtpk(float lo, float hi) { f32x2_t v = {lo, hi}; bf16x2_t b = __builtin_convertvector(v, bf16x2_t); return __builtin_bit_cast(unsigned, b); }
; template <int X> __device__ __forceinline__ float swz_xor(float v) { return __int_as_float(__builtin_amdgcn_ds_swizzle(__float_as_int(v), (X << 10) | 0x1F)); }
; __device__ __forceinline__ float silu_f(float g) { return g * __builtin_amdgcn_rcpf(1.0f + __expf(-g)); }
; template <bool GLA>
; __device__ __forceinline__ void chunk_pass_c(const ChunkIn& ci, const float* wgl, int unit, unsigned char* wl, int lane, const float* Sb, const float* ng, bf16_t* omix) {
;     ...
;         for (int r = 0; r < 4; ++r) {
;             ss[r] += swz_xor<1>(ss[r]); ss[r] += swz_xor<2>(ss[r]); ss[r] += swz_xor<4>(ss[r]); ss[r] += swz_xor<8>(ss[r]);
;             const float rs = rsqrtf(ss[r] * (1.0f / 64.0f) + EPS);
;             const int t = t0 + 16 * it + 4 * kq + r;
; #pragma unroll
;             for (int et = 0; et < 4; ++et) {
;                 const int e = 16 * et + row;
;                 const float gt = __uint_as_float((unsigned)ci.proj[(size_t)t * DINP + gcol + e] << 16);
;                 const float val = o[et][r] * rs * gn[et] * pg8::silu_f(gt);
;                 omix[(size_t)t * 1024 + ocol + e] = (bf16_t)(cvtpk(val, 0.f) & 0xffffu);
;             }
;         }
;     }
;     __builtin_amdgcn_s_waitcnt(0); asm volatile("" ::: "memory");
	v_mov_b32_e32 v0, v213
	v_lshlrev_b32_e32 v0, 16, v0
	v_mul_f32_e32 v13, 0xbfb8aa3b, v0
	v_exp_f32_e32 v13, v13
	s_nop 0
	v_add_f32_e32 v13, 1.0, v13
	v_rcp_f32_e32 v13, v13
	s_nop 0
	v_mul_f32_e32 v0, v13, v0
	v_mul_f32_e32 v0, v1, v0
	v_cvt_pk_bf16_f32 v0, v0, s0
	global_store_short v[8:9], v0, off offset:1088
	v_lshl_add_u64 v[0:1], v[20:21], 0, v[118:119]
	v_mul_f32_e32 v1, v5, v4
	v_mul_f32_e32 v1, v146, v1
	v_mov_b32_e32 v20, v42
	v_mov_b32_e32 v21, v40
	v_mov_b32_e32 v40, v43
	v_pk_add_f32 v[20:21], v[20:21], v[40:41]
	s_waitcnt vmcnt(63)
	v_mov_b32_e32 v0, v214
	v_lshlrev_b32_e32 v0, 16, v0
	v_mul_f32_e32 v4, 0xbfb8aa3b, v0
	v_exp_f32_e32 v4, v4
	v_pk_add_f32 v[20:21], v[20:21], v[22:23]
	v_add_f32_e32 v4, 1.0, v4
	v_rcp_f32_e32 v4, v4
	v_pk_add_f32 v[14:15], v[20:21], v[14:15]
	ds_swizzle_b32 v17, v15 offset:swizzle(SWAP,1)
	ds_swizzle_b32 v16, v14 offset:swizzle(SWAP,1)
	v_mul_f32_e32 v0, v4, v0
	v_mul_f32_e32 v0, v1, v0
	v_cvt_pk_bf16_f32 v4, v0, s0
	v_lshl_add_u64 v[0:1], v[18:19], 0, v[118:119]
	global_store_short v[0:1], v4, off offset:1024
	v_or_b32_e32 v0, 2, v12
	v_ashrrev_i32_e32 v1, 31, v0
	v_lshlrev_b64 v[4:5], 12, v[0:1]
	v_lshl_add_u64 v[4:5], s[58:59], 0, v[4:5]
	v_lshl_add_u64 v[8:9], v[4:5], 0, v[210:211]
	s_waitcnt lgkmcnt(0)
	v_pk_add_f32 v[14:15], v[14:15], v[16:17]
	ds_swizzle_b32 v17, v15 offset:swizzle(SWAP,2)
	ds_swizzle_b32 v16, v14 offset:swizzle(SWAP,2)
	v_lshlrev_b64 v[0:1], 11, v[0:1]
	v_lshl_add_u64 v[0:1], s[60:61], 0, v[0:1]
	v_lshl_add_u64 v[4:5], v[4:5], 0, v[118:119]
	s_waitcnt lgkmcnt(0)
	v_pk_add_f32 v[14:15], v[14:15], v[16:17]
	ds_swizzle_b32 v17, v15 offset:swizzle(SWAP,4)
	ds_swizzle_b32 v16, v14 offset:swizzle(SWAP,4)
	s_waitcnt lgkmcnt(0)
	v_pk_add_f32 v[14:15], v[14:15], v[16:17]
	ds_swizzle_b32 v17, v15 offset:swizzle(SWAP,8)
	ds_swizzle_b32 v16, v14 offset:swizzle(SWAP,8)
	s_waitcnt lgkmcnt(0)
	v_pk_add_f32 v[14:15], v[14:15], v[16:17]
	s_nop 0
	v_pk_fma_f32 v[14:15], v[14:15], s[6:7], v[120:121] op_sel_hi:[1,0,0]
	s_waitcnt vmcnt(63)
	v_mov_b32_e32 v13, v215
	v_lshlrev_b32_e32 v13, 16, v13
	v_mul_f32_e32 v18, 0xbfb8aa3b, v13
	v_exp_f32_e32 v18, v18
	v_mul_f32_e32 v16, 0x4b800000, v15
	v_cmp_gt_f32_e64 s[42:43], s96, v15
	v_cmp_gt_f32_e32 vcc, s96, v14
	v_add_f32_e32 v18, 1.0, v18
	v_cndmask_b32_e64 v15, v15, v16, s[42:43]
	v_rsq_f32_e32 v15, v15
	v_rcp_f32_e32 v18, v18
	v_mul_f32_e32 v16, 0x45800000, v15
	v_cndmask_b32_e64 v15, v15, v16, s[42:43]
	v_mul_f32_e32 v10, v10, v15
	v_mul_f32_e32 v13, v18, v13
	v_mul_f32_e32 v10, v149, v10
	v_mul_f32_e32 v10, v13, v10
	v_lshl_add_u64 v[18:19], v[0:1], 0, v[210:211]
	v_cvt_pk_bf16_f32 v10, v10, s0
	global_store_short v[18:19], v10, off offset:1024
	v_mul_f32_e32 v2, v2, v15
	v_mul_f32_e32 v2, v148, v2
	v_lshl_add_u64 v[0:1], v[0:1], 0, v[118:119]
	s_waitcnt vmcnt(63)
	v_mov_b32_e32 v10, v216
	v_lshlrev_b32_e32 v10, 16, v10
	v_mul_f32_e32 v13, 0xbfb8aa3b, v10
	v_exp_f32_e32 v13, v13
	s_nop 0
	v_add_f32_e32 v13, 1.0, v13
	v_rcp_f32_e32 v13, v13
	s_nop 0
	v_mul_f32_e32 v10, v13, v10
	v_mul_f32_e32 v2, v2, v10
	v_cvt_pk_bf16_f32 v2, v2, s0
	global_store_short v[18:19], v2, off offset:1056
	v_mul_f32_e32 v8, v30, v15
	v_mul_f32_e32 v8, v147, v8
	s_waitcnt vmcnt(63)
	v_mov_b32_e32 v2, v217
	v_lshlrev_b32_e32 v2, 16, v2
	v_mul_f32_e32 v9, 0xbfb8aa3b, v2
	v_exp_f32_e32 v9, v9
	s_nop 0
	v_add_f32_e32 v9, 1.0, v9
	v_rcp_f32_e32 v9, v9
	s_nop 0
	v_mul_f32_e32 v2, v9, v2
	v_mul_f32_e32 v2, v8, v2
	v_cvt_pk_bf16_f32 v2, v2, s0
	global_store_short v[18:19], v2, off offset:1088
	v_mul_f32_e32 v4, v6, v15
	v_mul_f32_e32 v4, v146, v4
	s_waitcnt vmcnt(63)
	v_mov_b32_e32 v2, v218
	v_lshlrev_b32_e32 v2, 16, v2
	v_mul_f32_e32 v5, 0xbfb8aa3b, v2
	v_exp_f32_e32 v5, v5
	s_nop 0
	v_add_f32_e32 v5, 1.0, v5
	v_rcp_f32_e32 v5, v5
	s_nop 0
	v_mul_f32_e32 v2, v5, v2
	v_mul_f32_e32 v2, v4, v2
	v_cvt_pk_bf16_f32 v2, v2, s0
	global_store_short v[0:1], v2, off offset:1024
	v_mul_f32_e32 v0, 0x4b800000, v14
	v_cndmask_b32_e32 v0, v14, v0, vcc
	v_rsq_f32_e32 v0, v0
	s_nop 0
	v_mul_f32_e32 v1, 0x45800000, v0
	v_cndmask_b32_e32 v6, v0, v1, vcc
	v_or_b32_e32 v0, 3, v12
	v_ashrrev_i32_e32 v1, 31, v0
	v_lshlrev_b64 v[4:5], 12, v[0:1]
	v_lshl_add_u64 v[4:5], s[58:59], 0, v[4:5]
	v_lshl_add_u64 v[8:9], v[4:5], 0, v[210:211]
	v_mul_f32_e32 v10, v11, v6
	v_lshlrev_b64 v[0:1], 11, v[0:1]
	v_mul_f32_e32 v10, v149, v10
	v_lshl_add_u64 v[0:1], s[60:61], 0, v[0:1]
	v_mul_f32_e32 v3, v3, v6
	v_mul_f32_e32 v3, v148, v3
	s_waitcnt vmcnt(63)
	v_mov_b32_e32 v2, v219
	v_lshlrev_b32_e32 v2, 16, v2
	v_mul_f32_e32 v11, 0xbfb8aa3b, v2
	v_exp_f32_e32 v11, v11
	s_nop 0
	v_add_f32_e32 v11, 1.0, v11
	v_rcp_f32_e32 v11, v11
	s_nop 0
	v_mul_f32_e32 v2, v11, v2
	v_mul_f32_e32 v2, v2, v10
	v_cvt_pk_bf16_f32 v2, v2, s0
	v_lshl_add_u64 v[10:11], v[0:1], 0, v[210:211]
	global_store_short v[10:11], v2, off offset:1024
	v_lshl_add_u64 v[0:1], v[0:1], 0, v[118:119]
	s_waitcnt vmcnt(63)
	v_mov_b32_e32 v2, v220
	v_lshlrev_b32_e32 v2, 16, v2
	v_mul_f32_e32 v12, 0xbfb8aa3b, v2
	v_exp_f32_e32 v12, v12
	s_nop 0
	v_add_f32_e32 v12, 1.0, v12
	v_rcp_f32_e32 v12, v12
	s_nop 0
	v_mul_f32_e32 v2, v12, v2
	v_mul_f32_e32 v2, v3, v2
	v_cvt_pk_bf16_f32 v2, v2, s0
	global_store_short v[10:11], v2, off offset:1056
	v_mul_f32_e32 v3, v31, v6
	v_mul_f32_e32 v3, v147, v3
	s_waitcnt vmcnt(63)
	v_mov_b32_e32 v2, v221
	v_lshlrev_b32_e32 v2, 16, v2
	v_mul_f32_e32 v8, 0xbfb8aa3b, v2
	v_exp_f32_e32 v8, v8
	s_nop 0
	v_add_f32_e32 v8, 1.0, v8
	v_rcp_f32_e32 v8, v8
	s_nop 0
	v_mul_f32_e32 v2, v8, v2
	v_mul_f32_e32 v2, v3, v2
	v_cvt_pk_bf16_f32 v2, v2, s0
	global_store_short v[10:11], v2, off offset:1088
	v_lshl_add_u64 v[2:3], v[4:5], 0, v[118:119]
	v_mul_f32_e32 v3, v7, v6
	v_mul_f32_e32 v3, v146, v3
	s_waitcnt vmcnt(63)
	v_mov_b32_e32 v2, v222
	v_lshlrev_b32_e32 v2, 16, v2
	v_mul_f32_e32 v4, 0xbfb8aa3b, v2
	v_exp_f32_e32 v4, v4
	s_nop 0
	v_add_f32_e32 v4, 1.0, v4
	v_rcp_f32_e32 v4, v4
	s_nop 0
	v_mul_f32_e32 v2, v4, v2
	v_mul_f32_e32 v2, v3, v2
	v_cvt_pk_bf16_f32 v2, v2, s0
	global_store_short v[0:1], v2, off offset:1024
	s_waitcnt lgkmcnt(0)

; __device__ __forceinline__ void chunk_load_vt(const bf16_t* proj, int t0, int vcol, unsigned char* wl, int lane) {
;     const bf16_t* vp = proj + (size_t)(t0 + lane) * DINP + vcol;
; #pragma unroll
;     for (int cidx = 0; cidx < 8; ++cidx) {
;         const u32x4 v = *(const u32x4*)(vp + cidx * 8);
;         const unsigned w4[4] = {v.x, v.y, v.z, v.w};
; #pragma unroll
;         for (int j = 0; j < 4; ++j) {
;             *(bf16_t*)(wl + (cidx * 8 + 2 * j) * GP + lane * 2) = (bf16_t)(w4[j] & 0xffffu);
;             *(bf16_t*)(wl + (cidx * 8 + 2 * j + 1) * GP + lane * 2) = (bf16_t)(w4[j] >> 16);
;         }
;     }
; template <bool GLA>
; __device__ __forceinline__ void chunk_pass_c(const ChunkIn& ci, const float* wgl, int unit, unsigned char* wl, int lane, const float* Sb, const float* ng, bf16_t* omix) {
;     ...
;     chunk_load_vt(ci.proj, t0, (GLA ? C_GV : C_RV) + h * 64, wl, lane);
;     unsigned char* sst = wl + 64 * GP;
;     { const float* sp = Sb + (size_t)unit * 2048 + lane;
;       float sv[32];
; #pragma unroll
;       for (int d = 0; d < 32; ++d) sv[d] = sp[d * 64];
.LBB0_215:
	v_mov_b32_e32 v0, v211
	v_readlane_b32 s3, v254, 60
	v_mbcnt_lo_u32_b32 v0, -1, v0
	s_waitcnt vmcnt(35)
	v_mbcnt_hi_u32_b32 v133, -1, v0
	v_and_b32_e32 v147, 63, v133
	v_lshrrev_b32_e32 v119, 4, v147
	s_mov_b64 s[6:7], -1
	s_cmpk_gt_i32 s25, 0x7ff
	v_and_b32_e32 v156, 15, v133
	v_lshlrev_b32_e32 v210, 2, v147
	v_lshl_add_u32 v158, v147, 1, s3
	v_lshl_add_u32 v157, v147, 6, s3
	v_lshlrev_b32_e32 v97, 2, v119
	v_lshlrev_b32_e32 v114, 3, v119
	s_cbranch_scc0 .LBB0_217
	s_load_dwordx2 s[4:5], s[0:1], 0x88
	s_mov_b32 s65, s17
	v_mov_b32_e32 v115, v211
	v_cmp_lt_u32_e64 s[42:43], v97, v156
	v_lshlrev_b32_e32 v110, 1, v156
	s_waitcnt lgkmcnt(0)
	s_add_u32 s48, s4, s56
	s_addc_u32 s49, s5, s57
	s_add_i32 s3, s90, 0xffff8000
	s_and_b32 s4, s3, 0x7fc0
	v_or_b32_e32 v0, s4, v147
	s_lshl_b64 s[4:5], s[64:65], 2
	s_add_u32 s4, s37, s4
	v_lshlrev_b32_e32 v28, 12, v0
	s_addc_u32 s5, s70, s5
	global_load_dwordx4 v[0:3], v28, s[58:59] offset:2912
	global_load_dwordx4 v[4:7], v28, s[58:59] offset:2928
	global_load_dwordx4 v[8:11], v28, s[58:59] offset:2944
	global_load_dwordx4 v[12:15], v28, s[58:59] offset:2960
	global_load_dwordx4 v[16:19], v28, s[58:59] offset:2976
	global_load_dwordx4 v[20:23], v28, s[58:59] offset:2992
	global_load_dwordx4 v[24:27], v28, s[58:59] offset:3008
	s_nop 0
	global_load_dwordx4 v[28:31], v28, s[58:59] offset:3024
	v_lshl_add_u64 v[32:33], s[4:5], 0, v[210:211]
	v_add_co_u32_e32 v32, vcc, s10, v32
	global_load_dword v34, v210, s[4:5]
	global_load_dword v35, v210, s[4:5] offset:256
	global_load_dword v36, v210, s[4:5] offset:512
	global_load_dword v37, v210, s[4:5] offset:768
	global_load_dword v38, v210, s[4:5] offset:1024
	global_load_dword v39, v210, s[4:5] offset:1280
	global_load_dword v40, v210, s[4:5] offset:1536
	global_load_dword v41, v210, s[4:5] offset:1792
	global_load_dword v42, v210, s[4:5] offset:2048
	global_load_dword v43, v210, s[4:5] offset:2304
	global_load_dword v44, v210, s[4:5] offset:2560
	global_load_dword v45, v210, s[4:5] offset:2816
	global_load_dword v46, v210, s[4:5] offset:3072
	global_load_dword v47, v210, s[4:5] offset:3328
	global_load_dword v48, v210, s[4:5] offset:3584
	global_load_dword v49, v210, s[4:5] offset:3840
	v_addc_co_u32_e32 v33, vcc, 0, v33, vcc
	global_load_dword v50, v[32:33], off
	global_load_dword v51, v[32:33], off offset:256
	global_load_dword v52, v[32:33], off offset:512
	global_load_dword v53, v[32:33], off offset:768
	global_load_dword v54, v[32:33], off offset:1024
	global_load_dword v55, v[32:33], off offset:1280
	global_load_dword v56, v[32:33], off offset:1536
	global_load_dword v57, v[32:33], off offset:1792
	global_load_dword v58, v[32:33], off offset:2048
	global_load_dword v59, v[32:33], off offset:2304
	global_load_dword v60, v[32:33], off offset:2560
	global_load_dword v61, v[32:33], off offset:2816
	global_load_dword v62, v[32:33], off offset:3072
	global_load_dword v63, v[32:33], off offset:3328
	global_load_dword v64, v[32:33], off offset:3584
	s_nop 0
	global_load_dword v32, v[32:33], off offset:3840
	s_and_b32 s6, s90, 0x7fc0
	v_readlane_b32 s4, v255, 14
	s_or_b32 s5, s6, 16
	s_or_b32 s3, s3, 48
	v_or_b32_e32 v165, s6, v97
	v_mov_b32_e32 v111, v211
	v_lshlrev_b32_e32 v159, 2, v156
	v_or_b32_e32 v177, 48, v147
	s_waitcnt vmcnt(39)
	ds_write_b16 v158, v0
	ds_write_b16_d16_hi v158, v0 offset:144
	ds_write_b16 v158, v1 offset:288
	ds_write_b16_d16_hi v158, v1 offset:432
	ds_write_b16 v158, v2 offset:576
	ds_write_b16_d16_hi v158, v2 offset:720
	ds_write_b16 v158, v3 offset:864
	ds_write_b16_d16_hi v158, v3 offset:1008
	s_waitcnt vmcnt(38)
	ds_write_b16 v158, v4 offset:1152
	ds_write_b16_d16_hi v158, v4 offset:1296
	ds_write_b16 v158, v5 offset:1440
	ds_write_b16_d16_hi v158, v5 offset:1584
	ds_write_b16 v158, v6 offset:1728
	ds_write_b16_d16_hi v158, v6 offset:1872
	ds_write_b16 v158, v7 offset:2016
	ds_write_b16_d16_hi v158, v7 offset:2160
	s_waitcnt vmcnt(37)
	ds_write_b16 v158, v8 offset:2304
	ds_write_b16_d16_hi v158, v8 offset:2448
	ds_write_b16 v158, v9 offset:2592
	ds_write_b16_d16_hi v158, v9 offset:2736
	ds_write_b16 v158, v10 offset:2880
	ds_write_b16_d16_hi v158, v10 offset:3024
	ds_write_b16 v158, v11 offset:3168
	ds_write_b16_d16_hi v158, v11 offset:3312
	s_waitcnt vmcnt(36)
	ds_write_b16 v158, v12 offset:3456
	ds_write_b16_d16_hi v158, v12 offset:3600
	ds_write_b16 v158, v13 offset:3744
	ds_write_b16_d16_hi v158, v13 offset:3888
	ds_write_b16 v158, v14 offset:4032
	ds_write_b16_d16_hi v158, v14 offset:4176
	ds_write_b16 v158, v15 offset:4320
	ds_write_b16_d16_hi v158, v15 offset:4464
	s_waitcnt vmcnt(35)
	ds_write_b16 v158, v16 offset:4608
	ds_write_b16_d16_hi v158, v16 offset:4752
	ds_write_b16 v158, v17 offset:4896
	ds_write_b16_d16_hi v158, v17 offset:5040
	ds_write_b16 v158, v18 offset:5184
	ds_write_b16_d16_hi v158, v18 offset:5328
	ds_write_b16 v158, v19 offset:5472
	ds_write_b16_d16_hi v158, v19 offset:5616
	s_waitcnt vmcnt(34)
	ds_write_b16 v158, v20 offset:5760
	ds_write_b16_d16_hi v158, v20 offset:5904
	ds_write_b16 v158, v21 offset:6048
	ds_write_b16_d16_hi v158, v21 offset:6192
	ds_write_b16 v158, v22 offset:6336
	ds_write_b16_d16_hi v158, v22 offset:6480
	ds_write_b16 v158, v23 offset:6624
	ds_write_b16_d16_hi v158, v23 offset:6768
	s_waitcnt vmcnt(33)
	ds_write_b16 v158, v24 offset:6912
	ds_write_b16_d16_hi v158, v24 offset:7056
	ds_write_b16 v158, v25 offset:7200
	ds_write_b16_d16_hi v158, v25 offset:7344
	ds_write_b16 v158, v26 offset:7488
	ds_write_b16_d16_hi v158, v26 offset:7632
	ds_write_b16 v158, v27 offset:7776
	ds_write_b16_d16_hi v158, v27 offset:7920
	s_waitcnt vmcnt(32)
; __device__ __forceinline__ unsigned cvtpk(float lo, float hi) { f32x2_t v = {lo, hi}; bf16x2_t b = __builtin_convertvector(v, bf16x2_t); return __builtin_bit_cast(unsigned, b); }
; template <bool GLA>
; __device__ __forceinline__ void chunk_load(const ChunkIn& ci, int t, int h, int kq, ChunkRaw& r) {
;     const bf16_t* pr = ci.proj + (size_t)t * DINP;
;     const int cq = GLA ? C_GQ : C_RQ, ck = GLA ? C_GK : C_RK;
;     r.qa = *(const u32x2*)(pr + cq + h * 32 + 4 * kq); r.qb = *(const u32x2*)(pr + cq + h * 32 + 16 + 4 * kq);
;     r.ka = *(const u32x2*)(pr + ck + h * 32 + 4 * kq); r.kb = *(const u32x2*)(pr + ck + h * 32 + 16 + 4 * kq);
;     if (GLA) { r.g0 = *(const u32x4*)(pr + C_GG); r.g1 = *(const u32x4*)(pr + C_GG + 8); }
;     ...
; }
; template <bool GLA>
; __device__ __forceinline__ void chunk_pass_c(const ChunkIn& ci, const float* wgl, int unit, unsigned char* wl, int lane, const float* Sb, const float* ng, bf16_t* omix) {
;     ...
;     { const float* sp = Sb + (size_t)unit * 2048 + lane;
;       float sv[32];
; #pragma unroll
;       for (int d = 0; d < 32; ++d) sv[d] = sp[d * 64];
; #pragma unroll
;       for (int q4 = 0; q4 < 4; ++q4) {
;           u32x4 w; w.x = cvtpk(sv[4 * q4 + 0], sv[4 * q4 + 1]); w.y = cvtpk(sv[4 * q4 + 2], sv[4 * q4 + 3]); w.z = cvtpk(sv[16 + 4 * q4 + 0], sv[16 + 4 * q4 + 1]); w.w = cvtpk(sv[16 + 4 * q4 + 2], sv[16 + 4 * q4 + 3]);
;           *(u32x4*)(sst + lane * 64 + q4 * 16) = w;
;       } }
;     asm volatile("" ::: "memory");
;     float carry[8] = {0.f, 0.f, 0.f, 0.f, 0.f, 0.f, 0.f, 0.f};
;     int hh_ = h; asm volatile("" : "+s"(hh_)); const float hf = (float)hh_;
;     const float lg = GLA ? 0.f : __logf(1.0f - __builtin_amdgcn_exp2f(-5.0f - hf));
;     bf16x8 qf[4], kf[4], qb[4], kb[4];
;     ChunkRaw raw[4];
; #pragma unroll
;     for (int it = 0; it < 4; ++it) chunk_load<GLA>(ci, t0 + 16 * it + row, h, kq, raw[it]);
;     bf16x8 wfr[2]; f32x4 bfr[2]; if (GLA) chunk_gate_frags(wgl, h, row, kq, wfr, bfr);
	ds_write_b16 v158, v28 offset:8064
	ds_write_b16_d16_hi v158, v28 offset:8208
	ds_write_b16 v158, v29 offset:8352
	ds_write_b16_d16_hi v158, v29 offset:8496
	ds_write_b16 v158, v30 offset:8640
	ds_write_b16_d16_hi v158, v30 offset:8784
	ds_write_b16 v158, v31 offset:8928
	ds_write_b16_d16_hi v158, v31 offset:9072
	s_waitcnt vmcnt(30)
	v_cvt_pk_bf16_f32 v0, v34, v35
	s_waitcnt vmcnt(28)
	v_cvt_pk_bf16_f32 v1, v36, v37
	s_waitcnt vmcnt(14)
	v_cvt_pk_bf16_f32 v2, v50, v51
	s_waitcnt vmcnt(12)
	v_cvt_pk_bf16_f32 v3, v52, v53
	ds_write_b128 v157, v[0:3] offset:9216
	v_cvt_pk_bf16_f32 v0, v38, v39
	v_cvt_pk_bf16_f32 v1, v40, v41
	s_waitcnt vmcnt(10)
	v_cvt_pk_bf16_f32 v2, v54, v55
	s_waitcnt vmcnt(8)
	v_cvt_pk_bf16_f32 v3, v56, v57
	ds_write_b128 v157, v[0:3] offset:9232
	v_cvt_pk_bf16_f32 v0, v42, v43
	v_cvt_pk_bf16_f32 v1, v44, v45
	s_waitcnt vmcnt(6)
	v_cvt_pk_bf16_f32 v2, v58, v59
	s_waitcnt vmcnt(4)
	v_cvt_pk_bf16_f32 v3, v60, v61
	ds_write_b128 v157, v[0:3] offset:9248
	v_cvt_pk_bf16_f32 v0, v46, v47
	v_cvt_pk_bf16_f32 v1, v48, v49
	s_waitcnt vmcnt(2)
	v_cvt_pk_bf16_f32 v2, v62, v63
	s_waitcnt vmcnt(0)
	v_cvt_pk_bf16_f32 v3, v64, v32
	v_or_b32_e32 v6, s6, v156
	ds_write_b128 v157, v[0:3] offset:9264
	v_and_b32_e32 v0, 48, v147
	v_mov_b32_e32 v1, v211
	v_lshlrev_b32_e32 v4, 12, v6
	v_mov_b32_e32 v5, v211
	v_lshl_add_u64 v[2:3], s[22:23], 0, v[0:1]
	v_lshl_add_u64 v[4:5], s[62:63], 0, v[4:5]
	v_lshlrev_b32_e32 v6, 6, v6
	v_mov_b32_e32 v7, v211
	v_lshl_add_u64 v[0:1], s[20:21], 0, v[0:1]
	v_lshl_add_u64 v[4:5], v[4:5], 0, v[114:115]
	v_lshl_add_u64 v[8:9], v[2:3], 0, v[6:7]
	global_load_dwordx2 v[24:25], v[4:5], off offset:2400
	global_load_dwordx2 v[26:27], v[4:5], off offset:2432
	v_lshl_add_u64 v[6:7], v[0:1], 0, v[6:7]
	global_load_dwordx4 v[8:11], v[8:9], off
	s_nop 0
	global_load_dwordx4 v[16:19], v[6:7], off
	global_load_dwordx2 v[32:33], v[4:5], off offset:2656
	global_load_dwordx2 v[34:35], v[4:5], off offset:2688
	v_cvt_f32_i32_e32 v12, s4
	v_mov_b32_e32 v5, v211
	s_or_b32 s4, s6, 32
	s_mov_b32 s6, 0x358637bd
	v_sub_f32_e32 v6, 0xc0a00000, v12
	v_exp_f32_e32 v6, v6
	s_waitcnt vmcnt(5)
	v_lshlrev_b32_e32 v40, 16, v24
	v_sub_f32_e32 v36, 1.0, v6
	v_or_b32_e32 v6, s5, v156
	v_lshlrev_b32_e32 v4, 12, v6
	v_lshl_add_u64 v[4:5], s[62:63], 0, v[4:5]
	v_lshl_add_u64 v[4:5], v[4:5], 0, v[114:115]
	global_load_dwordx2 v[144:145], v[4:5], off offset:2400
	global_load_dwordx2 v[142:143], v[4:5], off offset:2432
	global_load_dwordx2 v[30:31], v[4:5], off offset:2656
	global_load_dwordx2 v[28:29], v[4:5], off offset:2688
	v_lshlrev_b32_e32 v4, 6, v6
	v_mov_b32_e32 v5, v211
	v_lshl_add_u64 v[6:7], v[2:3], 0, v[4:5]
	v_lshl_add_u64 v[4:5], v[0:1], 0, v[4:5]
	global_load_dwordx4 v[76:79], v[6:7], off
	global_load_dwordx4 v[80:83], v[4:5], off
	v_or_b32_e32 v6, s4, v156
	v_lshlrev_b32_e32 v4, 12, v6
	v_mov_b32_e32 v5, v211
	v_lshl_add_u64 v[4:5], s[62:63], 0, v[4:5]
	v_lshl_add_u64 v[4:5], v[4:5], 0, v[114:115]
	global_load_dwordx2 v[130:131], v[4:5], off offset:2400
	global_load_dwordx2 v[128:129], v[4:5], off offset:2432
	global_load_dwordx2 v[22:23], v[4:5], off offset:2656
	global_load_dwordx2 v[20:21], v[4:5], off offset:2688
	v_lshlrev_b32_e32 v4, 6, v6
	v_mov_b32_e32 v5, v211
	v_lshl_add_u64 v[6:7], v[2:3], 0, v[4:5]
	v_lshl_add_u64 v[4:5], v[0:1], 0, v[4:5]
	global_load_dwordx4 v[64:67], v[6:7], off
	global_load_dwordx4 v[68:71], v[4:5], off
	v_or_b32_e32 v4, s3, v156
	v_mov_b32_e32 v5, v211
	v_lshlrev_b64 v[6:7], 12, v[4:5]
	v_lshl_add_u64 v[6:7], s[62:63], 0, v[6:7]
	v_cmp_gt_f32_e32 vcc, s96, v36
	v_lshl_add_u64 v[6:7], v[6:7], 0, v[114:115]
	s_and_b64 s[8:9], vcc, exec
	global_load_dwordx2 v[108:109], v[6:7], off offset:2400
	global_load_dwordx2 v[106:107], v[6:7], off offset:2432
	global_load_dwordx2 v[14:15], v[6:7], off offset:2656
	global_load_dwordx2 v[12:13], v[6:7], off offset:2688
	v_lshlrev_b64 v[4:5], 6, v[4:5]
	s_cselect_b32 s7, 32, 0
	v_lshl_add_u64 v[2:3], v[2:3], 0, v[4:5]
	v_ldexp_f32 v6, v36, s7
	v_lshl_add_u64 v[4:5], v[0:1], 0, v[4:5]
	v_log_f32_e32 v36, v6
	global_load_dwordx4 v[0:3], v[2:3], off
	s_nop 0
	global_load_dwordx4 v[4:7], v[4:5], off
	s_mov_b32 s7, 0x3f317217
	v_cndmask_b32_e32 v37, 0, v237, vcc
	v_mul_f32_e32 v38, 0x3f317217, v36
	v_fma_f32 v38, v36, s7, -v38
	v_fmac_f32_e32 v38, 0x3377d1cf, v36
	s_mov_b32 s7, 0x7f800000
	v_fmac_f32_e32 v38, 0x3f317217, v36
	v_cmp_lt_f32_e64 vcc, |v36|, s7
	v_and_b32_e32 v41, 0xffff0000, v24
	s_waitcnt vmcnt(18)
; __device__ __forceinline__ unsigned cvtpk(float lo, float hi) { f32x2_t v = {lo, hi}; bf16x2_t b = __builtin_convertvector(v, bf16x2_t); return __builtin_bit_cast(unsigned, b); }
; template <bool GLA>
; __device__ __forceinline__ void chunk_tile(const ChunkRaw& raw, const bf16x8 (&wfr)[2], const f32x4 (&bfr)[2], int h, int it, int row, int kq, float lg, float (&carry)[8], float (&bq)[8], float (&qv)[8], float (&kv)[8]) {
;     ...
; #pragma unroll
;         for (int j = 0; j < 4; ++j) {
;             qv[j] = (q[j] * cc[j] - q[4 + j] * ss[j]) * qs; qv[4 + j] = (q[j] * ss[j] + q[4 + j] * cc[j]) * qs;
;             kv[j] = k[j] * cc[j] - k[4 + j] * ss[j];        kv[4 + j] = k[j] * ss[j] + k[4 + j] * cc[j];
;         }
; #pragma unroll
;         for (int j = 0; j < 8; ++j) { bq[j] = (float)(16 * it + row + 1) * lg; carry[j] = 64.0f * lg; }
;     }
; template <bool GLA>
; __device__ __forceinline__ void chunk_pass_c(const ChunkIn& ci, const float* wgl, int unit, unsigned char* wl, int lane, const float* Sb, const float* ng, bf16_t* omix) {
;     ...
;     for (int it = 0; it < 4; ++it) {
;         float bq[8], qv[8], kv[8];
;         chunk_tile<GLA>(raw[it], wfr, bfr, h, it, row, kq, lg, carry, bq, qv, kv);
;         float a[8], bneg[8], cpos[8], dneg[8];
; #pragma unroll
;         for (int j = 0; j < 8; ++j) { const float eb = __expf(bq[j]), enb = __expf(-bq[j]); a[j] = qv[j] * eb; bneg[j] = kv[j] * enb; cpos[j] = qv[j] * enb; dneg[j] = kv[j] * eb; }
;         qf[it] = __builtin_bit_cast(bf16x8, (u32x4){cvtpk(a[0], a[1]), cvtpk(a[2], a[3]), cvtpk(a[4], a[5]), cvtpk(a[6], a[7])});
;         kf[it] = __builtin_bit_cast(bf16x8, (u32x4){cvtpk(bneg[0], bneg[1]), cvtpk(bneg[2], bneg[3]), cvtpk(bneg[4], bneg[5]), cvtpk(bneg[6], bneg[7])});
;         qb[it] = __builtin_bit_cast(bf16x8, (u32x4){cvtpk(cpos[0], cpos[1]), cvtpk(cpos[2], cpos[3]), cvtpk(cpos[4], cpos[5]), cvtpk(cpos[6], cpos[7])});
;         kb[it] = __builtin_bit_cast(bf16x8, (u32x4){cvtpk(dneg[0], dneg[1]), cvtpk(dneg[2], dneg[3]), cvtpk(dneg[4], dneg[5]), cvtpk(dneg[6], dneg[7])});
	v_lshlrev_b32_e32 v50, 16, v34
	v_cndmask_b32_e32 v36, v36, v38, vcc
	v_sub_f32_e32 v39, v36, v37
	v_add_u32_e32 v36, 1, v156
	v_cvt_f32_ubyte0_e32 v36, v36
	v_mul_f32_e32 v37, v39, v36
	v_mul_f32_e32 v36, 0x3fb8aa3b, v37
	v_mul_f32_e32 v37, 0xbfb8aa3b, v37
	v_exp_f32_e32 v36, v36
	v_exp_f32_e32 v38, v37
	v_and_b32_e32 v51, 0xffff0000, v34
	v_lshlrev_b32_e32 v42, 16, v26
	v_and_b32_e32 v43, 0xffff0000, v26
	v_pk_mul_f32 v[44:45], v[16:17], v[40:41]
	v_lshlrev_b32_e32 v48, 16, v32
	v_and_b32_e32 v49, 0xffff0000, v32
	v_pk_mul_f32 v[52:53], v[8:9], v[50:51]
	v_pk_fma_f32 v[44:45], v[8:9], v[42:43], v[44:45]
	v_pk_mul_f32 v[42:43], v[16:17], v[42:43]
	v_pk_fma_f32 v[52:53], v[16:17], v[48:49], v[52:53]
	v_pk_mul_f32 v[16:17], v[16:17], v[50:51]
	v_pk_fma_f32 v[40:41], v[8:9], v[40:41], v[42:43] neg_lo:[0,0,1] neg_hi:[0,0,1]
	v_pk_fma_f32 v[8:9], v[8:9], v[48:49], v[16:17] neg_lo:[0,0,1] neg_hi:[0,0,1]
	v_lshlrev_b32_e32 v24, 16, v27
	v_pk_mul_f32 v[16:17], v[38:39], v[8:9] op_sel_hi:[0,1]
	v_pk_mul_f32 v[48:49], v[36:37], v[8:9] op_sel_hi:[0,1]
	v_lshlrev_b32_e32 v8, 16, v25
	v_and_b32_e32 v9, 0xffff0000, v25
	v_and_b32_e32 v25, 0xffff0000, v27
	v_pk_mul_f32 v[26:27], v[18:19], v[8:9]
	v_lshlrev_b32_e32 v34, 16, v35
	v_and_b32_e32 v35, 0xffff0000, v35
	v_pk_fma_f32 v[26:27], v[10:11], v[24:25], v[26:27]
	v_pk_mul_f32 v[24:25], v[18:19], v[24:25]
	v_lshlrev_b32_e32 v32, 16, v33
	v_and_b32_e32 v33, 0xffff0000, v33
	v_pk_mul_f32 v[56:57], v[10:11], v[34:35]
	s_mov_b32 s8, 0x3e3504f3
	v_pk_fma_f32 v[8:9], v[10:11], v[8:9], v[24:25] neg_lo:[0,0,1] neg_hi:[0,0,1]
	v_pk_fma_f32 v[56:57], v[18:19], v[32:33], v[56:57]
	v_pk_mul_f32 v[18:19], v[18:19], v[34:35]
	v_pk_mul_f32 v[8:9], v[8:9], s[8:9] op_sel_hi:[1,0]
	v_pk_fma_f32 v[10:11], v[10:11], v[32:33], v[18:19] neg_lo:[0,0,1] neg_hi:[0,0,1]
	v_pk_mul_f32 v[24:25], v[36:37], v[8:9] op_sel_hi:[0,1]
	v_pk_mul_f32 v[32:33], v[36:37], v[10:11] op_sel_hi:[0,1]
	v_cvt_pk_bf16_f32 v89, v24, v25
	v_cvt_pk_bf16_f32 v25, v32, v33
	v_add_u32_e32 v32, 17, v156
	v_cvt_f32_ubyte0_e32 v32, v32
	v_mul_f32_e32 v164, v39, v32
	v_pk_mul_f32 v[44:45], v[44:45], s[8:9] op_sel_hi:[1,0]
	v_pk_mul_f32 v[40:41], v[40:41], s[8:9] op_sel_hi:[1,0]
	v_pk_mul_f32 v[26:27], v[26:27], s[8:9] op_sel_hi:[1,0]
	v_pk_mul_f32 v[34:35], v[38:39], v[56:57] op_sel_hi:[0,1]
	v_mul_f32_e32 v32, 0x3fb8aa3b, v164
	v_pk_mul_f32 v[42:43], v[36:37], v[40:41] op_sel_hi:[0,1]
	v_pk_mul_f32 v[46:47], v[36:37], v[44:45] op_sel_hi:[0,1]
	v_pk_mul_f32 v[50:51], v[38:39], v[52:53] op_sel_hi:[0,1]
	v_pk_mul_f32 v[52:53], v[36:37], v[52:53] op_sel_hi:[0,1]
	v_pk_mul_f32 v[54:55], v[38:39], v[8:9] op_sel_hi:[0,1]
	v_pk_mul_f32 v[8:9], v[36:37], v[26:27] op_sel_hi:[0,1]
	v_pk_mul_f32 v[26:27], v[38:39], v[26:27] op_sel_hi:[0,1]
	v_pk_mul_f32 v[18:19], v[38:39], v[10:11] op_sel_hi:[0,1]
	v_pk_mul_f32 v[36:37], v[36:37], v[56:57] op_sel_hi:[0,1]
	v_cvt_pk_bf16_f32 v11, v34, v35
	v_exp_f32_e32 v146, v32
	s_waitcnt vmcnt(14)
	v_lshlrev_b32_e32 v34, 16, v28
	v_and_b32_e32 v35, 0xffff0000, v28
	v_cvt_pk_bf16_f32 v91, v8, v9
	v_cvt_pk_bf16_f32 v9, v18, v19
	v_cvt_pk_bf16_f32 v19, v26, v27
	v_cvt_pk_bf16_f32 v27, v36, v37
	v_lshlrev_b32_e32 v32, 16, v30
	v_and_b32_e32 v33, 0xffff0000, v30
	s_waitcnt vmcnt(13)
	v_pk_mul_f32 v[36:37], v[76:77], v[34:35]
	v_lshlrev_b32_e32 v28, 16, v29
	v_and_b32_e32 v29, 0xffff0000, v29
	s_waitcnt vmcnt(12)
	v_pk_fma_f32 v[148:149], v[80:81], v[32:33], v[36:37]
	v_lshlrev_b32_e32 v30, 16, v31
	v_and_b32_e32 v31, 0xffff0000, v31
	v_pk_mul_f32 v[36:37], v[78:79], v[28:29]
	v_pk_mul_f32 v[28:29], v[82:83], v[28:29]
	v_pk_mul_f32 v[34:35], v[80:81], v[34:35]
	v_pk_fma_f32 v[154:155], v[78:79], v[30:31], v[28:29] neg_lo:[0,0,1] neg_hi:[0,0,1]
	v_pk_fma_f32 v[152:153], v[82:83], v[30:31], v[36:37]
	v_pk_mul_f32 v[28:29], v[146:147], v[154:155] op_sel_hi:[0,1]
	v_cvt_pk_bf16_f32 v85, v28, v29
	v_add_u32_e32 v28, 33, v156
	v_cvt_f32_ubyte0_e32 v28, v28
	v_mul_f32_e32 v163, v39, v28
	v_pk_fma_f32 v[150:151], v[76:77], v[32:33], v[34:35] neg_lo:[0,0,1] neg_hi:[0,0,1]
	v_pk_mul_f32 v[30:31], v[146:147], v[152:153] op_sel_hi:[0,1]
	v_mul_f32_e32 v28, 0x3fb8aa3b, v163
	v_pk_mul_f32 v[32:33], v[146:147], v[150:151] op_sel_hi:[0,1]
	v_cvt_pk_bf16_f32 v87, v30, v31
	v_exp_f32_e32 v132, v28
	s_waitcnt vmcnt(8)
	v_lshlrev_b32_e32 v30, 16, v20
	v_and_b32_e32 v31, 0xffff0000, v20
	v_cvt_pk_bf16_f32 v84, v32, v33
	v_lshlrev_b32_e32 v28, 16, v22
	v_and_b32_e32 v29, 0xffff0000, v22
	s_waitcnt vmcnt(7)
	v_pk_mul_f32 v[32:33], v[64:65], v[30:31]
	v_lshlrev_b32_e32 v20, 16, v21
	v_and_b32_e32 v21, 0xffff0000, v21
	s_waitcnt vmcnt(6)
	v_pk_fma_f32 v[134:135], v[68:69], v[28:29], v[32:33]
	v_lshlrev_b32_e32 v22, 16, v23
	v_and_b32_e32 v23, 0xffff0000, v23
	v_pk_mul_f32 v[32:33], v[66:67], v[20:21]
	v_pk_mul_f32 v[20:21], v[70:71], v[20:21]
	v_cvt_pk_bf16_f32 v8, v16, v17
	v_pk_fma_f32 v[140:141], v[66:67], v[22:23], v[20:21] neg_lo:[0,0,1] neg_hi:[0,0,1]
	v_cvt_pk_bf16_f32 v10, v50, v51
	v_pk_mul_f32 v[20:21], v[132:133], v[140:141] op_sel_hi:[0,1]
	v_cvt_pk_bf16_f32 v73, v20, v21
	v_add_u32_e32 v20, 49, v156
	v_cvt_pk_bf16_f32 v24, v48, v49
	v_cvt_pk_bf16_f32 v26, v52, v53
	v_cvt_f32_ubyte0_e32 v20, v20
	v_pk_mul_f32 v[30:31], v[68:69], v[30:31]
	v_pk_fma_f32 v[138:139], v[70:71], v[22:23], v[32:33]
	v_mul_f32_e32 v162, v39, v20
	v_pk_fma_f32 v[136:137], v[64:65], v[28:29], v[30:31] neg_lo:[0,0,1] neg_hi:[0,0,1]
	v_pk_mul_f32 v[22:23], v[132:133], v[138:139] op_sel_hi:[0,1]
	v_mul_f32_e32 v20, 0x3fb8aa3b, v162
	v_pk_mul_f32 v[40:41], v[38:39], v[40:41] op_sel_hi:[0,1]
	v_pk_mul_f32 v[44:45], v[38:39], v[44:45] op_sel_hi:[0,1]
	v_pk_mul_f32 v[34:35], v[146:147], v[148:149] op_sel_hi:[0,1]
	v_pk_mul_f32 v[28:29], v[132:133], v[136:137] op_sel_hi:[0,1]
	v_cvt_pk_bf16_f32 v75, v22, v23
	v_exp_f32_e32 v118, v20
	s_waitcnt vmcnt(2)
; __device__ __forceinline__ unsigned cvtpk(float lo, float hi) { f32x2_t v = {lo, hi}; bf16x2_t b = __builtin_convertvector(v, bf16x2_t); return __builtin_bit_cast(unsigned, b); }
; __device__ __forceinline__ float silu_f(float g) { return g * __builtin_amdgcn_rcpf(1.0f + __expf(-g)); }
; template <bool GLA>
; __device__ __forceinline__ void chunk_pass_c(const ChunkIn& ci, const float* wgl, int unit, unsigned char* wl, int lane, const float* Sb, const float* ng, bf16_t* omix) {
;     ...
;     for (int it = 0; it < 4; ++it) {
;         f32x4 st[4];
; #pragma unroll
;         for (int jt = 0; jt < 4; ++jt) {
;             const f32x4 z = {0.f, 0.f, 0.f, 0.f};
;             if (jt < it) st[jt] = __builtin_amdgcn_mfma_f32_16x16x32_bf16(kf[jt], qf[it], z, 0, 0, 0);
;             else if (jt > it) st[jt] = __builtin_amdgcn_mfma_f32_16x16x32_bf16(kb[jt], qb[it], z, 0, 0, 0);
;             else {
;                 const f32x4 lo = __builtin_amdgcn_mfma_f32_16x16x32_bf16(kf[jt], qf[it], z, 0, 0, 0), up = __builtin_amdgcn_mfma_f32_16x16x32_bf16(kb[jt], qb[it], z, 0, 0, 0);
; #pragma unroll
;                 for (int r = 0; r < 4; ++r) st[jt][r] = (4 * kq + r <= row) ? lo[r] : up[r];
;             }
;         }
;         bf16x8 af[2];
; #pragma unroll
;         for (int p = 0; p < 2; ++p)
;             af[p] = __builtin_bit_cast(bf16x8, (u32x4){cvtpk(st[2 * p][0], st[2 * p][1]), cvtpk(st[2 * p][2], st[2 * p][3]), cvtpk(st[2 * p + 1][0], st[2 * p + 1][1]), cvtpk(st[2 * p + 1][2], st[2 * p + 1][3])});
;     ...
;                 const float gt = __uint_as_float((unsigned)ci.proj[(size_t)t * DINP + gcol + e] << 16);
;                 const float val = o[et][r] * rs * gn[et] * pg8::silu_f(gt);
;                 omix[(size_t)t * 1024 + ocol + e] = (bf16_t)(cvtpk(val, 0.f) & 0xffffu);
	v_lshlrev_b32_e32 v22, 16, v12
	v_and_b32_e32 v23, 0xffff0000, v12
	v_cvt_pk_bf16_f32 v88, v42, v43
	v_cvt_pk_bf16_f32 v90, v46, v47
	v_cvt_pk_bf16_f32 v16, v40, v41
	v_cvt_pk_bf16_f32 v17, v54, v55
	v_cvt_pk_bf16_f32 v18, v44, v45
	v_cvt_pk_bf16_f32 v86, v34, v35
	v_cvt_pk_bf16_f32 v72, v28, v29
	v_lshlrev_b32_e32 v20, 16, v14
	v_and_b32_e32 v21, 0xffff0000, v14
	s_waitcnt vmcnt(1)
	v_pk_mul_f32 v[28:29], v[0:1], v[22:23]
	v_lshlrev_b32_e32 v12, 16, v13
	v_and_b32_e32 v13, 0xffff0000, v13
	s_waitcnt vmcnt(0)
	v_pk_fma_f32 v[120:121], v[4:5], v[20:21], v[28:29]
	v_pk_mul_f32 v[22:23], v[4:5], v[22:23]
	v_lshlrev_b32_e32 v14, 16, v15
	v_and_b32_e32 v15, 0xffff0000, v15
	v_pk_mul_f32 v[28:29], v[2:3], v[12:13]
	v_pk_mul_f32 v[12:13], v[6:7], v[12:13]
	v_mfma_f32_16x16x32_bf16 v[32:35], v[8:11], v[88:91], 0
	v_fma_f32 v122, v0, v20, -v22
	v_fma_f32 v123, v1, v21, -v23
	v_pk_fma_f32 v[124:125], v[6:7], v[14:15], v[28:29]
	v_pk_fma_f32 v[126:127], v[2:3], v[14:15], v[12:13] neg_lo:[0,0,1] neg_hi:[0,0,1]
	v_mfma_f32_16x16x32_bf16 v[24:27], v[24:27], v[16:19], 0
	v_mul_f32_e64 v30, v132, v134
	v_mul_f32_e64 v31, v132, v135
	v_pk_mul_f32 v[20:21], v[118:119], v[122:123] op_sel_hi:[0,1]
	v_pk_mul_f32 v[22:23], v[118:119], v[120:121] op_sel_hi:[0,1]
	v_pk_mul_f32 v[14:15], v[118:119], v[126:127] op_sel_hi:[0,1]
	v_pk_mul_f32 v[28:29], v[118:119], v[124:125] op_sel_hi:[0,1]
	v_cvt_pk_bf16_f32 v74, v30, v31
	v_cvt_pk_bf16_f32 v12, v20, v21
	v_cvt_pk_bf16_f32 v13, v14, v15
	v_cvt_pk_bf16_f32 v14, v22, v23
	v_cvt_pk_bf16_f32 v15, v28, v29
	v_cmp_gt_u32_e32 vcc, v97, v156
	v_mfma_f32_16x16x32_bf16 v[36:39], v[84:87], v[16:19], 0
	v_mul_u32_u24_e32 v20, 0x90, v156
	v_cndmask_b32_e32 v24, v32, v24, vcc
	v_or_b32_e32 v32, 2, v97
	v_cmp_gt_u32_e64 s[44:45], v32, v156
	v_or_b32_e32 v32, 3, v97
	v_cmp_gt_u32_e64 s[46:47], v32, v156
	v_readlane_b32 s7, v254, 60
	v_cndmask_b32_e64 v25, v25, v33, s[42:43]
	v_cndmask_b32_e64 v26, v34, v26, s[44:45]
	v_cndmask_b32_e64 v27, v35, v27, s[46:47]
	s_waitcnt vmcnt(0) expcnt(0) lgkmcnt(0)
	v_mov_b32_e32 v213, v211
	v_lshlrev_b32_e32 v212, 12, v165
	v_lshl_add_u64 v[214:215], s[58:59], 0, v[212:213]
	v_lshl_add_u64 v[216:217], v[214:215], 0, v[110:111]
	global_load_ushort v178, v[216:217], off offset:3424
	v_mov_b32_e32 v213, v211
	v_lshlrev_b32_e32 v212, 12, v165
	v_lshl_add_u64 v[214:215], s[58:59], 0, v[212:213]
	v_lshl_add_u64 v[216:217], v[214:215], 0, v[110:111]
	global_load_ushort v179, v[216:217], off offset:3456
	v_mov_b32_e32 v213, v211
	v_lshlrev_b32_e32 v212, 12, v165
	v_lshl_add_u64 v[214:215], s[58:59], 0, v[212:213]
	v_lshl_add_u64 v[216:217], v[214:215], 0, v[110:111]
	global_load_ushort v180, v[216:217], off offset:3488
	v_mov_b32_e32 v213, v211
	v_lshlrev_b32_e32 v212, 12, v165
	v_lshl_add_u64 v[214:215], s[58:59], 0, v[212:213]
	v_lshlrev_b32_e32 v216, 1, v177
	v_mov_b32_e32 v217, v211
	v_lshl_add_u64 v[218:219], v[214:215], 0, v[216:217]
	global_load_ushort v181, v[218:219], off offset:3424
	v_or_b32_e32 v212, 1, v165
	v_lshlrev_b32_e32 v214, 12, v212
	v_mov_b32_e32 v215, v211
	v_lshl_add_u64 v[214:215], s[58:59], 0, v[214:215]
	v_lshl_add_u64 v[216:217], v[214:215], 0, v[110:111]
	global_load_ushort v182, v[216:217], off offset:3424
	v_or_b32_e32 v212, 1, v165
	v_lshlrev_b32_e32 v214, 12, v212
	v_mov_b32_e32 v215, v211
	v_lshl_add_u64 v[214:215], s[58:59], 0, v[214:215]
	v_lshl_add_u64 v[216:217], v[214:215], 0, v[110:111]
	global_load_ushort v183, v[216:217], off offset:3456
	v_or_b32_e32 v212, 1, v165
	v_lshlrev_b32_e32 v214, 12, v212
	v_mov_b32_e32 v215, v211
	v_lshl_add_u64 v[214:215], s[58:59], 0, v[214:215]
	v_lshl_add_u64 v[216:217], v[214:215], 0, v[110:111]
	global_load_ushort v184, v[216:217], off offset:3488
	v_lshlrev_b32_e32 v212, 1, v177
	v_mov_b32_e32 v213, v211
	v_or_b32_e32 v214, 1, v165
	v_lshlrev_b32_e32 v216, 12, v214
	v_mov_b32_e32 v217, v211
	v_lshl_add_u64 v[216:217], s[58:59], 0, v[216:217]
	v_lshl_add_u64 v[218:219], v[216:217], 0, v[212:213]
	global_load_ushort v185, v[218:219], off offset:3424
	v_or_b32_e32 v212, 2, v165
	v_mov_b32_e32 v215, v211
	v_lshlrev_b32_e32 v214, 12, v212
	v_lshl_add_u64 v[214:215], s[58:59], 0, v[214:215]
	v_lshl_add_u64 v[216:217], v[214:215], 0, v[110:111]
	global_load_ushort v186, v[216:217], off offset:3424
	v_or_b32_e32 v212, 2, v165
	v_mov_b32_e32 v215, v211
	v_lshlrev_b32_e32 v214, 12, v212
	v_lshl_add_u64 v[214:215], s[58:59], 0, v[214:215]
	v_lshl_add_u64 v[216:217], v[214:215], 0, v[110:111]
	global_load_ushort v187, v[216:217], off offset:3456
	v_or_b32_e32 v212, 2, v165
	v_mov_b32_e32 v215, v211
	v_lshlrev_b32_e32 v214, 12, v212
	v_lshl_add_u64 v[214:215], s[58:59], 0, v[214:215]
	v_lshl_add_u64 v[216:217], v[214:215], 0, v[110:111]
	global_load_ushort v188, v[216:217], off offset:3488
	v_lshlrev_b32_e32 v212, 1, v177
	v_mov_b32_e32 v213, v211
	v_or_b32_e32 v214, 2, v165
	v_mov_b32_e32 v217, v211
	v_lshlrev_b32_e32 v216, 12, v214
	v_lshl_add_u64 v[216:217], s[58:59], 0, v[216:217]
	v_lshl_add_u64 v[216:217], v[216:217], 0, v[212:213]
	global_load_ushort v189, v[216:217], off offset:3424
	v_or_b32_e32 v212, 3, v165
	v_mov_b32_e32 v215, v211
	v_lshlrev_b32_e32 v214, 12, v212
	v_lshl_add_u64 v[216:217], s[58:59], 0, v[214:215]
	v_lshl_add_u64 v[218:219], v[216:217], 0, v[110:111]
	global_load_ushort v190, v[218:219], off offset:3424
	v_or_b32_e32 v212, 3, v165
	v_mov_b32_e32 v215, v211
	v_lshlrev_b32_e32 v214, 12, v212
	v_lshl_add_u64 v[216:217], s[58:59], 0, v[214:215]
	v_lshl_add_u64 v[218:219], v[216:217], 0, v[110:111]
	global_load_ushort v191, v[218:219], off offset:3456
	v_or_b32_e32 v212, 3, v165
	v_mov_b32_e32 v215, v211
; template <bool GLA>
; __device__ __forceinline__ void chunk_pass_c(const ChunkIn& ci, const float* wgl, int unit, unsigned char* wl, int lane, const float* Sb, const float* ng, bf16_t* omix) {
;     ...
;     bf16x8 vfr[4][2], sfr[4];
; #pragma unroll
;     for (int et = 0; et < 4; ++et) {
; #pragma unroll
;         for (int p = 0; p < 2; ++p) {
;             const u32x2 lo = *(const u32x2*)(wl + (16 * et + row) * GP + (32 * p + 4 * kq) * 2), hh = *(const u32x2*)(wl + (16 * et + row) * GP + (32 * p + 16 + 4 * kq) * 2);
;             vfr[et][p] = __builtin_bit_cast(bf16x8, (u32x4){lo.x, lo.y, hh.x, hh.y});
;         }
;         sfr[et] = *(const bf16x8*)(sst + (16 * et + row) * 64 + kq * 16);
;     }
;     const int gcol = (GLA ? C_GR : C_RG) + h * 64, ocol = (GLA ? 512 : 768) + h * 64;
;     float gn[4];
; #pragma unroll
;     for (int et = 0; et < 4; ++et) gn[et] = ng[16 * et + row];
; #pragma unroll
;     for (int it = 0; it < 4; ++it) {
;         f32x4 st[4];
; #pragma unroll
;         for (int jt = 0; jt < 4; ++jt) {
;             const f32x4 z = {0.f, 0.f, 0.f, 0.f};
;             if (jt < it) st[jt] = __builtin_amdgcn_mfma_f32_16x16x32_bf16(kf[jt], qf[it], z, 0, 0, 0);
;             else if (jt > it) st[jt] = __builtin_amdgcn_mfma_f32_16x16x32_bf16(kb[jt], qb[it], z, 0, 0, 0);
;             else {
;                 const f32x4 lo = __builtin_amdgcn_mfma_f32_16x16x32_bf16(kf[jt], qf[it], z, 0, 0, 0), up = __builtin_amdgcn_mfma_f32_16x16x32_bf16(kb[jt], qb[it], z, 0, 0, 0);
; #pragma unroll
;                 for (int r = 0; r < 4; ++r) st[jt][r] = (4 * kq + r <= row) ? lo[r] : up[r];
;             }
;         }
;         bf16x8 af[2];
; #pragma unroll
;         for (int p = 0; p < 2; ++p)
;             af[p] = __builtin_bit_cast(bf16x8, (u32x4){cvtpk(st[2 * p][0], st[2 * p][1]), cvtpk(st[2 * p][2], st[2 * p][3]), cvtpk(st[2 * p + 1][0], st[2 * p + 1][1]), cvtpk(st[2 * p + 1][2], st[2 * p + 1][3])});
;         f32x4 o[4]; float ss[4] = {0.f, 0.f, 0.f, 0.f};
; #pragma unroll
;         for (int et = 0; et < 4; ++et) {
;             f32x4 acc = {0.f, 0.f, 0.f, 0.f};
;             acc = __builtin_amdgcn_mfma_f32_16x16x32_bf16(af[0], vfr[et][0], acc, 0, 0, 0);
;             acc = __builtin_amdgcn_mfma_f32_16x16x32_bf16(af[1], vfr[et][1], acc, 0, 0, 0);
;             acc = __builtin_amdgcn_mfma_f32_16x16x32_bf16(qf[it], sfr[et], acc, 0, 0, 0);
	v_lshlrev_b32_e32 v214, 12, v212
	v_lshl_add_u64 v[216:217], s[58:59], 0, v[214:215]
	v_lshl_add_u64 v[218:219], v[216:217], 0, v[110:111]
	global_load_ushort v192, v[218:219], off offset:3488
	v_lshlrev_b32_e32 v212, 1, v177
	v_mov_b32_e32 v213, v211
	v_or_b32_e32 v214, 3, v165
	v_mov_b32_e32 v217, v211
	v_lshlrev_b32_e32 v216, 12, v214
	v_lshl_add_u64 v[218:219], s[58:59], 0, v[216:217]
	v_lshl_add_u64 v[220:221], v[218:219], 0, v[212:213]
	global_load_ushort v193, v[220:221], off offset:3424
	v_mov_b32_e32 v213, v211
	v_or_b32_e32 v214, s5, v97
	v_lshlrev_b32_e32 v212, 12, v214
	v_lshl_add_u64 v[212:213], s[58:59], 0, v[212:213]
	v_lshl_add_u64 v[216:217], v[212:213], 0, v[110:111]
	global_load_ushort v194, v[216:217], off offset:3424
	v_mov_b32_e32 v213, v211
	v_or_b32_e32 v214, s5, v97
	v_lshlrev_b32_e32 v212, 12, v214
	v_lshl_add_u64 v[212:213], s[58:59], 0, v[212:213]
	v_lshl_add_u64 v[216:217], v[212:213], 0, v[110:111]
	global_load_ushort v195, v[216:217], off offset:3456
	v_mov_b32_e32 v213, v211
	v_or_b32_e32 v214, s5, v97
	v_lshlrev_b32_e32 v212, 12, v214
	v_lshl_add_u64 v[212:213], s[58:59], 0, v[212:213]
	v_lshl_add_u64 v[216:217], v[212:213], 0, v[110:111]
	global_load_ushort v196, v[216:217], off offset:3488
	v_lshlrev_b32_e32 v212, 1, v177
	v_mov_b32_e32 v213, v211
	v_mov_b32_e32 v215, v211
	v_or_b32_e32 v216, s5, v97
	v_lshlrev_b32_e32 v214, 12, v216
	v_lshl_add_u64 v[214:215], s[58:59], 0, v[214:215]
	v_lshl_add_u64 v[214:215], v[214:215], 0, v[212:213]
	global_load_ushort v197, v[214:215], off offset:3424
	v_or_b32_e32 v212, s5, v97
	v_or_b32_e32 v214, 1, v212
	v_mov_b32_e32 v217, v211
	v_lshlrev_b32_e32 v216, 12, v214
	v_lshl_add_u64 v[216:217], s[58:59], 0, v[216:217]
	v_lshl_add_u64 v[218:219], v[216:217], 0, v[110:111]
	global_load_ushort v198, v[218:219], off offset:3424
	v_or_b32_e32 v212, s5, v97
	v_or_b32_e32 v214, 1, v212
	v_mov_b32_e32 v217, v211
	v_lshlrev_b32_e32 v216, 12, v214
	v_lshl_add_u64 v[216:217], s[58:59], 0, v[216:217]
	v_lshl_add_u64 v[218:219], v[216:217], 0, v[110:111]
	global_load_ushort v199, v[218:219], off offset:3456
	v_or_b32_e32 v212, s5, v97
	v_or_b32_e32 v214, 1, v212
	v_mov_b32_e32 v217, v211
	v_lshlrev_b32_e32 v216, 12, v214
	v_lshl_add_u64 v[216:217], s[58:59], 0, v[216:217]
	v_lshl_add_u64 v[218:219], v[216:217], 0, v[110:111]
	global_load_ushort v200, v[218:219], off offset:3488
	v_lshlrev_b32_e32 v212, 1, v177
	v_mov_b32_e32 v213, v211
	v_or_b32_e32 v214, s5, v97
	v_or_b32_e32 v216, 1, v214
	v_mov_b32_e32 v219, v211
	v_lshlrev_b32_e32 v218, 12, v216
	v_lshl_add_u64 v[218:219], s[58:59], 0, v[218:219]
	v_lshl_add_u64 v[218:219], v[218:219], 0, v[212:213]
	global_load_ushort v201, v[218:219], off offset:3424
	v_or_b32_e32 v212, s5, v97
	v_or_b32_e32 v214, 2, v212
	v_mov_b32_e32 v217, v211
	v_lshlrev_b32_e32 v216, 12, v214
	v_lshl_add_u64 v[216:217], s[58:59], 0, v[216:217]
	v_lshl_add_u64 v[218:219], v[216:217], 0, v[110:111]
	global_load_ushort v202, v[218:219], off offset:3424
	v_or_b32_e32 v212, s5, v97
	v_or_b32_e32 v214, 2, v212
	v_mov_b32_e32 v217, v211
	v_lshlrev_b32_e32 v216, 12, v214
	v_lshl_add_u64 v[216:217], s[58:59], 0, v[216:217]
	v_lshl_add_u64 v[218:219], v[216:217], 0, v[110:111]
	global_load_ushort v203, v[218:219], off offset:3456
	v_or_b32_e32 v212, s5, v97
	v_or_b32_e32 v214, 2, v212
	v_mov_b32_e32 v217, v211
	v_lshlrev_b32_e32 v216, 12, v214
	v_lshl_add_u64 v[216:217], s[58:59], 0, v[216:217]
	v_lshl_add_u64 v[218:219], v[216:217], 0, v[110:111]
	global_load_ushort v204, v[218:219], off offset:3488
	v_lshlrev_b32_e32 v212, 1, v177
	v_mov_b32_e32 v213, v211
	v_or_b32_e32 v214, s5, v97
	v_or_b32_e32 v216, 2, v214
	v_mov_b32_e32 v219, v211
	v_lshlrev_b32_e32 v218, 12, v216
	v_lshl_add_u64 v[218:219], s[58:59], 0, v[218:219]
	v_lshl_add_u64 v[218:219], v[218:219], 0, v[212:213]
	global_load_ushort v205, v[218:219], off offset:3424
	v_or_b32_e32 v212, s5, v97
	v_or_b32_e32 v214, 3, v212
	v_mov_b32_e32 v217, v211
	v_lshlrev_b32_e32 v216, 12, v214
	v_lshl_add_u64 v[216:217], s[58:59], 0, v[216:217]
	v_lshl_add_u64 v[218:219], v[216:217], 0, v[110:111]
	global_load_ushort v206, v[218:219], off offset:3424
	v_or_b32_e32 v212, s5, v97
	v_or_b32_e32 v214, 3, v212
	v_mov_b32_e32 v217, v211
	v_lshlrev_b32_e32 v216, 12, v214
	v_lshl_add_u64 v[216:217], s[58:59], 0, v[216:217]
	v_lshl_add_u64 v[218:219], v[216:217], 0, v[110:111]
	global_load_ushort v207, v[218:219], off offset:3456
	v_or_b32_e32 v212, s5, v97
	v_or_b32_e32 v214, 3, v212
	v_mov_b32_e32 v217, v211
	v_lshlrev_b32_e32 v216, 12, v214
	v_lshl_add_u64 v[216:217], s[58:59], 0, v[216:217]
	v_lshl_add_u64 v[218:219], v[216:217], 0, v[110:111]
	global_load_ushort v208, v[218:219], off offset:3488
	v_lshlrev_b32_e32 v212, 1, v177
	v_mov_b32_e32 v213, v211
	v_or_b32_e32 v214, s5, v97
	v_or_b32_e32 v216, 3, v214
	v_mov_b32_e32 v219, v211
	v_lshlrev_b32_e32 v218, 12, v216
	v_lshl_add_u64 v[218:219], s[58:59], 0, v[218:219]
	v_lshl_add_u64 v[220:221], v[218:219], 0, v[212:213]
	global_load_ushort v209, v[220:221], off offset:3424
	v_add3_u32 v48, s7, v20, v114
	v_mfma_f32_16x16x32_bf16 v[40:43], v[72:75], v[16:19], 0
	v_cvt_pk_bf16_f32 v166, v24, v25
	v_cvt_pk_bf16_f32 v167, v26, v27
	v_cvt_pk_bf16_f32 v168, v36, v37
	v_mfma_f32_16x16x32_bf16 v[16:19], v[12:15], v[16:19], 0
	v_cvt_pk_bf16_f32 v169, v38, v39
	ds_read2_b64 v[28:31], v48 offset1:4
	ds_read2_b64 v[20:23], v48 offset0:8 offset1:12
	s_nop 0
	v_cvt_pk_bf16_f32 v170, v40, v41
	v_cvt_pk_bf16_f32 v171, v42, v43
	s_nop 1
	v_cvt_pk_bf16_f32 v172, v16, v17
	v_cvt_pk_bf16_f32 v173, v18, v19
	s_waitcnt lgkmcnt(1)
; template <bool GLA>
; __device__ __forceinline__ void chunk_pass_c(const ChunkIn& ci, const float* wgl, int unit, unsigned char* wl, int lane, const float* Sb, const float* ng, bf16_t* omix) {
;     ...
;     for (int et = 0; et < 4; ++et) gn[et] = ng[16 * et + row];
; #pragma unroll
;     for (int it = 0; it < 4; ++it) {
;         f32x4 st[4];
; #pragma unroll
;         for (int jt = 0; jt < 4; ++jt) {
;             const f32x4 z = {0.f, 0.f, 0.f, 0.f};
;             if (jt < it) st[jt] = __builtin_amdgcn_mfma_f32_16x16x32_bf16(kf[jt], qf[it], z, 0, 0, 0);
;             else if (jt > it) st[jt] = __builtin_amdgcn_mfma_f32_16x16x32_bf16(kb[jt], qb[it], z, 0, 0, 0);
;             else {
;                 const f32x4 lo = __builtin_amdgcn_mfma_f32_16x16x32_bf16(kf[jt], qf[it], z, 0, 0, 0), up = __builtin_amdgcn_mfma_f32_16x16x32_bf16(kb[jt], qb[it], z, 0, 0, 0);
; #pragma unroll
;                 for (int r = 0; r < 4; ++r) st[jt][r] = (4 * kq + r <= row) ? lo[r] : up[r];
;             }
;         }
;         bf16x8 af[2];
; #pragma unroll
;         for (int p = 0; p < 2; ++p)
;             af[p] = __builtin_bit_cast(bf16x8, (u32x4){cvtpk(st[2 * p][0], st[2 * p][1]), cvtpk(st[2 * p][2], st[2 * p][3]), cvtpk(st[2 * p + 1][0], st[2 * p + 1][1]), cvtpk(st[2 * p + 1][2], st[2 * p + 1][3])});
;         f32x4 o[4]; float ss[4] = {0.f, 0.f, 0.f, 0.f};
; #pragma unroll
;         for (int et = 0; et < 4; ++et) {
;             f32x4 acc = {0.f, 0.f, 0.f, 0.f};
;             acc = __builtin_amdgcn_mfma_f32_16x16x32_bf16(af[0], vfr[et][0], acc, 0, 0, 0);
;             acc = __builtin_amdgcn_mfma_f32_16x16x32_bf16(af[1], vfr[et][1], acc, 0, 0, 0);
;             acc = __builtin_amdgcn_mfma_f32_16x16x32_bf16(qf[it], sfr[et], acc, 0, 0, 0);
;             o[et] = acc;
; #pragma unroll
;             for (int r = 0; r < 4; ++r) ss[r] += acc[r] * acc[r];
;         }
; #pragma unroll
;         for (int r = 0; r < 4; ++r) {
;             ss[r] += swz_xor<1>(ss[r]); ss[r] += swz_xor<2>(ss[r]); ss[r] += swz_xor<4>(ss[r]); ss[r] += swz_xor<8>(ss[r]);
;             const float rs = rsqrtf(ss[r] * (1.0f / 64.0f) + EPS);
;             const int t = t0 + 16 * it + 4 * kq + r;
; #pragma unroll
;             for (int et = 0; et < 4; ++et) {
;                 const int e = 16 * et + row;
;                 const float gt = __uint_as_float((unsigned)ci.proj[(size_t)t * DINP + gcol + e] << 16);
	v_mfma_f32_16x16x32_bf16 v[16:19], v[166:169], v[28:31], 0
	v_lshlrev_b32_e32 v24, 6, v156
	v_and_b32_e32 v25, 48, v133
	v_add3_u32 v60, s7, v25, v24
	ds_read_b128 v[24:27], v60 offset:9216
	s_waitcnt lgkmcnt(1)
	v_mfma_f32_16x16x32_bf16 v[32:35], v[170:173], v[20:23], v[16:19]
	v_add_u32_e32 v40, 0x800, v48
	ds_read2_b64 v[44:47], v40 offset0:32 offset1:36
	v_mov_b32_e32 v41, v211
	ds_read_b128 v[16:19], v60 offset:10240
	s_waitcnt lgkmcnt(2)
	v_mfma_f32_16x16x32_bf16 v[92:95], v[88:91], v[24:27], v[32:35]
	s_nop 2
	ds_read2_b64 v[32:35], v40 offset0:40 offset1:44
	v_lshlrev_b32_e32 v40, 12, v165
	v_lshl_add_u64 v[174:175], s[58:59], 0, v[40:41]
	v_lshl_add_u64 v[112:113], v[174:175], 0, v[110:111]
	s_waitcnt lgkmcnt(2)
	v_mfma_f32_16x16x32_bf16 v[36:39], v[166:169], v[44:47], 0
	v_add_u32_e32 v40, 0x1000, v48
	v_mov_b32_e32 v160, v93
	s_waitcnt lgkmcnt(0)
	v_mfma_f32_16x16x32_bf16 v[36:39], v[170:173], v[32:35], v[36:39]
	v_mfma_f32_16x16x32_bf16 v[102:105], v[88:91], v[16:19], v[36:39]
	ds_read2_b64 v[56:59], v40 offset0:64 offset1:68
	ds_read2_b64 v[52:55], v40 offset0:72 offset1:76
	s_nop 4
	ds_read_b128 v[36:39], v60 offset:11264
	global_load_dword v115, v159, s[48:49]
	v_mov_b32_e32 v117, v102
	s_waitcnt lgkmcnt(2)
	v_mfma_f32_16x16x32_bf16 v[40:43], v[166:169], v[56:59], 0
	v_mov_b32_e32 v161, v103
	v_pk_mul_f32 v[160:161], v[160:161], v[160:161]
	s_waitcnt lgkmcnt(1)
	v_mfma_f32_16x16x32_bf16 v[48:51], v[170:173], v[52:55], v[40:43]
	s_waitcnt lgkmcnt(0)
	v_mfma_f32_16x16x32_bf16 v[98:101], v[88:91], v[36:39], v[48:51]
	s_nop 1
	v_mul_u32_u24_e32 v40, 0x90, v177
	v_add3_u32 v116, s7, v40, v114
	ds_read_b128 v[40:43], v60 offset:12288
	ds_read2_b64 v[60:63], v116 offset1:4
	ds_read2_b64 v[48:51], v116 offset0:8 offset1:12
	s_waitcnt lgkmcnt(1)
	v_mfma_f32_16x16x32_bf16 v[166:169], v[166:169], v[60:63], 0
	v_mov_b32_e32 v116, v92
	v_pk_mul_f32 v[116:117], v[116:117], v[116:117]
	s_waitcnt lgkmcnt(0)
	v_mfma_f32_16x16x32_bf16 v[166:169], v[170:173], v[48:51], v[166:169]
	v_mov_b32_e32 v170, v160
	v_mov_b32_e32 v171, v116
	v_mov_b32_e32 v116, v161
	v_mfma_f32_16x16x32_bf16 v[88:91], v[88:91], v[40:43], v[166:169]
	v_add_f32_e64 v116, v170, v116
	v_add_f32_e64 v117, v171, v117
	s_waitcnt vmcnt(1)
	v_mov_b32_e32 v176, v178
	v_mov_b32_e32 v213, v211
	v_or_b32_e32 v214, s4, v97
	v_lshlrev_b32_e32 v212, 12, v214
	v_lshl_add_u64 v[212:213], s[58:59], 0, v[212:213]
	v_lshl_add_u64 v[216:217], v[212:213], 0, v[110:111]
	global_load_ushort v178, v[216:217], off offset:3424
	v_lshlrev_b32_e32 v170, 16, v176
	v_mov_b32_e32 v166, v98
	s_nop 2
	v_mov_b32_e32 v167, v88
	v_mov_b32_e32 v168, v99
	v_mov_b32_e32 v169, v89
	v_pk_mul_f32 v[166:167], v[166:167], v[166:167]
	v_pk_mul_f32 v[168:169], v[168:169], v[168:169]
	v_mov_b32_e32 v161, v166
	v_mov_b32_e32 v160, v168
	v_pk_add_f32 v[116:117], v[116:117], v[160:161]
	v_mov_b32_e32 v166, v169
	v_pk_add_f32 v[116:117], v[116:117], v[166:167]
	ds_swizzle_b32 v161, v117 offset:swizzle(SWAP,1)
	ds_swizzle_b32 v160, v116 offset:swizzle(SWAP,1)
	v_lshlrev_b32_e32 v168, 2, v177
	v_mov_b32_e32 v169, v211
	s_waitcnt lgkmcnt(0)
	v_pk_add_f32 v[116:117], v[116:117], v[160:161]
	ds_swizzle_b32 v161, v117 offset:swizzle(SWAP,2)
	ds_swizzle_b32 v160, v116 offset:swizzle(SWAP,2)
	s_waitcnt lgkmcnt(0)
	v_pk_add_f32 v[116:117], v[116:117], v[160:161]
	ds_swizzle_b32 v167, v117 offset:swizzle(SWAP,4)
	ds_swizzle_b32 v166, v116 offset:swizzle(SWAP,4)
	global_load_dword v161, v159, s[48:49] offset:64
	global_load_dword v160, v159, s[48:49] offset:128
	s_nop 0
	global_load_dword v159, v168, s[48:49]
	v_mul_f32_e32 v168, 0xbfb8aa3b, v170
	v_exp_f32_e32 v171, v168
	v_lshlrev_b32_e32 v168, 11, v165
	s_waitcnt lgkmcnt(0)
	v_pk_add_f32 v[116:117], v[116:117], v[166:167]
	ds_swizzle_b32 v167, v117 offset:swizzle(SWAP,8)
	ds_swizzle_b32 v166, v116 offset:swizzle(SWAP,8)
	v_add_f32_e32 v171, 1.0, v171
	v_rcp_f32_e32 v171, v171
	v_lshl_add_u64 v[168:169], s[60:61], 0, v[168:169]
	s_waitcnt lgkmcnt(0)
	v_pk_add_f32 v[166:167], v[116:117], v[166:167]
	v_mov_b64_e32 v[116:117], s[6:7]
	s_mov_b32 s6, 0x3c800000
	v_pk_fma_f32 v[166:167], v[166:167], s[6:7], v[116:117] op_sel_hi:[1,0,0]
	s_nop 0
	v_mul_f32_e32 v172, 0x4b800000, v167
	v_cmp_gt_f32_e64 s[48:49], s96, v167
	s_nop 1
	v_cndmask_b32_e64 v167, v167, v172, s[48:49]
	v_rsq_f32_e32 v167, v167
	v_mul_f32_e32 v172, v171, v170
	v_lshl_add_u64 v[170:171], v[168:169], 0, v[110:111]
	v_mul_f32_e32 v173, 0x45800000, v167
	v_cndmask_b32_e64 v167, v167, v173, s[48:49]
	v_mul_f32_e32 v92, v92, v167
	s_waitcnt vmcnt(3)
	v_mul_f32_e32 v92, v115, v92
	v_mul_f32_e32 v92, v172, v92
	v_cvt_pk_bf16_f32 v92, v92, s0
	global_store_short v[170:171], v92, off offset:1536
	v_mul_f32_e32 v102, v102, v167
	v_mul_f32_e32 v98, v98, v167
	v_mul_f32_e32 v88, v88, v167
	v_cmp_gt_f32_e64 s[48:49], s96, v166
	s_waitcnt vmcnt(3)
	v_mul_f32_e32 v102, v161, v102
	s_waitcnt vmcnt(2)
	v_mul_f32_e32 v98, v160, v98
	s_waitcnt vmcnt(1)
	v_mul_f32_e32 v88, v159, v88
	s_waitcnt vmcnt(0)
	v_mov_b32_e32 v92, v179
	v_mov_b32_e32 v213, v211
	v_or_b32_e32 v214, s4, v97
	v_lshlrev_b32_e32 v212, 12, v214
	v_lshl_add_u64 v[212:213], s[58:59], 0, v[212:213]
	v_lshl_add_u64 v[216:217], v[212:213], 0, v[110:111]
	global_load_ushort v179, v[216:217], off offset:3456
	v_lshlrev_b32_e32 v92, 16, v92
	v_mul_f32_e32 v172, 0xbfb8aa3b, v92
	v_exp_f32_e32 v172, v172
	s_nop 0
	v_add_f32_e32 v172, 1.0, v172
	v_rcp_f32_e32 v172, v172
	s_nop 0
	v_mul_f32_e32 v92, v172, v92
	v_mul_f32_e32 v92, v92, v102
	v_cvt_pk_bf16_f32 v92, v92, s0
	global_store_short v[170:171], v92, off offset:1568
	v_lshlrev_b32_e32 v112, 1, v177
	v_mov_b32_e32 v113, v211
	v_lshl_add_u64 v[172:173], v[174:175], 0, v[112:113]
	v_lshl_add_u64 v[168:169], v[168:169], 0, v[112:113]
	s_waitcnt vmcnt(37)
; __device__ __forceinline__ unsigned cvtpk(float lo, float hi) { f32x2_t v = {lo, hi}; bf16x2_t b = __builtin_convertvector(v, bf16x2_t); return __builtin_bit_cast(unsigned, b); }
; template <int X> __device__ __forceinline__ float swz_xor(float v) { return __int_as_float(__builtin_amdgcn_ds_swizzle(__float_as_int(v), (X << 10) | 0x1F)); }
; __device__ __forceinline__ float silu_f(float g) { return g * __builtin_amdgcn_rcpf(1.0f + __expf(-g)); }
; template <bool GLA>
; __device__ __forceinline__ void chunk_pass_c(const ChunkIn& ci, const float* wgl, int unit, unsigned char* wl, int lane, const float* Sb, const float* ng, bf16_t* omix) {
;     ...
;         for (int r = 0; r < 4; ++r) {
;             ss[r] += swz_xor<1>(ss[r]); ss[r] += swz_xor<2>(ss[r]); ss[r] += swz_xor<4>(ss[r]); ss[r] += swz_xor<8>(ss[r]);
;             const float rs = rsqrtf(ss[r] * (1.0f / 64.0f) + EPS);
;             const int t = t0 + 16 * it + 4 * kq + r;
; #pragma unroll
;             for (int et = 0; et < 4; ++et) {
;                 const int e = 16 * et + row;
;                 const float gt = __uint_as_float((unsigned)ci.proj[(size_t)t * DINP + gcol + e] << 16);
;                 const float val = o[et][r] * rs * gn[et] * pg8::silu_f(gt);
;                 omix[(size_t)t * 1024 + ocol + e] = (bf16_t)(cvtpk(val, 0.f) & 0xffffu);
;             }
	v_mov_b32_e32 v92, v180
	v_mov_b32_e32 v213, v211
	v_or_b32_e32 v214, s4, v97
	v_lshlrev_b32_e32 v212, 12, v214
	v_lshl_add_u64 v[212:213], s[58:59], 0, v[212:213]
	v_lshl_add_u64 v[216:217], v[212:213], 0, v[110:111]
	global_load_ushort v180, v[216:217], off offset:3488
	v_lshlrev_b32_e32 v92, 16, v92
	v_mul_f32_e32 v102, 0xbfb8aa3b, v92
	v_exp_f32_e32 v102, v102
	s_nop 0
	v_add_f32_e32 v102, 1.0, v102
	v_rcp_f32_e32 v102, v102
	s_nop 0
	v_mul_f32_e32 v92, v102, v92
	v_mul_f32_e32 v92, v98, v92
	v_cvt_pk_bf16_f32 v92, v92, s0
	global_store_short v[170:171], v92, off offset:1600
	v_mov_b32_e32 v173, v211
	s_waitcnt vmcnt(38)
	v_mov_b32_e32 v92, v181
	v_lshlrev_b32_e32 v212, 1, v177
	v_mov_b32_e32 v213, v211
	v_mov_b32_e32 v215, v211
	v_or_b32_e32 v216, s4, v97
	v_lshlrev_b32_e32 v214, 12, v216
	v_lshl_add_u64 v[214:215], s[58:59], 0, v[214:215]
	v_lshl_add_u64 v[214:215], v[214:215], 0, v[212:213]
	global_load_ushort v181, v[214:215], off offset:3424
	v_lshlrev_b32_e32 v92, 16, v92
	v_mul_f32_e32 v98, 0xbfb8aa3b, v92
	v_exp_f32_e32 v98, v98
	s_nop 0
	v_add_f32_e32 v98, 1.0, v98
	v_rcp_f32_e32 v98, v98
	s_nop 0
	v_mul_f32_e32 v92, v98, v92
	v_mul_f32_e32 v88, v88, v92
	v_cvt_pk_bf16_f32 v88, v88, s0
	global_store_short v[168:169], v88, off offset:1536
	v_or_b32_e32 v88, 1, v165
	v_lshlrev_b32_e32 v168, 12, v88
	v_mov_b32_e32 v169, v211
	v_lshl_add_u64 v[168:169], s[58:59], 0, v[168:169]
	v_lshl_add_u64 v[170:171], v[168:169], 0, v[110:111]
	v_lshlrev_b32_e32 v172, 11, v88
	v_mul_f32_e32 v88, 0x4b800000, v166
	v_cndmask_b32_e64 v88, v166, v88, s[48:49]
	v_rsq_f32_e32 v88, v88
	v_lshl_add_u64 v[166:167], s[60:61], 0, v[172:173]
	v_lshl_add_u64 v[172:173], v[166:167], 0, v[110:111]
	v_mul_f32_e32 v102, 0x45800000, v88
	v_cndmask_b32_e64 v88, v88, v102, s[48:49]
	v_mul_f32_e32 v93, v93, v88
	v_mul_f32_e32 v93, v115, v93
	v_mul_f32_e32 v99, v99, v88
	v_mul_f32_e32 v99, v160, v99
	s_waitcnt vmcnt(39)
	v_mov_b32_e32 v92, v182
	v_or_b32_e32 v212, s4, v97
	v_or_b32_e32 v214, 1, v212
	v_mov_b32_e32 v217, v211
	v_lshlrev_b32_e32 v216, 12, v214
	v_lshl_add_u64 v[216:217], s[58:59], 0, v[216:217]
	v_lshl_add_u64 v[218:219], v[216:217], 0, v[110:111]
	global_load_ushort v182, v[218:219], off offset:3424
	v_lshlrev_b32_e32 v92, 16, v92
	v_mul_f32_e32 v98, 0xbfb8aa3b, v92
	v_exp_f32_e32 v98, v98
	s_nop 0
	v_add_f32_e32 v98, 1.0, v98
	v_rcp_f32_e32 v98, v98
	s_nop 0
	v_mul_f32_e32 v92, v98, v92
	v_mul_f32_e32 v92, v92, v93
	v_cvt_pk_bf16_f32 v92, v92, s0
	global_store_short v[172:173], v92, off offset:1536
	v_mul_f32_e32 v98, v103, v88
	v_mul_f32_e32 v98, v161, v98
	v_mul_f32_e32 v88, v89, v88
	v_mul_f32_e32 v88, v159, v88
	s_waitcnt vmcnt(40)
	v_mov_b32_e32 v92, v183
	v_or_b32_e32 v212, s4, v97
	v_or_b32_e32 v214, 1, v212
	v_mov_b32_e32 v217, v211
	v_lshlrev_b32_e32 v216, 12, v214
	v_lshl_add_u64 v[216:217], s[58:59], 0, v[216:217]
	v_lshl_add_u64 v[218:219], v[216:217], 0, v[110:111]
	global_load_ushort v183, v[218:219], off offset:3456
	v_lshlrev_b32_e32 v92, 16, v92
	v_mul_f32_e32 v93, 0xbfb8aa3b, v92
	v_exp_f32_e32 v93, v93
	s_nop 0
	v_add_f32_e32 v93, 1.0, v93
	v_rcp_f32_e32 v93, v93
	s_nop 0
	v_mul_f32_e32 v92, v93, v92
	v_mul_f32_e32 v92, v98, v92
	v_cvt_pk_bf16_f32 v92, v92, s0
	global_store_short v[172:173], v92, off offset:1568
	s_waitcnt vmcnt(41)
	v_mov_b32_e32 v92, v184
	v_or_b32_e32 v212, s4, v97
	v_or_b32_e32 v214, 1, v212
	v_mov_b32_e32 v217, v211
	v_lshlrev_b32_e32 v216, 12, v214
	v_lshl_add_u64 v[216:217], s[58:59], 0, v[216:217]
	v_lshl_add_u64 v[218:219], v[216:217], 0, v[110:111]
	global_load_ushort v184, v[218:219], off offset:3488
	v_lshlrev_b32_e32 v98, 16, v92
	v_mul_f32_e32 v92, 0xbfb8aa3b, v98
	v_exp_f32_e32 v92, v92
	s_nop 0
	v_add_f32_e32 v92, 1.0, v92
	v_rcp_f32_e32 v102, v92
	v_lshl_add_u64 v[92:93], v[168:169], 0, v[112:113]
	v_mov_b32_e32 v169, v91
	v_mul_f32_e32 v98, v102, v98
	v_mul_f32_e32 v98, v99, v98
	v_cvt_pk_bf16_f32 v98, v98, s0
	global_store_short v[172:173], v98, off offset:1600
	v_lshl_add_u64 v[98:99], v[166:167], 0, v[112:113]
	v_or_b32_e32 v172, 2, v165
	v_mov_b32_e32 v93, v211
	v_mov_b32_e32 v167, v90
	s_waitcnt vmcnt(42)
	v_mov_b32_e32 v92, v185
	v_lshlrev_b32_e32 v212, 1, v177
	v_mov_b32_e32 v213, v211
	v_or_b32_e32 v214, s4, v97
	v_or_b32_e32 v216, 1, v214
	v_mov_b32_e32 v219, v211
	v_lshlrev_b32_e32 v218, 12, v216
	v_lshl_add_u64 v[218:219], s[58:59], 0, v[218:219]
	v_lshl_add_u64 v[218:219], v[218:219], 0, v[212:213]
	global_load_ushort v185, v[218:219], off offset:3424
	v_lshlrev_b32_e32 v168, 16, v92
	v_mul_f32_e32 v92, 0xbfb8aa3b, v168
	v_exp_f32_e32 v102, v92
	v_lshlrev_b32_e32 v92, 12, v172
	v_lshl_add_u64 v[92:93], s[58:59], 0, v[92:93]
	v_add_f32_e32 v102, 1.0, v102
	v_rcp_f32_e32 v166, v102
	v_lshl_add_u64 v[102:103], v[92:93], 0, v[110:111]
	v_lshl_add_u64 v[92:93], v[92:93], 0, v[112:113]
	v_mul_f32_e32 v89, v166, v168
	v_mul_f32_e32 v88, v88, v89
	v_cvt_pk_bf16_f32 v88, v88, s0
	global_store_short v[98:99], v88, off offset:1536
	v_mov_b32_e32 v88, v94
	v_mov_b32_e32 v89, v104
	v_mov_b32_e32 v98, v95
	v_mov_b32_e32 v99, v105
	v_mov_b32_e32 v166, v100
	v_mov_b32_e32 v168, v101
	v_pk_mul_f32 v[88:89], v[88:89], v[88:89]
	v_pk_mul_f32 v[98:99], v[98:99], v[98:99]
	v_pk_mul_f32 v[166:167], v[166:167], v[166:167]
	v_pk_mul_f32 v[168:169], v[168:169], v[168:169]
	v_mov_b32_e32 v170, v98
	v_mov_b32_e32 v171, v88
	v_mov_b32_e32 v88, v99
	v_mov_b32_e32 v98, v168
	v_mov_b32_e32 v99, v166
	v_pk_add_f32 v[88:89], v[170:171], v[88:89]
	v_mov_b32_e32 v166, v169
	v_pk_add_f32 v[88:89], v[88:89], v[98:99]
	s_waitcnt vmcnt(43)
; __device__ __forceinline__ unsigned cvtpk(float lo, float hi) { f32x2_t v = {lo, hi}; bf16x2_t b = __builtin_convertvector(v, bf16x2_t); return __builtin_bit_cast(unsigned, b); }
; template <int X> __device__ __forceinline__ float swz_xor(float v) { return __int_as_float(__builtin_amdgcn_ds_swizzle(__float_as_int(v), (X << 10) | 0x1F)); }
; __device__ __forceinline__ float silu_f(float g) { return g * __builtin_amdgcn_rcpf(1.0f + __expf(-g)); }
; template <bool GLA>
; __device__ __forceinline__ void chunk_pass_c(const ChunkIn& ci, const float* wgl, int unit, unsigned char* wl, int lane, const float* Sb, const float* ng, bf16_t* omix) {
;     ...
; #pragma unroll
;     for (int it = 0; it < 4; ++it) {
;         float bq[8], qv[8], kv[8];
;         chunk_tile<GLA>(raw[it], wfr, bfr, h, it, row, kq, lg, carry, bq, qv, kv);
;         float a[8], bneg[8], cpos[8], dneg[8];
; #pragma unroll
;         for (int j = 0; j < 8; ++j) { const float eb = __expf(bq[j]), enb = __expf(-bq[j]); a[j] = qv[j] * eb; bneg[j] = kv[j] * enb; cpos[j] = qv[j] * enb; dneg[j] = kv[j] * eb; }
;         qf[it] = __builtin_bit_cast(bf16x8, (u32x4){cvtpk(a[0], a[1]), cvtpk(a[2], a[3]), cvtpk(a[4], a[5]), cvtpk(a[6], a[7])});
;         kf[it] = __builtin_bit_cast(bf16x8, (u32x4){cvtpk(bneg[0], bneg[1]), cvtpk(bneg[2], bneg[3]), cvtpk(bneg[4], bneg[5]), cvtpk(bneg[6], bneg[7])});
;         qb[it] = __builtin_bit_cast(bf16x8, (u32x4){cvtpk(cpos[0], cpos[1]), cvtpk(cpos[2], cpos[3]), cvtpk(cpos[4], cpos[5]), cvtpk(cpos[6], cpos[7])});
;         kb[it] = __builtin_bit_cast(bf16x8, (u32x4){cvtpk(dneg[0], dneg[1]), cvtpk(dneg[2], dneg[3]), cvtpk(dneg[4], dneg[5]), cvtpk(dneg[6], dneg[7])});
;     ...
;         for (int r = 0; r < 4; ++r) {
;             ss[r] += swz_xor<1>(ss[r]); ss[r] += swz_xor<2>(ss[r]); ss[r] += swz_xor<4>(ss[r]); ss[r] += swz_xor<8>(ss[r]);
;             const float rs = rsqrtf(ss[r] * (1.0f / 64.0f) + EPS);
;             const int t = t0 + 16 * it + 4 * kq + r;
; #pragma unroll
;             for (int et = 0; et < 4; ++et) {
;                 const int e = 16 * et + row;
;                 const float gt = __uint_as_float((unsigned)ci.proj[(size_t)t * DINP + gcol + e] << 16);
;                 const float val = o[et][r] * rs * gn[et] * pg8::silu_f(gt);
;                 omix[(size_t)t * 1024 + ocol + e] = (bf16_t)(cvtpk(val, 0.f) & 0xffffu);
;             }
	v_mov_b32_e32 v173, v186
	v_or_b32_e32 v212, s4, v97
	v_or_b32_e32 v214, 2, v212
	v_mov_b32_e32 v217, v211
	v_lshlrev_b32_e32 v216, 12, v214
	v_lshl_add_u64 v[216:217], s[58:59], 0, v[216:217]
	v_lshl_add_u64 v[218:219], v[216:217], 0, v[110:111]
	global_load_ushort v186, v[218:219], off offset:3424
	v_lshlrev_b32_e32 v168, 16, v173
	v_pk_add_f32 v[88:89], v[88:89], v[166:167]
	ds_swizzle_b32 v99, v89 offset:swizzle(SWAP,1)
	ds_swizzle_b32 v98, v88 offset:swizzle(SWAP,1)
	v_mov_b32_e32 v167, v211
	v_lshlrev_b32_e32 v166, 11, v172
	s_waitcnt lgkmcnt(0)
	v_pk_add_f32 v[88:89], v[88:89], v[98:99]
	ds_swizzle_b32 v99, v89 offset:swizzle(SWAP,2)
	ds_swizzle_b32 v98, v88 offset:swizzle(SWAP,2)
	s_waitcnt lgkmcnt(0)
	v_pk_add_f32 v[88:89], v[88:89], v[98:99]
	ds_swizzle_b32 v99, v89 offset:swizzle(SWAP,4)
	ds_swizzle_b32 v98, v88 offset:swizzle(SWAP,4)
	s_waitcnt lgkmcnt(0)
	v_pk_add_f32 v[88:89], v[88:89], v[98:99]
	ds_swizzle_b32 v99, v89 offset:swizzle(SWAP,8)
	ds_swizzle_b32 v98, v88 offset:swizzle(SWAP,8)
	s_waitcnt lgkmcnt(0)
	v_pk_add_f32 v[88:89], v[88:89], v[98:99]
	s_nop 0
	v_pk_fma_f32 v[88:89], v[88:89], s[6:7], v[116:117] op_sel_hi:[1,0,0]
	s_nop 0
	v_mul_f32_e32 v98, 0x4b800000, v89
	v_cmp_gt_f32_e64 s[48:49], s96, v89
	s_nop 1
	v_cndmask_b32_e64 v89, v89, v98, s[48:49]
	v_mul_f32_e32 v98, 0xbfb8aa3b, v168
	v_exp_f32_e32 v169, v98
	v_rsq_f32_e32 v89, v89
	v_lshl_add_u64 v[98:99], s[60:61], 0, v[166:167]
	v_lshl_add_u64 v[166:167], v[98:99], 0, v[110:111]
	v_add_f32_e32 v169, 1.0, v169
	v_rcp_f32_e32 v169, v169
	v_mul_f32_e32 v170, 0x45800000, v89
	v_cndmask_b32_e64 v89, v89, v170, s[48:49]
	v_mul_f32_e32 v94, v94, v89
	v_mul_f32_e32 v94, v115, v94
	v_mul_f32_e32 v168, v169, v168
	v_mul_f32_e32 v94, v168, v94
	v_cvt_pk_bf16_f32 v94, v94, s0
	global_store_short v[166:167], v94, off offset:1536
	v_mul_f32_e32 v104, v104, v89
	v_mul_f32_e32 v104, v161, v104
	v_mul_f32_e32 v100, v100, v89
	v_mul_f32_e32 v100, v160, v100
	v_mul_f32_e32 v89, v90, v89
	v_mul_f32_e32 v89, v159, v89
	v_cmp_gt_f32_e64 s[48:49], s96, v88
	s_waitcnt vmcnt(44)
	v_mov_b32_e32 v94, v187
	v_or_b32_e32 v212, s4, v97
	v_or_b32_e32 v214, 2, v212
	v_mov_b32_e32 v217, v211
	v_lshlrev_b32_e32 v216, 12, v214
	v_lshl_add_u64 v[216:217], s[58:59], 0, v[216:217]
	v_lshl_add_u64 v[218:219], v[216:217], 0, v[110:111]
	global_load_ushort v187, v[218:219], off offset:3456
	v_lshlrev_b32_e32 v94, 16, v94
	v_mul_f32_e32 v168, 0xbfb8aa3b, v94
	v_exp_f32_e32 v168, v168
	s_nop 0
	v_add_f32_e32 v168, 1.0, v168
	v_rcp_f32_e32 v168, v168
	s_nop 0
	v_mul_f32_e32 v94, v168, v94
	v_mul_f32_e32 v94, v104, v94
	v_cvt_pk_bf16_f32 v94, v94, s0
	global_store_short v[166:167], v94, off offset:1568
	v_and_b32_e32 v103, 0xffff0000, v142
	s_waitcnt vmcnt(45)
	v_mov_b32_e32 v94, v188
	v_or_b32_e32 v212, s4, v97
	v_or_b32_e32 v214, 2, v212
	v_mov_b32_e32 v217, v211
	v_lshlrev_b32_e32 v216, 12, v214
	v_lshl_add_u64 v[216:217], s[58:59], 0, v[216:217]
	v_lshl_add_u64 v[218:219], v[216:217], 0, v[110:111]
	global_load_ushort v188, v[218:219], off offset:3488
	v_lshlrev_b32_e32 v94, 16, v94
	v_mul_f32_e32 v102, 0xbfb8aa3b, v94
	v_exp_f32_e32 v102, v102
	s_nop 0
	v_add_f32_e32 v102, 1.0, v102
	v_rcp_f32_e32 v102, v102
	s_nop 0
	v_mul_f32_e32 v94, v102, v94
	v_mul_f32_e32 v94, v100, v94
	v_cvt_pk_bf16_f32 v94, v94, s0
	global_store_short v[166:167], v94, off offset:1600
	v_or_b32_e32 v94, 3, v165
	v_mov_b32_e32 v93, v211
	s_waitcnt vmcnt(46)
	v_mov_b32_e32 v92, v189
	v_lshlrev_b32_e32 v212, 1, v177
	v_mov_b32_e32 v213, v211
	v_or_b32_e32 v214, s4, v97
	v_or_b32_e32 v216, 2, v214
	v_mov_b32_e32 v219, v211
	v_lshlrev_b32_e32 v218, 12, v216
	v_lshl_add_u64 v[218:219], s[58:59], 0, v[218:219]
	v_lshl_add_u64 v[218:219], v[218:219], 0, v[212:213]
	global_load_ushort v189, v[218:219], off offset:3424
	v_lshlrev_b32_e32 v100, 16, v92
	v_mul_f32_e32 v92, 0xbfb8aa3b, v100
	v_exp_f32_e32 v102, v92
	v_lshlrev_b32_e32 v92, 12, v94
	v_lshl_add_u64 v[168:169], s[58:59], 0, v[92:93]
	v_lshl_add_u64 v[92:93], v[98:99], 0, v[112:113]
	v_add_f32_e32 v98, 1.0, v102
	v_rcp_f32_e32 v102, v98
	v_lshl_add_u64 v[98:99], v[168:169], 0, v[110:111]
	v_mul_f32_e32 v90, v102, v100
	v_mul_f32_e32 v89, v89, v90
	v_cvt_pk_bf16_f32 v89, v89, s0
	global_store_short v[92:93], v89, off offset:1536
	v_mul_f32_e32 v90, 0xbfb8aa3b, v164
	v_mov_b32_e32 v93, v211
	v_lshlrev_b32_e32 v92, 11, v94
	v_exp_f32_e32 v90, v90
	v_lshl_add_u64 v[170:171], s[60:61], 0, v[92:93]
	v_lshlrev_b32_e32 v92, 16, v144
	v_and_b32_e32 v93, 0xffff0000, v144
	v_lshlrev_b32_e32 v102, 16, v142
	v_lshlrev_b32_e32 v144, 16, v145
	v_and_b32_e32 v145, 0xffff0000, v145
	v_lshlrev_b32_e32 v142, 16, v143
	v_and_b32_e32 v143, 0xffff0000, v143
	v_pk_mul_f32 v[164:165], v[80:81], v[92:93]
	v_pk_mul_f32 v[80:81], v[80:81], v[102:103]
	v_pk_mul_f32 v[166:167], v[82:83], v[144:145]
	v_pk_mul_f32 v[82:83], v[82:83], v[142:143]
	v_pk_fma_f32 v[102:103], v[76:77], v[102:103], v[164:165]
	v_pk_fma_f32 v[76:77], v[76:77], v[92:93], v[80:81] neg_lo:[0,0,1] neg_hi:[0,0,1]
	v_pk_fma_f32 v[80:81], v[78:79], v[142:143], v[166:167]
	v_pk_fma_f32 v[78:79], v[78:79], v[144:145], v[82:83] neg_lo:[0,0,1] neg_hi:[0,0,1]
	v_pk_mul_f32 v[82:83], v[102:103], s[8:9] op_sel_hi:[1,0]
	v_pk_mul_f32 v[76:77], v[76:77], s[8:9] op_sel_hi:[1,0]
	v_pk_mul_f32 v[92:93], v[90:91], v[150:151] op_sel_hi:[0,1]
	v_pk_mul_f32 v[102:103], v[90:91], v[148:149] op_sel_hi:[0,1]
	v_pk_mul_f32 v[148:149], v[80:81], s[8:9] op_sel_hi:[1,0]
	v_pk_mul_f32 v[150:151], v[78:79], s[8:9] op_sel_hi:[1,0]
	v_pk_mul_f32 v[78:79], v[90:91], v[154:155] op_sel_hi:[0,1]
	v_pk_mul_f32 v[80:81], v[90:91], v[152:153] op_sel_hi:[0,1]
	v_pk_mul_f32 v[142:143], v[146:147], v[76:77] op_sel_hi:[0,1]
	v_pk_mul_f32 v[152:153], v[90:91], v[76:77] op_sel_hi:[0,1]
	v_pk_mul_f32 v[164:165], v[90:91], v[82:83] op_sel_hi:[0,1]
	v_cvt_pk_bf16_f32 v76, v92, v93
	v_cvt_pk_bf16_f32 v77, v78, v79
	v_cvt_pk_bf16_f32 v78, v102, v103
	v_pk_mul_f32 v[92:93], v[90:91], v[150:151] op_sel_hi:[0,1]
	v_pk_mul_f32 v[102:103], v[90:91], v[148:149] op_sel_hi:[0,1]
	v_mul_f32_e32 v90, 0x4b800000, v88
	v_pk_mul_f32 v[154:155], v[146:147], v[148:149] op_sel_hi:[0,1]
	v_cvt_pk_bf16_f32 v149, v92, v93
	v_cndmask_b32_e64 v88, v88, v90, s[48:49]
	v_rsq_f32_e32 v90, v88
	v_cvt_pk_bf16_f32 v79, v80, v81
	v_pk_mul_f32 v[144:145], v[146:147], v[82:83] op_sel_hi:[0,1]
	v_pk_mul_f32 v[82:83], v[146:147], v[150:151] op_sel_hi:[0,1]
	v_mul_f32_e32 v94, 0x45800000, v90
	v_cndmask_b32_e64 v90, v90, v94, s[48:49]
	v_mul_f32_e32 v94, v95, v90
	v_mul_f32_e32 v94, v115, v94
	v_cvt_pk_bf16_f32 v80, v142, v143
	v_cvt_pk_bf16_f32 v81, v82, v83
	v_cvt_pk_bf16_f32 v82, v144, v145
	v_cvt_pk_bf16_f32 v83, v154, v155
	v_cvt_pk_bf16_f32 v148, v152, v153
	v_cvt_pk_bf16_f32 v150, v164, v165
	v_cvt_pk_bf16_f32 v151, v102, v103
	v_mfma_f32_16x16x32_bf16 v[152:155], v[76:79], v[80:83], 0
	v_mul_f32_e32 v101, v101, v90
	v_mul_f32_e32 v101, v160, v101
	s_waitcnt vmcnt(47)
; template <bool GLA>
; __device__ __forceinline__ void chunk_pass_c(const ChunkIn& ci, const float* wgl, int unit, unsigned char* wl, int lane, const float* Sb, const float* ng, bf16_t* omix) {
;     ...
;     for (int it = 0; it < 4; ++it) {
;         f32x4 st[4];
; #pragma unroll
;         for (int jt = 0; jt < 4; ++jt) {
;             const f32x4 z = {0.f, 0.f, 0.f, 0.f};
;             if (jt < it) st[jt] = __builtin_amdgcn_mfma_f32_16x16x32_bf16(kf[jt], qf[it], z, 0, 0, 0);
;             else if (jt > it) st[jt] = __builtin_amdgcn_mfma_f32_16x16x32_bf16(kb[jt], qb[it], z, 0, 0, 0);
;             else {
;                 const f32x4 lo = __builtin_amdgcn_mfma_f32_16x16x32_bf16(kf[jt], qf[it], z, 0, 0, 0), up = __builtin_amdgcn_mfma_f32_16x16x32_bf16(kb[jt], qb[it], z, 0, 0, 0);
; #pragma unroll
;                 for (int r = 0; r < 4; ++r) st[jt][r] = (4 * kq + r <= row) ? lo[r] : up[r];
;             }
;         }
;         bf16x8 af[2];
; #pragma unroll
;         for (int p = 0; p < 2; ++p)
;             af[p] = __builtin_bit_cast(bf16x8, (u32x4){cvtpk(st[2 * p][0], st[2 * p][1]), cvtpk(st[2 * p][2], st[2 * p][3]), cvtpk(st[2 * p + 1][0], st[2 * p + 1][1]), cvtpk(st[2 * p + 1][2], st[2 * p + 1][3])});
;         f32x4 o[4]; float ss[4] = {0.f, 0.f, 0.f, 0.f};
; #pragma unroll
;         for (int et = 0; et < 4; ++et) {
;             f32x4 acc = {0.f, 0.f, 0.f, 0.f};
;             acc = __builtin_amdgcn_mfma_f32_16x16x32_bf16(af[0], vfr[et][0], acc, 0, 0, 0);
;             acc = __builtin_amdgcn_mfma_f32_16x16x32_bf16(af[1], vfr[et][1], acc, 0, 0, 0);
;             acc = __builtin_amdgcn_mfma_f32_16x16x32_bf16(qf[it], sfr[et], acc, 0, 0, 0);
;             o[et] = acc;
; #pragma unroll
;             for (int r = 0; r < 4; ++r) ss[r] += acc[r] * acc[r];
;         }
; #pragma unroll
;         for (int r = 0; r < 4; ++r) {
;             ss[r] += swz_xor<1>(ss[r]); ss[r] += swz_xor<2>(ss[r]); ss[r] += swz_xor<4>(ss[r]); ss[r] += swz_xor<8>(ss[r]);
;             const float rs = rsqrtf(ss[r] * (1.0f / 64.0f) + EPS);
;             const int t = t0 + 16 * it + 4 * kq + r;
; #pragma unroll
;             for (int et = 0; et < 4; ++et) {
;                 const int e = 16 * et + row;
;                 const float gt = __uint_as_float((unsigned)ci.proj[(size_t)t * DINP + gcol + e] << 16);
;                 const float val = o[et][r] * rs * gn[et] * pg8::silu_f(gt);
	v_mov_b32_e32 v89, v190
	v_or_b32_e32 v212, s4, v97
	v_or_b32_e32 v214, 3, v212
	v_mov_b32_e32 v217, v211
	v_lshlrev_b32_e32 v216, 12, v214
	v_lshl_add_u64 v[216:217], s[58:59], 0, v[216:217]
	v_lshl_add_u64 v[218:219], v[216:217], 0, v[110:111]
	global_load_ushort v190, v[218:219], off offset:3424
	v_lshlrev_b32_e32 v92, 16, v89
	v_mul_f32_e32 v88, 0xbfb8aa3b, v92
	v_exp_f32_e32 v93, v88
	v_lshl_add_u64 v[88:89], v[170:171], 0, v[110:111]
	v_mfma_f32_16x16x32_bf16 v[84:87], v[84:87], v[148:151], 0
	v_add_f32_e32 v93, 1.0, v93
	v_rcp_f32_e32 v93, v93
	v_mfma_f32_16x16x32_bf16 v[142:145], v[8:11], v[80:83], 0
	v_mul_f32_e32 v92, v93, v92
	v_mul_f32_e32 v92, v92, v94
	v_cvt_pk_bf16_f32 v92, v92, s0
	global_store_short v[88:89], v92, off offset:1536
	v_cndmask_b32_e32 v102, v152, v84, vcc
	v_cndmask_b32_e64 v103, v85, v153, s[42:43]
	v_cndmask_b32_e64 v104, v154, v86, s[44:45]
	v_cvt_pk_bf16_f32 v86, v102, v103
	v_mul_f32_e32 v103, v105, v90
	v_mul_f32_e32 v103, v161, v103
	v_cndmask_b32_e64 v87, v155, v87, s[46:47]
	v_mfma_f32_16x16x32_bf16 v[164:167], v[72:75], v[148:151], 0
	v_cvt_pk_bf16_f32 v84, v142, v143
	v_cvt_pk_bf16_f32 v85, v144, v145
	v_cvt_pk_bf16_f32 v87, v104, v87
	v_mfma_f32_16x16x32_bf16 v[92:95], v[12:15], v[148:151], 0
	v_mul_f32_e32 v90, v91, v90
	s_nop 2
	v_cvt_pk_bf16_f32 v152, v164, v165
	v_cvt_pk_bf16_f32 v153, v166, v167
	v_mfma_f32_16x16x32_bf16 v[142:145], v[84:87], v[28:31], 0
	v_mul_f32_e32 v90, v159, v90
	v_cvt_pk_bf16_f32 v154, v92, v93
	v_cvt_pk_bf16_f32 v155, v94, v95
	v_mfma_f32_16x16x32_bf16 v[148:151], v[84:87], v[44:47], 0
	s_waitcnt vmcnt(48)
	v_mov_b32_e32 v100, v191
	v_or_b32_e32 v212, s4, v97
	v_or_b32_e32 v214, 3, v212
	v_mov_b32_e32 v217, v211
	v_lshlrev_b32_e32 v216, 12, v214
	v_lshl_add_u64 v[216:217], s[58:59], 0, v[216:217]
	v_lshl_add_u64 v[218:219], v[216:217], 0, v[110:111]
	global_load_ushort v191, v[218:219], off offset:3456
	v_lshlrev_b32_e32 v100, 16, v100
	v_mul_f32_e32 v102, 0xbfb8aa3b, v100
	v_exp_f32_e32 v102, v102
	v_mfma_f32_16x16x32_bf16 v[92:95], v[152:155], v[20:23], v[142:145]
	v_add_f32_e32 v102, 1.0, v102
	v_rcp_f32_e32 v102, v102
	v_mfma_f32_16x16x32_bf16 v[142:145], v[152:155], v[32:35], v[148:151]
	v_mul_f32_e32 v100, v102, v100
	v_mul_f32_e32 v100, v103, v100
	v_cvt_pk_bf16_f32 v100, v100, s0
	global_store_short v[88:89], v100, off offset:1568
	v_mfma_f32_16x16x32_bf16 v[102:105], v[84:87], v[56:59], 0
	s_waitcnt vmcnt(49)
	v_mov_b32_e32 v98, v192
	v_or_b32_e32 v212, s4, v97
	v_or_b32_e32 v214, 3, v212
	v_mov_b32_e32 v217, v211
	v_lshlrev_b32_e32 v216, 12, v214
	v_lshl_add_u64 v[216:217], s[58:59], 0, v[216:217]
	v_lshl_add_u64 v[218:219], v[216:217], 0, v[110:111]
	global_load_ushort v192, v[218:219], off offset:3488
	v_lshlrev_b32_e32 v100, 16, v98
	v_mul_f32_e32 v98, 0xbfb8aa3b, v100
	v_exp_f32_e32 v146, v98
	v_lshl_add_u64 v[98:99], v[168:169], 0, v[112:113]
	v_mfma_f32_16x16x32_bf16 v[84:87], v[84:87], v[60:63], 0
	v_add_f32_e32 v146, 1.0, v146
	v_rcp_f32_e32 v146, v146
	v_mfma_f32_16x16x32_bf16 v[148:151], v[152:155], v[48:51], v[84:87]
	v_mul_f32_e32 v100, v146, v100
	v_mul_f32_e32 v100, v101, v100
	v_cvt_pk_bf16_f32 v100, v100, s0
	global_store_short v[88:89], v100, off offset:1600
	v_mfma_f32_16x16x32_bf16 v[98:101], v[80:83], v[24:27], v[92:95]
	v_mov_b32_e32 v89, v211
	s_waitcnt vmcnt(50)
	v_mov_b32_e32 v146, v193
	v_lshlrev_b32_e32 v212, 1, v177
	v_mov_b32_e32 v213, v211
	v_or_b32_e32 v214, s4, v97
	v_or_b32_e32 v216, 3, v214
	v_mov_b32_e32 v219, v211
	v_lshlrev_b32_e32 v218, 12, v216
	v_lshl_add_u64 v[218:219], s[58:59], 0, v[218:219]
	v_lshl_add_u64 v[220:221], v[218:219], 0, v[212:213]
	global_load_ushort v193, v[220:221], off offset:3424
	v_lshlrev_b32_e32 v146, 16, v146
	v_mul_f32_e32 v84, 0xbfb8aa3b, v146
	v_exp_f32_e32 v84, v84
	v_mfma_f32_16x16x32_bf16 v[92:95], v[80:83], v[16:19], v[142:145]
	v_add_f32_e32 v84, 1.0, v84
	s_nop 1
	v_rcp_f32_e32 v144, v84
	v_mfma_f32_16x16x32_bf16 v[102:105], v[152:155], v[52:55], v[102:105]
	v_or_b32_e32 v154, s5, v97
	v_lshlrev_b32_e32 v88, 12, v154
	v_mul_f32_e32 v91, v144, v146
	v_mul_f32_e32 v90, v90, v91
	v_lshl_add_u64 v[88:89], s[58:59], 0, v[88:89]
	v_lshl_add_u64 v[152:153], v[170:171], 0, v[112:113]
	v_cvt_pk_bf16_f32 v90, v90, s0
	v_lshl_add_u64 v[142:143], v[88:89], 0, v[110:111]
	global_store_short v[152:153], v90, off offset:1536
	v_mfma_f32_16x16x32_bf16 v[84:87], v[80:83], v[36:39], v[102:105]
	v_mov_b32_e32 v90, v98
	v_mov_b32_e32 v91, v92
	v_pk_mul_f32 v[90:91], v[90:91], v[90:91]
	v_mfma_f32_16x16x32_bf16 v[80:83], v[80:83], v[40:43], v[148:151]
	v_mov_b32_e32 v102, v99
	v_mov_b32_e32 v103, v93
	s_nop 1
	v_mov_b32_e32 v104, v84
	v_mov_b32_e32 v144, v85
	v_pk_mul_f32 v[102:103], v[102:103], v[102:103]
	s_nop 0
	v_mov_b32_e32 v105, v80
	v_mov_b32_e32 v145, v81
	v_pk_mul_f32 v[104:105], v[104:105], v[104:105]
	v_pk_mul_f32 v[144:145], v[144:145], v[144:145]
	v_mov_b32_e32 v148, v102
	v_mov_b32_e32 v149, v90
	v_mov_b32_e32 v90, v103
	v_mov_b32_e32 v102, v144
	v_mov_b32_e32 v103, v104
	v_pk_add_f32 v[90:91], v[148:149], v[90:91]
	v_mov_b32_e32 v104, v145
	v_pk_add_f32 v[90:91], v[90:91], v[102:103]
	v_lshl_add_u64 v[88:89], v[88:89], 0, v[112:113]
	v_pk_add_f32 v[90:91], v[90:91], v[104:105]
	ds_swizzle_b32 v103, v91 offset:swizzle(SWAP,1)
	ds_swizzle_b32 v102, v90 offset:swizzle(SWAP,1)
	v_mov_b32_e32 v105, v211
	v_lshlrev_b32_e32 v104, 11, v154
	s_waitcnt lgkmcnt(0)
	v_pk_add_f32 v[90:91], v[90:91], v[102:103]
	ds_swizzle_b32 v103, v91 offset:swizzle(SWAP,2)
	ds_swizzle_b32 v102, v90 offset:swizzle(SWAP,2)
	s_waitcnt lgkmcnt(0)
; __device__ __forceinline__ unsigned cvtpk(float lo, float hi) { f32x2_t v = {lo, hi}; bf16x2_t b = __builtin_convertvector(v, bf16x2_t); return __builtin_bit_cast(unsigned, b); }
; template <int X> __device__ __forceinline__ float swz_xor(float v) { return __int_as_float(__builtin_amdgcn_ds_swizzle(__float_as_int(v), (X << 10) | 0x1F)); }
; __device__ __forceinline__ float silu_f(float g) { return g * __builtin_amdgcn_rcpf(1.0f + __expf(-g)); }
; template <bool GLA>
; __device__ __forceinline__ void chunk_pass_c(const ChunkIn& ci, const float* wgl, int unit, unsigned char* wl, int lane, const float* Sb, const float* ng, bf16_t* omix) {
;     ...
; #pragma unroll
;         for (int r = 0; r < 4; ++r) {
;             ss[r] += swz_xor<1>(ss[r]); ss[r] += swz_xor<2>(ss[r]); ss[r] += swz_xor<4>(ss[r]); ss[r] += swz_xor<8>(ss[r]);
;             const float rs = rsqrtf(ss[r] * (1.0f / 64.0f) + EPS);
;             const int t = t0 + 16 * it + 4 * kq + r;
; #pragma unroll
;             for (int et = 0; et < 4; ++et) {
;                 const int e = 16 * et + row;
;                 const float gt = __uint_as_float((unsigned)ci.proj[(size_t)t * DINP + gcol + e] << 16);
;                 const float val = o[et][r] * rs * gn[et] * pg8::silu_f(gt);
;                 omix[(size_t)t * 1024 + ocol + e] = (bf16_t)(cvtpk(val, 0.f) & 0xffffu);
;             }
;         }
	v_pk_add_f32 v[90:91], v[90:91], v[102:103]
	ds_swizzle_b32 v103, v91 offset:swizzle(SWAP,4)
	ds_swizzle_b32 v102, v90 offset:swizzle(SWAP,4)
	s_waitcnt lgkmcnt(0)
	v_pk_add_f32 v[90:91], v[90:91], v[102:103]
	ds_swizzle_b32 v103, v91 offset:swizzle(SWAP,8)
	ds_swizzle_b32 v102, v90 offset:swizzle(SWAP,8)
	s_waitcnt lgkmcnt(0)
	v_pk_add_f32 v[90:91], v[90:91], v[102:103]
	s_nop 0
	v_pk_fma_f32 v[90:91], v[90:91], s[6:7], v[116:117] op_sel_hi:[1,0,0]
	s_waitcnt vmcnt(51)
	v_mov_b32_e32 v146, v194
	v_mov_b32_e32 v213, v211
	v_or_b32_e32 v212, s3, v97
	v_lshlrev_b64 v[214:215], 12, v[212:213]
	v_lshl_add_u64 v[216:217], s[58:59], 0, v[214:215]
	v_lshl_add_u64 v[218:219], v[216:217], 0, v[110:111]
	global_load_ushort v194, v[218:219], off offset:3424
	v_lshlrev_b32_e32 v144, 16, v146
	v_mul_f32_e32 v102, 0x4b800000, v91
	v_cmp_gt_f32_e64 s[48:49], s96, v91
	s_nop 1
	v_cndmask_b32_e64 v91, v91, v102, s[48:49]
	v_mul_f32_e32 v102, 0xbfb8aa3b, v144
	v_exp_f32_e32 v145, v102
	v_rsq_f32_e32 v91, v91
	v_lshl_add_u64 v[102:103], s[60:61], 0, v[104:105]
	v_lshl_add_u64 v[104:105], v[102:103], 0, v[110:111]
	v_add_f32_e32 v145, 1.0, v145
	v_rcp_f32_e32 v145, v145
	v_mul_f32_e32 v146, 0x45800000, v91
	v_cndmask_b32_e64 v91, v91, v146, s[48:49]
	v_mul_f32_e32 v98, v98, v91
	v_mul_f32_e32 v98, v115, v98
	v_mul_f32_e32 v144, v145, v144
	v_mul_f32_e32 v98, v144, v98
	v_cvt_pk_bf16_f32 v98, v98, s0
	global_store_short v[104:105], v98, off offset:1536
	v_mul_f32_e32 v92, v92, v91
	v_mul_f32_e32 v92, v161, v92
	v_mul_f32_e32 v84, v84, v91
	v_mul_f32_e32 v84, v160, v84
	v_mul_f32_e32 v80, v80, v91
	v_mul_f32_e32 v80, v159, v80
	v_lshl_add_u64 v[102:103], v[102:103], 0, v[112:113]
	v_cmp_gt_f32_e64 s[48:49], s96, v90
	s_waitcnt vmcnt(52)
	v_mov_b32_e32 v98, v195
	v_mov_b32_e32 v213, v211
	v_or_b32_e32 v212, s3, v97
	v_lshlrev_b64 v[214:215], 12, v[212:213]
	v_lshl_add_u64 v[216:217], s[58:59], 0, v[214:215]
	v_lshl_add_u64 v[218:219], v[216:217], 0, v[110:111]
	global_load_ushort v195, v[218:219], off offset:3456
	v_lshlrev_b32_e32 v98, 16, v98
	v_mul_f32_e32 v144, 0xbfb8aa3b, v98
	v_exp_f32_e32 v144, v144
	s_nop 0
	v_add_f32_e32 v144, 1.0, v144
	v_rcp_f32_e32 v144, v144
	s_nop 0
	v_mul_f32_e32 v98, v144, v98
	v_mul_f32_e32 v92, v98, v92
	v_cvt_pk_bf16_f32 v92, v92, s0
	global_store_short v[104:105], v92, off offset:1568
	s_waitcnt vmcnt(53)
	v_mov_b32_e32 v92, v196
	v_mov_b32_e32 v213, v211
	v_or_b32_e32 v212, s3, v97
	v_lshlrev_b64 v[214:215], 12, v[212:213]
	v_lshl_add_u64 v[216:217], s[58:59], 0, v[214:215]
	v_lshl_add_u64 v[218:219], v[216:217], 0, v[110:111]
	global_load_ushort v196, v[218:219], off offset:3488
	v_lshlrev_b32_e32 v92, 16, v92
	v_mul_f32_e32 v98, 0xbfb8aa3b, v92
	v_exp_f32_e32 v98, v98
	s_nop 0
	v_add_f32_e32 v98, 1.0, v98
	v_rcp_f32_e32 v98, v98
	s_nop 0
	v_mul_f32_e32 v92, v98, v92
	v_mul_f32_e32 v84, v84, v92
	v_cvt_pk_bf16_f32 v84, v84, s0
	global_store_short v[104:105], v84, off offset:1600
	v_or_b32_e32 v92, 1, v154
	v_mov_b32_e32 v89, v211
	s_waitcnt vmcnt(54)
	v_mov_b32_e32 v84, v197
	v_lshlrev_b32_e32 v212, 1, v177
	v_mov_b32_e32 v213, v211
	v_mov_b32_e32 v215, v211
	v_or_b32_e32 v214, s3, v97
	v_lshlrev_b64 v[216:217], 12, v[214:215]
	v_lshl_add_u64 v[218:219], s[58:59], 0, v[216:217]
	v_lshl_add_u64 v[218:219], v[218:219], 0, v[212:213]
	global_load_ushort v197, v[218:219], off offset:3424
	v_lshlrev_b32_e32 v84, 16, v84
	v_mul_f32_e32 v88, 0xbfb8aa3b, v84
	v_exp_f32_e32 v98, v88
	v_lshlrev_b32_e32 v88, 12, v92
	v_lshl_add_u64 v[88:89], s[58:59], 0, v[88:89]
	v_lshl_add_u64 v[104:105], v[88:89], 0, v[110:111]
	v_add_f32_e32 v98, 1.0, v98
	v_rcp_f32_e32 v98, v98
	v_lshl_add_u64 v[88:89], v[88:89], 0, v[112:113]
	v_mul_f32_e32 v84, v98, v84
	v_mul_f32_e32 v80, v80, v84
	v_cvt_pk_bf16_f32 v80, v80, s0
	global_store_short v[102:103], v80, off offset:1536
	v_mul_f32_e32 v84, 0x4b800000, v90
	v_cndmask_b32_e64 v84, v90, v84, s[48:49]
	v_lshlrev_b32_e32 v102, 11, v92
	v_rsq_f32_e32 v84, v84
	v_mov_b32_e32 v103, v211
	v_mul_f32_e32 v98, 0x45800000, v84
	v_cndmask_b32_e64 v98, v84, v98, s[48:49]
	v_mul_f32_e32 v84, v99, v98
	v_mul_f32_e32 v84, v115, v84
	v_mul_f32_e32 v85, v85, v98
	v_mul_f32_e32 v85, v160, v85
	v_mul_f32_e32 v81, v81, v98
	v_mul_f32_e32 v81, v159, v81
	v_mov_b32_e32 v99, v83
	s_waitcnt vmcnt(55)
	v_mov_b32_e32 v80, v198
	v_or_b32_e32 v212, s3, v97
	v_mov_b32_e32 v215, v211
	v_or_b32_e32 v214, 1, v212
	v_lshlrev_b64 v[216:217], 12, v[214:215]
	v_lshl_add_u64 v[216:217], s[58:59], 0, v[216:217]
	v_lshl_add_u64 v[218:219], v[216:217], 0, v[110:111]
	global_load_ushort v198, v[218:219], off offset:3424
	v_lshlrev_b32_e32 v80, 16, v80
	v_mul_f32_e32 v90, 0xbfb8aa3b, v80
	v_exp_f32_e32 v92, v90
	v_lshl_add_u64 v[90:91], s[60:61], 0, v[102:103]
	v_lshl_add_u64 v[102:103], v[90:91], 0, v[110:111]
	v_add_f32_e32 v92, 1.0, v92
	v_rcp_f32_e32 v92, v92
	s_nop 0
	v_mul_f32_e32 v80, v92, v80
	v_mul_f32_e32 v80, v80, v84
	v_cvt_pk_bf16_f32 v80, v80, s0
	global_store_short v[102:103], v80, off offset:1536
	v_mul_f32_e32 v92, v93, v98
	v_mul_f32_e32 v92, v161, v92
	v_mov_b32_e32 v93, v82
	v_mov_b32_e32 v98, v87
	v_pk_mul_f32 v[98:99], v[98:99], v[98:99]
	s_waitcnt vmcnt(56)
	v_mov_b32_e32 v80, v199
	v_or_b32_e32 v212, s3, v97
	v_mov_b32_e32 v215, v211
	v_or_b32_e32 v214, 1, v212
	v_lshlrev_b64 v[216:217], 12, v[214:215]
	v_lshl_add_u64 v[216:217], s[58:59], 0, v[216:217]
	v_lshl_add_u64 v[218:219], v[216:217], 0, v[110:111]
	global_load_ushort v199, v[218:219], off offset:3456
	v_lshlrev_b32_e32 v80, 16, v80
	v_mul_f32_e32 v84, 0xbfb8aa3b, v80
	v_exp_f32_e32 v84, v84
	s_nop 0
	v_add_f32_e32 v84, 1.0, v84
	v_rcp_f32_e32 v84, v84
	s_nop 0
	v_mul_f32_e32 v80, v84, v80
	v_mul_f32_e32 v80, v92, v80
	v_cvt_pk_bf16_f32 v80, v80, s0
	global_store_short v[102:103], v80, off offset:1568
	v_or_b32_e32 v104, 2, v154
	s_waitcnt vmcnt(57)
; __device__ __forceinline__ unsigned cvtpk(float lo, float hi) { f32x2_t v = {lo, hi}; bf16x2_t b = __builtin_convertvector(v, bf16x2_t); return __builtin_bit_cast(unsigned, b); }
; template <int X> __device__ __forceinline__ float swz_xor(float v) { return __int_as_float(__builtin_amdgcn_ds_swizzle(__float_as_int(v), (X << 10) | 0x1F)); }
; __device__ __forceinline__ float silu_f(float g) { return g * __builtin_amdgcn_rcpf(1.0f + __expf(-g)); }
; template <bool GLA>
; __device__ __forceinline__ void chunk_pass_c(const ChunkIn& ci, const float* wgl, int unit, unsigned char* wl, int lane, const float* Sb, const float* ng, bf16_t* omix) {
;     ...
; #pragma unroll
;         for (int r = 0; r < 4; ++r) {
;             ss[r] += swz_xor<1>(ss[r]); ss[r] += swz_xor<2>(ss[r]); ss[r] += swz_xor<4>(ss[r]); ss[r] += swz_xor<8>(ss[r]);
;             const float rs = rsqrtf(ss[r] * (1.0f / 64.0f) + EPS);
;             const int t = t0 + 16 * it + 4 * kq + r;
; #pragma unroll
;             for (int et = 0; et < 4; ++et) {
;                 const int e = 16 * et + row;
;                 const float gt = __uint_as_float((unsigned)ci.proj[(size_t)t * DINP + gcol + e] << 16);
;                 const float val = o[et][r] * rs * gn[et] * pg8::silu_f(gt);
;                 omix[(size_t)t * 1024 + ocol + e] = (bf16_t)(cvtpk(val, 0.f) & 0xffffu);
;             }
;         }
	v_mov_b32_e32 v80, v200
	v_or_b32_e32 v212, s3, v97
	v_mov_b32_e32 v215, v211
	v_or_b32_e32 v214, 1, v212
	v_lshlrev_b64 v[216:217], 12, v[214:215]
	v_lshl_add_u64 v[216:217], s[58:59], 0, v[216:217]
	v_lshl_add_u64 v[218:219], v[216:217], 0, v[110:111]
	global_load_ushort v200, v[218:219], off offset:3488
	v_lshlrev_b32_e32 v80, 16, v80
	v_mul_f32_e32 v84, 0xbfb8aa3b, v80
	v_exp_f32_e32 v84, v84
	s_nop 0
	v_add_f32_e32 v84, 1.0, v84
	v_rcp_f32_e32 v84, v84
	s_nop 0
	v_mul_f32_e32 v80, v84, v80
	v_mul_f32_e32 v80, v85, v80
	v_cvt_pk_bf16_f32 v80, v80, s0
	global_store_short v[102:103], v80, off offset:1600
	v_lshl_add_u64 v[88:89], v[90:91], 0, v[112:113]
	v_mov_b32_e32 v85, v211
	s_waitcnt vmcnt(58)
	v_mov_b32_e32 v80, v201
	v_lshlrev_b32_e32 v212, 1, v177
	v_mov_b32_e32 v213, v211
	v_or_b32_e32 v214, s3, v97
	v_mov_b32_e32 v217, v211
	v_or_b32_e32 v216, 1, v214
	v_lshlrev_b64 v[218:219], 12, v[216:217]
	v_lshl_add_u64 v[218:219], s[58:59], 0, v[218:219]
	v_lshl_add_u64 v[220:221], v[218:219], 0, v[212:213]
	global_load_ushort v201, v[220:221], off offset:3424
	v_lshlrev_b32_e32 v80, 16, v80
	v_mul_f32_e32 v84, 0xbfb8aa3b, v80
	v_exp_f32_e32 v92, v84
	v_lshlrev_b32_e32 v84, 12, v104
	v_lshl_add_u64 v[84:85], s[58:59], 0, v[84:85]
	v_add_f32_e32 v90, 1.0, v92
	v_rcp_f32_e32 v92, v90
	v_lshl_add_u64 v[90:91], v[84:85], 0, v[110:111]
	v_lshl_add_u64 v[84:85], v[84:85], 0, v[112:113]
	v_mul_f32_e32 v80, v92, v80
	v_mul_f32_e32 v80, v81, v80
	v_cvt_pk_bf16_f32 v80, v80, s0
	global_store_short v[88:89], v80, off offset:1536
	v_mov_b32_e32 v80, v100
	v_mov_b32_e32 v81, v94
	v_mov_b32_e32 v88, v101
	v_mov_b32_e32 v89, v95
	v_mov_b32_e32 v92, v86
	v_pk_mul_f32 v[80:81], v[80:81], v[80:81]
	v_pk_mul_f32 v[88:89], v[88:89], v[88:89]
	v_pk_mul_f32 v[92:93], v[92:93], v[92:93]
	v_mov_b32_e32 v102, v88
	v_mov_b32_e32 v103, v80
	v_mov_b32_e32 v80, v89
	v_mov_b32_e32 v88, v98
	v_mov_b32_e32 v89, v92
	v_pk_add_f32 v[80:81], v[102:103], v[80:81]
	v_mov_b32_e32 v92, v99
	v_pk_add_f32 v[80:81], v[80:81], v[88:89]
	v_and_b32_e32 v103, 0xffff0000, v129
	v_pk_add_f32 v[80:81], v[80:81], v[92:93]
	ds_swizzle_b32 v89, v81 offset:swizzle(SWAP,1)
	ds_swizzle_b32 v88, v80 offset:swizzle(SWAP,1)
	v_mov_b32_e32 v93, v211
	v_lshlrev_b32_e32 v92, 11, v104
	s_waitcnt lgkmcnt(0)
	v_pk_add_f32 v[80:81], v[80:81], v[88:89]
	ds_swizzle_b32 v89, v81 offset:swizzle(SWAP,2)
	ds_swizzle_b32 v88, v80 offset:swizzle(SWAP,2)
	s_waitcnt lgkmcnt(0)
	v_pk_add_f32 v[80:81], v[80:81], v[88:89]
	ds_swizzle_b32 v89, v81 offset:swizzle(SWAP,4)
	ds_swizzle_b32 v88, v80 offset:swizzle(SWAP,4)
	s_waitcnt lgkmcnt(0)
	v_pk_add_f32 v[80:81], v[80:81], v[88:89]
	ds_swizzle_b32 v89, v81 offset:swizzle(SWAP,8)
	ds_swizzle_b32 v88, v80 offset:swizzle(SWAP,8)
	s_waitcnt lgkmcnt(0)
	v_pk_add_f32 v[80:81], v[80:81], v[88:89]
	s_nop 0
	v_pk_fma_f32 v[80:81], v[80:81], s[6:7], v[116:117] op_sel_hi:[1,0,0]
	s_waitcnt vmcnt(59)
	v_mov_b32_e32 v105, v202
	v_or_b32_e32 v212, s3, v97
	v_mov_b32_e32 v215, v211
	v_or_b32_e32 v214, 2, v212
	v_lshlrev_b64 v[216:217], 12, v[214:215]
	v_lshl_add_u64 v[216:217], s[58:59], 0, v[216:217]
	v_lshl_add_u64 v[218:219], v[216:217], 0, v[110:111]
	global_load_ushort v202, v[218:219], off offset:3424
	v_lshlrev_b32_e32 v98, 16, v105
	v_mul_f32_e32 v88, 0x4b800000, v81
	v_cmp_gt_f32_e64 s[48:49], s96, v81
	s_nop 1
	v_cndmask_b32_e64 v81, v81, v88, s[48:49]
	v_mul_f32_e32 v88, 0xbfb8aa3b, v98
	v_exp_f32_e32 v99, v88
	v_rsq_f32_e32 v81, v81
	v_lshl_add_u64 v[88:89], s[60:61], 0, v[92:93]
	v_lshl_add_u64 v[92:93], v[88:89], 0, v[110:111]
	v_add_f32_e32 v99, 1.0, v99
	v_rcp_f32_e32 v99, v99
	v_mul_f32_e32 v102, 0x45800000, v81
	v_cndmask_b32_e64 v81, v81, v102, s[48:49]
	v_mul_f32_e32 v100, v100, v81
	v_mul_f32_e32 v100, v115, v100
	v_mul_f32_e32 v98, v99, v98
	v_mul_f32_e32 v98, v98, v100
	v_cvt_pk_bf16_f32 v98, v98, s0
	global_store_short v[92:93], v98, off offset:1536
	v_mul_f32_e32 v94, v94, v81
	v_mul_f32_e32 v94, v161, v94
	v_mul_f32_e32 v86, v86, v81
	v_mul_f32_e32 v86, v160, v86
	v_mul_f32_e32 v81, v82, v81
	v_mul_f32_e32 v81, v159, v81
	v_lshl_add_u64 v[88:89], v[88:89], 0, v[112:113]
	v_lshlrev_b32_e32 v102, 16, v129
	v_cmp_gt_f32_e64 s[48:49], s96, v80
	s_waitcnt vmcnt(60)
	v_mov_b32_e32 v98, v203
	v_or_b32_e32 v212, s3, v97
	v_mov_b32_e32 v215, v211
	v_or_b32_e32 v214, 2, v212
	v_lshlrev_b64 v[216:217], 12, v[214:215]
	v_lshl_add_u64 v[216:217], s[58:59], 0, v[216:217]
	v_lshl_add_u64 v[218:219], v[216:217], 0, v[110:111]
	global_load_ushort v203, v[218:219], off offset:3456
	v_lshlrev_b32_e32 v98, 16, v98
	v_mul_f32_e32 v99, 0xbfb8aa3b, v98
	v_exp_f32_e32 v99, v99
	s_nop 0
	v_add_f32_e32 v99, 1.0, v99
	v_rcp_f32_e32 v99, v99
	s_nop 0
	v_mul_f32_e32 v98, v99, v98
	v_mul_f32_e32 v94, v94, v98
	v_cvt_pk_bf16_f32 v94, v94, s0
	global_store_short v[92:93], v94, off offset:1568
	v_lshlrev_b32_e32 v98, 16, v131
	v_and_b32_e32 v99, 0xffff0000, v131
	s_waitcnt vmcnt(61)
	v_mov_b32_e32 v90, v204
	v_or_b32_e32 v212, s3, v97
	v_mov_b32_e32 v215, v211
	v_or_b32_e32 v214, 2, v212
	v_lshlrev_b64 v[216:217], 12, v[214:215]
	v_lshl_add_u64 v[216:217], s[58:59], 0, v[216:217]
	v_lshl_add_u64 v[218:219], v[216:217], 0, v[110:111]
	global_load_ushort v204, v[218:219], off offset:3488
	v_lshlrev_b32_e32 v90, 16, v90
	v_mul_f32_e32 v91, 0xbfb8aa3b, v90
	v_exp_f32_e32 v91, v91
	s_nop 0
	v_add_f32_e32 v91, 1.0, v91
	v_rcp_f32_e32 v91, v91
	s_nop 0
	v_mul_f32_e32 v90, v91, v90
	v_mul_f32_e32 v86, v86, v90
	v_cvt_pk_bf16_f32 v86, v86, s0
	global_store_short v[92:93], v86, off offset:1600
	v_or_b32_e32 v86, 3, v154
	v_mov_b32_e32 v85, v211
	s_waitcnt vmcnt(62)
; template <bool GLA>
; __device__ __forceinline__ void chunk_pass_c(const ChunkIn& ci, const float* wgl, int unit, unsigned char* wl, int lane, const float* Sb, const float* ng, bf16_t* omix) {
;     ...
; #pragma unroll
;     for (int it = 0; it < 4; ++it) {
;         float bq[8], qv[8], kv[8];
;         chunk_tile<GLA>(raw[it], wfr, bfr, h, it, row, kq, lg, carry, bq, qv, kv);
;         float a[8], bneg[8], cpos[8], dneg[8];
; #pragma unroll
;         for (int j = 0; j < 8; ++j) { const float eb = __expf(bq[j]), enb = __expf(-bq[j]); a[j] = qv[j] * eb; bneg[j] = kv[j] * enb; cpos[j] = qv[j] * enb; dneg[j] = kv[j] * eb; }
;         qf[it] = __builtin_bit_cast(bf16x8, (u32x4){cvtpk(a[0], a[1]), cvtpk(a[2], a[3]), cvtpk(a[4], a[5]), cvtpk(a[6], a[7])});
;         kf[it] = __builtin_bit_cast(bf16x8, (u32x4){cvtpk(bneg[0], bneg[1]), cvtpk(bneg[2], bneg[3]), cvtpk(bneg[4], bneg[5]), cvtpk(bneg[6], bneg[7])});
;         qb[it] = __builtin_bit_cast(bf16x8, (u32x4){cvtpk(cpos[0], cpos[1]), cvtpk(cpos[2], cpos[3]), cvtpk(cpos[4], cpos[5]), cvtpk(cpos[6], cpos[7])});
;         kb[it] = __builtin_bit_cast(bf16x8, (u32x4){cvtpk(dneg[0], dneg[1]), cvtpk(dneg[2], dneg[3]), cvtpk(dneg[4], dneg[5]), cvtpk(dneg[6], dneg[7])});
;         asm volatile("" ::: "memory");
;     }
;     __builtin_amdgcn_s_waitcnt(0); asm volatile("" ::: "memory");
;     bf16x8 vfr[4][2], sfr[4];
; #pragma unroll
;     for (int et = 0; et < 4; ++et) {
; #pragma unroll
;         for (int p = 0; p < 2; ++p) {
;             const u32x2 lo = *(const u32x2*)(wl + (16 * et + row) * GP + (32 * p + 4 * kq) * 2), hh = *(const u32x2*)(wl + (16 * et + row) * GP + (32 * p + 16 + 4 * kq) * 2);
;     ...
;         for (int r = 0; r < 4; ++r) {
;             ss[r] += swz_xor<1>(ss[r]); ss[r] += swz_xor<2>(ss[r]); ss[r] += swz_xor<4>(ss[r]); ss[r] += swz_xor<8>(ss[r]);
;             const float rs = rsqrtf(ss[r] * (1.0f / 64.0f) + EPS);
;             const int t = t0 + 16 * it + 4 * kq + r;
; #pragma unroll
;             for (int et = 0; et < 4; ++et) {
;                 const int e = 16 * et + row;
;                 const float gt = __uint_as_float((unsigned)ci.proj[(size_t)t * DINP + gcol + e] << 16);
;                 const float val = o[et][r] * rs * gn[et] * pg8::silu_f(gt);
;                 omix[(size_t)t * 1024 + ocol + e] = (bf16_t)(cvtpk(val, 0.f) & 0xffffu);
;             }
;         }
	v_mov_b32_e32 v84, v205
	v_lshlrev_b32_e32 v212, 1, v177
	v_mov_b32_e32 v213, v211
	v_or_b32_e32 v214, s3, v97
	v_mov_b32_e32 v217, v211
	v_or_b32_e32 v216, 2, v214
	v_lshlrev_b64 v[218:219], 12, v[216:217]
	v_lshl_add_u64 v[218:219], s[58:59], 0, v[218:219]
	v_lshl_add_u64 v[218:219], v[218:219], 0, v[212:213]
	global_load_ushort v205, v[218:219], off offset:3424
	v_lshlrev_b32_e32 v90, 16, v84
	v_mul_f32_e32 v84, 0xbfb8aa3b, v90
	v_exp_f32_e32 v91, v84
	v_lshlrev_b32_e32 v84, 12, v86
	v_lshl_add_u64 v[84:85], s[58:59], 0, v[84:85]
	v_lshl_add_u64 v[92:93], v[84:85], 0, v[110:111]
	v_add_f32_e32 v91, 1.0, v91
	v_rcp_f32_e32 v91, v91
	s_nop 0
	v_mul_f32_e32 v82, v91, v90
	v_mul_f32_e32 v81, v81, v82
	v_cvt_pk_bf16_f32 v81, v81, s0
	global_store_short v[88:89], v81, off offset:1536
	v_mov_b32_e32 v89, v211
	v_lshlrev_b32_e32 v88, 11, v86
	v_mul_f32_e32 v82, 0xbfb8aa3b, v163
	v_lshl_add_u64 v[142:143], s[60:61], 0, v[88:89]
	v_exp_f32_e32 v82, v82
	v_lshlrev_b32_e32 v88, 16, v130
	v_and_b32_e32 v89, 0xffff0000, v130
	v_lshlrev_b32_e32 v90, 16, v128
	v_and_b32_e32 v91, 0xffff0000, v128
	v_pk_mul_f32 v[104:105], v[68:69], v[88:89]
	v_pk_mul_f32 v[68:69], v[68:69], v[90:91]
	v_pk_mul_f32 v[128:129], v[70:71], v[98:99]
	v_pk_mul_f32 v[70:71], v[70:71], v[102:103]
	v_pk_fma_f32 v[90:91], v[64:65], v[90:91], v[104:105]
	v_pk_fma_f32 v[64:65], v[64:65], v[88:89], v[68:69] neg_lo:[0,0,1] neg_hi:[0,0,1]
	v_pk_fma_f32 v[68:69], v[66:67], v[102:103], v[128:129]
	v_pk_fma_f32 v[66:67], v[66:67], v[98:99], v[70:71] neg_lo:[0,0,1] neg_hi:[0,0,1]
	v_pk_mul_f32 v[70:71], v[90:91], s[8:9] op_sel_hi:[1,0]
	v_pk_mul_f32 v[64:65], v[64:65], s[8:9] op_sel_hi:[1,0]
	v_pk_mul_f32 v[68:69], v[68:69], s[8:9] op_sel_hi:[1,0]
	v_pk_mul_f32 v[66:67], v[66:67], s[8:9] op_sel_hi:[1,0]
	v_pk_mul_f32 v[88:89], v[82:83], v[136:137] op_sel_hi:[0,1]
	v_pk_mul_f32 v[98:99], v[82:83], v[134:135] op_sel_hi:[0,1]
	v_pk_mul_f32 v[102:103], v[82:83], v[140:141] op_sel_hi:[0,1]
	v_pk_mul_f32 v[104:105], v[82:83], v[138:139] op_sel_hi:[0,1]
	v_pk_mul_f32 v[128:129], v[82:83], v[64:65] op_sel_hi:[0,1]
	v_pk_mul_f32 v[134:135], v[82:83], v[70:71] op_sel_hi:[0,1]
	v_pk_mul_f32 v[136:137], v[82:83], v[66:67] op_sel_hi:[0,1]
	v_pk_mul_f32 v[138:139], v[82:83], v[68:69] op_sel_hi:[0,1]
	v_mul_f32_e32 v82, 0x4b800000, v80
	v_cndmask_b32_e64 v80, v80, v82, s[48:49]
	v_rsq_f32_e32 v80, v80
	v_pk_mul_f32 v[90:91], v[132:133], v[64:65] op_sel_hi:[0,1]
	v_pk_mul_f32 v[130:131], v[132:133], v[70:71] op_sel_hi:[0,1]
	v_pk_mul_f32 v[70:71], v[132:133], v[66:67] op_sel_hi:[0,1]
	v_mul_f32_e32 v86, 0x45800000, v80
	v_pk_mul_f32 v[66:67], v[132:133], v[68:69] op_sel_hi:[0,1]
	v_cndmask_b32_e64 v132, v80, v86, s[48:49]
	v_mul_f32_e32 v80, v101, v132
	v_mul_f32_e32 v80, v115, v80
	v_lshl_add_u64 v[144:145], v[142:143], 0, v[110:111]
	v_cvt_pk_bf16_f32 v64, v88, v89
	v_cvt_pk_bf16_f32 v69, v70, v71
	v_cvt_pk_bf16_f32 v71, v66, v67
	v_cvt_pk_bf16_f32 v65, v102, v103
	v_cvt_pk_bf16_f32 v66, v98, v99
	v_cvt_pk_bf16_f32 v67, v104, v105
	v_cvt_pk_bf16_f32 v68, v90, v91
	v_cvt_pk_bf16_f32 v70, v130, v131
	v_cvt_pk_bf16_f32 v128, v128, v129
	v_cvt_pk_bf16_f32 v129, v136, v137
	v_cvt_pk_bf16_f32 v130, v134, v135
	v_cvt_pk_bf16_f32 v131, v138, v139
	v_mfma_f32_16x16x32_bf16 v[134:137], v[64:67], v[68:71], 0
	v_mul_f32_e32 v83, v83, v132
	v_mul_f32_e32 v83, v159, v83
	s_waitcnt vmcnt(63)
	v_mov_b32_e32 v81, v206
	v_or_b32_e32 v212, s3, v97
	v_mov_b32_e32 v215, v211
	v_or_b32_e32 v214, 3, v212
	v_lshlrev_b64 v[216:217], 12, v[214:215]
	v_lshl_add_u64 v[216:217], s[58:59], 0, v[216:217]
	v_lshl_add_u64 v[218:219], v[216:217], 0, v[110:111]
	global_load_ushort v206, v[218:219], off offset:3424
	v_lshlrev_b32_e32 v81, 16, v81
	v_mul_f32_e32 v82, 0xbfb8aa3b, v81
	v_exp_f32_e32 v82, v82
	v_mfma_f32_16x16x32_bf16 v[72:75], v[72:75], v[128:131], 0
	v_add_f32_e32 v82, 1.0, v82
	v_rcp_f32_e32 v82, v82
	v_mfma_f32_16x16x32_bf16 v[98:101], v[12:15], v[128:131], 0
	s_nop 4
	v_cndmask_b32_e64 v86, v136, v74, s[44:45]
	v_cndmask_b32_e64 v129, v137, v75, s[46:47]
	v_mul_f32_e32 v81, v82, v81
	v_mul_f32_e32 v80, v81, v80
	v_cvt_pk_bf16_f32 v80, v80, s0
	global_store_short v[144:145], v80, off offset:1536
	v_mul_f32_e32 v82, v95, v132
	v_mul_f32_e32 v82, v161, v82
	v_cvt_pk_bf16_f32 v129, v86, v129
	v_mfma_f32_16x16x32_bf16 v[88:91], v[8:11], v[68:71], 0
	v_cvt_pk_bf16_f32 v130, v98, v99
	v_cvt_pk_bf16_f32 v131, v100, v101
	s_waitcnt vmcnt(63)
	v_mov_b32_e32 v80, v207
	v_or_b32_e32 v212, s3, v97
	v_mov_b32_e32 v215, v211
	v_or_b32_e32 v214, 3, v212
	v_lshlrev_b64 v[216:217], 12, v[214:215]
	v_lshl_add_u64 v[216:217], s[58:59], 0, v[216:217]
	v_lshl_add_u64 v[218:219], v[216:217], 0, v[110:111]
	global_load_ushort v207, v[218:219], off offset:3456
	v_lshlrev_b32_e32 v80, 16, v80
	v_mul_f32_e32 v81, 0xbfb8aa3b, v80
	v_exp_f32_e32 v81, v81
	v_mfma_f32_16x16x32_bf16 v[102:105], v[76:79], v[68:71], 0
	s_nop 0
	v_cvt_pk_bf16_f32 v88, v88, v89
	v_cvt_pk_bf16_f32 v89, v90, v91
	v_add_f32_e32 v81, 1.0, v81
	v_rcp_f32_e32 v81, v81
	s_nop 0
	v_mul_f32_e32 v80, v81, v80
	v_mul_f32_e32 v80, v82, v80
	v_cvt_pk_bf16_f32 v80, v80, s0
	global_store_short v[144:145], v80, off offset:1568
	v_cndmask_b32_e32 v81, v134, v72, vcc
	v_cndmask_b32_e64 v82, v73, v135, s[42:43]
	v_cvt_pk_bf16_f32 v128, v81, v82
	v_cvt_pk_bf16_f32 v90, v102, v103
	v_cvt_pk_bf16_f32 v91, v104, v105
	s_waitcnt vmcnt(63)
; template <bool GLA>
; __device__ __forceinline__ void chunk_pass_c(const ChunkIn& ci, const float* wgl, int unit, unsigned char* wl, int lane, const float* Sb, const float* ng, bf16_t* omix) {
;     ...
;     for (int it = 0; it < 4; ++it) {
;         f32x4 st[4];
; #pragma unroll
;         for (int jt = 0; jt < 4; ++jt) {
;             const f32x4 z = {0.f, 0.f, 0.f, 0.f};
;             if (jt < it) st[jt] = __builtin_amdgcn_mfma_f32_16x16x32_bf16(kf[jt], qf[it], z, 0, 0, 0);
;             else if (jt > it) st[jt] = __builtin_amdgcn_mfma_f32_16x16x32_bf16(kb[jt], qb[it], z, 0, 0, 0);
;             else {
;                 const f32x4 lo = __builtin_amdgcn_mfma_f32_16x16x32_bf16(kf[jt], qf[it], z, 0, 0, 0), up = __builtin_amdgcn_mfma_f32_16x16x32_bf16(kb[jt], qb[it], z, 0, 0, 0);
; #pragma unroll
;                 for (int r = 0; r < 4; ++r) st[jt][r] = (4 * kq + r <= row) ? lo[r] : up[r];
;             }
;         }
;         bf16x8 af[2];
; #pragma unroll
;         for (int p = 0; p < 2; ++p)
;             af[p] = __builtin_bit_cast(bf16x8, (u32x4){cvtpk(st[2 * p][0], st[2 * p][1]), cvtpk(st[2 * p][2], st[2 * p][3]), cvtpk(st[2 * p + 1][0], st[2 * p + 1][1]), cvtpk(st[2 * p + 1][2], st[2 * p + 1][3])});
;         f32x4 o[4]; float ss[4] = {0.f, 0.f, 0.f, 0.f};
; #pragma unroll
;         for (int et = 0; et < 4; ++et) {
;             f32x4 acc = {0.f, 0.f, 0.f, 0.f};
;             acc = __builtin_amdgcn_mfma_f32_16x16x32_bf16(af[0], vfr[et][0], acc, 0, 0, 0);
;             acc = __builtin_amdgcn_mfma_f32_16x16x32_bf16(af[1], vfr[et][1], acc, 0, 0, 0);
;             acc = __builtin_amdgcn_mfma_f32_16x16x32_bf16(qf[it], sfr[et], acc, 0, 0, 0);
;             o[et] = acc;
; #pragma unroll
;             for (int r = 0; r < 4; ++r) ss[r] += acc[r] * acc[r];
;         }
; #pragma unroll
;         for (int r = 0; r < 4; ++r) {
;             ss[r] += swz_xor<1>(ss[r]); ss[r] += swz_xor<2>(ss[r]); ss[r] += swz_xor<4>(ss[r]); ss[r] += swz_xor<8>(ss[r]);
;             const float rs = rsqrtf(ss[r] * (1.0f / 64.0f) + EPS);
;             const int t = t0 + 16 * it + 4 * kq + r;
; #pragma unroll
;             for (int et = 0; et < 4; ++et) {
;                 const int e = 16 * et + row;
;                 const float gt = __uint_as_float((unsigned)ci.proj[(size_t)t * DINP + gcol + e] << 16);
;                 const float val = o[et][r] * rs * gn[et] * pg8::silu_f(gt);
	v_mov_b32_e32 v80, v208
	v_or_b32_e32 v212, s3, v97
	v_mov_b32_e32 v215, v211
	v_or_b32_e32 v214, 3, v212
	v_lshlrev_b64 v[216:217], 12, v[214:215]
	v_lshl_add_u64 v[216:217], s[58:59], 0, v[216:217]
	v_lshl_add_u64 v[218:219], v[216:217], 0, v[110:111]
	global_load_ushort v208, v[218:219], off offset:3488
	v_lshlrev_b32_e32 v82, 16, v80
	v_mul_f32_e32 v80, 0xbfb8aa3b, v82
	v_exp_f32_e32 v86, v80
	v_lshl_add_u64 v[80:81], v[84:85], 0, v[112:113]
	v_mul_f32_e32 v85, v87, v132
	v_mul_f32_e32 v85, v160, v85
	v_add_f32_e32 v84, 1.0, v86
	v_rcp_f32_e32 v84, v84
	v_mfma_f32_16x16x32_bf16 v[102:105], v[88:91], v[28:31], 0
	v_mul_f32_e32 v82, v84, v82
	v_mul_f32_e32 v82, v85, v82
	v_cvt_pk_bf16_f32 v82, v82, s0
	global_store_short v[144:145], v82, off offset:1600
	v_mfma_f32_16x16x32_bf16 v[92:95], v[88:91], v[44:47], 0
	v_mov_b32_e32 v81, v211
	s_waitcnt vmcnt(63)
	v_mov_b32_e32 v82, v209
	v_lshlrev_b32_e32 v212, 1, v177
	v_mov_b32_e32 v213, v211
	v_or_b32_e32 v214, s3, v97
	v_mov_b32_e32 v217, v211
	v_or_b32_e32 v216, 3, v214
	v_lshlrev_b64 v[218:219], 12, v[216:217]
	v_lshl_add_u64 v[218:219], s[58:59], 0, v[218:219]
	v_lshl_add_u64 v[216:217], v[218:219], 0, v[212:213]
	global_load_ushort v209, v[216:217], off offset:3424
	v_lshlrev_b32_e32 v82, 16, v82
	v_mfma_f32_16x16x32_bf16 v[72:75], v[88:91], v[56:59], 0
	v_mul_f32_e32 v84, 0xbfb8aa3b, v82
	v_mfma_f32_16x16x32_bf16 v[88:91], v[88:91], v[60:63], 0
	v_mfma_f32_16x16x32_bf16 v[98:101], v[128:131], v[20:23], v[102:105]
	v_mfma_f32_16x16x32_bf16 v[92:95], v[128:131], v[32:35], v[92:95]
	v_mfma_f32_16x16x32_bf16 v[102:105], v[128:131], v[48:51], v[88:91]
	v_mfma_f32_16x16x32_bf16 v[88:91], v[68:71], v[24:27], v[98:101]
	s_nop 4
	v_exp_f32_e32 v100, v84
	v_mfma_f32_16x16x32_bf16 v[84:87], v[68:71], v[16:19], v[92:95]
	s_nop 2
	v_add_f32_e32 v94, 1.0, v100
	v_rcp_f32_e32 v94, v94
	v_mfma_f32_16x16x32_bf16 v[72:75], v[128:131], v[52:55], v[72:75]
	v_or_b32_e32 v128, s4, v97
	v_lshlrev_b32_e32 v80, 12, v128
	v_mul_f32_e32 v82, v94, v82
	v_mul_f32_e32 v82, v83, v82
	v_lshl_add_u64 v[80:81], s[58:59], 0, v[80:81]
	v_lshl_add_u64 v[92:93], v[142:143], 0, v[112:113]
	v_cvt_pk_bf16_f32 v82, v82, s0
	v_lshl_add_u64 v[98:99], v[80:81], 0, v[110:111]
	global_store_short v[92:93], v82, off offset:1536
	v_mfma_f32_16x16x32_bf16 v[72:75], v[68:71], v[36:39], v[72:75]
	v_mov_b32_e32 v82, v88
	v_mov_b32_e32 v83, v84
	v_mov_b32_e32 v92, v89
	v_mfma_f32_16x16x32_bf16 v[68:71], v[68:71], v[40:43], v[102:105]
	v_mov_b32_e32 v93, v85
	s_nop 2
	v_mov_b32_e32 v94, v72
	v_mov_b32_e32 v100, v73
	v_pk_mul_f32 v[82:83], v[82:83], v[82:83]
	v_pk_mul_f32 v[92:93], v[92:93], v[92:93]
	v_mov_b32_e32 v95, v68
	v_mov_b32_e32 v101, v69
	v_pk_mul_f32 v[94:95], v[94:95], v[94:95]
	v_pk_mul_f32 v[100:101], v[100:101], v[100:101]
	v_mov_b32_e32 v102, v92
	v_mov_b32_e32 v103, v82
	v_mov_b32_e32 v82, v93
	v_mov_b32_e32 v92, v100
	v_mov_b32_e32 v93, v94
	v_pk_add_f32 v[82:83], v[102:103], v[82:83]
	v_mov_b32_e32 v94, v101
	v_pk_add_f32 v[82:83], v[82:83], v[92:93]
	v_lshl_add_u64 v[80:81], v[80:81], 0, v[112:113]
	v_pk_add_f32 v[82:83], v[82:83], v[94:95]
	ds_swizzle_b32 v93, v83 offset:swizzle(SWAP,1)
	ds_swizzle_b32 v92, v82 offset:swizzle(SWAP,1)
	v_mov_b32_e32 v95, v211
	v_lshlrev_b32_e32 v94, 11, v128
	s_waitcnt lgkmcnt(0)
	v_pk_add_f32 v[82:83], v[82:83], v[92:93]
	ds_swizzle_b32 v93, v83 offset:swizzle(SWAP,2)
	ds_swizzle_b32 v92, v82 offset:swizzle(SWAP,2)
	s_waitcnt lgkmcnt(0)
	v_pk_add_f32 v[82:83], v[82:83], v[92:93]
	ds_swizzle_b32 v93, v83 offset:swizzle(SWAP,4)
	ds_swizzle_b32 v92, v82 offset:swizzle(SWAP,4)
	s_waitcnt lgkmcnt(0)
	v_pk_add_f32 v[82:83], v[82:83], v[92:93]
	ds_swizzle_b32 v93, v83 offset:swizzle(SWAP,8)
	ds_swizzle_b32 v92, v82 offset:swizzle(SWAP,8)
	s_waitcnt lgkmcnt(0)
	v_pk_add_f32 v[82:83], v[82:83], v[92:93]
	s_nop 0
	v_pk_fma_f32 v[82:83], v[82:83], s[6:7], v[116:117] op_sel_hi:[1,0,0]
	s_waitcnt vmcnt(63)
	v_mov_b32_e32 v129, v178
	v_lshlrev_b32_e32 v100, 16, v129
	v_mul_f32_e32 v92, 0x4b800000, v83
	v_cmp_gt_f32_e64 s[48:49], s96, v83
	s_nop 1
	v_cndmask_b32_e64 v83, v83, v92, s[48:49]
	v_mul_f32_e32 v92, 0xbfb8aa3b, v100
	v_exp_f32_e32 v101, v92
	v_rsq_f32_e32 v83, v83
	v_lshl_add_u64 v[92:93], s[60:61], 0, v[94:95]
	v_lshl_add_u64 v[94:95], v[92:93], 0, v[110:111]
	v_add_f32_e32 v101, 1.0, v101
	v_rcp_f32_e32 v101, v101
	v_mul_f32_e32 v102, 0x45800000, v83
	v_cndmask_b32_e64 v83, v83, v102, s[48:49]
	v_mul_f32_e32 v88, v88, v83
	v_mul_f32_e32 v88, v115, v88
	v_mul_f32_e32 v100, v101, v100
	v_mul_f32_e32 v88, v100, v88
	v_cvt_pk_bf16_f32 v88, v88, s0
	global_store_short v[94:95], v88, off offset:1536
	v_mul_f32_e32 v84, v84, v83
	v_mul_f32_e32 v84, v161, v84
	v_mul_f32_e32 v72, v72, v83
	v_mul_f32_e32 v72, v160, v72
	v_mul_f32_e32 v68, v68, v83
	v_mul_f32_e32 v68, v159, v68
	v_lshl_add_u64 v[92:93], v[92:93], 0, v[112:113]
	v_cmp_gt_f32_e64 s[48:49], s96, v82
	s_waitcnt vmcnt(62)
	v_mov_b32_e32 v88, v179
	v_lshlrev_b32_e32 v88, 16, v88
	v_mul_f32_e32 v100, 0xbfb8aa3b, v88
	v_exp_f32_e32 v100, v100
	s_nop 0
	v_add_f32_e32 v100, 1.0, v100
	v_rcp_f32_e32 v100, v100
	s_nop 0
	v_mul_f32_e32 v88, v100, v88
	v_mul_f32_e32 v84, v88, v84
	v_cvt_pk_bf16_f32 v84, v84, s0
	global_store_short v[94:95], v84, off offset:1568
	s_waitcnt vmcnt(61)
	v_mov_b32_e32 v84, v180
	v_lshlrev_b32_e32 v84, 16, v84
	v_mul_f32_e32 v88, 0xbfb8aa3b, v84
	v_exp_f32_e32 v88, v88
	s_nop 0
	v_add_f32_e32 v88, 1.0, v88
	v_rcp_f32_e32 v88, v88
	s_nop 0
	v_mul_f32_e32 v84, v88, v84
	v_mul_f32_e32 v72, v72, v84
	v_cvt_pk_bf16_f32 v72, v72, s0
	global_store_short v[94:95], v72, off offset:1600
	v_or_b32_e32 v84, 1, v128
	v_mov_b32_e32 v81, v211
	s_waitcnt vmcnt(60)
; __device__ __forceinline__ unsigned cvtpk(float lo, float hi) { f32x2_t v = {lo, hi}; bf16x2_t b = __builtin_convertvector(v, bf16x2_t); return __builtin_bit_cast(unsigned, b); }
; template <int X> __device__ __forceinline__ float swz_xor(float v) { return __int_as_float(__builtin_amdgcn_ds_swizzle(__float_as_int(v), (X << 10) | 0x1F)); }
; __device__ __forceinline__ float silu_f(float g) { return g * __builtin_amdgcn_rcpf(1.0f + __expf(-g)); }
; template <bool GLA>
; __device__ __forceinline__ void chunk_pass_c(const ChunkIn& ci, const float* wgl, int unit, unsigned char* wl, int lane, const float* Sb, const float* ng, bf16_t* omix) {
;     ...
; #pragma unroll
;         for (int r = 0; r < 4; ++r) {
;             ss[r] += swz_xor<1>(ss[r]); ss[r] += swz_xor<2>(ss[r]); ss[r] += swz_xor<4>(ss[r]); ss[r] += swz_xor<8>(ss[r]);
;             const float rs = rsqrtf(ss[r] * (1.0f / 64.0f) + EPS);
;             const int t = t0 + 16 * it + 4 * kq + r;
; #pragma unroll
;             for (int et = 0; et < 4; ++et) {
;                 const int e = 16 * et + row;
;                 const float gt = __uint_as_float((unsigned)ci.proj[(size_t)t * DINP + gcol + e] << 16);
;                 const float val = o[et][r] * rs * gn[et] * pg8::silu_f(gt);
;                 omix[(size_t)t * 1024 + ocol + e] = (bf16_t)(cvtpk(val, 0.f) & 0xffffu);
;             }
;         }
	v_mov_b32_e32 v72, v181
	v_lshlrev_b32_e32 v72, 16, v72
	v_mul_f32_e32 v80, 0xbfb8aa3b, v72
	v_exp_f32_e32 v88, v80
	v_lshlrev_b32_e32 v80, 12, v84
	v_lshl_add_u64 v[80:81], s[58:59], 0, v[80:81]
	v_lshl_add_u64 v[94:95], v[80:81], 0, v[110:111]
	v_add_f32_e32 v88, 1.0, v88
	v_rcp_f32_e32 v88, v88
	v_lshl_add_u64 v[80:81], v[80:81], 0, v[112:113]
	v_mul_f32_e32 v72, v88, v72
	v_mul_f32_e32 v68, v68, v72
	v_cvt_pk_bf16_f32 v68, v68, s0
	global_store_short v[92:93], v68, off offset:1536
	v_mul_f32_e32 v72, 0x4b800000, v82
	v_cndmask_b32_e64 v72, v82, v72, s[48:49]
	v_lshlrev_b32_e32 v92, 11, v84
	v_rsq_f32_e32 v72, v72
	v_mov_b32_e32 v93, v211
	v_mul_f32_e32 v88, 0x45800000, v72
	v_cndmask_b32_e64 v88, v72, v88, s[48:49]
	v_mul_f32_e32 v72, v89, v88
	v_mul_f32_e32 v72, v115, v72
	v_mul_f32_e32 v73, v73, v88
	v_mul_f32_e32 v73, v160, v73
	v_mul_f32_e32 v69, v69, v88
	v_mul_f32_e32 v69, v159, v69
	v_mov_b32_e32 v89, v71
	s_waitcnt vmcnt(59)
	v_mov_b32_e32 v68, v182
	v_lshlrev_b32_e32 v68, 16, v68
	v_mul_f32_e32 v82, 0xbfb8aa3b, v68
	v_exp_f32_e32 v84, v82
	v_lshl_add_u64 v[82:83], s[60:61], 0, v[92:93]
	v_lshl_add_u64 v[92:93], v[82:83], 0, v[110:111]
	v_add_f32_e32 v84, 1.0, v84
	v_rcp_f32_e32 v84, v84
	s_nop 0
	v_mul_f32_e32 v68, v84, v68
	v_mul_f32_e32 v68, v68, v72
	v_cvt_pk_bf16_f32 v68, v68, s0
	global_store_short v[92:93], v68, off offset:1536
	v_mul_f32_e32 v84, v85, v88
	v_mul_f32_e32 v84, v161, v84
	v_mov_b32_e32 v85, v70
	v_mov_b32_e32 v88, v75
	v_pk_mul_f32 v[88:89], v[88:89], v[88:89]
	s_waitcnt vmcnt(58)
	v_mov_b32_e32 v68, v183
	v_lshlrev_b32_e32 v68, 16, v68
	v_mul_f32_e32 v72, 0xbfb8aa3b, v68
	v_exp_f32_e32 v72, v72
	s_nop 0
	v_add_f32_e32 v72, 1.0, v72
	v_rcp_f32_e32 v72, v72
	s_nop 0
	v_mul_f32_e32 v68, v72, v68
	v_mul_f32_e32 v68, v84, v68
	v_cvt_pk_bf16_f32 v68, v68, s0
	global_store_short v[92:93], v68, off offset:1568
	v_or_b32_e32 v94, 2, v128
	s_waitcnt vmcnt(57)
	v_mov_b32_e32 v68, v184
	v_lshlrev_b32_e32 v68, 16, v68
	v_mul_f32_e32 v72, 0xbfb8aa3b, v68
	v_exp_f32_e32 v72, v72
	s_nop 0
	v_add_f32_e32 v72, 1.0, v72
	v_rcp_f32_e32 v72, v72
	s_nop 0
	v_mul_f32_e32 v68, v72, v68
	v_mul_f32_e32 v68, v73, v68
	v_cvt_pk_bf16_f32 v68, v68, s0
	global_store_short v[92:93], v68, off offset:1600
	v_lshl_add_u64 v[80:81], v[82:83], 0, v[112:113]
	v_mov_b32_e32 v73, v211
	s_waitcnt vmcnt(56)
	v_mov_b32_e32 v68, v185
	v_lshlrev_b32_e32 v68, 16, v68
	v_mul_f32_e32 v72, 0xbfb8aa3b, v68
	v_exp_f32_e32 v84, v72
	v_lshlrev_b32_e32 v72, 12, v94
	v_lshl_add_u64 v[72:73], s[58:59], 0, v[72:73]
	v_add_f32_e32 v82, 1.0, v84
	v_rcp_f32_e32 v84, v82
	v_lshl_add_u64 v[82:83], v[72:73], 0, v[110:111]
	v_lshl_add_u64 v[72:73], v[72:73], 0, v[112:113]
	v_mul_f32_e32 v68, v84, v68
	v_mul_f32_e32 v68, v69, v68
	v_cvt_pk_bf16_f32 v68, v68, s0
	global_store_short v[80:81], v68, off offset:1536
	v_mov_b32_e32 v68, v90
	v_mov_b32_e32 v69, v86
	v_mov_b32_e32 v80, v91
	v_mov_b32_e32 v81, v87
	v_mov_b32_e32 v84, v74
	v_pk_mul_f32 v[68:69], v[68:69], v[68:69]
	v_pk_mul_f32 v[80:81], v[80:81], v[80:81]
	v_pk_mul_f32 v[84:85], v[84:85], v[84:85]
	v_mov_b32_e32 v92, v80
	v_mov_b32_e32 v93, v68
	v_mov_b32_e32 v68, v81
	v_mov_b32_e32 v80, v88
	v_mov_b32_e32 v81, v84
	v_pk_add_f32 v[68:69], v[92:93], v[68:69]
	v_mov_b32_e32 v84, v89
	v_pk_add_f32 v[68:69], v[68:69], v[80:81]
	v_and_b32_e32 v93, 0xffff0000, v107
	v_pk_add_f32 v[68:69], v[68:69], v[84:85]
	ds_swizzle_b32 v81, v69 offset:swizzle(SWAP,1)
	ds_swizzle_b32 v80, v68 offset:swizzle(SWAP,1)
	v_mov_b32_e32 v85, v211
	v_lshlrev_b32_e32 v84, 11, v94
	s_waitcnt lgkmcnt(0)
	v_pk_add_f32 v[68:69], v[68:69], v[80:81]
	ds_swizzle_b32 v81, v69 offset:swizzle(SWAP,2)
	ds_swizzle_b32 v80, v68 offset:swizzle(SWAP,2)
	s_waitcnt lgkmcnt(0)
	v_pk_add_f32 v[68:69], v[68:69], v[80:81]
	ds_swizzle_b32 v81, v69 offset:swizzle(SWAP,4)
	ds_swizzle_b32 v80, v68 offset:swizzle(SWAP,4)
	s_waitcnt lgkmcnt(0)
	v_pk_add_f32 v[68:69], v[68:69], v[80:81]
	ds_swizzle_b32 v81, v69 offset:swizzle(SWAP,8)
	ds_swizzle_b32 v80, v68 offset:swizzle(SWAP,8)
	s_waitcnt lgkmcnt(0)
	v_pk_add_f32 v[68:69], v[68:69], v[80:81]
	s_nop 0
	v_pk_fma_f32 v[68:69], v[68:69], s[6:7], v[116:117] op_sel_hi:[1,0,0]
	s_waitcnt vmcnt(55)
	v_mov_b32_e32 v95, v186
	v_lshlrev_b32_e32 v88, 16, v95
	v_mul_f32_e32 v80, 0x4b800000, v69
	v_cmp_gt_f32_e64 s[48:49], s96, v69
	s_nop 1
	v_cndmask_b32_e64 v69, v69, v80, s[48:49]
	v_mul_f32_e32 v80, 0xbfb8aa3b, v88
	v_exp_f32_e32 v89, v80
	v_rsq_f32_e32 v69, v69
	v_lshl_add_u64 v[80:81], s[60:61], 0, v[84:85]
	v_lshl_add_u64 v[84:85], v[80:81], 0, v[110:111]
	v_add_f32_e32 v89, 1.0, v89
	v_rcp_f32_e32 v89, v89
	v_mul_f32_e32 v92, 0x45800000, v69
	v_cndmask_b32_e64 v69, v69, v92, s[48:49]
	v_mul_f32_e32 v90, v90, v69
	v_mul_f32_e32 v90, v115, v90
	v_mul_f32_e32 v88, v89, v88
	v_mul_f32_e32 v88, v88, v90
	v_cvt_pk_bf16_f32 v88, v88, s0
	global_store_short v[84:85], v88, off offset:1536
	v_mul_f32_e32 v86, v86, v69
	v_mul_f32_e32 v86, v161, v86
	v_mul_f32_e32 v74, v74, v69
	v_mul_f32_e32 v74, v160, v74
	v_mul_f32_e32 v69, v70, v69
	v_mul_f32_e32 v69, v159, v69
	v_lshl_add_u64 v[80:81], v[80:81], 0, v[112:113]
	v_cmp_gt_f32_e64 s[48:49], s96, v68
	v_lshlrev_b32_e32 v90, 16, v109
	v_lshlrev_b32_e32 v92, 16, v107
	s_waitcnt vmcnt(54)
	v_mov_b32_e32 v88, v187
	v_lshlrev_b32_e32 v88, 16, v88
	v_mul_f32_e32 v89, 0xbfb8aa3b, v88
	v_exp_f32_e32 v89, v89
	s_nop 0
	v_add_f32_e32 v89, 1.0, v89
	v_rcp_f32_e32 v89, v89
	s_nop 0
	v_mul_f32_e32 v88, v89, v88
	v_mul_f32_e32 v86, v86, v88
	v_cvt_pk_bf16_f32 v86, v86, s0
	global_store_short v[84:85], v86, off offset:1568
	s_waitcnt vmcnt(53)
; template <bool GLA>
; __device__ __forceinline__ void chunk_pass_c(const ChunkIn& ci, const float* wgl, int unit, unsigned char* wl, int lane, const float* Sb, const float* ng, bf16_t* omix) {
;     ...
; #pragma unroll
;     for (int it = 0; it < 4; ++it) {
;         float bq[8], qv[8], kv[8];
;         chunk_tile<GLA>(raw[it], wfr, bfr, h, it, row, kq, lg, carry, bq, qv, kv);
;         float a[8], bneg[8], cpos[8], dneg[8];
; #pragma unroll
;         for (int j = 0; j < 8; ++j) { const float eb = __expf(bq[j]), enb = __expf(-bq[j]); a[j] = qv[j] * eb; bneg[j] = kv[j] * enb; cpos[j] = qv[j] * enb; dneg[j] = kv[j] * eb; }
;         qf[it] = __builtin_bit_cast(bf16x8, (u32x4){cvtpk(a[0], a[1]), cvtpk(a[2], a[3]), cvtpk(a[4], a[5]), cvtpk(a[6], a[7])});
;         kf[it] = __builtin_bit_cast(bf16x8, (u32x4){cvtpk(bneg[0], bneg[1]), cvtpk(bneg[2], bneg[3]), cvtpk(bneg[4], bneg[5]), cvtpk(bneg[6], bneg[7])});
;         qb[it] = __builtin_bit_cast(bf16x8, (u32x4){cvtpk(cpos[0], cpos[1]), cvtpk(cpos[2], cpos[3]), cvtpk(cpos[4], cpos[5]), cvtpk(cpos[6], cpos[7])});
;         kb[it] = __builtin_bit_cast(bf16x8, (u32x4){cvtpk(dneg[0], dneg[1]), cvtpk(dneg[2], dneg[3]), cvtpk(dneg[4], dneg[5]), cvtpk(dneg[6], dneg[7])});
;         asm volatile("" ::: "memory");
;     }
;     __builtin_amdgcn_s_waitcnt(0); asm volatile("" ::: "memory");
;     bf16x8 vfr[4][2], sfr[4];
; #pragma unroll
;     for (int et = 0; et < 4; ++et) {
; #pragma unroll
;         for (int p = 0; p < 2; ++p) {
;             const u32x2 lo = *(const u32x2*)(wl + (16 * et + row) * GP + (32 * p + 4 * kq) * 2), hh = *(const u32x2*)(wl + (16 * et + row) * GP + (32 * p + 16 + 4 * kq) * 2);
;     ...
;         for (int r = 0; r < 4; ++r) {
;             ss[r] += swz_xor<1>(ss[r]); ss[r] += swz_xor<2>(ss[r]); ss[r] += swz_xor<4>(ss[r]); ss[r] += swz_xor<8>(ss[r]);
;             const float rs = rsqrtf(ss[r] * (1.0f / 64.0f) + EPS);
;             const int t = t0 + 16 * it + 4 * kq + r;
; #pragma unroll
;             for (int et = 0; et < 4; ++et) {
;                 const int e = 16 * et + row;
;                 const float gt = __uint_as_float((unsigned)ci.proj[(size_t)t * DINP + gcol + e] << 16);
;                 const float val = o[et][r] * rs * gn[et] * pg8::silu_f(gt);
;                 omix[(size_t)t * 1024 + ocol + e] = (bf16_t)(cvtpk(val, 0.f) & 0xffffu);
;             }
;         }
	v_mov_b32_e32 v82, v188
	v_lshlrev_b32_e32 v82, 16, v82
	v_mul_f32_e32 v83, 0xbfb8aa3b, v82
	v_exp_f32_e32 v83, v83
	s_nop 0
	v_add_f32_e32 v83, 1.0, v83
	v_rcp_f32_e32 v83, v83
	s_nop 0
	v_mul_f32_e32 v82, v83, v82
	v_mul_f32_e32 v74, v74, v82
	v_cvt_pk_bf16_f32 v74, v74, s0
	global_store_short v[84:85], v74, off offset:1600
	v_or_b32_e32 v74, 3, v128
	v_mov_b32_e32 v73, v211
	s_waitcnt vmcnt(52)
	v_mov_b32_e32 v72, v189
	v_lshlrev_b32_e32 v82, 16, v72
	v_mul_f32_e32 v72, 0xbfb8aa3b, v82
	v_exp_f32_e32 v83, v72
	v_lshlrev_b32_e32 v72, 12, v74
	v_lshl_add_u64 v[72:73], s[58:59], 0, v[72:73]
	v_lshl_add_u64 v[84:85], v[72:73], 0, v[110:111]
	v_add_f32_e32 v83, 1.0, v83
	v_rcp_f32_e32 v83, v83
	s_nop 0
	v_mul_f32_e32 v70, v83, v82
	v_mul_f32_e32 v69, v69, v70
	v_cvt_pk_bf16_f32 v69, v69, s0
	global_store_short v[80:81], v69, off offset:1536
	v_mul_f32_e32 v70, 0x4b800000, v68
	v_lshlrev_b32_e32 v80, 11, v74
	v_cndmask_b32_e64 v68, v68, v70, s[48:49]
	v_rsq_f32_e32 v70, v68
	v_mov_b32_e32 v81, v211
	v_and_b32_e32 v83, 0xffff0000, v106
	s_waitcnt vmcnt(51)
	v_mov_b32_e32 v69, v190
	v_lshlrev_b32_e32 v74, 16, v69
	v_mul_f32_e32 v68, 0xbfb8aa3b, v74
	v_exp_f32_e32 v82, v68
	v_lshl_add_u64 v[68:69], s[60:61], 0, v[80:81]
	v_mul_f32_e32 v80, 0x45800000, v70
	v_cndmask_b32_e64 v86, v70, v80, s[48:49]
	v_add_f32_e32 v81, 1.0, v82
	v_rcp_f32_e32 v81, v81
	v_mul_f32_e32 v70, v91, v86
	v_mul_f32_e32 v70, v115, v70
	v_lshl_add_u64 v[88:89], v[68:69], 0, v[110:111]
	v_mul_f32_e32 v74, v81, v74
	v_mul_f32_e32 v70, v74, v70
	v_cvt_pk_bf16_f32 v70, v70, s0
	global_store_short v[88:89], v70, off offset:1536
	v_lshlrev_b32_e32 v80, 16, v108
	v_and_b32_e32 v81, 0xffff0000, v108
	v_lshlrev_b32_e32 v82, 16, v106
	v_and_b32_e32 v91, 0xffff0000, v109
	v_pk_mul_f32 v[94:95], v[4:5], v[80:81]
	v_pk_mul_f32 v[4:5], v[4:5], v[82:83]
	v_pk_mul_f32 v[98:99], v[6:7], v[90:91]
	v_pk_mul_f32 v[6:7], v[6:7], v[92:93]
	v_pk_fma_f32 v[82:83], v[0:1], v[82:83], v[94:95]
	v_pk_fma_f32 v[0:1], v[0:1], v[80:81], v[4:5] neg_lo:[0,0,1] neg_hi:[0,0,1]
	v_pk_fma_f32 v[4:5], v[2:3], v[92:93], v[98:99]
	v_pk_fma_f32 v[2:3], v[2:3], v[90:91], v[6:7] neg_lo:[0,0,1] neg_hi:[0,0,1]
	v_mul_f32_e32 v70, 0xbfb8aa3b, v162
	v_pk_mul_f32 v[80:81], v[82:83], s[8:9] op_sel_hi:[1,0]
	v_pk_mul_f32 v[82:83], v[0:1], s[8:9] op_sel_hi:[1,0]
	v_pk_mul_f32 v[94:95], v[4:5], s[8:9] op_sel_hi:[1,0]
	v_pk_mul_f32 v[98:99], v[2:3], s[8:9] op_sel_hi:[1,0]
	v_exp_f32_e32 v70, v70
	v_pk_mul_f32 v[0:1], v[118:119], v[82:83] op_sel_hi:[0,1]
	v_pk_mul_f32 v[2:3], v[118:119], v[80:81] op_sel_hi:[0,1]
	v_pk_mul_f32 v[4:5], v[118:119], v[98:99] op_sel_hi:[0,1]
	v_pk_mul_f32 v[6:7], v[118:119], v[94:95] op_sel_hi:[0,1]
	v_cvt_pk_bf16_f32 v0, v0, v1
	v_cvt_pk_bf16_f32 v1, v4, v5
	v_cvt_pk_bf16_f32 v2, v2, v3
	v_cvt_pk_bf16_f32 v3, v6, v7
	v_pk_mul_f32 v[90:91], v[70:71], v[122:123] op_sel_hi:[0,1]
	v_pk_mul_f32 v[92:93], v[70:71], v[120:121] op_sel_hi:[0,1]
	v_mfma_f32_16x16x32_bf16 v[4:7], v[8:11], v[0:3], 0
	v_mul_f32_e64 v100, v70, v126
	v_mul_f32_e64 v101, v70, v127
	v_pk_mul_f32 v[102:103], v[70:71], v[124:125] op_sel_hi:[0,1]
	v_pk_mul_f32 v[82:83], v[70:71], v[82:83] op_sel_hi:[0,1]
	v_pk_mul_f32 v[104:105], v[70:71], v[80:81] op_sel_hi:[0,1]
	v_cvt_pk_bf16_f32 v8, v90, v91
	v_cvt_pk_bf16_f32 v10, v92, v93
	v_pk_mul_f32 v[90:91], v[70:71], v[98:99] op_sel_hi:[0,1]
	v_pk_mul_f32 v[92:93], v[70:71], v[94:95] op_sel_hi:[0,1]
	v_cvt_pk_bf16_f32 v4, v4, v5
	v_cvt_pk_bf16_f32 v5, v6, v7
	v_mfma_f32_16x16x32_bf16 v[76:79], v[76:79], v[0:3], 0
	v_cvt_pk_bf16_f32 v9, v100, v101
	v_cvt_pk_bf16_f32 v11, v102, v103
	v_cvt_pk_bf16_f32 v80, v82, v83
	v_cvt_pk_bf16_f32 v81, v90, v91
	v_cvt_pk_bf16_f32 v82, v104, v105
	s_nop 2
	v_cvt_pk_bf16_f32 v6, v76, v77
	v_mul_f32_e32 v76, v87, v86
	v_mul_f32_e32 v76, v161, v76
	v_cvt_pk_bf16_f32 v83, v92, v93
	v_mfma_f32_16x16x32_bf16 v[8:11], v[8:11], v[0:3], 0
	s_waitcnt vmcnt(50)
	v_mov_b32_e32 v74, v191
	v_lshlrev_b32_e32 v70, 16, v74
	v_mul_f32_e32 v7, 0xbfb8aa3b, v70
	v_exp_f32_e32 v74, v7
	v_mfma_f32_16x16x32_bf16 v[12:15], v[12:15], v[80:83], 0
	v_cvt_pk_bf16_f32 v7, v78, v79
	v_add_f32_e32 v74, 1.0, v74
	v_rcp_f32_e32 v74, v74
	v_mfma_f32_16x16x32_bf16 v[64:67], v[64:67], v[0:3], 0
	s_nop 3
	v_cndmask_b32_e64 v15, v11, v15, s[46:47]
	v_cndmask_b32_e64 v77, v10, v14, s[44:45]
	v_mul_f32_e32 v70, v74, v70
	v_mul_f32_e32 v70, v76, v70
	v_cvt_pk_bf16_f32 v70, v70, s0
	global_store_short v[88:89], v70, off offset:1568
	v_cndmask_b32_e32 v74, v8, v12, vcc
	v_cndmask_b32_e64 v76, v13, v9, s[42:43]
	v_cvt_pk_bf16_f32 v12, v64, v65
	v_cvt_pk_bf16_f32 v13, v66, v67
	v_cvt_pk_bf16_f32 v14, v74, v76
	v_cvt_pk_bf16_f32 v15, v77, v15
	v_mfma_f32_16x16x32_bf16 v[28:31], v[4:7], v[28:31], 0
	s_nop 0
	v_mfma_f32_16x16x32_bf16 v[28:31], v[12:15], v[20:23], v[28:31]
	s_waitcnt vmcnt(49)
	v_mov_b32_e32 v70, v192
	v_lshlrev_b32_e32 v22, 16, v70
	v_mul_f32_e32 v20, 0xbfb8aa3b, v22
	v_exp_f32_e32 v23, v20
	v_mfma_f32_16x16x32_bf16 v[44:47], v[4:7], v[44:47], 0
	v_lshl_add_u64 v[20:21], v[72:73], 0, v[112:113]
	v_add_f32_e32 v23, 1.0, v23
	v_mfma_f32_16x16x32_bf16 v[8:11], v[4:7], v[56:59], 0
	v_rcp_f32_e32 v23, v23
	v_mfma_f32_16x16x32_bf16 v[32:35], v[12:15], v[32:35], v[44:47]
	v_mfma_f32_16x16x32_bf16 v[44:47], v[12:15], v[52:55], v[8:11]
	s_nop 4
	v_mul_f32_e32 v8, v75, v86
	v_mul_f32_e32 v8, v160, v8
	v_mul_f32_e32 v9, v23, v22
	v_mul_f32_e32 v8, v8, v9
	v_cvt_pk_bf16_f32 v8, v8, s0
	global_store_short v[88:89], v8, off offset:1600
	v_mfma_f32_16x16x32_bf16 v[4:7], v[4:7], v[60:63], 0
	v_mov_b32_e32 v21, v211
	v_or_b32_e32 v20, s3, v97
	v_mfma_f32_16x16x32_bf16 v[48:51], v[12:15], v[48:51], v[4:7]
	v_mfma_f32_16x16x32_bf16 v[12:15], v[0:3], v[24:27], v[28:31]
	s_nop 3
	v_lshlrev_b64 v[4:5], 12, v[20:21]
	v_lshl_add_u64 v[22:23], s[58:59], 0, v[4:5]
	v_lshl_add_u64 v[24:25], v[22:23], 0, v[110:111]
	v_lshl_add_u64 v[22:23], v[22:23], 0, v[112:113]
	s_waitcnt vmcnt(48)
; __device__ __forceinline__ unsigned cvtpk(float lo, float hi) { f32x2_t v = {lo, hi}; bf16x2_t b = __builtin_convertvector(v, bf16x2_t); return __builtin_bit_cast(unsigned, b); }
; template <int X> __device__ __forceinline__ float swz_xor(float v) { return __int_as_float(__builtin_amdgcn_ds_swizzle(__float_as_int(v), (X << 10) | 0x1F)); }
; __device__ __forceinline__ float silu_f(float g) { return g * __builtin_amdgcn_rcpf(1.0f + __expf(-g)); }
; template <bool GLA>
; __device__ __forceinline__ void chunk_pass_c(const ChunkIn& ci, const float* wgl, int unit, unsigned char* wl, int lane, const float* Sb, const float* ng, bf16_t* omix) {
;     ...
;         for (int et = 0; et < 4; ++et) {
;             f32x4 acc = {0.f, 0.f, 0.f, 0.f};
;             acc = __builtin_amdgcn_mfma_f32_16x16x32_bf16(af[0], vfr[et][0], acc, 0, 0, 0);
;             acc = __builtin_amdgcn_mfma_f32_16x16x32_bf16(af[1], vfr[et][1], acc, 0, 0, 0);
;             acc = __builtin_amdgcn_mfma_f32_16x16x32_bf16(qf[it], sfr[et], acc, 0, 0, 0);
;             o[et] = acc;
; #pragma unroll
;             for (int r = 0; r < 4; ++r) ss[r] += acc[r] * acc[r];
;         }
; #pragma unroll
;         for (int r = 0; r < 4; ++r) {
;             ss[r] += swz_xor<1>(ss[r]); ss[r] += swz_xor<2>(ss[r]); ss[r] += swz_xor<4>(ss[r]); ss[r] += swz_xor<8>(ss[r]);
;             const float rs = rsqrtf(ss[r] * (1.0f / 64.0f) + EPS);
;             const int t = t0 + 16 * it + 4 * kq + r;
; #pragma unroll
;             for (int et = 0; et < 4; ++et) {
;                 const int e = 16 * et + row;
;                 const float gt = __uint_as_float((unsigned)ci.proj[(size_t)t * DINP + gcol + e] << 16);
;                 const float val = o[et][r] * rs * gn[et] * pg8::silu_f(gt);
;                 omix[(size_t)t * 1024 + ocol + e] = (bf16_t)(cvtpk(val, 0.f) & 0xffffu);
;             }
;         }
	v_mov_b32_e32 v8, v193
	v_lshlrev_b32_e32 v26, 16, v8
	v_mul_f32_e32 v4, 0xbfb8aa3b, v26
	v_exp_f32_e32 v4, v4
	v_mfma_f32_16x16x32_bf16 v[8:11], v[0:3], v[16:19], v[32:35]
	v_mul_f32_e32 v19, v71, v86
	v_mul_f32_e32 v19, v159, v19
	v_add_f32_e32 v4, 1.0, v4
	v_rcp_f32_e32 v18, v4
	v_lshl_add_u64 v[16:17], v[68:69], 0, v[112:113]
	v_mfma_f32_16x16x32_bf16 v[4:7], v[0:3], v[36:39], v[44:47]
	v_mul_f32_e32 v18, v18, v26
	v_mul_f32_e32 v18, v19, v18
	v_cvt_pk_bf16_f32 v18, v18, s0
	global_store_short v[16:17], v18, off offset:1536
	v_mfma_f32_16x16x32_bf16 v[0:3], v[0:3], v[40:43], v[48:51]
	v_mov_b32_e32 v16, v12
	v_mov_b32_e32 v17, v8
	v_mov_b32_e32 v18, v13
	v_mov_b32_e32 v19, v9
	v_mov_b32_e32 v26, v4
	s_nop 2
	v_mov_b32_e32 v27, v0
	v_mov_b32_e32 v28, v5
	v_mov_b32_e32 v29, v1
	v_pk_mul_f32 v[16:17], v[16:17], v[16:17]
	v_pk_mul_f32 v[18:19], v[18:19], v[18:19]
	v_pk_mul_f32 v[26:27], v[26:27], v[26:27]
	v_pk_mul_f32 v[28:29], v[28:29], v[28:29]
	v_mov_b32_e32 v30, v18
	v_mov_b32_e32 v31, v16
	v_mov_b32_e32 v16, v19
	v_mov_b32_e32 v18, v28
	v_mov_b32_e32 v19, v26
	v_pk_add_f32 v[16:17], v[30:31], v[16:17]
	v_mov_b32_e32 v26, v29
	v_pk_add_f32 v[16:17], v[16:17], v[18:19]
	s_nop 0
	v_pk_add_f32 v[16:17], v[16:17], v[26:27]
	ds_swizzle_b32 v19, v17 offset:swizzle(SWAP,1)
	ds_swizzle_b32 v18, v16 offset:swizzle(SWAP,1)
	v_lshlrev_b64 v[26:27], 11, v[20:21]
	s_waitcnt lgkmcnt(0)
	v_pk_add_f32 v[16:17], v[16:17], v[18:19]
	ds_swizzle_b32 v19, v17 offset:swizzle(SWAP,2)
	ds_swizzle_b32 v18, v16 offset:swizzle(SWAP,2)
	s_waitcnt lgkmcnt(0)
	v_pk_add_f32 v[16:17], v[16:17], v[18:19]
	ds_swizzle_b32 v19, v17 offset:swizzle(SWAP,4)
	ds_swizzle_b32 v18, v16 offset:swizzle(SWAP,4)
	s_waitcnt lgkmcnt(0)
	v_pk_add_f32 v[16:17], v[16:17], v[18:19]
	ds_swizzle_b32 v19, v17 offset:swizzle(SWAP,8)
	ds_swizzle_b32 v18, v16 offset:swizzle(SWAP,8)
	s_waitcnt lgkmcnt(0)
	v_pk_add_f32 v[16:17], v[16:17], v[18:19]
	s_nop 0
	v_pk_fma_f32 v[16:17], v[16:17], s[6:7], v[116:117] op_sel_hi:[1,0,0]
	s_waitcnt vmcnt(47)
	v_mov_b32_e32 v32, v194
	v_lshlrev_b32_e32 v21, 16, v32
	v_mul_f32_e32 v18, 0x4b800000, v17
	v_cmp_gt_f32_e32 vcc, s96, v17
	s_nop 1
	v_cndmask_b32_e32 v17, v17, v18, vcc
	v_mul_f32_e32 v18, 0xbfb8aa3b, v21
	v_exp_f32_e32 v28, v18
	v_rsq_f32_e32 v17, v17
	v_lshl_add_u64 v[18:19], s[60:61], 0, v[26:27]
	v_lshl_add_u64 v[26:27], v[18:19], 0, v[110:111]
	v_add_f32_e32 v28, 1.0, v28
	v_rcp_f32_e32 v28, v28
	v_mul_f32_e32 v29, 0x45800000, v17
	v_cndmask_b32_e32 v17, v17, v29, vcc
	v_mul_f32_e32 v12, v12, v17
	v_mul_f32_e32 v12, v115, v12
	v_mul_f32_e32 v21, v28, v21
	v_mul_f32_e32 v12, v21, v12
	v_cvt_pk_bf16_f32 v12, v12, s0
	global_store_short v[26:27], v12, off offset:1536
	v_mul_f32_e32 v8, v8, v17
	v_mul_f32_e32 v8, v161, v8
	v_mul_f32_e32 v4, v4, v17
	v_mul_f32_e32 v4, v160, v4
	v_mul_f32_e32 v0, v0, v17
	v_mul_f32_e32 v0, v159, v0
	v_lshl_add_u64 v[18:19], v[18:19], 0, v[112:113]
	v_cmp_gt_f32_e32 vcc, s96, v16
	s_waitcnt vmcnt(46)
	v_mov_b32_e32 v12, v195
	v_lshlrev_b32_e32 v12, 16, v12
	v_mul_f32_e32 v21, 0xbfb8aa3b, v12
	v_exp_f32_e32 v21, v21
	s_nop 0
	v_add_f32_e32 v21, 1.0, v21
	v_rcp_f32_e32 v21, v21
	s_nop 0
	v_mul_f32_e32 v12, v21, v12
	v_mul_f32_e32 v8, v12, v8
	v_cvt_pk_bf16_f32 v8, v8, s0
	global_store_short v[26:27], v8, off offset:1568
	s_waitcnt vmcnt(45)
	v_mov_b32_e32 v8, v196
	v_lshlrev_b32_e32 v8, 16, v8
	v_mul_f32_e32 v12, 0xbfb8aa3b, v8
	v_exp_f32_e32 v12, v12
	s_nop 0
	v_add_f32_e32 v12, 1.0, v12
	v_rcp_f32_e32 v12, v12
	s_nop 0
	v_mul_f32_e32 v8, v12, v8
	v_mul_f32_e32 v4, v4, v8
	v_cvt_pk_bf16_f32 v4, v4, s0
	global_store_short v[26:27], v4, off offset:1600
	v_mov_b32_e32 v23, v211
	v_or_b32_e32 v22, 1, v20
	v_lshlrev_b64 v[24:25], 12, v[22:23]
	v_lshl_add_u64 v[24:25], s[58:59], 0, v[24:25]
	v_lshl_add_u64 v[26:27], v[24:25], 0, v[110:111]
	s_waitcnt vmcnt(44)
	v_mov_b32_e32 v4, v197
	v_lshlrev_b32_e32 v4, 16, v4
	v_mul_f32_e32 v8, 0xbfb8aa3b, v4
	v_exp_f32_e32 v8, v8
	s_nop 0
	v_add_f32_e32 v8, 1.0, v8
	v_rcp_f32_e32 v8, v8
	s_nop 0
	v_mul_f32_e32 v4, v8, v4
	v_mul_f32_e32 v0, v0, v4
	v_cvt_pk_bf16_f32 v0, v0, s0
	global_store_short v[18:19], v0, off offset:1536
	v_mul_f32_e32 v4, 0x4b800000, v16
	v_cndmask_b32_e32 v4, v16, v4, vcc
	v_rsq_f32_e32 v4, v4
	v_lshlrev_b64 v[18:19], 11, v[22:23]
	v_lshl_add_u64 v[16:17], s[60:61], 0, v[18:19]
	v_lshl_add_u64 v[18:19], v[16:17], 0, v[110:111]
	v_mul_f32_e32 v12, 0x45800000, v4
	v_cndmask_b32_e32 v21, v4, v12, vcc
	v_mul_f32_e32 v4, v13, v21
	v_mul_f32_e32 v4, v115, v4
	v_mul_f32_e32 v5, v5, v21
	v_mul_f32_e32 v5, v160, v5
	v_lshl_add_u64 v[12:13], v[16:17], 0, v[112:113]
	v_mul_f32_e32 v1, v1, v21
	v_mul_f32_e32 v1, v159, v1
	v_mov_b32_e32 v22, v7
	v_mov_b32_e32 v23, v3
	v_pk_mul_f32 v[22:23], v[22:23], v[22:23]
	s_waitcnt vmcnt(43)
	v_mov_b32_e32 v0, v198
	v_lshlrev_b32_e32 v0, 16, v0
	v_mul_f32_e32 v8, 0xbfb8aa3b, v0
	v_exp_f32_e32 v8, v8
	s_nop 0
	v_add_f32_e32 v8, 1.0, v8
	v_rcp_f32_e32 v8, v8
	s_nop 0
	v_mul_f32_e32 v0, v8, v0
	v_mul_f32_e32 v0, v0, v4
	v_cvt_pk_bf16_f32 v0, v0, s0
	global_store_short v[18:19], v0, off offset:1536
	v_mul_f32_e32 v8, v9, v21
	v_mul_f32_e32 v8, v161, v8
	s_waitcnt vmcnt(42)
	v_mov_b32_e32 v0, v199
	v_lshlrev_b32_e32 v0, 16, v0
	v_mul_f32_e32 v4, 0xbfb8aa3b, v0
	v_exp_f32_e32 v4, v4
	s_nop 0
	v_add_f32_e32 v4, 1.0, v4
	v_rcp_f32_e32 v4, v4
	s_nop 0
	v_mul_f32_e32 v0, v4, v0
	v_mul_f32_e32 v0, v8, v0
	v_cvt_pk_bf16_f32 v0, v0, s0
	global_store_short v[18:19], v0, off offset:1568
	v_lshl_add_u64 v[8:9], v[24:25], 0, v[112:113]
	s_waitcnt vmcnt(41)
; __device__ __forceinline__ unsigned cvtpk(float lo, float hi) { f32x2_t v = {lo, hi}; bf16x2_t b = __builtin_convertvector(v, bf16x2_t); return __builtin_bit_cast(unsigned, b); }
; template <int X> __device__ __forceinline__ float swz_xor(float v) { return __int_as_float(__builtin_amdgcn_ds_swizzle(__float_as_int(v), (X << 10) | 0x1F)); }
; __device__ __forceinline__ float silu_f(float g) { return g * __builtin_amdgcn_rcpf(1.0f + __expf(-g)); }
; template <bool GLA>
; __device__ __forceinline__ void chunk_pass_c(const ChunkIn& ci, const float* wgl, int unit, unsigned char* wl, int lane, const float* Sb, const float* ng, bf16_t* omix) {
;     ...
; #pragma unroll
;         for (int r = 0; r < 4; ++r) {
;             ss[r] += swz_xor<1>(ss[r]); ss[r] += swz_xor<2>(ss[r]); ss[r] += swz_xor<4>(ss[r]); ss[r] += swz_xor<8>(ss[r]);
;             const float rs = rsqrtf(ss[r] * (1.0f / 64.0f) + EPS);
;             const int t = t0 + 16 * it + 4 * kq + r;
; #pragma unroll
;             for (int et = 0; et < 4; ++et) {
;                 const int e = 16 * et + row;
;                 const float gt = __uint_as_float((unsigned)ci.proj[(size_t)t * DINP + gcol + e] << 16);
;                 const float val = o[et][r] * rs * gn[et] * pg8::silu_f(gt);
;                 omix[(size_t)t * 1024 + ocol + e] = (bf16_t)(cvtpk(val, 0.f) & 0xffffu);
;             }
;         }
	v_mov_b32_e32 v0, v200
	v_lshlrev_b32_e32 v0, 16, v0
	v_mul_f32_e32 v4, 0xbfb8aa3b, v0
	v_exp_f32_e32 v4, v4
	s_nop 0
	v_add_f32_e32 v4, 1.0, v4
	v_rcp_f32_e32 v4, v4
	s_nop 0
	v_mul_f32_e32 v0, v4, v0
	v_mul_f32_e32 v0, v5, v0
	v_cvt_pk_bf16_f32 v0, v0, s0
	global_store_short v[18:19], v0, off offset:1600
	v_mov_b32_e32 v5, v211
	v_or_b32_e32 v4, 2, v20
	v_mov_b32_e32 v19, v2
	s_waitcnt vmcnt(40)
	v_mov_b32_e32 v0, v201
	v_lshlrev_b32_e32 v0, 16, v0
	v_mul_f32_e32 v8, 0xbfb8aa3b, v0
	v_exp_f32_e32 v18, v8
	v_lshlrev_b64 v[8:9], 12, v[4:5]
	v_lshl_add_u64 v[8:9], s[58:59], 0, v[8:9]
	v_lshlrev_b64 v[4:5], 11, v[4:5]
	v_add_f32_e32 v16, 1.0, v18
	v_rcp_f32_e32 v18, v16
	v_lshl_add_u64 v[16:17], v[8:9], 0, v[110:111]
	v_lshl_add_u64 v[4:5], s[60:61], 0, v[4:5]
	v_lshl_add_u64 v[8:9], v[8:9], 0, v[112:113]
	v_mul_f32_e32 v0, v18, v0
	v_mul_f32_e32 v0, v1, v0
	v_cvt_pk_bf16_f32 v0, v0, s0
	global_store_short v[12:13], v0, off offset:1536
	v_mov_b32_e32 v0, v14
	v_mov_b32_e32 v1, v10
	v_mov_b32_e32 v12, v15
	v_mov_b32_e32 v13, v11
	v_mov_b32_e32 v18, v6
	v_pk_mul_f32 v[0:1], v[0:1], v[0:1]
	v_pk_mul_f32 v[12:13], v[12:13], v[12:13]
	v_pk_mul_f32 v[18:19], v[18:19], v[18:19]
	v_mov_b32_e32 v24, v12
	v_mov_b32_e32 v25, v0
	v_mov_b32_e32 v0, v13
	v_mov_b32_e32 v12, v22
	v_mov_b32_e32 v13, v18
	v_pk_add_f32 v[0:1], v[24:25], v[0:1]
	v_mov_b32_e32 v18, v23
	v_pk_add_f32 v[0:1], v[0:1], v[12:13]
	s_nop 0
	v_pk_add_f32 v[0:1], v[0:1], v[18:19]
	ds_swizzle_b32 v13, v1 offset:swizzle(SWAP,1)
	ds_swizzle_b32 v12, v0 offset:swizzle(SWAP,1)
	s_waitcnt lgkmcnt(0)
	v_pk_add_f32 v[0:1], v[0:1], v[12:13]
	ds_swizzle_b32 v13, v1 offset:swizzle(SWAP,2)
	ds_swizzle_b32 v12, v0 offset:swizzle(SWAP,2)
	s_waitcnt lgkmcnt(0)
	v_pk_add_f32 v[0:1], v[0:1], v[12:13]
	ds_swizzle_b32 v13, v1 offset:swizzle(SWAP,4)
	ds_swizzle_b32 v12, v0 offset:swizzle(SWAP,4)
	s_waitcnt lgkmcnt(0)
	v_pk_add_f32 v[0:1], v[0:1], v[12:13]
	ds_swizzle_b32 v13, v1 offset:swizzle(SWAP,8)
	ds_swizzle_b32 v12, v0 offset:swizzle(SWAP,8)
	s_waitcnt lgkmcnt(0)
	v_pk_add_f32 v[0:1], v[0:1], v[12:13]
	s_nop 0
	v_pk_fma_f32 v[0:1], v[0:1], s[6:7], v[116:117] op_sel_hi:[1,0,0]
	s_mov_b64 s[6:7], 0
	v_mul_f32_e32 v12, 0x4b800000, v1
	v_cmp_gt_f32_e32 vcc, s96, v1
	s_waitcnt vmcnt(39)
	v_mov_b32_e32 v21, v202
	v_lshlrev_b32_e32 v18, 16, v21
	v_cndmask_b32_e32 v1, v1, v12, vcc
	v_mul_f32_e32 v12, 0xbfb8aa3b, v18
	v_exp_f32_e32 v19, v12
	v_rsq_f32_e32 v1, v1
	v_lshl_add_u64 v[12:13], v[4:5], 0, v[110:111]
	v_lshl_add_u64 v[4:5], v[4:5], 0, v[112:113]
	v_add_f32_e32 v19, 1.0, v19
	v_rcp_f32_e32 v19, v19
	v_mul_f32_e32 v21, 0x45800000, v1
	v_cndmask_b32_e32 v1, v1, v21, vcc
	v_mul_f32_e32 v14, v14, v1
	v_mul_f32_e32 v14, v115, v14
	v_mul_f32_e32 v18, v19, v18
	v_mul_f32_e32 v14, v18, v14
	v_cvt_pk_bf16_f32 v14, v14, s0
	global_store_short v[12:13], v14, off offset:1536
	v_mul_f32_e32 v10, v10, v1
	v_mul_f32_e32 v10, v161, v10
	v_mul_f32_e32 v6, v6, v1
	v_mul_f32_e32 v6, v160, v6
	v_mul_f32_e32 v1, v2, v1
	v_mul_f32_e32 v1, v159, v1
	v_cmp_gt_f32_e32 vcc, s96, v0
	s_waitcnt vmcnt(38)
	v_mov_b32_e32 v14, v203
	v_lshlrev_b32_e32 v14, 16, v14
	v_mul_f32_e32 v18, 0xbfb8aa3b, v14
	v_exp_f32_e32 v18, v18
	s_nop 0
	v_add_f32_e32 v18, 1.0, v18
	v_rcp_f32_e32 v18, v18
	s_nop 0
	v_mul_f32_e32 v14, v18, v14
	v_mul_f32_e32 v10, v10, v14
	v_cvt_pk_bf16_f32 v10, v10, s0
	global_store_short v[12:13], v10, off offset:1568
	s_waitcnt vmcnt(37)
	v_mov_b32_e32 v10, v204
	v_lshlrev_b32_e32 v10, 16, v10
	v_mul_f32_e32 v14, 0xbfb8aa3b, v10
	v_exp_f32_e32 v14, v14
	s_nop 0
	v_add_f32_e32 v14, 1.0, v14
	v_rcp_f32_e32 v14, v14
	s_nop 0
	v_mul_f32_e32 v10, v14, v10
	v_mul_f32_e32 v6, v6, v10
	v_cvt_pk_bf16_f32 v6, v6, s0
	global_store_short v[12:13], v6, off offset:1600
	v_mov_b32_e32 v9, v211
	v_or_b32_e32 v8, 3, v20
	v_lshlrev_b64 v[12:13], 12, v[8:9]
	v_lshl_add_u64 v[12:13], s[58:59], 0, v[12:13]
	v_lshl_add_u64 v[16:17], v[12:13], 0, v[110:111]
	s_waitcnt vmcnt(36)
	v_mov_b32_e32 v6, v205
	v_lshlrev_b32_e32 v6, 16, v6
	v_mul_f32_e32 v10, 0xbfb8aa3b, v6
	v_exp_f32_e32 v10, v10
	s_nop 0
	v_add_f32_e32 v10, 1.0, v10
	v_rcp_f32_e32 v10, v10
	s_nop 0
	v_mul_f32_e32 v2, v10, v6
	v_mul_f32_e32 v1, v1, v2
	v_cvt_pk_bf16_f32 v1, v1, s0
	global_store_short v[4:5], v1, off offset:1536
	v_mul_f32_e32 v2, 0x4b800000, v0
	v_cndmask_b32_e32 v0, v0, v2, vcc
	v_rsq_f32_e32 v2, v0
	v_lshlrev_b64 v[4:5], 11, v[8:9]
	v_mul_f32_e32 v9, 0x45800000, v2
	v_cndmask_b32_e32 v2, v2, v9, vcc
	v_mul_f32_e32 v9, v15, v2
	v_mul_f32_e32 v9, v115, v9
	v_mul_f32_e32 v7, v7, v2
	v_mul_f32_e32 v7, v160, v7
	s_waitcnt vmcnt(35)
	v_mov_b32_e32 v1, v206
	v_lshlrev_b32_e32 v6, 16, v1
	v_mul_f32_e32 v0, 0xbfb8aa3b, v6
	v_exp_f32_e32 v8, v0
	v_lshl_add_u64 v[0:1], s[60:61], 0, v[4:5]
	v_lshl_add_u64 v[4:5], v[0:1], 0, v[110:111]
	v_lshl_add_u64 v[0:1], v[0:1], 0, v[112:113]
	v_add_f32_e32 v8, 1.0, v8
	v_rcp_f32_e32 v8, v8
	s_nop 0
	v_mul_f32_e32 v6, v8, v6
	v_mul_f32_e32 v6, v6, v9
	v_cvt_pk_bf16_f32 v6, v6, s0
	global_store_short v[4:5], v6, off offset:1536
	v_mul_f32_e32 v9, v11, v2
	v_mul_f32_e32 v9, v161, v9
	v_mul_f32_e32 v2, v3, v2
	v_mul_f32_e32 v2, v159, v2
	s_waitcnt vmcnt(34)
	v_mov_b32_e32 v6, v207
	v_lshlrev_b32_e32 v6, 16, v6
	v_mul_f32_e32 v8, 0xbfb8aa3b, v6
	v_exp_f32_e32 v8, v8
	s_nop 0
	v_add_f32_e32 v8, 1.0, v8
	v_rcp_f32_e32 v8, v8
	s_nop 0
	v_mul_f32_e32 v6, v8, v6
	v_mul_f32_e32 v6, v9, v6
	v_cvt_pk_bf16_f32 v6, v6, s0
	global_store_short v[4:5], v6, off offset:1568
	s_waitcnt vmcnt(33)
	v_mov_b32_e32 v6, v208
	v_lshlrev_b32_e32 v6, 16, v6
	v_mul_f32_e32 v8, 0xbfb8aa3b, v6
	v_exp_f32_e32 v8, v8
	s_nop 0
	v_add_f32_e32 v8, 1.0, v8
	v_rcp_f32_e32 v10, v8
	v_lshl_add_u64 v[8:9], v[12:13], 0, v[112:113]
	v_mul_f32_e32 v6, v10, v6
	v_mul_f32_e32 v6, v7, v6
	v_cvt_pk_bf16_f32 v6, v6, s0
	global_store_short v[4:5], v6, off offset:1600
	s_waitcnt vmcnt(32)
	v_mov_b32_e32 v4, v209
	v_lshlrev_b32_e32 v4, 16, v4
	v_mul_f32_e32 v5, 0xbfb8aa3b, v4
	v_exp_f32_e32 v5, v5
	s_nop 0
	v_add_f32_e32 v5, 1.0, v5
	v_rcp_f32_e32 v5, v5
	s_nop 0
	v_mul_f32_e32 v3, v5, v4
	v_mul_f32_e32 v2, v2, v3
	v_cvt_pk_bf16_f32 v2, v2, s0
	global_store_short v[0:1], v2, off offset:1536
	s_waitcnt lgkmcnt(0)
